# Resid GEMM epilogues (6 phases): residual f32 tile loads re-addressed to 8 rows x 128 B full lines per wave load, swapped back with DPP row_ror:8
# baseline (speedup 1.0000x reference)
.LBB0_397:
	ds_read_b128 v[128:131], v187
	ds_read_b128 v[132:135], v188
	ds_read_b128 v[136:139], v189
	ds_read_b128 v[140:143], v190
	s_add_u32 s20, s16, 0xfff50080
	s_addc_u32 s21, s17, -1
	s_cmp_eq_u32 s19, 40
	s_cselect_b32 s57, s13, s21
	s_cselect_b32 s56, s12, s20
	s_cselect_b32 s39, s15, s18
	s_cselect_b32 s38, s14, s37
	s_mov_b32 m0, s90
	v_lshl_add_u64 v[228:229], s[16:17], 0, v[158:159]
	ds_read_b128 v[164:167], v145
	ds_read_b128 v[168:171], v145 offset:1024
	ds_read_b128 v[204:207], v145 offset:2048
	ds_read_b128 v[208:211], v145 offset:3072
	ds_read_b128 v[212:215], v145 offset:4096
	ds_read_b128 v[216:219], v145 offset:5120
	ds_read_b128 v[220:223], v145 offset:6144
	ds_read_b128 v[224:227], v145 offset:7168
	global_load_lds_dwordx4 v[228:229], off
	v_lshl_add_u64 v[228:229], s[16:17], 0, v[156:157]
	s_mov_b32 m0, s91
	s_nop 0
	global_load_lds_dwordx4 v[228:229], off
	s_waitcnt lgkmcnt(8)
	s_barrier
	s_waitcnt lgkmcnt(0)
	s_setprio 1
	s_waitcnt lgkmcnt(0)
	v_mfma_f32_16x16x32_bf16 v[124:127], v[128:131], v[164:167], v[124:127]
	v_mfma_f32_16x16x32_bf16 v[120:123], v[136:139], v[164:167], v[120:123]
	v_mfma_f32_16x16x32_bf16 v[108:111], v[128:131], v[204:207], v[108:111]
	v_mfma_f32_16x16x32_bf16 v[104:107], v[136:139], v[204:207], v[104:107]
	v_mfma_f32_16x16x32_bf16 v[92:95], v[128:131], v[212:215], v[92:95]
	v_mfma_f32_16x16x32_bf16 v[88:91], v[136:139], v[212:215], v[88:91]
	v_mfma_f32_16x16x32_bf16 v[76:79], v[128:131], v[220:223], v[76:79]
	v_mfma_f32_16x16x32_bf16 v[72:75], v[136:139], v[220:223], v[72:75]
	v_mfma_f32_16x16x32_bf16 v[124:127], v[132:135], v[168:171], v[124:127]
	v_mfma_f32_16x16x32_bf16 v[120:123], v[140:143], v[168:171], v[120:123]
	v_mfma_f32_16x16x32_bf16 v[108:111], v[132:135], v[208:211], v[108:111]
	v_mfma_f32_16x16x32_bf16 v[104:107], v[140:143], v[208:211], v[104:107]
	v_mfma_f32_16x16x32_bf16 v[92:95], v[132:135], v[216:219], v[92:95]
	v_mfma_f32_16x16x32_bf16 v[88:91], v[140:143], v[216:219], v[88:91]
	v_mfma_f32_16x16x32_bf16 v[76:79], v[132:135], v[224:227], v[76:79]
	v_mfma_f32_16x16x32_bf16 v[72:75], v[140:143], v[224:227], v[72:75]
	s_setprio 0
	s_barrier
	s_mov_b32 m0, s68
	v_lshl_add_u64 v[244:245], s[38:39], 0, v[146:147]
	ds_read_b128 v[228:231], v191
	ds_read_b128 v[232:235], v192
	ds_read_b128 v[236:239], v193
	ds_read_b128 v[240:243], v194
	global_load_lds_dwordx4 v[244:245], off
	v_lshl_add_u64 v[246:247], s[38:39], 0, v[148:149]
	s_mov_b32 m0, s69
	s_nop 0
	global_load_lds_dwordx4 v[246:247], off
	s_barrier
	s_waitcnt lgkmcnt(0)
	s_setprio 1
	s_waitcnt lgkmcnt(0)
	v_mfma_f32_16x16x32_bf16 v[116:119], v[228:231], v[164:167], v[116:119]
	v_mfma_f32_16x16x32_bf16 v[112:115], v[236:239], v[164:167], v[112:115]
	v_mfma_f32_16x16x32_bf16 v[100:103], v[228:231], v[204:207], v[100:103]
	v_mfma_f32_16x16x32_bf16 v[96:99], v[236:239], v[204:207], v[96:99]
	v_mfma_f32_16x16x32_bf16 v[84:87], v[228:231], v[212:215], v[84:87]
	v_mfma_f32_16x16x32_bf16 v[80:83], v[236:239], v[212:215], v[80:83]
	v_mfma_f32_16x16x32_bf16 v[68:71], v[228:231], v[220:223], v[68:71]
	v_mfma_f32_16x16x32_bf16 v[64:67], v[236:239], v[220:223], v[64:67]
	v_mfma_f32_16x16x32_bf16 v[116:119], v[232:235], v[168:171], v[116:119]
	v_mfma_f32_16x16x32_bf16 v[112:115], v[240:243], v[168:171], v[112:115]
	v_mfma_f32_16x16x32_bf16 v[100:103], v[232:235], v[208:211], v[100:103]
	v_mfma_f32_16x16x32_bf16 v[96:99], v[240:243], v[208:211], v[96:99]
	v_mfma_f32_16x16x32_bf16 v[84:87], v[232:235], v[216:219], v[84:87]
	v_mfma_f32_16x16x32_bf16 v[80:83], v[240:243], v[216:219], v[80:83]
	v_mfma_f32_16x16x32_bf16 v[68:71], v[232:235], v[224:227], v[68:71]
	v_mfma_f32_16x16x32_bf16 v[64:67], v[240:243], v[224:227], v[64:67]
	s_setprio 0
	s_mov_b32 m0, s67
	v_lshl_add_u64 v[248:249], s[56:57], 0, v[146:147]
	s_barrier
	ds_read_b128 v[164:167], v145 offset:16384
	ds_read_b128 v[168:171], v145 offset:17408
	ds_read_b128 v[204:207], v145 offset:18432
	ds_read_b128 v[208:211], v145 offset:19456
	ds_read_b128 v[212:215], v145 offset:20480
	ds_read_b128 v[216:219], v145 offset:21504
	ds_read_b128 v[220:223], v145 offset:22528
	ds_read_b128 v[224:227], v145 offset:23552
	global_load_lds_dwordx4 v[248:249], off
	v_lshl_add_u64 v[250:251], s[56:57], 0, v[148:149]
	s_mov_b32 m0, s70
	s_nop 0
	global_load_lds_dwordx4 v[250:251], off
	s_barrier
	s_waitcnt lgkmcnt(0)
	s_setprio 1
	s_waitcnt lgkmcnt(0)
	v_mfma_f32_16x16x32_bf16 v[60:63], v[128:131], v[164:167], v[60:63]
	v_mfma_f32_16x16x32_bf16 v[56:59], v[136:139], v[164:167], v[56:59]
	v_mfma_f32_16x16x32_bf16 v[44:47], v[128:131], v[204:207], v[44:47]
	v_mfma_f32_16x16x32_bf16 v[40:43], v[136:139], v[204:207], v[40:43]
	v_mfma_f32_16x16x32_bf16 v[28:31], v[128:131], v[212:215], v[28:31]
	v_mfma_f32_16x16x32_bf16 v[24:27], v[136:139], v[212:215], v[24:27]
	v_mfma_f32_16x16x32_bf16 v[12:15], v[128:131], v[220:223], v[12:15]
	v_mfma_f32_16x16x32_bf16 v[8:11], v[136:139], v[220:223], v[8:11]
	v_mfma_f32_16x16x32_bf16 v[60:63], v[132:135], v[168:171], v[60:63]
	v_mfma_f32_16x16x32_bf16 v[56:59], v[140:143], v[168:171], v[56:59]
	v_mfma_f32_16x16x32_bf16 v[44:47], v[132:135], v[208:211], v[44:47]
	v_mfma_f32_16x16x32_bf16 v[40:43], v[140:143], v[208:211], v[40:43]
	v_mfma_f32_16x16x32_bf16 v[28:31], v[132:135], v[216:219], v[28:31]
	v_mfma_f32_16x16x32_bf16 v[24:27], v[140:143], v[216:219], v[24:27]
	v_mfma_f32_16x16x32_bf16 v[12:15], v[132:135], v[224:227], v[12:15]
	v_mfma_f32_16x16x32_bf16 v[8:11], v[140:143], v[224:227], v[8:11]
	s_setprio 0
	s_barrier
	s_add_u32 s20, s38, 0xb0000
	s_addc_u32 s21, s39, 0
	s_mov_b32 m0, s71
	v_lshl_add_u64 v[128:129], s[20:21], 0, v[146:147]
	global_load_lds_dwordx4 v[128:129], off
	v_lshl_add_u64 v[128:129], s[20:21], 0, v[148:149]
	s_mov_b32 m0, s80
	s_nop 0
	global_load_lds_dwordx4 v[128:129], off
	s_waitcnt vmcnt(6)
	s_barrier
	s_setprio 1
	v_mfma_f32_16x16x32_bf16 v[52:55], v[228:231], v[164:167], v[52:55]
	v_mfma_f32_16x16x32_bf16 v[48:51], v[236:239], v[164:167], v[48:51]
	v_mfma_f32_16x16x32_bf16 v[36:39], v[228:231], v[204:207], v[36:39]
	v_mfma_f32_16x16x32_bf16 v[32:35], v[236:239], v[204:207], v[32:35]
	v_mfma_f32_16x16x32_bf16 v[20:23], v[228:231], v[212:215], v[20:23]
	v_mfma_f32_16x16x32_bf16 v[16:19], v[236:239], v[212:215], v[16:19]
	v_mfma_f32_16x16x32_bf16 v[4:7], v[228:231], v[220:223], v[4:7]
	v_mfma_f32_16x16x32_bf16 v[0:3], v[236:239], v[220:223], v[0:3]
	v_mfma_f32_16x16x32_bf16 v[52:55], v[232:235], v[168:171], v[52:55]
	v_mfma_f32_16x16x32_bf16 v[48:51], v[240:243], v[168:171], v[48:51]
	v_mfma_f32_16x16x32_bf16 v[36:39], v[232:235], v[208:211], v[36:39]
	v_mfma_f32_16x16x32_bf16 v[32:35], v[240:243], v[208:211], v[32:35]
	v_mfma_f32_16x16x32_bf16 v[20:23], v[232:235], v[216:219], v[20:23]
	v_mfma_f32_16x16x32_bf16 v[16:19], v[240:243], v[216:219], v[16:19]
	v_mfma_f32_16x16x32_bf16 v[4:7], v[232:235], v[224:227], v[4:7]
	v_mfma_f32_16x16x32_bf16 v[0:3], v[240:243], v[224:227], v[0:3]
	s_setprio 0
	s_barrier
	ds_read_b128 v[128:131], v195
	ds_read_b128 v[132:135], v196
	ds_read_b128 v[136:139], v197
	ds_read_b128 v[140:143], v198
	s_add_u32 s20, s56, 0xb0000
	s_addc_u32 s21, s57, 0
	s_mov_b32 m0, s81
	v_lshl_add_u64 v[228:229], s[20:21], 0, v[146:147]
	ds_read_b128 v[164:167], v145 offset:32768
	ds_read_b128 v[168:171], v145 offset:33792
	ds_read_b128 v[204:207], v145 offset:34816
	ds_read_b128 v[208:211], v145 offset:35840
	ds_read_b128 v[212:215], v145 offset:36864
	ds_read_b128 v[216:219], v145 offset:37888
	ds_read_b128 v[220:223], v145 offset:38912
	ds_read_b128 v[224:227], v145 offset:39936
	global_load_lds_dwordx4 v[228:229], off
	v_lshl_add_u64 v[228:229], s[20:21], 0, v[148:149]
	s_mov_b32 m0, s82
	s_nop 0
	global_load_lds_dwordx4 v[228:229], off
	s_waitcnt lgkmcnt(8)
	s_barrier
	s_waitcnt lgkmcnt(0)
	s_setprio 1
	s_waitcnt lgkmcnt(0)
	v_mfma_f32_16x16x32_bf16 v[124:127], v[128:131], v[164:167], v[124:127]
	v_mfma_f32_16x16x32_bf16 v[120:123], v[136:139], v[164:167], v[120:123]
	v_mfma_f32_16x16x32_bf16 v[108:111], v[128:131], v[204:207], v[108:111]
	v_mfma_f32_16x16x32_bf16 v[104:107], v[136:139], v[204:207], v[104:107]
	v_mfma_f32_16x16x32_bf16 v[92:95], v[128:131], v[212:215], v[92:95]
	v_mfma_f32_16x16x32_bf16 v[88:91], v[136:139], v[212:215], v[88:91]
	v_mfma_f32_16x16x32_bf16 v[76:79], v[128:131], v[220:223], v[76:79]
	v_mfma_f32_16x16x32_bf16 v[72:75], v[136:139], v[220:223], v[72:75]
	v_mfma_f32_16x16x32_bf16 v[124:127], v[132:135], v[168:171], v[124:127]
	v_mfma_f32_16x16x32_bf16 v[120:123], v[140:143], v[168:171], v[120:123]
	v_mfma_f32_16x16x32_bf16 v[108:111], v[132:135], v[208:211], v[108:111]
	v_mfma_f32_16x16x32_bf16 v[104:107], v[140:143], v[208:211], v[104:107]
	v_mfma_f32_16x16x32_bf16 v[92:95], v[132:135], v[216:219], v[92:95]
	v_mfma_f32_16x16x32_bf16 v[88:91], v[140:143], v[216:219], v[88:91]
	v_mfma_f32_16x16x32_bf16 v[76:79], v[132:135], v[224:227], v[76:79]
	v_mfma_f32_16x16x32_bf16 v[72:75], v[140:143], v[224:227], v[72:75]
	s_setprio 0
	s_barrier
	s_mov_b32 m0, s84
	v_lshl_add_u64 v[244:245], v[244:245], 0, s[4:5]
	ds_read_b128 v[228:231], v199
	ds_read_b128 v[232:235], v200
	ds_read_b128 v[236:239], v201
	ds_read_b128 v[240:243], v202
	global_load_lds_dwordx4 v[244:245], off
	v_lshl_add_u64 v[244:245], v[246:247], 0, s[4:5]
	s_mov_b32 m0, s85
	s_nop 0
	global_load_lds_dwordx4 v[244:245], off
	s_barrier
	s_waitcnt lgkmcnt(0)
	s_setprio 1
	s_waitcnt lgkmcnt(0)
	v_mfma_f32_16x16x32_bf16 v[116:119], v[228:231], v[164:167], v[116:119]
	v_mfma_f32_16x16x32_bf16 v[112:115], v[236:239], v[164:167], v[112:115]
	v_mfma_f32_16x16x32_bf16 v[100:103], v[228:231], v[204:207], v[100:103]
	v_mfma_f32_16x16x32_bf16 v[96:99], v[236:239], v[204:207], v[96:99]
	v_mfma_f32_16x16x32_bf16 v[84:87], v[228:231], v[212:215], v[84:87]
	v_mfma_f32_16x16x32_bf16 v[80:83], v[236:239], v[212:215], v[80:83]
	v_mfma_f32_16x16x32_bf16 v[68:71], v[228:231], v[220:223], v[68:71]
	v_mfma_f32_16x16x32_bf16 v[64:67], v[236:239], v[220:223], v[64:67]
	v_mfma_f32_16x16x32_bf16 v[116:119], v[232:235], v[168:171], v[116:119]
	v_mfma_f32_16x16x32_bf16 v[112:115], v[240:243], v[168:171], v[112:115]
	v_mfma_f32_16x16x32_bf16 v[100:103], v[232:235], v[208:211], v[100:103]
	v_mfma_f32_16x16x32_bf16 v[96:99], v[240:243], v[208:211], v[96:99]
	v_mfma_f32_16x16x32_bf16 v[84:87], v[232:235], v[216:219], v[84:87]
	v_mfma_f32_16x16x32_bf16 v[80:83], v[240:243], v[216:219], v[80:83]
	v_mfma_f32_16x16x32_bf16 v[68:71], v[232:235], v[224:227], v[68:71]
	v_mfma_f32_16x16x32_bf16 v[64:67], v[240:243], v[224:227], v[64:67]
	s_setprio 0
	s_mov_b32 m0, s86
	v_lshl_add_u64 v[244:245], v[248:249], 0, s[4:5]
	s_barrier
	ds_read_b128 v[164:167], v145 offset:49152
	ds_read_b128 v[168:171], v145 offset:50176
	ds_read_b128 v[204:207], v145 offset:51200
	ds_read_b128 v[208:211], v145 offset:52224
	ds_read_b128 v[212:215], v145 offset:53248
	ds_read_b128 v[216:219], v145 offset:54272
	ds_read_b128 v[220:223], v145 offset:55296
	ds_read_b128 v[224:227], v145 offset:56320
	global_load_lds_dwordx4 v[244:245], off
	v_lshl_add_u64 v[244:245], v[250:251], 0, s[4:5]
	s_mov_b32 m0, s87
	s_nop 0
	global_load_lds_dwordx4 v[244:245], off
	s_barrier
	s_waitcnt lgkmcnt(0)
	s_setprio 1
	s_waitcnt lgkmcnt(0)
	v_mfma_f32_16x16x32_bf16 v[60:63], v[128:131], v[164:167], v[60:63]
	v_mfma_f32_16x16x32_bf16 v[56:59], v[136:139], v[164:167], v[56:59]
	v_mfma_f32_16x16x32_bf16 v[44:47], v[128:131], v[204:207], v[44:47]
	v_mfma_f32_16x16x32_bf16 v[40:43], v[136:139], v[204:207], v[40:43]
	v_mfma_f32_16x16x32_bf16 v[28:31], v[128:131], v[212:215], v[28:31]
	v_mfma_f32_16x16x32_bf16 v[24:27], v[136:139], v[212:215], v[24:27]
	v_mfma_f32_16x16x32_bf16 v[12:15], v[128:131], v[220:223], v[12:15]
	v_mfma_f32_16x16x32_bf16 v[8:11], v[136:139], v[220:223], v[8:11]
	v_mfma_f32_16x16x32_bf16 v[60:63], v[132:135], v[168:171], v[60:63]
	v_mfma_f32_16x16x32_bf16 v[56:59], v[140:143], v[168:171], v[56:59]
	v_mfma_f32_16x16x32_bf16 v[44:47], v[132:135], v[208:211], v[44:47]
	v_mfma_f32_16x16x32_bf16 v[40:43], v[140:143], v[208:211], v[40:43]
	v_mfma_f32_16x16x32_bf16 v[28:31], v[132:135], v[216:219], v[28:31]
	v_mfma_f32_16x16x32_bf16 v[24:27], v[140:143], v[216:219], v[24:27]
	v_mfma_f32_16x16x32_bf16 v[12:15], v[132:135], v[224:227], v[12:15]
	v_mfma_f32_16x16x32_bf16 v[8:11], v[140:143], v[224:227], v[8:11]
	s_setprio 0
	s_barrier
	s_add_u32 s20, s38, 0xb0080
	s_addc_u32 s21, s39, 0
	s_mov_b32 m0, s88
	v_lshl_add_u64 v[128:129], s[20:21], 0, v[146:147]
	global_load_lds_dwordx4 v[128:129], off
	v_lshl_add_u64 v[128:129], s[20:21], 0, v[148:149]
	s_mov_b32 m0, s89
	s_nop 0
	global_load_lds_dwordx4 v[128:129], off
	s_waitcnt vmcnt(6)
	s_barrier
	s_setprio 1
	v_mfma_f32_16x16x32_bf16 v[52:55], v[228:231], v[164:167], v[52:55]
	v_mfma_f32_16x16x32_bf16 v[48:51], v[236:239], v[164:167], v[48:51]
	v_mfma_f32_16x16x32_bf16 v[36:39], v[228:231], v[204:207], v[36:39]
	v_mfma_f32_16x16x32_bf16 v[32:35], v[236:239], v[204:207], v[32:35]
	v_mfma_f32_16x16x32_bf16 v[20:23], v[228:231], v[212:215], v[20:23]
	v_mfma_f32_16x16x32_bf16 v[16:19], v[236:239], v[212:215], v[16:19]
	v_mfma_f32_16x16x32_bf16 v[4:7], v[228:231], v[220:223], v[4:7]
	v_mfma_f32_16x16x32_bf16 v[0:3], v[236:239], v[220:223], v[0:3]
	v_mfma_f32_16x16x32_bf16 v[52:55], v[232:235], v[168:171], v[52:55]
	v_mfma_f32_16x16x32_bf16 v[48:51], v[240:243], v[168:171], v[48:51]
	v_mfma_f32_16x16x32_bf16 v[36:39], v[232:235], v[208:211], v[36:39]
	v_mfma_f32_16x16x32_bf16 v[32:35], v[240:243], v[208:211], v[32:35]
	v_mfma_f32_16x16x32_bf16 v[20:23], v[232:235], v[216:219], v[20:23]
	v_mfma_f32_16x16x32_bf16 v[16:19], v[240:243], v[216:219], v[16:19]
	v_mfma_f32_16x16x32_bf16 v[4:7], v[232:235], v[224:227], v[4:7]
	v_mfma_f32_16x16x32_bf16 v[0:3], v[240:243], v[224:227], v[0:3]
	s_setprio 0
	s_add_i32 s19, s19, 2
	s_add_u32 s37, s37, 0x100
	s_addc_u32 s18, s18, 0
	s_add_u32 s16, s16, 0x100
	s_addc_u32 s17, s17, 0
	s_cmp_gt_u32 s19, 41
	s_barrier
	s_cbranch_scc0 .LBB0_397
	v_bfe_i32 v249, v176, 3, 1
	v_and_b32_e32 v248, 0xffff8040, v249
	v_mov_b32_e32 v250, 0x8000
	v_mov_b32_e32 v251, 0
	s_ashr_i32 s37, s36, 31
	s_lshl_b64 s[16:17], s[36:37], 8
	s_lshl_b32 s18, s6, 8
	v_lshl_add_u64 v[166:167], s[16:17], 0, v[150:151]
	s_ashr_i32 s19, s18, 31
	v_lshl_add_u64 v[168:169], s[18:19], 2, v[154:155]
	v_lshlrev_b64 v[128:129], 12, v[166:167]
	v_lshl_add_u64 v[128:129], v[168:169], 0, v[128:129]
	v_lshl_add_u64 v[232:233], v[128:129], 0, v[248:249]
	v_lshl_add_u64 v[234:235], v[232:233], 0, v[250:251]
	global_load_dwordx4 v[204:207], v[232:233], off
	global_load_dwordx4 v[208:211], v[234:235], off
	global_load_dwordx4 v[212:215], v[232:233], off offset:512
	global_load_dwordx4 v[216:219], v[234:235], off offset:512
	v_or_b32_e32 v170, 16, v166
	v_mov_b32_e32 v171, v167
	v_lshlrev_b64 v[128:129], 12, v[170:171]
	v_lshl_add_u64 v[128:129], v[168:169], 0, v[128:129]
	v_lshl_add_u64 v[236:237], v[128:129], 0, v[248:249]
	v_lshl_add_u64 v[238:239], v[236:237], 0, v[250:251]
	global_load_dwordx4 v[140:143], v[236:237], off
	global_load_dwordx4 v[136:139], v[238:239], off
	global_load_dwordx4 v[132:135], v[236:237], off offset:512
	s_nop 0
	global_load_dwordx4 v[128:131], v[238:239], off offset:512
	v_mov_b32_e32 v165, s19
	v_or_b32_e32 v164, s18, v152
	v_lshlrev_b64 v[220:221], 10, v[166:167]
	v_lshl_add_u64 v[220:221], v[220:221], 0, v[164:165]
	s_waitcnt vmcnt(0)
	s_lshl_b32 s16, s6, 2
	s_ashr_i32 s17, s16, 31
	s_waitcnt vmcnt(0)
	v_mov_b32_dpp v224, v204 row_ror:8 row_mask:0xf bank_mask:0xf
	v_mov_b32_dpp v225, v205 row_ror:8 row_mask:0xf bank_mask:0xf
	v_mov_b32_dpp v226, v206 row_ror:8 row_mask:0xf bank_mask:0xf
	v_mov_b32_dpp v227, v207 row_ror:8 row_mask:0xf bank_mask:0xf
	v_mov_b32_dpp v204, v208 row_ror:8 row_mask:0xf bank_mask:0xc
	v_mov_b32_dpp v205, v209 row_ror:8 row_mask:0xf bank_mask:0xc
	v_mov_b32_dpp v206, v210 row_ror:8 row_mask:0xf bank_mask:0xc
	v_mov_b32_dpp v207, v211 row_ror:8 row_mask:0xf bank_mask:0xc
	v_mov_b32_dpp v208, v224 quad_perm:[0,1,2,3] row_mask:0xf bank_mask:0x3
	v_mov_b32_dpp v209, v225 quad_perm:[0,1,2,3] row_mask:0xf bank_mask:0x3
	v_mov_b32_dpp v210, v226 quad_perm:[0,1,2,3] row_mask:0xf bank_mask:0x3
	v_mov_b32_dpp v211, v227 quad_perm:[0,1,2,3] row_mask:0xf bank_mask:0x3
	v_mov_b32_dpp v224, v212 row_ror:8 row_mask:0xf bank_mask:0xf
	v_mov_b32_dpp v225, v213 row_ror:8 row_mask:0xf bank_mask:0xf
	v_mov_b32_dpp v226, v214 row_ror:8 row_mask:0xf bank_mask:0xf
	v_mov_b32_dpp v227, v215 row_ror:8 row_mask:0xf bank_mask:0xf
	v_mov_b32_dpp v212, v216 row_ror:8 row_mask:0xf bank_mask:0xc
	v_mov_b32_dpp v213, v217 row_ror:8 row_mask:0xf bank_mask:0xc
	v_mov_b32_dpp v214, v218 row_ror:8 row_mask:0xf bank_mask:0xc
	v_mov_b32_dpp v215, v219 row_ror:8 row_mask:0xf bank_mask:0xc
	v_mov_b32_dpp v216, v224 quad_perm:[0,1,2,3] row_mask:0xf bank_mask:0x3
	v_mov_b32_dpp v217, v225 quad_perm:[0,1,2,3] row_mask:0xf bank_mask:0x3
	v_mov_b32_dpp v218, v226 quad_perm:[0,1,2,3] row_mask:0xf bank_mask:0x3
	v_mov_b32_dpp v219, v227 quad_perm:[0,1,2,3] row_mask:0xf bank_mask:0x3
	v_pk_fma_f32 v[126:127], v[126:127], 0.5, v[206:207] op_sel_hi:[1,0,1]
	v_lshlrev_b64 v[206:207], 1, v[220:221]
	v_pk_fma_f32 v[124:125], v[124:125], 0.5, v[204:205] op_sel_hi:[1,0,1]
	v_lshl_add_u64 v[204:205], v[220:221], 2, s[78:79]
	v_lshl_add_u64 v[220:221], s[0:1], 0, v[206:207]
	global_store_dwordx4 v[204:205], v[124:127], off
	v_cvt_pk_bf16_f32 v222, v124, v125
	v_cvt_pk_bf16_f32 v223, v126, v127
	v_bfe_u32 v246, v176, 4, 1
	v_mul_u32_u24_e32 v246, 24, v246
	v_mov_b32_e32 v247, 0
	s_nop 1
	v_mov_b32_e32 v240, v222
	v_mov_b32_e32 v241, v223
	v_lshl_add_u64 v[244:245], v[220:221], 0, v[246:247]
	v_mul_f32_e32 v220, v124, v124
	v_fmac_f32_e32 v220, v125, v125
	v_pk_fma_f32 v[122:123], v[122:123], 0.5, v[210:211] op_sel_hi:[1,0,1]
	v_pk_fma_f32 v[120:121], v[120:121], 0.5, v[208:209] op_sel_hi:[1,0,1]
	v_fmac_f32_e32 v220, v126, v126
	global_store_dwordx4 v[204:205], v[120:123], off offset:64
	v_cvt_pk_bf16_f32 v126, v120, v121
	v_or_b32_e32 v124, 32, v206
	v_mov_b32_e32 v125, v207
	v_mul_f32_e32 v120, v120, v120
	v_fmac_f32_e32 v120, v121, v121
	v_fmac_f32_e32 v120, v122, v122
	v_fmac_f32_e32 v220, v127, v127
	v_lshl_add_u64 v[124:125], s[0:1], 0, v[124:125]
	v_fmac_f32_e32 v120, v123, v123
	v_pk_fma_f32 v[118:119], v[118:119], 0.5, v[214:215] op_sel_hi:[1,0,1]
	v_pk_fma_f32 v[116:117], v[116:117], 0.5, v[212:213] op_sel_hi:[1,0,1]
	v_cvt_pk_bf16_f32 v127, v122, v123
	v_mov_b32_e32 v242, v126
	v_mov_b32_e32 v243, v127
	s_nop 1
	v_permlane16_swap_b32 v240, v242
	v_permlane16_swap_b32 v241, v243
	global_store_dwordx4 v[244:245], v[240:243], off
	v_add_f32_e32 v124, v220, v120
	global_store_dwordx4 v[204:205], v[116:119], off offset:512
	v_or_b32_e32 v120, 0x100, v206
	v_mov_b32_e32 v121, v207
	v_cvt_pk_bf16_f32 v122, v116, v117
	v_mul_f32_e32 v116, v116, v116
	v_lshl_add_u64 v[120:121], s[0:1], 0, v[120:121]
	v_fmac_f32_e32 v116, v117, v117
	v_pk_fma_f32 v[114:115], v[114:115], 0.5, v[218:219] op_sel_hi:[1,0,1]
	v_pk_fma_f32 v[112:113], v[112:113], 0.5, v[216:217] op_sel_hi:[1,0,1]
	v_cvt_pk_bf16_f32 v123, v118, v119
	s_nop 1
	v_mov_b32_e32 v240, v122
	v_mov_b32_e32 v241, v123
	v_lshl_add_u64 v[244:245], v[120:121], 0, v[246:247]
	v_fmac_f32_e32 v116, v118, v118
	global_store_dwordx4 v[204:205], v[112:115], off offset:576
	v_cvt_pk_bf16_f32 v118, v112, v113
	v_fmac_f32_e32 v116, v119, v119
	v_cvt_pk_bf16_f32 v119, v114, v115
	v_or_b32_e32 v206, 0x120, v206
	v_mul_f32_e32 v112, v112, v112
	v_fmac_f32_e32 v112, v113, v113
	v_fmac_f32_e32 v112, v114, v114
	v_and_b32_e32 v114, 64, v203
	v_xor_b32_e32 v113, 16, v203
	v_add_u32_e32 v114, 64, v114
	v_cmp_lt_i32_e32 vcc, v113, v114
	v_add_f32_e32 v120, v124, v116
	v_lshl_add_u64 v[116:117], s[0:1], 0, v[206:207]
	v_fmac_f32_e32 v112, v115, v115
	v_cndmask_b32_e32 v113, v203, v113, vcc
	v_mov_b32_e32 v242, v118
	v_mov_b32_e32 v243, v119
	s_nop 1
	v_permlane16_swap_b32 v240, v242
	v_permlane16_swap_b32 v241, v243
	global_store_dwordx4 v[244:245], v[240:243], off
	v_add_f32_e32 v112, v120, v112
	v_lshlrev_b32_e32 v116, 2, v113
	ds_bpermute_b32 v113, v116, v112
	s_waitcnt lgkmcnt(0)
	v_add_f32_e32 v112, v112, v113
	v_xor_b32_e32 v113, 32, v203
	v_cmp_lt_i32_e32 vcc, v113, v114
	s_nop 1
	v_cndmask_b32_e32 v113, v203, v113, vcc
	v_lshlrev_b32_e32 v117, 2, v113
	ds_bpermute_b32 v113, v117, v112
	s_and_saveexec_b64 s[36:37], s[8:9]
	s_cbranch_execz .LBB0_400
	v_lshlrev_b64 v[114:115], 6, v[166:167]
	v_lshl_add_u64 v[114:115], s[2:3], 0, v[114:115]
	v_lshl_add_u64 v[114:115], s[16:17], 2, v[114:115]
	s_lshl_b32 s6, s83, 2
	v_lshl_add_u64 v[114:115], v[114:115], 0, s[6:7]
	s_waitcnt lgkmcnt(0)
	v_add_f32_e32 v112, v112, v113
	flat_store_dword v[114:115], v112
.LBB0_400:
	s_or_b64 exec, exec, s[36:37]
	s_waitcnt lgkmcnt(0)
	v_lshlrev_b64 v[112:113], 10, v[170:171]
	v_lshl_add_u64 v[112:113], v[112:113], 0, v[164:165]
	v_lshl_add_u64 v[114:115], v[112:113], 2, s[78:79]
	v_lshlrev_b64 v[112:113], 1, v[112:113]
	v_mov_b32_dpp v224, v140 row_ror:8 row_mask:0xf bank_mask:0xf
	v_mov_b32_dpp v225, v141 row_ror:8 row_mask:0xf bank_mask:0xf
	v_mov_b32_dpp v226, v142 row_ror:8 row_mask:0xf bank_mask:0xf
	v_mov_b32_dpp v227, v143 row_ror:8 row_mask:0xf bank_mask:0xf
	v_mov_b32_dpp v140, v136 row_ror:8 row_mask:0xf bank_mask:0xc
	v_mov_b32_dpp v141, v137 row_ror:8 row_mask:0xf bank_mask:0xc
	v_mov_b32_dpp v142, v138 row_ror:8 row_mask:0xf bank_mask:0xc
	v_mov_b32_dpp v143, v139 row_ror:8 row_mask:0xf bank_mask:0xc
	v_mov_b32_dpp v136, v224 quad_perm:[0,1,2,3] row_mask:0xf bank_mask:0x3
	v_mov_b32_dpp v137, v225 quad_perm:[0,1,2,3] row_mask:0xf bank_mask:0x3
	v_mov_b32_dpp v138, v226 quad_perm:[0,1,2,3] row_mask:0xf bank_mask:0x3
	v_mov_b32_dpp v139, v227 quad_perm:[0,1,2,3] row_mask:0xf bank_mask:0x3
	v_mov_b32_dpp v224, v132 row_ror:8 row_mask:0xf bank_mask:0xf
	v_mov_b32_dpp v225, v133 row_ror:8 row_mask:0xf bank_mask:0xf
	v_mov_b32_dpp v226, v134 row_ror:8 row_mask:0xf bank_mask:0xf
	v_mov_b32_dpp v227, v135 row_ror:8 row_mask:0xf bank_mask:0xf
	v_mov_b32_dpp v132, v128 row_ror:8 row_mask:0xf bank_mask:0xc
	v_mov_b32_dpp v133, v129 row_ror:8 row_mask:0xf bank_mask:0xc
	v_mov_b32_dpp v134, v130 row_ror:8 row_mask:0xf bank_mask:0xc
	v_mov_b32_dpp v135, v131 row_ror:8 row_mask:0xf bank_mask:0xc
	v_mov_b32_dpp v128, v224 quad_perm:[0,1,2,3] row_mask:0xf bank_mask:0x3
	v_mov_b32_dpp v129, v225 quad_perm:[0,1,2,3] row_mask:0xf bank_mask:0x3
	v_mov_b32_dpp v130, v226 quad_perm:[0,1,2,3] row_mask:0xf bank_mask:0x3
	v_mov_b32_dpp v131, v227 quad_perm:[0,1,2,3] row_mask:0xf bank_mask:0x3
	v_pk_fma_f32 v[110:111], v[110:111], 0.5, v[142:143] op_sel_hi:[1,0,1]
	v_pk_fma_f32 v[108:109], v[108:109], 0.5, v[140:141] op_sel_hi:[1,0,1]
	v_lshl_add_u64 v[118:119], s[0:1], 0, v[112:113]
	global_store_dwordx4 v[114:115], v[108:111], off
	v_cvt_pk_bf16_f32 v120, v108, v109
	v_cvt_pk_bf16_f32 v121, v110, v111
	s_nop 1
	v_mov_b32_e32 v240, v120
	v_mov_b32_e32 v241, v121
	v_lshl_add_u64 v[244:245], v[118:119], 0, v[246:247]
	v_mul_f32_e32 v118, v108, v108
	v_fmac_f32_e32 v118, v109, v109
	v_pk_fma_f32 v[106:107], v[106:107], 0.5, v[138:139] op_sel_hi:[1,0,1]
	v_pk_fma_f32 v[104:105], v[104:105], 0.5, v[136:137] op_sel_hi:[1,0,1]
	v_fmac_f32_e32 v118, v110, v110
	global_store_dwordx4 v[114:115], v[104:107], off offset:64
	v_or_b32_e32 v108, 32, v112
	v_mov_b32_e32 v109, v113
	v_cvt_pk_bf16_f32 v110, v104, v105
	v_mul_f32_e32 v104, v104, v104
	v_lshl_add_u64 v[108:109], s[0:1], 0, v[108:109]
	v_fmac_f32_e32 v104, v105, v105
	v_pk_fma_f32 v[102:103], v[102:103], 0.5, v[134:135] op_sel_hi:[1,0,1]
	v_pk_fma_f32 v[100:101], v[100:101], 0.5, v[132:133] op_sel_hi:[1,0,1]
	v_fmac_f32_e32 v118, v111, v111
	v_cvt_pk_bf16_f32 v111, v106, v107
	v_mov_b32_e32 v242, v110
	v_mov_b32_e32 v243, v111
	s_nop 1
	v_permlane16_swap_b32 v240, v242
	v_permlane16_swap_b32 v241, v243
	global_store_dwordx4 v[244:245], v[240:243], off
	v_fmac_f32_e32 v104, v106, v106
	global_store_dwordx4 v[114:115], v[100:103], off offset:512
	v_cvt_pk_bf16_f32 v106, v100, v101
	v_fmac_f32_e32 v104, v107, v107
	v_add_f32_e32 v107, v118, v104
	v_mul_f32_e32 v100, v100, v100
	v_fmac_f32_e32 v100, v101, v101
	v_fmac_f32_e32 v100, v102, v102
	v_fmac_f32_e32 v100, v103, v103
	v_add_f32_e32 v107, v107, v100
	v_pk_fma_f32 v[100:101], v[98:99], 0.5, v[130:131] op_sel_hi:[1,0,1]
	v_pk_fma_f32 v[98:99], v[96:97], 0.5, v[128:129] op_sel_hi:[1,0,1]
	v_or_b32_e32 v104, 0x100, v112
	v_mul_f32_e32 v96, v98, v98
	v_fmac_f32_e32 v96, v99, v99
	v_fmac_f32_e32 v96, v100, v100
	v_fmac_f32_e32 v96, v101, v101
	v_add_f32_e32 v96, v107, v96
	ds_bpermute_b32 v97, v116, v96
	v_mov_b32_e32 v105, v113
	v_or_b32_e32 v112, 0x120, v112
	v_lshl_add_u64 v[104:105], s[0:1], 0, v[104:105]
	v_cvt_pk_bf16_f32 v107, v102, v103
	s_waitcnt lgkmcnt(0)
	v_add_f32_e32 v96, v96, v97
	ds_bpermute_b32 v97, v117, v96
	v_lshl_add_u64 v[102:103], s[0:1], 0, v[112:113]
	s_nop 1
	v_mov_b32_e32 v240, v106
	v_mov_b32_e32 v241, v107
	v_lshl_add_u64 v[244:245], v[104:105], 0, v[246:247]
	global_store_dwordx4 v[114:115], v[98:101], off offset:576
	s_nop 1
	v_cvt_pk_bf16_f32 v98, v98, v99
	v_cvt_pk_bf16_f32 v99, v100, v101
	v_mov_b32_e32 v242, v98
	v_mov_b32_e32 v243, v99
	s_nop 1
	v_permlane16_swap_b32 v240, v242
	v_permlane16_swap_b32 v241, v243
	global_store_dwordx4 v[244:245], v[240:243], off
	s_and_saveexec_b64 s[36:37], s[8:9]
	s_cbranch_execz .LBB0_402
	v_lshlrev_b64 v[98:99], 6, v[170:171]
	v_lshl_add_u64 v[98:99], s[2:3], 0, v[98:99]
	v_lshl_add_u64 v[98:99], s[16:17], 2, v[98:99]
	s_lshl_b32 s6, s83, 2
	v_lshl_add_u64 v[98:99], v[98:99], 0, s[6:7]
	s_waitcnt lgkmcnt(0)
	v_add_f32_e32 v96, v96, v97
	flat_store_dword v[98:99], v96
.LBB0_402:
	s_or_b64 exec, exec, s[36:37]
	v_or_b32_e32 v114, 32, v166
	v_mov_b32_e32 v115, v167
	s_waitcnt lgkmcnt(0)
	v_lshlrev_b64 v[96:97], 12, v[114:115]
	v_lshl_add_u64 v[96:97], v[168:169], 0, v[96:97]
	v_lshl_add_u64 v[232:233], v[96:97], 0, v[248:249]
	v_lshl_add_u64 v[234:235], v[232:233], 0, v[250:251]
	global_load_dwordx4 v[118:121], v[232:233], off
	global_load_dwordx4 v[122:125], v[234:235], off
	global_load_dwordx4 v[126:129], v[232:233], off offset:512
	global_load_dwordx4 v[130:133], v[234:235], off offset:512
	v_or_b32_e32 v112, 48, v166
	v_mov_b32_e32 v113, v167
	v_lshlrev_b64 v[96:97], 12, v[112:113]
	v_lshl_add_u64 v[96:97], v[168:169], 0, v[96:97]
	v_lshl_add_u64 v[236:237], v[96:97], 0, v[248:249]
	v_lshl_add_u64 v[238:239], v[236:237], 0, v[250:251]
	global_load_dwordx4 v[108:111], v[236:237], off
	global_load_dwordx4 v[104:107], v[238:239], off
	global_load_dwordx4 v[100:103], v[236:237], off offset:512
	s_nop 0
	global_load_dwordx4 v[96:99], v[238:239], off offset:512
	v_lshlrev_b64 v[134:135], 10, v[114:115]
	v_lshl_add_u64 v[134:135], v[134:135], 0, v[164:165]
	s_waitcnt vmcnt(0)
	s_waitcnt vmcnt(0)
	v_mov_b32_dpp v224, v118 row_ror:8 row_mask:0xf bank_mask:0xf
	v_mov_b32_dpp v225, v119 row_ror:8 row_mask:0xf bank_mask:0xf
	v_mov_b32_dpp v226, v120 row_ror:8 row_mask:0xf bank_mask:0xf
	v_mov_b32_dpp v227, v121 row_ror:8 row_mask:0xf bank_mask:0xf
	v_mov_b32_dpp v118, v122 row_ror:8 row_mask:0xf bank_mask:0xc
	v_mov_b32_dpp v119, v123 row_ror:8 row_mask:0xf bank_mask:0xc
	v_mov_b32_dpp v120, v124 row_ror:8 row_mask:0xf bank_mask:0xc
	v_mov_b32_dpp v121, v125 row_ror:8 row_mask:0xf bank_mask:0xc
	v_mov_b32_dpp v122, v224 quad_perm:[0,1,2,3] row_mask:0xf bank_mask:0x3
	v_mov_b32_dpp v123, v225 quad_perm:[0,1,2,3] row_mask:0xf bank_mask:0x3
	v_mov_b32_dpp v124, v226 quad_perm:[0,1,2,3] row_mask:0xf bank_mask:0x3
	v_mov_b32_dpp v125, v227 quad_perm:[0,1,2,3] row_mask:0xf bank_mask:0x3
	v_mov_b32_dpp v224, v126 row_ror:8 row_mask:0xf bank_mask:0xf
	v_mov_b32_dpp v225, v127 row_ror:8 row_mask:0xf bank_mask:0xf
	v_mov_b32_dpp v226, v128 row_ror:8 row_mask:0xf bank_mask:0xf
	v_mov_b32_dpp v227, v129 row_ror:8 row_mask:0xf bank_mask:0xf
	v_mov_b32_dpp v126, v130 row_ror:8 row_mask:0xf bank_mask:0xc
	v_mov_b32_dpp v127, v131 row_ror:8 row_mask:0xf bank_mask:0xc
	v_mov_b32_dpp v128, v132 row_ror:8 row_mask:0xf bank_mask:0xc
	v_mov_b32_dpp v129, v133 row_ror:8 row_mask:0xf bank_mask:0xc
	v_mov_b32_dpp v130, v224 quad_perm:[0,1,2,3] row_mask:0xf bank_mask:0x3
	v_mov_b32_dpp v131, v225 quad_perm:[0,1,2,3] row_mask:0xf bank_mask:0x3
	v_mov_b32_dpp v132, v226 quad_perm:[0,1,2,3] row_mask:0xf bank_mask:0x3
	v_mov_b32_dpp v133, v227 quad_perm:[0,1,2,3] row_mask:0xf bank_mask:0x3
	v_pk_fma_f32 v[94:95], v[94:95], 0.5, v[120:121] op_sel_hi:[1,0,1]
	v_lshlrev_b64 v[120:121], 1, v[134:135]
	v_pk_fma_f32 v[92:93], v[92:93], 0.5, v[118:119] op_sel_hi:[1,0,1]
	v_lshl_add_u64 v[118:119], v[134:135], 2, s[78:79]
	v_lshl_add_u64 v[134:135], s[0:1], 0, v[120:121]
	global_store_dwordx4 v[118:119], v[92:95], off
	v_cvt_pk_bf16_f32 v136, v92, v93
	v_cvt_pk_bf16_f32 v137, v94, v95
	s_nop 1
	v_mov_b32_e32 v240, v136
	v_mov_b32_e32 v241, v137
	v_lshl_add_u64 v[244:245], v[134:135], 0, v[246:247]
	v_mul_f32_e32 v134, v92, v92
	v_fmac_f32_e32 v134, v93, v93
	v_pk_fma_f32 v[90:91], v[90:91], 0.5, v[124:125] op_sel_hi:[1,0,1]
	v_pk_fma_f32 v[88:89], v[88:89], 0.5, v[122:123] op_sel_hi:[1,0,1]
	v_fmac_f32_e32 v134, v94, v94
	global_store_dwordx4 v[118:119], v[88:91], off offset:64
	v_cvt_pk_bf16_f32 v94, v88, v89
	v_or_b32_e32 v92, 32, v120
	v_mov_b32_e32 v93, v121
	v_mul_f32_e32 v88, v88, v88
	v_fmac_f32_e32 v88, v89, v89
	v_fmac_f32_e32 v88, v90, v90
	v_fmac_f32_e32 v134, v95, v95
	v_lshl_add_u64 v[92:93], s[0:1], 0, v[92:93]
	v_fmac_f32_e32 v88, v91, v91
	v_pk_fma_f32 v[86:87], v[86:87], 0.5, v[128:129] op_sel_hi:[1,0,1]
	v_pk_fma_f32 v[84:85], v[84:85], 0.5, v[126:127] op_sel_hi:[1,0,1]
	v_cvt_pk_bf16_f32 v95, v90, v91
	v_mov_b32_e32 v242, v94
	v_mov_b32_e32 v243, v95
	s_nop 1
	v_permlane16_swap_b32 v240, v242
	v_permlane16_swap_b32 v241, v243
	global_store_dwordx4 v[244:245], v[240:243], off
	v_add_f32_e32 v92, v134, v88
	global_store_dwordx4 v[118:119], v[84:87], off offset:512
	v_or_b32_e32 v88, 0x100, v120
	v_mov_b32_e32 v89, v121
	v_cvt_pk_bf16_f32 v90, v84, v85
	v_mul_f32_e32 v84, v84, v84
	v_lshl_add_u64 v[88:89], s[0:1], 0, v[88:89]
	v_fmac_f32_e32 v84, v85, v85
	v_pk_fma_f32 v[82:83], v[82:83], 0.5, v[132:133] op_sel_hi:[1,0,1]
	v_pk_fma_f32 v[80:81], v[80:81], 0.5, v[130:131] op_sel_hi:[1,0,1]
	v_cvt_pk_bf16_f32 v91, v86, v87
	s_nop 1
	v_mov_b32_e32 v240, v90
	v_mov_b32_e32 v241, v91
	v_lshl_add_u64 v[244:245], v[88:89], 0, v[246:247]
	v_fmac_f32_e32 v84, v86, v86
	global_store_dwordx4 v[118:119], v[80:83], off offset:576
	v_cvt_pk_bf16_f32 v86, v80, v81
	v_fmac_f32_e32 v84, v87, v87
	v_add_f32_e32 v88, v92, v84
	v_mul_f32_e32 v80, v80, v80
	v_fmac_f32_e32 v80, v81, v81
	v_fmac_f32_e32 v80, v82, v82
	v_fmac_f32_e32 v80, v83, v83
	v_add_f32_e32 v80, v88, v80
	ds_bpermute_b32 v81, v116, v80
	v_or_b32_e32 v120, 0x120, v120
	v_lshl_add_u64 v[84:85], s[0:1], 0, v[120:121]
	v_cvt_pk_bf16_f32 v87, v82, v83
	v_mov_b32_e32 v242, v86
	v_mov_b32_e32 v243, v87
	s_nop 1
	v_permlane16_swap_b32 v240, v242
	v_permlane16_swap_b32 v241, v243
	global_store_dwordx4 v[244:245], v[240:243], off
	s_waitcnt lgkmcnt(0)
	v_add_f32_e32 v80, v80, v81
	ds_bpermute_b32 v81, v117, v80
	s_and_saveexec_b64 s[36:37], s[8:9]
	s_cbranch_execz .LBB0_404
	v_lshlrev_b64 v[82:83], 6, v[114:115]
	v_lshl_add_u64 v[82:83], s[2:3], 0, v[82:83]
	v_lshl_add_u64 v[82:83], s[16:17], 2, v[82:83]
	s_lshl_b32 s6, s83, 2
	v_lshl_add_u64 v[82:83], v[82:83], 0, s[6:7]
	s_waitcnt lgkmcnt(0)
	v_add_f32_e32 v80, v80, v81
	flat_store_dword v[82:83], v80
.LBB0_404:
	s_or_b64 exec, exec, s[36:37]
	s_waitcnt lgkmcnt(0)
	v_lshlrev_b64 v[80:81], 10, v[112:113]
	v_lshl_add_u64 v[80:81], v[80:81], 0, v[164:165]
	v_lshl_add_u64 v[82:83], v[80:81], 2, s[78:79]
	v_lshlrev_b64 v[80:81], 1, v[80:81]
	v_mov_b32_dpp v224, v108 row_ror:8 row_mask:0xf bank_mask:0xf
	v_mov_b32_dpp v225, v109 row_ror:8 row_mask:0xf bank_mask:0xf
	v_mov_b32_dpp v226, v110 row_ror:8 row_mask:0xf bank_mask:0xf
	v_mov_b32_dpp v227, v111 row_ror:8 row_mask:0xf bank_mask:0xf
	v_mov_b32_dpp v108, v104 row_ror:8 row_mask:0xf bank_mask:0xc
	v_mov_b32_dpp v109, v105 row_ror:8 row_mask:0xf bank_mask:0xc
	v_mov_b32_dpp v110, v106 row_ror:8 row_mask:0xf bank_mask:0xc
	v_mov_b32_dpp v111, v107 row_ror:8 row_mask:0xf bank_mask:0xc
	v_mov_b32_dpp v104, v224 quad_perm:[0,1,2,3] row_mask:0xf bank_mask:0x3
	v_mov_b32_dpp v105, v225 quad_perm:[0,1,2,3] row_mask:0xf bank_mask:0x3
	v_mov_b32_dpp v106, v226 quad_perm:[0,1,2,3] row_mask:0xf bank_mask:0x3
	v_mov_b32_dpp v107, v227 quad_perm:[0,1,2,3] row_mask:0xf bank_mask:0x3
	v_mov_b32_dpp v224, v100 row_ror:8 row_mask:0xf bank_mask:0xf
	v_mov_b32_dpp v225, v101 row_ror:8 row_mask:0xf bank_mask:0xf
	v_mov_b32_dpp v226, v102 row_ror:8 row_mask:0xf bank_mask:0xf
	v_mov_b32_dpp v227, v103 row_ror:8 row_mask:0xf bank_mask:0xf
	v_mov_b32_dpp v100, v96 row_ror:8 row_mask:0xf bank_mask:0xc
	v_mov_b32_dpp v101, v97 row_ror:8 row_mask:0xf bank_mask:0xc
	v_mov_b32_dpp v102, v98 row_ror:8 row_mask:0xf bank_mask:0xc
	v_mov_b32_dpp v103, v99 row_ror:8 row_mask:0xf bank_mask:0xc
	v_mov_b32_dpp v96, v224 quad_perm:[0,1,2,3] row_mask:0xf bank_mask:0x3
	v_mov_b32_dpp v97, v225 quad_perm:[0,1,2,3] row_mask:0xf bank_mask:0x3
	v_mov_b32_dpp v98, v226 quad_perm:[0,1,2,3] row_mask:0xf bank_mask:0x3
	v_mov_b32_dpp v99, v227 quad_perm:[0,1,2,3] row_mask:0xf bank_mask:0x3
	v_pk_fma_f32 v[78:79], v[78:79], 0.5, v[110:111] op_sel_hi:[1,0,1]
	v_pk_fma_f32 v[76:77], v[76:77], 0.5, v[108:109] op_sel_hi:[1,0,1]
	v_lshl_add_u64 v[84:85], s[0:1], 0, v[80:81]
	global_store_dwordx4 v[82:83], v[76:79], off
	v_cvt_pk_bf16_f32 v86, v76, v77
	v_cvt_pk_bf16_f32 v87, v78, v79
	s_nop 1
	v_mov_b32_e32 v240, v86
	v_mov_b32_e32 v241, v87
	v_lshl_add_u64 v[244:245], v[84:85], 0, v[246:247]
	v_mul_f32_e32 v84, v76, v76
	v_fmac_f32_e32 v84, v77, v77
	v_pk_fma_f32 v[74:75], v[74:75], 0.5, v[106:107] op_sel_hi:[1,0,1]
	v_pk_fma_f32 v[72:73], v[72:73], 0.5, v[104:105] op_sel_hi:[1,0,1]
	v_fmac_f32_e32 v84, v78, v78
	global_store_dwordx4 v[82:83], v[72:75], off offset:64
	v_or_b32_e32 v76, 32, v80
	v_mov_b32_e32 v77, v81
	v_cvt_pk_bf16_f32 v78, v72, v73
	v_mul_f32_e32 v72, v72, v72
	v_lshl_add_u64 v[76:77], s[0:1], 0, v[76:77]
	v_fmac_f32_e32 v72, v73, v73
	v_pk_fma_f32 v[70:71], v[70:71], 0.5, v[102:103] op_sel_hi:[1,0,1]
	v_pk_fma_f32 v[68:69], v[68:69], 0.5, v[100:101] op_sel_hi:[1,0,1]
	v_fmac_f32_e32 v84, v79, v79
	v_cvt_pk_bf16_f32 v79, v74, v75
	v_mov_b32_e32 v242, v78
	v_mov_b32_e32 v243, v79
	s_nop 1
	v_permlane16_swap_b32 v240, v242
	v_permlane16_swap_b32 v241, v243
	global_store_dwordx4 v[244:245], v[240:243], off
	v_fmac_f32_e32 v72, v74, v74
	global_store_dwordx4 v[82:83], v[68:71], off offset:512
	v_cvt_pk_bf16_f32 v74, v68, v69
	v_fmac_f32_e32 v72, v75, v75
	v_add_f32_e32 v75, v84, v72
	v_mul_f32_e32 v68, v68, v68
	v_fmac_f32_e32 v68, v69, v69
	v_fmac_f32_e32 v68, v70, v70
	v_fmac_f32_e32 v68, v71, v71
	v_add_f32_e32 v75, v75, v68
	v_pk_fma_f32 v[68:69], v[66:67], 0.5, v[98:99] op_sel_hi:[1,0,1]
	v_pk_fma_f32 v[66:67], v[64:65], 0.5, v[96:97] op_sel_hi:[1,0,1]
	v_or_b32_e32 v72, 0x100, v80
	v_mul_f32_e32 v64, v66, v66
	v_fmac_f32_e32 v64, v67, v67
	v_fmac_f32_e32 v64, v68, v68
	v_fmac_f32_e32 v64, v69, v69
	v_add_f32_e32 v64, v75, v64
	ds_bpermute_b32 v65, v116, v64
	v_mov_b32_e32 v73, v81
	v_or_b32_e32 v80, 0x120, v80
	v_lshl_add_u64 v[72:73], s[0:1], 0, v[72:73]
	v_cvt_pk_bf16_f32 v75, v70, v71
	s_waitcnt lgkmcnt(0)
	v_add_f32_e32 v64, v64, v65
	ds_bpermute_b32 v65, v117, v64
	v_lshl_add_u64 v[70:71], s[0:1], 0, v[80:81]
	s_nop 1
	v_mov_b32_e32 v240, v74
	v_mov_b32_e32 v241, v75
	v_lshl_add_u64 v[244:245], v[72:73], 0, v[246:247]
	global_store_dwordx4 v[82:83], v[66:69], off offset:576
	s_nop 1
	v_cvt_pk_bf16_f32 v66, v66, v67
	v_cvt_pk_bf16_f32 v67, v68, v69
	v_mov_b32_e32 v242, v66
	v_mov_b32_e32 v243, v67
	s_nop 1
	v_permlane16_swap_b32 v240, v242
	v_permlane16_swap_b32 v241, v243
	global_store_dwordx4 v[244:245], v[240:243], off
	s_and_saveexec_b64 s[36:37], s[8:9]
	s_cbranch_execz .LBB0_406
	v_lshlrev_b64 v[66:67], 6, v[112:113]
	v_lshl_add_u64 v[66:67], s[2:3], 0, v[66:67]
	v_lshl_add_u64 v[66:67], s[16:17], 2, v[66:67]
	s_lshl_b32 s6, s83, 2
	v_lshl_add_u64 v[66:67], v[66:67], 0, s[6:7]
	s_waitcnt lgkmcnt(0)
	v_add_f32_e32 v64, v64, v65
	flat_store_dword v[66:67], v64
.LBB0_406:
	s_or_b64 exec, exec, s[36:37]
	v_lshl_add_u64 v[82:83], v[166:167], 0, s[4:5]
	s_waitcnt lgkmcnt(0)
	v_lshlrev_b64 v[64:65], 12, v[82:83]
	v_lshl_add_u64 v[64:65], v[168:169], 0, v[64:65]
	v_lshl_add_u64 v[232:233], v[64:65], 0, v[248:249]
	v_lshl_add_u64 v[234:235], v[232:233], 0, v[250:251]
	global_load_dwordx4 v[84:87], v[232:233], off
	global_load_dwordx4 v[88:91], v[234:235], off
	global_load_dwordx4 v[92:95], v[232:233], off offset:512
	global_load_dwordx4 v[96:99], v[234:235], off offset:512
	s_mov_b64 s[18:19], 0x90
	v_lshl_add_u64 v[80:81], v[166:167], 0, s[18:19]
	v_lshlrev_b64 v[64:65], 12, v[80:81]
	v_lshl_add_u64 v[64:65], v[168:169], 0, v[64:65]
	v_lshl_add_u64 v[236:237], v[64:65], 0, v[248:249]
	v_lshl_add_u64 v[238:239], v[236:237], 0, v[250:251]
	global_load_dwordx4 v[76:79], v[236:237], off
	global_load_dwordx4 v[72:75], v[238:239], off
	global_load_dwordx4 v[68:71], v[236:237], off offset:512
	s_nop 0
	global_load_dwordx4 v[64:67], v[238:239], off offset:512
	v_lshlrev_b64 v[100:101], 10, v[82:83]
	v_lshl_add_u64 v[100:101], v[100:101], 0, v[164:165]
	s_waitcnt vmcnt(0)
	s_waitcnt vmcnt(0)
	v_mov_b32_dpp v224, v84 row_ror:8 row_mask:0xf bank_mask:0xf
	v_mov_b32_dpp v225, v85 row_ror:8 row_mask:0xf bank_mask:0xf
	v_mov_b32_dpp v226, v86 row_ror:8 row_mask:0xf bank_mask:0xf
	v_mov_b32_dpp v227, v87 row_ror:8 row_mask:0xf bank_mask:0xf
	v_mov_b32_dpp v84, v88 row_ror:8 row_mask:0xf bank_mask:0xc
	v_mov_b32_dpp v85, v89 row_ror:8 row_mask:0xf bank_mask:0xc
	v_mov_b32_dpp v86, v90 row_ror:8 row_mask:0xf bank_mask:0xc
	v_mov_b32_dpp v87, v91 row_ror:8 row_mask:0xf bank_mask:0xc
	v_mov_b32_dpp v88, v224 quad_perm:[0,1,2,3] row_mask:0xf bank_mask:0x3
	v_mov_b32_dpp v89, v225 quad_perm:[0,1,2,3] row_mask:0xf bank_mask:0x3
	v_mov_b32_dpp v90, v226 quad_perm:[0,1,2,3] row_mask:0xf bank_mask:0x3
	v_mov_b32_dpp v91, v227 quad_perm:[0,1,2,3] row_mask:0xf bank_mask:0x3
	v_mov_b32_dpp v224, v92 row_ror:8 row_mask:0xf bank_mask:0xf
	v_mov_b32_dpp v225, v93 row_ror:8 row_mask:0xf bank_mask:0xf
	v_mov_b32_dpp v226, v94 row_ror:8 row_mask:0xf bank_mask:0xf
	v_mov_b32_dpp v227, v95 row_ror:8 row_mask:0xf bank_mask:0xf
	v_mov_b32_dpp v92, v96 row_ror:8 row_mask:0xf bank_mask:0xc
	v_mov_b32_dpp v93, v97 row_ror:8 row_mask:0xf bank_mask:0xc
	v_mov_b32_dpp v94, v98 row_ror:8 row_mask:0xf bank_mask:0xc
	v_mov_b32_dpp v95, v99 row_ror:8 row_mask:0xf bank_mask:0xc
	v_mov_b32_dpp v96, v224 quad_perm:[0,1,2,3] row_mask:0xf bank_mask:0x3
	v_mov_b32_dpp v97, v225 quad_perm:[0,1,2,3] row_mask:0xf bank_mask:0x3
	v_mov_b32_dpp v98, v226 quad_perm:[0,1,2,3] row_mask:0xf bank_mask:0x3
	v_mov_b32_dpp v99, v227 quad_perm:[0,1,2,3] row_mask:0xf bank_mask:0x3
	v_pk_fma_f32 v[62:63], v[62:63], 0.5, v[86:87] op_sel_hi:[1,0,1]
	v_lshlrev_b64 v[86:87], 1, v[100:101]
	v_pk_fma_f32 v[60:61], v[60:61], 0.5, v[84:85] op_sel_hi:[1,0,1]
	v_lshl_add_u64 v[84:85], v[100:101], 2, s[78:79]
	v_lshl_add_u64 v[100:101], s[0:1], 0, v[86:87]
	global_store_dwordx4 v[84:85], v[60:63], off
	v_cvt_pk_bf16_f32 v102, v60, v61
	v_cvt_pk_bf16_f32 v103, v62, v63
	s_nop 1
	v_mov_b32_e32 v240, v102
	v_mov_b32_e32 v241, v103
	v_lshl_add_u64 v[244:245], v[100:101], 0, v[246:247]
	v_mul_f32_e32 v100, v60, v60
	v_fmac_f32_e32 v100, v61, v61
	v_pk_fma_f32 v[58:59], v[58:59], 0.5, v[90:91] op_sel_hi:[1,0,1]
	v_pk_fma_f32 v[56:57], v[56:57], 0.5, v[88:89] op_sel_hi:[1,0,1]
	v_fmac_f32_e32 v100, v62, v62
	global_store_dwordx4 v[84:85], v[56:59], off offset:64
	v_cvt_pk_bf16_f32 v62, v56, v57
	v_or_b32_e32 v60, 32, v86
	v_mov_b32_e32 v61, v87
	v_mul_f32_e32 v56, v56, v56
	v_fmac_f32_e32 v56, v57, v57
	v_fmac_f32_e32 v56, v58, v58
	v_fmac_f32_e32 v100, v63, v63
	v_lshl_add_u64 v[60:61], s[0:1], 0, v[60:61]
	v_fmac_f32_e32 v56, v59, v59
	v_pk_fma_f32 v[54:55], v[54:55], 0.5, v[94:95] op_sel_hi:[1,0,1]
	v_pk_fma_f32 v[52:53], v[52:53], 0.5, v[92:93] op_sel_hi:[1,0,1]
	v_cvt_pk_bf16_f32 v63, v58, v59
	v_mov_b32_e32 v242, v62
	v_mov_b32_e32 v243, v63
	s_nop 1
	v_permlane16_swap_b32 v240, v242
	v_permlane16_swap_b32 v241, v243
	global_store_dwordx4 v[244:245], v[240:243], off
	v_add_f32_e32 v60, v100, v56
	global_store_dwordx4 v[84:85], v[52:55], off offset:512
	v_or_b32_e32 v56, 0x100, v86
	v_mov_b32_e32 v57, v87
	v_cvt_pk_bf16_f32 v58, v52, v53
	v_mul_f32_e32 v52, v52, v52
	v_lshl_add_u64 v[56:57], s[0:1], 0, v[56:57]
	v_fmac_f32_e32 v52, v53, v53
	v_pk_fma_f32 v[50:51], v[50:51], 0.5, v[98:99] op_sel_hi:[1,0,1]
	v_pk_fma_f32 v[48:49], v[48:49], 0.5, v[96:97] op_sel_hi:[1,0,1]
	v_cvt_pk_bf16_f32 v59, v54, v55
	s_nop 1
	v_mov_b32_e32 v240, v58
	v_mov_b32_e32 v241, v59
	v_lshl_add_u64 v[244:245], v[56:57], 0, v[246:247]
	v_fmac_f32_e32 v52, v54, v54
	global_store_dwordx4 v[84:85], v[48:51], off offset:576
	v_cvt_pk_bf16_f32 v54, v48, v49
	v_fmac_f32_e32 v52, v55, v55
	v_add_f32_e32 v56, v60, v52
	v_mul_f32_e32 v48, v48, v48
	v_fmac_f32_e32 v48, v49, v49
	v_fmac_f32_e32 v48, v50, v50
	v_fmac_f32_e32 v48, v51, v51
	v_add_f32_e32 v48, v56, v48
	ds_bpermute_b32 v49, v116, v48
	v_or_b32_e32 v86, 0x120, v86
	v_lshl_add_u64 v[52:53], s[0:1], 0, v[86:87]
	v_cvt_pk_bf16_f32 v55, v50, v51
	v_mov_b32_e32 v242, v54
	v_mov_b32_e32 v243, v55
	s_nop 1
	v_permlane16_swap_b32 v240, v242
	v_permlane16_swap_b32 v241, v243
	global_store_dwordx4 v[244:245], v[240:243], off
	s_waitcnt lgkmcnt(0)
	v_add_f32_e32 v48, v48, v49
	ds_bpermute_b32 v49, v117, v48
	s_and_saveexec_b64 s[36:37], s[8:9]
	s_cbranch_execz .LBB0_408
	v_lshlrev_b64 v[50:51], 6, v[82:83]
	v_lshl_add_u64 v[50:51], s[2:3], 0, v[50:51]
	v_lshl_add_u64 v[50:51], s[16:17], 2, v[50:51]
	s_lshl_b32 s6, s83, 2
	v_lshl_add_u64 v[50:51], v[50:51], 0, s[6:7]
	s_waitcnt lgkmcnt(0)
	v_add_f32_e32 v48, v48, v49
	flat_store_dword v[50:51], v48
.LBB0_408:
	s_or_b64 exec, exec, s[36:37]
	s_waitcnt lgkmcnt(0)
	v_lshlrev_b64 v[48:49], 10, v[80:81]
	v_lshl_add_u64 v[48:49], v[48:49], 0, v[164:165]
	v_lshl_add_u64 v[50:51], v[48:49], 2, s[78:79]
	v_lshlrev_b64 v[48:49], 1, v[48:49]
	v_mov_b32_dpp v224, v76 row_ror:8 row_mask:0xf bank_mask:0xf
	v_mov_b32_dpp v225, v77 row_ror:8 row_mask:0xf bank_mask:0xf
	v_mov_b32_dpp v226, v78 row_ror:8 row_mask:0xf bank_mask:0xf
	v_mov_b32_dpp v227, v79 row_ror:8 row_mask:0xf bank_mask:0xf
	v_mov_b32_dpp v76, v72 row_ror:8 row_mask:0xf bank_mask:0xc
	v_mov_b32_dpp v77, v73 row_ror:8 row_mask:0xf bank_mask:0xc
	v_mov_b32_dpp v78, v74 row_ror:8 row_mask:0xf bank_mask:0xc
	v_mov_b32_dpp v79, v75 row_ror:8 row_mask:0xf bank_mask:0xc
	v_mov_b32_dpp v72, v224 quad_perm:[0,1,2,3] row_mask:0xf bank_mask:0x3
	v_mov_b32_dpp v73, v225 quad_perm:[0,1,2,3] row_mask:0xf bank_mask:0x3
	v_mov_b32_dpp v74, v226 quad_perm:[0,1,2,3] row_mask:0xf bank_mask:0x3
	v_mov_b32_dpp v75, v227 quad_perm:[0,1,2,3] row_mask:0xf bank_mask:0x3
	v_mov_b32_dpp v224, v68 row_ror:8 row_mask:0xf bank_mask:0xf
	v_mov_b32_dpp v225, v69 row_ror:8 row_mask:0xf bank_mask:0xf
	v_mov_b32_dpp v226, v70 row_ror:8 row_mask:0xf bank_mask:0xf
	v_mov_b32_dpp v227, v71 row_ror:8 row_mask:0xf bank_mask:0xf
	v_mov_b32_dpp v68, v64 row_ror:8 row_mask:0xf bank_mask:0xc
	v_mov_b32_dpp v69, v65 row_ror:8 row_mask:0xf bank_mask:0xc
	v_mov_b32_dpp v70, v66 row_ror:8 row_mask:0xf bank_mask:0xc
	v_mov_b32_dpp v71, v67 row_ror:8 row_mask:0xf bank_mask:0xc
	v_mov_b32_dpp v64, v224 quad_perm:[0,1,2,3] row_mask:0xf bank_mask:0x3
	v_mov_b32_dpp v65, v225 quad_perm:[0,1,2,3] row_mask:0xf bank_mask:0x3
	v_mov_b32_dpp v66, v226 quad_perm:[0,1,2,3] row_mask:0xf bank_mask:0x3
	v_mov_b32_dpp v67, v227 quad_perm:[0,1,2,3] row_mask:0xf bank_mask:0x3
	v_pk_fma_f32 v[46:47], v[46:47], 0.5, v[78:79] op_sel_hi:[1,0,1]
	v_pk_fma_f32 v[44:45], v[44:45], 0.5, v[76:77] op_sel_hi:[1,0,1]
	v_lshl_add_u64 v[52:53], s[0:1], 0, v[48:49]
	global_store_dwordx4 v[50:51], v[44:47], off
	v_cvt_pk_bf16_f32 v54, v44, v45
	v_cvt_pk_bf16_f32 v55, v46, v47
	s_nop 1
	v_mov_b32_e32 v240, v54
	v_mov_b32_e32 v241, v55
	v_lshl_add_u64 v[244:245], v[52:53], 0, v[246:247]
	v_mul_f32_e32 v52, v44, v44
	v_fmac_f32_e32 v52, v45, v45
	v_pk_fma_f32 v[42:43], v[42:43], 0.5, v[74:75] op_sel_hi:[1,0,1]
	v_pk_fma_f32 v[40:41], v[40:41], 0.5, v[72:73] op_sel_hi:[1,0,1]
	v_fmac_f32_e32 v52, v46, v46
	global_store_dwordx4 v[50:51], v[40:43], off offset:64
	v_or_b32_e32 v44, 32, v48
	v_mov_b32_e32 v45, v49
	v_cvt_pk_bf16_f32 v46, v40, v41
	v_mul_f32_e32 v40, v40, v40
	v_lshl_add_u64 v[44:45], s[0:1], 0, v[44:45]
	v_fmac_f32_e32 v40, v41, v41
	v_pk_fma_f32 v[38:39], v[38:39], 0.5, v[70:71] op_sel_hi:[1,0,1]
	v_pk_fma_f32 v[36:37], v[36:37], 0.5, v[68:69] op_sel_hi:[1,0,1]
	v_fmac_f32_e32 v52, v47, v47
	v_cvt_pk_bf16_f32 v47, v42, v43
	v_mov_b32_e32 v242, v46
	v_mov_b32_e32 v243, v47
	s_nop 1
	v_permlane16_swap_b32 v240, v242
	v_permlane16_swap_b32 v241, v243
	global_store_dwordx4 v[244:245], v[240:243], off
	v_fmac_f32_e32 v40, v42, v42
	global_store_dwordx4 v[50:51], v[36:39], off offset:512
	v_cvt_pk_bf16_f32 v42, v36, v37
	v_fmac_f32_e32 v40, v43, v43
	v_add_f32_e32 v43, v52, v40
	v_mul_f32_e32 v36, v36, v36
	v_fmac_f32_e32 v36, v37, v37
	v_fmac_f32_e32 v36, v38, v38
	v_fmac_f32_e32 v36, v39, v39
	v_add_f32_e32 v43, v43, v36
	v_pk_fma_f32 v[36:37], v[34:35], 0.5, v[66:67] op_sel_hi:[1,0,1]
	v_pk_fma_f32 v[34:35], v[32:33], 0.5, v[64:65] op_sel_hi:[1,0,1]
	v_or_b32_e32 v40, 0x100, v48
	v_mul_f32_e32 v32, v34, v34
	v_fmac_f32_e32 v32, v35, v35
	v_fmac_f32_e32 v32, v36, v36
	v_fmac_f32_e32 v32, v37, v37
	v_add_f32_e32 v32, v43, v32
	ds_bpermute_b32 v33, v116, v32
	v_mov_b32_e32 v41, v49
	v_or_b32_e32 v48, 0x120, v48
	v_lshl_add_u64 v[40:41], s[0:1], 0, v[40:41]
	v_cvt_pk_bf16_f32 v43, v38, v39
	s_waitcnt lgkmcnt(0)
	v_add_f32_e32 v32, v32, v33
	ds_bpermute_b32 v33, v117, v32
	v_lshl_add_u64 v[38:39], s[0:1], 0, v[48:49]
	s_nop 1
	v_mov_b32_e32 v240, v42
	v_mov_b32_e32 v241, v43
	v_lshl_add_u64 v[244:245], v[40:41], 0, v[246:247]
	global_store_dwordx4 v[50:51], v[34:37], off offset:576
	s_nop 1
	v_cvt_pk_bf16_f32 v34, v34, v35
	v_cvt_pk_bf16_f32 v35, v36, v37
	v_mov_b32_e32 v242, v34
	v_mov_b32_e32 v243, v35
	s_nop 1
	v_permlane16_swap_b32 v240, v242
	v_permlane16_swap_b32 v241, v243
	global_store_dwordx4 v[244:245], v[240:243], off
	s_and_saveexec_b64 s[36:37], s[8:9]
	s_cbranch_execz .LBB0_410
	v_lshlrev_b64 v[34:35], 6, v[80:81]
	v_lshl_add_u64 v[34:35], s[2:3], 0, v[34:35]
	v_lshl_add_u64 v[34:35], s[16:17], 2, v[34:35]
	s_lshl_b32 s6, s83, 2
	v_lshl_add_u64 v[34:35], v[34:35], 0, s[6:7]
	s_waitcnt lgkmcnt(0)
	v_add_f32_e32 v32, v32, v33
	flat_store_dword v[34:35], v32
.LBB0_410:
	s_or_b64 exec, exec, s[36:37]
	s_mov_b64 s[18:19], 0xa0
	v_lshl_add_u64 v[50:51], v[166:167], 0, s[18:19]
	s_waitcnt lgkmcnt(0)
	v_lshlrev_b64 v[32:33], 12, v[50:51]
	v_lshl_add_u64 v[32:33], v[168:169], 0, v[32:33]
	v_lshl_add_u64 v[232:233], v[32:33], 0, v[248:249]
	v_lshl_add_u64 v[234:235], v[232:233], 0, v[250:251]
	global_load_dwordx4 v[52:55], v[232:233], off
	global_load_dwordx4 v[56:59], v[234:235], off
	global_load_dwordx4 v[60:63], v[232:233], off offset:512
	global_load_dwordx4 v[64:67], v[234:235], off offset:512
	s_mov_b64 s[18:19], 0xb0
	v_lshl_add_u64 v[48:49], v[166:167], 0, s[18:19]
	v_lshlrev_b64 v[32:33], 12, v[48:49]
	v_lshl_add_u64 v[32:33], v[168:169], 0, v[32:33]
	v_lshl_add_u64 v[236:237], v[32:33], 0, v[248:249]
	v_lshl_add_u64 v[238:239], v[236:237], 0, v[250:251]
	global_load_dwordx4 v[44:47], v[236:237], off
	global_load_dwordx4 v[40:43], v[238:239], off
	global_load_dwordx4 v[36:39], v[236:237], off offset:512
	s_nop 0
	global_load_dwordx4 v[32:35], v[238:239], off offset:512
	v_lshlrev_b64 v[68:69], 10, v[50:51]
	v_lshl_add_u64 v[68:69], v[68:69], 0, v[164:165]
	s_waitcnt vmcnt(0)
	s_waitcnt vmcnt(0)
	v_mov_b32_dpp v224, v52 row_ror:8 row_mask:0xf bank_mask:0xf
	v_mov_b32_dpp v225, v53 row_ror:8 row_mask:0xf bank_mask:0xf
	v_mov_b32_dpp v226, v54 row_ror:8 row_mask:0xf bank_mask:0xf
	v_mov_b32_dpp v227, v55 row_ror:8 row_mask:0xf bank_mask:0xf
	v_mov_b32_dpp v52, v56 row_ror:8 row_mask:0xf bank_mask:0xc
	v_mov_b32_dpp v53, v57 row_ror:8 row_mask:0xf bank_mask:0xc
	v_mov_b32_dpp v54, v58 row_ror:8 row_mask:0xf bank_mask:0xc
	v_mov_b32_dpp v55, v59 row_ror:8 row_mask:0xf bank_mask:0xc
	v_mov_b32_dpp v56, v224 quad_perm:[0,1,2,3] row_mask:0xf bank_mask:0x3
	v_mov_b32_dpp v57, v225 quad_perm:[0,1,2,3] row_mask:0xf bank_mask:0x3
	v_mov_b32_dpp v58, v226 quad_perm:[0,1,2,3] row_mask:0xf bank_mask:0x3
	v_mov_b32_dpp v59, v227 quad_perm:[0,1,2,3] row_mask:0xf bank_mask:0x3
	v_mov_b32_dpp v224, v60 row_ror:8 row_mask:0xf bank_mask:0xf
	v_mov_b32_dpp v225, v61 row_ror:8 row_mask:0xf bank_mask:0xf
	v_mov_b32_dpp v226, v62 row_ror:8 row_mask:0xf bank_mask:0xf
	v_mov_b32_dpp v227, v63 row_ror:8 row_mask:0xf bank_mask:0xf
	v_mov_b32_dpp v60, v64 row_ror:8 row_mask:0xf bank_mask:0xc
	v_mov_b32_dpp v61, v65 row_ror:8 row_mask:0xf bank_mask:0xc
	v_mov_b32_dpp v62, v66 row_ror:8 row_mask:0xf bank_mask:0xc
	v_mov_b32_dpp v63, v67 row_ror:8 row_mask:0xf bank_mask:0xc
	v_mov_b32_dpp v64, v224 quad_perm:[0,1,2,3] row_mask:0xf bank_mask:0x3
	v_mov_b32_dpp v65, v225 quad_perm:[0,1,2,3] row_mask:0xf bank_mask:0x3
	v_mov_b32_dpp v66, v226 quad_perm:[0,1,2,3] row_mask:0xf bank_mask:0x3
	v_mov_b32_dpp v67, v227 quad_perm:[0,1,2,3] row_mask:0xf bank_mask:0x3
	v_pk_fma_f32 v[30:31], v[30:31], 0.5, v[54:55] op_sel_hi:[1,0,1]
	v_lshlrev_b64 v[54:55], 1, v[68:69]
	v_pk_fma_f32 v[28:29], v[28:29], 0.5, v[52:53] op_sel_hi:[1,0,1]
	v_lshl_add_u64 v[52:53], v[68:69], 2, s[78:79]
	v_lshl_add_u64 v[68:69], s[0:1], 0, v[54:55]
	global_store_dwordx4 v[52:53], v[28:31], off
	v_cvt_pk_bf16_f32 v70, v28, v29
	v_cvt_pk_bf16_f32 v71, v30, v31
	s_nop 1
	v_mov_b32_e32 v240, v70
	v_mov_b32_e32 v241, v71
	v_lshl_add_u64 v[244:245], v[68:69], 0, v[246:247]
	v_mul_f32_e32 v68, v28, v28
	v_fmac_f32_e32 v68, v29, v29
	v_pk_fma_f32 v[26:27], v[26:27], 0.5, v[58:59] op_sel_hi:[1,0,1]
	v_pk_fma_f32 v[24:25], v[24:25], 0.5, v[56:57] op_sel_hi:[1,0,1]
	v_fmac_f32_e32 v68, v30, v30
	global_store_dwordx4 v[52:53], v[24:27], off offset:64
	v_cvt_pk_bf16_f32 v30, v24, v25
	v_or_b32_e32 v28, 32, v54
	v_mov_b32_e32 v29, v55
	v_mul_f32_e32 v24, v24, v24
	v_fmac_f32_e32 v24, v25, v25
	v_fmac_f32_e32 v24, v26, v26
	v_fmac_f32_e32 v68, v31, v31
	v_lshl_add_u64 v[28:29], s[0:1], 0, v[28:29]
	v_fmac_f32_e32 v24, v27, v27
	v_pk_fma_f32 v[22:23], v[22:23], 0.5, v[62:63] op_sel_hi:[1,0,1]
	v_pk_fma_f32 v[20:21], v[20:21], 0.5, v[60:61] op_sel_hi:[1,0,1]
	v_cvt_pk_bf16_f32 v31, v26, v27
	v_mov_b32_e32 v242, v30
	v_mov_b32_e32 v243, v31
	s_nop 1
	v_permlane16_swap_b32 v240, v242
	v_permlane16_swap_b32 v241, v243
	global_store_dwordx4 v[244:245], v[240:243], off
	v_add_f32_e32 v28, v68, v24
	global_store_dwordx4 v[52:53], v[20:23], off offset:512
	v_or_b32_e32 v24, 0x100, v54
	v_mov_b32_e32 v25, v55
	v_cvt_pk_bf16_f32 v26, v20, v21
	v_mul_f32_e32 v20, v20, v20
	v_lshl_add_u64 v[24:25], s[0:1], 0, v[24:25]
	v_fmac_f32_e32 v20, v21, v21
	v_pk_fma_f32 v[18:19], v[18:19], 0.5, v[66:67] op_sel_hi:[1,0,1]
	v_pk_fma_f32 v[16:17], v[16:17], 0.5, v[64:65] op_sel_hi:[1,0,1]
	v_cvt_pk_bf16_f32 v27, v22, v23
	s_nop 1
	v_mov_b32_e32 v240, v26
	v_mov_b32_e32 v241, v27
	v_lshl_add_u64 v[244:245], v[24:25], 0, v[246:247]
	v_fmac_f32_e32 v20, v22, v22
	global_store_dwordx4 v[52:53], v[16:19], off offset:576
	v_cvt_pk_bf16_f32 v22, v16, v17
	v_fmac_f32_e32 v20, v23, v23
	v_add_f32_e32 v24, v28, v20
	v_mul_f32_e32 v16, v16, v16
	v_fmac_f32_e32 v16, v17, v17
	v_fmac_f32_e32 v16, v18, v18
	v_fmac_f32_e32 v16, v19, v19
	v_add_f32_e32 v16, v24, v16
	ds_bpermute_b32 v17, v116, v16
	v_or_b32_e32 v54, 0x120, v54
	v_lshl_add_u64 v[20:21], s[0:1], 0, v[54:55]
	v_cvt_pk_bf16_f32 v23, v18, v19
	v_mov_b32_e32 v242, v22
	v_mov_b32_e32 v243, v23
	s_nop 1
	v_permlane16_swap_b32 v240, v242
	v_permlane16_swap_b32 v241, v243
	global_store_dwordx4 v[244:245], v[240:243], off
	s_waitcnt lgkmcnt(0)
	v_add_f32_e32 v16, v16, v17
	ds_bpermute_b32 v17, v117, v16
	s_and_saveexec_b64 s[36:37], s[8:9]
	s_cbranch_execz .LBB0_412
	v_lshlrev_b64 v[18:19], 6, v[50:51]
	v_lshl_add_u64 v[18:19], s[2:3], 0, v[18:19]
	v_lshl_add_u64 v[18:19], s[16:17], 2, v[18:19]
	s_lshl_b32 s6, s83, 2
	v_lshl_add_u64 v[18:19], v[18:19], 0, s[6:7]
	s_waitcnt lgkmcnt(0)
	v_add_f32_e32 v16, v16, v17
	flat_store_dword v[18:19], v16
.LBB0_412:
	s_or_b64 exec, exec, s[36:37]
	s_waitcnt lgkmcnt(0)
	v_lshlrev_b64 v[16:17], 10, v[48:49]
	v_lshl_add_u64 v[16:17], v[16:17], 0, v[164:165]
	v_lshl_add_u64 v[18:19], v[16:17], 2, s[78:79]
	v_lshlrev_b64 v[16:17], 1, v[16:17]
	v_mov_b32_dpp v224, v44 row_ror:8 row_mask:0xf bank_mask:0xf
	v_mov_b32_dpp v225, v45 row_ror:8 row_mask:0xf bank_mask:0xf
	v_mov_b32_dpp v226, v46 row_ror:8 row_mask:0xf bank_mask:0xf
	v_mov_b32_dpp v227, v47 row_ror:8 row_mask:0xf bank_mask:0xf
	v_mov_b32_dpp v44, v40 row_ror:8 row_mask:0xf bank_mask:0xc
	v_mov_b32_dpp v45, v41 row_ror:8 row_mask:0xf bank_mask:0xc
	v_mov_b32_dpp v46, v42 row_ror:8 row_mask:0xf bank_mask:0xc
	v_mov_b32_dpp v47, v43 row_ror:8 row_mask:0xf bank_mask:0xc
	v_mov_b32_dpp v40, v224 quad_perm:[0,1,2,3] row_mask:0xf bank_mask:0x3
	v_mov_b32_dpp v41, v225 quad_perm:[0,1,2,3] row_mask:0xf bank_mask:0x3
	v_mov_b32_dpp v42, v226 quad_perm:[0,1,2,3] row_mask:0xf bank_mask:0x3
	v_mov_b32_dpp v43, v227 quad_perm:[0,1,2,3] row_mask:0xf bank_mask:0x3
	v_mov_b32_dpp v224, v36 row_ror:8 row_mask:0xf bank_mask:0xf
	v_mov_b32_dpp v225, v37 row_ror:8 row_mask:0xf bank_mask:0xf
	v_mov_b32_dpp v226, v38 row_ror:8 row_mask:0xf bank_mask:0xf
	v_mov_b32_dpp v227, v39 row_ror:8 row_mask:0xf bank_mask:0xf
	v_mov_b32_dpp v36, v32 row_ror:8 row_mask:0xf bank_mask:0xc
	v_mov_b32_dpp v37, v33 row_ror:8 row_mask:0xf bank_mask:0xc
	v_mov_b32_dpp v38, v34 row_ror:8 row_mask:0xf bank_mask:0xc
	v_mov_b32_dpp v39, v35 row_ror:8 row_mask:0xf bank_mask:0xc
	v_mov_b32_dpp v32, v224 quad_perm:[0,1,2,3] row_mask:0xf bank_mask:0x3
	v_mov_b32_dpp v33, v225 quad_perm:[0,1,2,3] row_mask:0xf bank_mask:0x3
	v_mov_b32_dpp v34, v226 quad_perm:[0,1,2,3] row_mask:0xf bank_mask:0x3
	v_mov_b32_dpp v35, v227 quad_perm:[0,1,2,3] row_mask:0xf bank_mask:0x3
	v_pk_fma_f32 v[14:15], v[14:15], 0.5, v[46:47] op_sel_hi:[1,0,1]
	v_pk_fma_f32 v[12:13], v[12:13], 0.5, v[44:45] op_sel_hi:[1,0,1]
	v_lshl_add_u64 v[20:21], s[0:1], 0, v[16:17]
	global_store_dwordx4 v[18:19], v[12:15], off
	v_cvt_pk_bf16_f32 v22, v12, v13
	v_cvt_pk_bf16_f32 v23, v14, v15
	s_nop 1
	v_mov_b32_e32 v240, v22
	v_mov_b32_e32 v241, v23
	v_lshl_add_u64 v[244:245], v[20:21], 0, v[246:247]
	v_mul_f32_e32 v20, v12, v12
	v_fmac_f32_e32 v20, v13, v13
	v_pk_fma_f32 v[10:11], v[10:11], 0.5, v[42:43] op_sel_hi:[1,0,1]
	v_pk_fma_f32 v[8:9], v[8:9], 0.5, v[40:41] op_sel_hi:[1,0,1]
	v_fmac_f32_e32 v20, v14, v14
	global_store_dwordx4 v[18:19], v[8:11], off offset:64
	v_or_b32_e32 v12, 32, v16
	v_mov_b32_e32 v13, v17
	v_cvt_pk_bf16_f32 v14, v8, v9
	v_mul_f32_e32 v8, v8, v8
	v_lshl_add_u64 v[12:13], s[0:1], 0, v[12:13]
	v_fmac_f32_e32 v8, v9, v9
	v_pk_fma_f32 v[6:7], v[6:7], 0.5, v[38:39] op_sel_hi:[1,0,1]
	v_pk_fma_f32 v[4:5], v[4:5], 0.5, v[36:37] op_sel_hi:[1,0,1]
	v_fmac_f32_e32 v20, v15, v15
	v_cvt_pk_bf16_f32 v15, v10, v11
	v_mov_b32_e32 v242, v14
	v_mov_b32_e32 v243, v15
	s_nop 1
	v_permlane16_swap_b32 v240, v242
	v_permlane16_swap_b32 v241, v243
	global_store_dwordx4 v[244:245], v[240:243], off
	v_fmac_f32_e32 v8, v10, v10
	global_store_dwordx4 v[18:19], v[4:7], off offset:512
	v_cvt_pk_bf16_f32 v10, v4, v5
	v_fmac_f32_e32 v8, v11, v11
	v_add_f32_e32 v11, v20, v8
	v_mul_f32_e32 v4, v4, v4
	v_fmac_f32_e32 v4, v5, v5
	v_fmac_f32_e32 v4, v6, v6
	v_fmac_f32_e32 v4, v7, v7
	v_add_f32_e32 v11, v11, v4
	v_pk_fma_f32 v[4:5], v[2:3], 0.5, v[34:35] op_sel_hi:[1,0,1]
	v_pk_fma_f32 v[2:3], v[0:1], 0.5, v[32:33] op_sel_hi:[1,0,1]
	v_or_b32_e32 v8, 0x100, v16
	v_mul_f32_e32 v0, v2, v2
	v_fmac_f32_e32 v0, v3, v3
	v_fmac_f32_e32 v0, v4, v4
	v_fmac_f32_e32 v0, v5, v5
	v_add_f32_e32 v0, v11, v0
	ds_bpermute_b32 v1, v116, v0
	v_mov_b32_e32 v9, v17
	v_or_b32_e32 v16, 0x120, v16
	v_lshl_add_u64 v[8:9], s[0:1], 0, v[8:9]
	v_cvt_pk_bf16_f32 v11, v6, v7
	s_waitcnt lgkmcnt(0)
	v_add_f32_e32 v0, v0, v1
	ds_bpermute_b32 v1, v117, v0
	v_lshl_add_u64 v[6:7], s[0:1], 0, v[16:17]
	s_nop 1
	v_mov_b32_e32 v240, v10
	v_mov_b32_e32 v241, v11
	v_lshl_add_u64 v[244:245], v[8:9], 0, v[246:247]
	global_store_dwordx4 v[18:19], v[2:5], off offset:576
	s_nop 1
	v_cvt_pk_bf16_f32 v2, v2, v3
	v_cvt_pk_bf16_f32 v3, v4, v5
	v_mov_b32_e32 v242, v2
	v_mov_b32_e32 v243, v3
	s_nop 1
	v_permlane16_swap_b32 v240, v242
	v_permlane16_swap_b32 v241, v243
	global_store_dwordx4 v[244:245], v[240:243], off
	s_and_saveexec_b64 s[36:37], s[8:9]
	s_cbranch_execz .LBB0_385
	v_lshlrev_b64 v[2:3], 6, v[48:49]
	v_lshl_add_u64 v[2:3], s[2:3], 0, v[2:3]
	v_lshl_add_u64 v[2:3], s[16:17], 2, v[2:3]
	s_lshl_b32 s6, s83, 2
	v_lshl_add_u64 v[2:3], v[2:3], 0, s[6:7]
	s_waitcnt lgkmcnt(0)
	v_add_f32_e32 v0, v0, v1
	flat_store_dword v[2:3], v0
	s_branch .LBB0_385

.LBB0_1480:
	ds_read_b128 v[128:131], v170
	ds_read_b128 v[132:135], v171
	ds_read_b128 v[136:139], v172
	ds_read_b128 v[140:143], v173
	s_add_u32 s34, s30, 0xfffc0080
	s_addc_u32 s35, s31, -1
	s_cmp_eq_u32 s69, 12
	s_cselect_b32 s37, s23, s35
	s_cselect_b32 s36, s29, s34
	s_cselect_b32 s35, s21, s68
	s_cselect_b32 s34, s66, s67
	s_mov_b32 m0, s63
	v_lshl_add_u64 v[214:215], s[30:31], 0, v[156:157]
	ds_read_b128 v[162:165], v151
	ds_read_b128 v[166:169], v151 offset:1024
	ds_read_b128 v[190:193], v151 offset:2048
	ds_read_b128 v[194:197], v151 offset:3072
	ds_read_b128 v[198:201], v151 offset:4096
	ds_read_b128 v[202:205], v151 offset:5120
	ds_read_b128 v[206:209], v151 offset:6144
	ds_read_b128 v[210:213], v151 offset:7168
	global_load_lds_dwordx4 v[214:215], off
	v_lshl_add_u64 v[214:215], s[30:31], 0, v[154:155]
	s_mov_b32 m0, s64
	s_nop 0
	global_load_lds_dwordx4 v[214:215], off
	s_waitcnt lgkmcnt(8)
	s_barrier
	s_waitcnt lgkmcnt(0)
	s_setprio 1
	s_waitcnt lgkmcnt(0)
	v_mfma_f32_16x16x32_bf16 v[124:127], v[128:131], v[162:165], v[124:127]
	v_mfma_f32_16x16x32_bf16 v[120:123], v[136:139], v[162:165], v[120:123]
	v_mfma_f32_16x16x32_bf16 v[108:111], v[128:131], v[190:193], v[108:111]
	v_mfma_f32_16x16x32_bf16 v[104:107], v[136:139], v[190:193], v[104:107]
	v_mfma_f32_16x16x32_bf16 v[92:95], v[128:131], v[198:201], v[92:95]
	v_mfma_f32_16x16x32_bf16 v[88:91], v[136:139], v[198:201], v[88:91]
	v_mfma_f32_16x16x32_bf16 v[76:79], v[128:131], v[206:209], v[76:79]
	v_mfma_f32_16x16x32_bf16 v[72:75], v[136:139], v[206:209], v[72:75]
	v_mfma_f32_16x16x32_bf16 v[124:127], v[132:135], v[166:169], v[124:127]
	v_mfma_f32_16x16x32_bf16 v[120:123], v[140:143], v[166:169], v[120:123]
	v_mfma_f32_16x16x32_bf16 v[108:111], v[132:135], v[194:197], v[108:111]
	v_mfma_f32_16x16x32_bf16 v[104:107], v[140:143], v[194:197], v[104:107]
	v_mfma_f32_16x16x32_bf16 v[92:95], v[132:135], v[202:205], v[92:95]
	v_mfma_f32_16x16x32_bf16 v[88:91], v[140:143], v[202:205], v[88:91]
	v_mfma_f32_16x16x32_bf16 v[76:79], v[132:135], v[210:213], v[76:79]
	v_mfma_f32_16x16x32_bf16 v[72:75], v[140:143], v[210:213], v[72:75]
	s_setprio 0
	s_barrier
	s_mov_b32 m0, s46
	v_lshl_add_u64 v[230:231], s[34:35], 0, v[144:145]
	ds_read_b128 v[214:217], v174
	ds_read_b128 v[218:221], v175
	ds_read_b128 v[222:225], v177
	ds_read_b128 v[226:229], v178
	global_load_lds_dwordx4 v[230:231], off
	v_lshl_add_u64 v[232:233], s[34:35], 0, v[146:147]
	s_mov_b32 m0, s47
	s_nop 0
	global_load_lds_dwordx4 v[232:233], off
	s_barrier
	s_waitcnt lgkmcnt(0)
	s_setprio 1
	s_waitcnt lgkmcnt(0)
	v_mfma_f32_16x16x32_bf16 v[116:119], v[214:217], v[162:165], v[116:119]
	v_mfma_f32_16x16x32_bf16 v[112:115], v[222:225], v[162:165], v[112:115]
	v_mfma_f32_16x16x32_bf16 v[100:103], v[214:217], v[190:193], v[100:103]
	v_mfma_f32_16x16x32_bf16 v[96:99], v[222:225], v[190:193], v[96:99]
	v_mfma_f32_16x16x32_bf16 v[84:87], v[214:217], v[198:201], v[84:87]
	v_mfma_f32_16x16x32_bf16 v[80:83], v[222:225], v[198:201], v[80:83]
	v_mfma_f32_16x16x32_bf16 v[68:71], v[214:217], v[206:209], v[68:71]
	v_mfma_f32_16x16x32_bf16 v[64:67], v[222:225], v[206:209], v[64:67]
	v_mfma_f32_16x16x32_bf16 v[116:119], v[218:221], v[166:169], v[116:119]
	v_mfma_f32_16x16x32_bf16 v[112:115], v[226:229], v[166:169], v[112:115]
	v_mfma_f32_16x16x32_bf16 v[100:103], v[218:221], v[194:197], v[100:103]
	v_mfma_f32_16x16x32_bf16 v[96:99], v[226:229], v[194:197], v[96:99]
	v_mfma_f32_16x16x32_bf16 v[84:87], v[218:221], v[202:205], v[84:87]
	v_mfma_f32_16x16x32_bf16 v[80:83], v[226:229], v[202:205], v[80:83]
	v_mfma_f32_16x16x32_bf16 v[68:71], v[218:221], v[210:213], v[68:71]
	v_mfma_f32_16x16x32_bf16 v[64:67], v[226:229], v[210:213], v[64:67]
	s_setprio 0
	s_mov_b32 m0, s45
	v_lshl_add_u64 v[234:235], s[36:37], 0, v[144:145]
	s_barrier
	ds_read_b128 v[162:165], v151 offset:16384
	ds_read_b128 v[166:169], v151 offset:17408
	ds_read_b128 v[190:193], v151 offset:18432
	ds_read_b128 v[194:197], v151 offset:19456
	ds_read_b128 v[198:201], v151 offset:20480
	ds_read_b128 v[202:205], v151 offset:21504
	ds_read_b128 v[206:209], v151 offset:22528
	ds_read_b128 v[210:213], v151 offset:23552
	global_load_lds_dwordx4 v[234:235], off
	v_lshl_add_u64 v[236:237], s[36:37], 0, v[146:147]
	s_mov_b32 m0, s48
	s_nop 0
	global_load_lds_dwordx4 v[236:237], off
	s_barrier
	s_waitcnt lgkmcnt(0)
	s_setprio 1
	s_waitcnt lgkmcnt(0)
	v_mfma_f32_16x16x32_bf16 v[60:63], v[128:131], v[162:165], v[60:63]
	v_mfma_f32_16x16x32_bf16 v[56:59], v[136:139], v[162:165], v[56:59]
	v_mfma_f32_16x16x32_bf16 v[44:47], v[128:131], v[190:193], v[44:47]
	v_mfma_f32_16x16x32_bf16 v[40:43], v[136:139], v[190:193], v[40:43]
	v_mfma_f32_16x16x32_bf16 v[28:31], v[128:131], v[198:201], v[28:31]
	v_mfma_f32_16x16x32_bf16 v[24:27], v[136:139], v[198:201], v[24:27]
	v_mfma_f32_16x16x32_bf16 v[12:15], v[128:131], v[206:209], v[12:15]
	v_mfma_f32_16x16x32_bf16 v[8:11], v[136:139], v[206:209], v[8:11]
	v_mfma_f32_16x16x32_bf16 v[60:63], v[132:135], v[166:169], v[60:63]
	v_mfma_f32_16x16x32_bf16 v[56:59], v[140:143], v[166:169], v[56:59]
	v_mfma_f32_16x16x32_bf16 v[44:47], v[132:135], v[194:197], v[44:47]
	v_mfma_f32_16x16x32_bf16 v[40:43], v[140:143], v[194:197], v[40:43]
	v_mfma_f32_16x16x32_bf16 v[28:31], v[132:135], v[202:205], v[28:31]
	v_mfma_f32_16x16x32_bf16 v[24:27], v[140:143], v[202:205], v[24:27]
	v_mfma_f32_16x16x32_bf16 v[12:15], v[132:135], v[210:213], v[12:15]
	v_mfma_f32_16x16x32_bf16 v[8:11], v[140:143], v[210:213], v[8:11]
	s_setprio 0
	s_barrier
	s_add_u32 s70, s34, 0x40000
	s_addc_u32 s71, s35, 0
	s_mov_b32 m0, s49
	v_lshl_add_u64 v[128:129], s[70:71], 0, v[144:145]
	global_load_lds_dwordx4 v[128:129], off
	v_lshl_add_u64 v[128:129], s[70:71], 0, v[146:147]
	s_mov_b32 m0, s52
	s_nop 0
	global_load_lds_dwordx4 v[128:129], off
	s_waitcnt vmcnt(6)
	s_barrier
	s_setprio 1
	v_mfma_f32_16x16x32_bf16 v[52:55], v[214:217], v[162:165], v[52:55]
	v_mfma_f32_16x16x32_bf16 v[48:51], v[222:225], v[162:165], v[48:51]
	v_mfma_f32_16x16x32_bf16 v[36:39], v[214:217], v[190:193], v[36:39]
	v_mfma_f32_16x16x32_bf16 v[32:35], v[222:225], v[190:193], v[32:35]
	v_mfma_f32_16x16x32_bf16 v[20:23], v[214:217], v[198:201], v[20:23]
	v_mfma_f32_16x16x32_bf16 v[16:19], v[222:225], v[198:201], v[16:19]
	v_mfma_f32_16x16x32_bf16 v[4:7], v[214:217], v[206:209], v[4:7]
	v_mfma_f32_16x16x32_bf16 v[0:3], v[222:225], v[206:209], v[0:3]
	v_mfma_f32_16x16x32_bf16 v[52:55], v[218:221], v[166:169], v[52:55]
	v_mfma_f32_16x16x32_bf16 v[48:51], v[226:229], v[166:169], v[48:51]
	v_mfma_f32_16x16x32_bf16 v[36:39], v[218:221], v[194:197], v[36:39]
	v_mfma_f32_16x16x32_bf16 v[32:35], v[226:229], v[194:197], v[32:35]
	v_mfma_f32_16x16x32_bf16 v[20:23], v[218:221], v[202:205], v[20:23]
	v_mfma_f32_16x16x32_bf16 v[16:19], v[226:229], v[202:205], v[16:19]
	v_mfma_f32_16x16x32_bf16 v[4:7], v[218:221], v[210:213], v[4:7]
	v_mfma_f32_16x16x32_bf16 v[0:3], v[226:229], v[210:213], v[0:3]
	s_setprio 0
	s_barrier
	ds_read_b128 v[128:131], v180
	ds_read_b128 v[132:135], v181
	ds_read_b128 v[136:139], v182
	ds_read_b128 v[140:143], v183
	s_add_u32 s36, s36, 0x40000
	s_addc_u32 s37, s37, 0
	s_mov_b32 m0, s53
	v_lshl_add_u64 v[214:215], s[36:37], 0, v[144:145]
	ds_read_b128 v[162:165], v151 offset:32768
	ds_read_b128 v[166:169], v151 offset:33792
	ds_read_b128 v[190:193], v151 offset:34816
	ds_read_b128 v[194:197], v151 offset:35840
	ds_read_b128 v[198:201], v151 offset:36864
	ds_read_b128 v[202:205], v151 offset:37888
	ds_read_b128 v[206:209], v151 offset:38912
	ds_read_b128 v[210:213], v151 offset:39936
	global_load_lds_dwordx4 v[214:215], off
	v_lshl_add_u64 v[214:215], s[36:37], 0, v[146:147]
	s_mov_b32 m0, s54
	s_nop 0
	global_load_lds_dwordx4 v[214:215], off
	s_waitcnt lgkmcnt(8)
	s_barrier
	s_waitcnt lgkmcnt(0)
	s_setprio 1
	s_waitcnt lgkmcnt(0)
	v_mfma_f32_16x16x32_bf16 v[124:127], v[128:131], v[162:165], v[124:127]
	v_mfma_f32_16x16x32_bf16 v[120:123], v[136:139], v[162:165], v[120:123]
	v_mfma_f32_16x16x32_bf16 v[108:111], v[128:131], v[190:193], v[108:111]
	v_mfma_f32_16x16x32_bf16 v[104:107], v[136:139], v[190:193], v[104:107]
	v_mfma_f32_16x16x32_bf16 v[92:95], v[128:131], v[198:201], v[92:95]
	v_mfma_f32_16x16x32_bf16 v[88:91], v[136:139], v[198:201], v[88:91]
	v_mfma_f32_16x16x32_bf16 v[76:79], v[128:131], v[206:209], v[76:79]
	v_mfma_f32_16x16x32_bf16 v[72:75], v[136:139], v[206:209], v[72:75]
	v_mfma_f32_16x16x32_bf16 v[124:127], v[132:135], v[166:169], v[124:127]
	v_mfma_f32_16x16x32_bf16 v[120:123], v[140:143], v[166:169], v[120:123]
	v_mfma_f32_16x16x32_bf16 v[108:111], v[132:135], v[194:197], v[108:111]
	v_mfma_f32_16x16x32_bf16 v[104:107], v[140:143], v[194:197], v[104:107]
	v_mfma_f32_16x16x32_bf16 v[92:95], v[132:135], v[202:205], v[92:95]
	v_mfma_f32_16x16x32_bf16 v[88:91], v[140:143], v[202:205], v[88:91]
	v_mfma_f32_16x16x32_bf16 v[76:79], v[132:135], v[210:213], v[76:79]
	v_mfma_f32_16x16x32_bf16 v[72:75], v[140:143], v[210:213], v[72:75]
	s_setprio 0
	s_barrier
	s_mov_b32 m0, s56
	v_lshl_add_u64 v[230:231], v[230:231], 0, s[10:11]
	ds_read_b128 v[214:217], v184
	ds_read_b128 v[218:221], v185
	ds_read_b128 v[222:225], v186
	ds_read_b128 v[226:229], v187
	global_load_lds_dwordx4 v[230:231], off
	v_lshl_add_u64 v[230:231], v[232:233], 0, s[10:11]
	s_mov_b32 m0, s57
	s_nop 0
	global_load_lds_dwordx4 v[230:231], off
	s_barrier
	s_waitcnt lgkmcnt(0)
	s_setprio 1
	s_waitcnt lgkmcnt(0)
	v_mfma_f32_16x16x32_bf16 v[116:119], v[214:217], v[162:165], v[116:119]
	v_mfma_f32_16x16x32_bf16 v[112:115], v[222:225], v[162:165], v[112:115]
	v_mfma_f32_16x16x32_bf16 v[100:103], v[214:217], v[190:193], v[100:103]
	v_mfma_f32_16x16x32_bf16 v[96:99], v[222:225], v[190:193], v[96:99]
	v_mfma_f32_16x16x32_bf16 v[84:87], v[214:217], v[198:201], v[84:87]
	v_mfma_f32_16x16x32_bf16 v[80:83], v[222:225], v[198:201], v[80:83]
	v_mfma_f32_16x16x32_bf16 v[68:71], v[214:217], v[206:209], v[68:71]
	v_mfma_f32_16x16x32_bf16 v[64:67], v[222:225], v[206:209], v[64:67]
	v_mfma_f32_16x16x32_bf16 v[116:119], v[218:221], v[166:169], v[116:119]
	v_mfma_f32_16x16x32_bf16 v[112:115], v[226:229], v[166:169], v[112:115]
	v_mfma_f32_16x16x32_bf16 v[100:103], v[218:221], v[194:197], v[100:103]
	v_mfma_f32_16x16x32_bf16 v[96:99], v[226:229], v[194:197], v[96:99]
	v_mfma_f32_16x16x32_bf16 v[84:87], v[218:221], v[202:205], v[84:87]
	v_mfma_f32_16x16x32_bf16 v[80:83], v[226:229], v[202:205], v[80:83]
	v_mfma_f32_16x16x32_bf16 v[68:71], v[218:221], v[210:213], v[68:71]
	v_mfma_f32_16x16x32_bf16 v[64:67], v[226:229], v[210:213], v[64:67]
	s_setprio 0
	s_mov_b32 m0, s58
	v_lshl_add_u64 v[230:231], v[234:235], 0, s[10:11]
	s_barrier
	ds_read_b128 v[162:165], v151 offset:49152
	ds_read_b128 v[166:169], v151 offset:50176
	ds_read_b128 v[190:193], v151 offset:51200
	ds_read_b128 v[194:197], v151 offset:52224
	ds_read_b128 v[198:201], v151 offset:53248
	ds_read_b128 v[202:205], v151 offset:54272
	ds_read_b128 v[206:209], v151 offset:55296
	ds_read_b128 v[210:213], v151 offset:56320
	global_load_lds_dwordx4 v[230:231], off
	v_lshl_add_u64 v[230:231], v[236:237], 0, s[10:11]
	s_mov_b32 m0, s59
	s_nop 0
	global_load_lds_dwordx4 v[230:231], off
	s_barrier
	s_waitcnt lgkmcnt(0)
	s_setprio 1
	s_waitcnt lgkmcnt(0)
	v_mfma_f32_16x16x32_bf16 v[60:63], v[128:131], v[162:165], v[60:63]
	v_mfma_f32_16x16x32_bf16 v[56:59], v[136:139], v[162:165], v[56:59]
	v_mfma_f32_16x16x32_bf16 v[44:47], v[128:131], v[190:193], v[44:47]
	v_mfma_f32_16x16x32_bf16 v[40:43], v[136:139], v[190:193], v[40:43]
	v_mfma_f32_16x16x32_bf16 v[28:31], v[128:131], v[198:201], v[28:31]
	v_mfma_f32_16x16x32_bf16 v[24:27], v[136:139], v[198:201], v[24:27]
	v_mfma_f32_16x16x32_bf16 v[12:15], v[128:131], v[206:209], v[12:15]
	v_mfma_f32_16x16x32_bf16 v[8:11], v[136:139], v[206:209], v[8:11]
	v_mfma_f32_16x16x32_bf16 v[60:63], v[132:135], v[166:169], v[60:63]
	v_mfma_f32_16x16x32_bf16 v[56:59], v[140:143], v[166:169], v[56:59]
	v_mfma_f32_16x16x32_bf16 v[44:47], v[132:135], v[194:197], v[44:47]
	v_mfma_f32_16x16x32_bf16 v[40:43], v[140:143], v[194:197], v[40:43]
	v_mfma_f32_16x16x32_bf16 v[28:31], v[132:135], v[202:205], v[28:31]
	v_mfma_f32_16x16x32_bf16 v[24:27], v[140:143], v[202:205], v[24:27]
	v_mfma_f32_16x16x32_bf16 v[12:15], v[132:135], v[210:213], v[12:15]
	v_mfma_f32_16x16x32_bf16 v[8:11], v[140:143], v[210:213], v[8:11]
	s_setprio 0
	s_barrier
	s_add_u32 s34, s34, 0x40080
	s_addc_u32 s35, s35, 0
	s_mov_b32 m0, s60
	v_lshl_add_u64 v[128:129], s[34:35], 0, v[144:145]
	global_load_lds_dwordx4 v[128:129], off
	v_lshl_add_u64 v[128:129], s[34:35], 0, v[146:147]
	s_mov_b32 m0, s61
	s_nop 0
	global_load_lds_dwordx4 v[128:129], off
	s_waitcnt vmcnt(6)
	s_barrier
	s_setprio 1
	v_mfma_f32_16x16x32_bf16 v[52:55], v[214:217], v[162:165], v[52:55]
	v_mfma_f32_16x16x32_bf16 v[48:51], v[222:225], v[162:165], v[48:51]
	v_mfma_f32_16x16x32_bf16 v[36:39], v[214:217], v[190:193], v[36:39]
	v_mfma_f32_16x16x32_bf16 v[32:35], v[222:225], v[190:193], v[32:35]
	v_mfma_f32_16x16x32_bf16 v[20:23], v[214:217], v[198:201], v[20:23]
	v_mfma_f32_16x16x32_bf16 v[16:19], v[222:225], v[198:201], v[16:19]
	v_mfma_f32_16x16x32_bf16 v[4:7], v[214:217], v[206:209], v[4:7]
	v_mfma_f32_16x16x32_bf16 v[0:3], v[222:225], v[206:209], v[0:3]
	v_mfma_f32_16x16x32_bf16 v[52:55], v[218:221], v[166:169], v[52:55]
	v_mfma_f32_16x16x32_bf16 v[48:51], v[226:229], v[166:169], v[48:51]
	v_mfma_f32_16x16x32_bf16 v[36:39], v[218:221], v[194:197], v[36:39]
	v_mfma_f32_16x16x32_bf16 v[32:35], v[226:229], v[194:197], v[32:35]
	v_mfma_f32_16x16x32_bf16 v[20:23], v[218:221], v[202:205], v[20:23]
	v_mfma_f32_16x16x32_bf16 v[16:19], v[226:229], v[202:205], v[16:19]
	v_mfma_f32_16x16x32_bf16 v[4:7], v[218:221], v[210:213], v[4:7]
	v_mfma_f32_16x16x32_bf16 v[0:3], v[226:229], v[210:213], v[0:3]
	s_setprio 0
	s_add_i32 s69, s69, 2
	s_add_u32 s67, s67, 0x100
	s_addc_u32 s68, s68, 0
	s_add_u32 s30, s30, 0x100
	s_addc_u32 s31, s31, 0
	s_cmp_gt_u32 s69, 13
	s_barrier
	s_cbranch_scc0 .LBB0_1480
	v_bfe_i32 v249, v176, 3, 1
	v_and_b32_e32 v248, 0xffff8040, v249
	v_mov_b32_e32 v250, 0x8000
	v_mov_b32_e32 v251, 0
	s_ashr_i32 s29, s28, 31
	s_lshl_b64 s[28:29], s[28:29], 8
	s_lshl_b32 s30, s12, 8
	v_lshl_add_u64 v[164:165], s[28:29], 0, v[148:149]
	s_ashr_i32 s31, s30, 31
	v_lshl_add_u64 v[166:167], s[30:31], 2, v[152:153]
	v_lshlrev_b64 v[128:129], 12, v[164:165]
	v_lshl_add_u64 v[128:129], v[166:167], 0, v[128:129]
	v_lshl_add_u64 v[232:233], v[128:129], 0, v[248:249]
	v_lshl_add_u64 v[234:235], v[232:233], 0, v[250:251]
	global_load_dwordx4 v[190:193], v[232:233], off
	global_load_dwordx4 v[194:197], v[234:235], off
	global_load_dwordx4 v[198:201], v[232:233], off offset:512
	global_load_dwordx4 v[202:205], v[234:235], off offset:512
	v_or_b32_e32 v168, 16, v164
	v_mov_b32_e32 v169, v165
	v_lshlrev_b64 v[128:129], 12, v[168:169]
	v_lshl_add_u64 v[128:129], v[166:167], 0, v[128:129]
	v_lshl_add_u64 v[236:237], v[128:129], 0, v[248:249]
	v_lshl_add_u64 v[238:239], v[236:237], 0, v[250:251]
	global_load_dwordx4 v[140:143], v[236:237], off
	global_load_dwordx4 v[136:139], v[238:239], off
	global_load_dwordx4 v[132:135], v[236:237], off offset:512
	s_nop 0
	global_load_dwordx4 v[128:131], v[238:239], off offset:512
	v_and_b32_e32 v163, 64, v188
	v_xor_b32_e32 v189, 16, v188
	v_add_u32_e32 v207, 64, v163
	v_xor_b32_e32 v206, 32, v188
	v_cmp_lt_i32_e32 vcc, v189, v207
	v_or_b32_e32 v162, s30, v150
	v_mov_b32_e32 v163, s31
	v_cndmask_b32_e32 v189, v188, v189, vcc
	v_cmp_lt_i32_e32 vcc, v206, v207
	s_waitcnt vmcnt(0)
	v_lshlrev_b32_e32 v189, 2, v189
	s_lshl_b32 s28, s12, 2
	v_cndmask_b32_e32 v216, v188, v206, vcc
	v_lshlrev_b64 v[206:207], 10, v[164:165]
	v_lshl_add_u64 v[206:207], v[206:207], 0, v[162:163]
	v_lshl_add_u64 v[208:209], v[206:207], 2, s[78:79]
	v_lshlrev_b64 v[206:207], 1, v[206:207]
	v_lshl_add_u64 v[210:211], s[2:3], 0, v[206:207]
	v_or_b32_e32 v212, 32, v206
	v_mov_b32_e32 v213, v207
	v_or_b32_e32 v214, 0x100, v206
	v_mov_b32_e32 v215, v207
	v_lshl_add_u64 v[212:213], s[2:3], 0, v[212:213]
	v_lshl_add_u64 v[214:215], s[2:3], 0, v[214:215]
	v_or_b32_e32 v206, 0x120, v206
	s_ashr_i32 s29, s28, 31
	s_waitcnt vmcnt(0)
	v_mov_b32_dpp v224, v190 row_ror:8 row_mask:0xf bank_mask:0xf
	v_mov_b32_dpp v225, v191 row_ror:8 row_mask:0xf bank_mask:0xf
	v_mov_b32_dpp v226, v192 row_ror:8 row_mask:0xf bank_mask:0xf
	v_mov_b32_dpp v227, v193 row_ror:8 row_mask:0xf bank_mask:0xf
	v_mov_b32_dpp v190, v194 row_ror:8 row_mask:0xf bank_mask:0xc
	v_mov_b32_dpp v191, v195 row_ror:8 row_mask:0xf bank_mask:0xc
	v_mov_b32_dpp v192, v196 row_ror:8 row_mask:0xf bank_mask:0xc
	v_mov_b32_dpp v193, v197 row_ror:8 row_mask:0xf bank_mask:0xc
	v_mov_b32_dpp v194, v224 quad_perm:[0,1,2,3] row_mask:0xf bank_mask:0x3
	v_mov_b32_dpp v195, v225 quad_perm:[0,1,2,3] row_mask:0xf bank_mask:0x3
	v_mov_b32_dpp v196, v226 quad_perm:[0,1,2,3] row_mask:0xf bank_mask:0x3
	v_mov_b32_dpp v197, v227 quad_perm:[0,1,2,3] row_mask:0xf bank_mask:0x3
	v_mov_b32_dpp v224, v198 row_ror:8 row_mask:0xf bank_mask:0xf
	v_mov_b32_dpp v225, v199 row_ror:8 row_mask:0xf bank_mask:0xf
	v_mov_b32_dpp v226, v200 row_ror:8 row_mask:0xf bank_mask:0xf
	v_mov_b32_dpp v227, v201 row_ror:8 row_mask:0xf bank_mask:0xf
	v_mov_b32_dpp v198, v202 row_ror:8 row_mask:0xf bank_mask:0xc
	v_mov_b32_dpp v199, v203 row_ror:8 row_mask:0xf bank_mask:0xc
	v_mov_b32_dpp v200, v204 row_ror:8 row_mask:0xf bank_mask:0xc
	v_mov_b32_dpp v201, v205 row_ror:8 row_mask:0xf bank_mask:0xc
	v_mov_b32_dpp v202, v224 quad_perm:[0,1,2,3] row_mask:0xf bank_mask:0x3
	v_mov_b32_dpp v203, v225 quad_perm:[0,1,2,3] row_mask:0xf bank_mask:0x3
	v_mov_b32_dpp v204, v226 quad_perm:[0,1,2,3] row_mask:0xf bank_mask:0x3
	v_mov_b32_dpp v205, v227 quad_perm:[0,1,2,3] row_mask:0xf bank_mask:0x3
	v_pk_add_f32 v[126:127], v[126:127], v[192:193]
	v_pk_add_f32 v[124:125], v[124:125], v[190:191]
	v_pk_add_f32 v[120:121], v[120:121], v[194:195]
	v_pk_add_f32 v[122:123], v[122:123], v[196:197]
	v_pk_add_f32 v[116:117], v[116:117], v[198:199]
	v_pk_add_f32 v[190:191], v[112:113], v[202:203]
	global_store_dwordx4 v[208:209], v[124:127], off
	v_cvt_pk_bf16_f32 v112, v124, v125
	v_mul_f32_e32 v196, v120, v120
	v_mul_f32_e32 v197, v116, v116
	v_mul_f32_e32 v124, v124, v124
	v_fmac_f32_e32 v124, v125, v125
	v_fmac_f32_e32 v196, v121, v121
	v_pk_add_f32 v[118:119], v[118:119], v[200:201]
	v_mul_f32_e32 v198, v190, v190
	v_fmac_f32_e32 v197, v117, v117
	v_fmac_f32_e32 v124, v126, v126
	v_fmac_f32_e32 v196, v122, v122
	v_pk_add_f32 v[192:193], v[114:115], v[204:205]
	v_fmac_f32_e32 v198, v191, v191
	v_fmac_f32_e32 v197, v118, v118
	v_fmac_f32_e32 v124, v127, v127
	v_fmac_f32_e32 v196, v123, v123
	v_cvt_pk_bf16_f32 v113, v126, v127
	v_bfe_u32 v246, v176, 4, 1
	v_mul_u32_u24_e32 v246, 24, v246
	v_mov_b32_e32 v247, 0
	s_nop 1
	v_mov_b32_e32 v240, v112
	v_mov_b32_e32 v241, v113
	v_lshl_add_u64 v[244:245], v[210:211], 0, v[246:247]
	v_fmac_f32_e32 v198, v192, v192
	v_fmac_f32_e32 v197, v119, v119
	v_add_f32_e32 v112, v124, v196
	v_fmac_f32_e32 v198, v193, v193
	v_add_f32_e32 v112, v112, v197
	v_add_f32_e32 v112, v112, v198
	ds_bpermute_b32 v113, v189, v112
	v_cvt_pk_bf16_f32 v114, v120, v121
	v_cvt_pk_bf16_f32 v115, v122, v123
	v_cvt_pk_bf16_f32 v194, v116, v117
	v_cvt_pk_bf16_f32 v195, v118, v119
	global_store_dwordx4 v[208:209], v[120:123], off offset:64
	v_mov_b32_e32 v242, v114
	v_mov_b32_e32 v243, v115
	s_nop 1
	v_permlane16_swap_b32 v240, v242
	v_permlane16_swap_b32 v241, v243
	global_store_dwordx4 v[244:245], v[240:243], off
	global_store_dwordx4 v[208:209], v[116:119], off offset:512
	s_nop 1
	v_mov_b32_e32 v240, v194
	v_mov_b32_e32 v241, v195
	v_lshl_add_u64 v[244:245], v[214:215], 0, v[246:247]
	global_store_dwordx4 v[208:209], v[190:193], off offset:576
	s_waitcnt lgkmcnt(0)
	v_add_f32_e32 v112, v112, v113
	v_lshlrev_b32_e32 v116, 2, v216
	ds_bpermute_b32 v113, v116, v112
	v_lshl_add_u64 v[114:115], s[2:3], 0, v[206:207]
	v_cvt_pk_bf16_f32 v118, v190, v191
	v_cvt_pk_bf16_f32 v119, v192, v193
	v_mov_b32_e32 v242, v118
	v_mov_b32_e32 v243, v119
	s_nop 1
	v_permlane16_swap_b32 v240, v242
	v_permlane16_swap_b32 v241, v243
	global_store_dwordx4 v[244:245], v[240:243], off
	s_and_saveexec_b64 s[30:31], s[6:7]
	s_cbranch_execz .LBB0_1483
	v_lshlrev_b64 v[114:115], 6, v[164:165]
	v_lshl_add_u64 v[114:115], s[4:5], 0, v[114:115]
	v_lshl_add_u64 v[114:115], s[28:29], 2, v[114:115]
	s_lshl_b32 s12, s55, 2
	v_lshl_add_u64 v[114:115], v[114:115], 0, s[12:13]
	s_waitcnt lgkmcnt(0)
	v_add_f32_e32 v112, v112, v113
	flat_store_dword v[114:115], v112
.LBB0_1483:
	s_or_b64 exec, exec, s[30:31]
	s_waitcnt lgkmcnt(0)
	v_lshlrev_b64 v[112:113], 10, v[168:169]
	v_lshl_add_u64 v[112:113], v[112:113], 0, v[162:163]
	v_mov_b32_dpp v224, v140 row_ror:8 row_mask:0xf bank_mask:0xf
	v_mov_b32_dpp v225, v141 row_ror:8 row_mask:0xf bank_mask:0xf
	v_mov_b32_dpp v226, v142 row_ror:8 row_mask:0xf bank_mask:0xf
	v_mov_b32_dpp v227, v143 row_ror:8 row_mask:0xf bank_mask:0xf
	v_mov_b32_dpp v140, v136 row_ror:8 row_mask:0xf bank_mask:0xc
	v_mov_b32_dpp v141, v137 row_ror:8 row_mask:0xf bank_mask:0xc
	v_mov_b32_dpp v142, v138 row_ror:8 row_mask:0xf bank_mask:0xc
	v_mov_b32_dpp v143, v139 row_ror:8 row_mask:0xf bank_mask:0xc
	v_mov_b32_dpp v136, v224 quad_perm:[0,1,2,3] row_mask:0xf bank_mask:0x3
	v_mov_b32_dpp v137, v225 quad_perm:[0,1,2,3] row_mask:0xf bank_mask:0x3
	v_mov_b32_dpp v138, v226 quad_perm:[0,1,2,3] row_mask:0xf bank_mask:0x3
	v_mov_b32_dpp v139, v227 quad_perm:[0,1,2,3] row_mask:0xf bank_mask:0x3
	v_mov_b32_dpp v224, v132 row_ror:8 row_mask:0xf bank_mask:0xf
	v_mov_b32_dpp v225, v133 row_ror:8 row_mask:0xf bank_mask:0xf
	v_mov_b32_dpp v226, v134 row_ror:8 row_mask:0xf bank_mask:0xf
	v_mov_b32_dpp v227, v135 row_ror:8 row_mask:0xf bank_mask:0xf
	v_mov_b32_dpp v132, v128 row_ror:8 row_mask:0xf bank_mask:0xc
	v_mov_b32_dpp v133, v129 row_ror:8 row_mask:0xf bank_mask:0xc
	v_mov_b32_dpp v134, v130 row_ror:8 row_mask:0xf bank_mask:0xc
	v_mov_b32_dpp v135, v131 row_ror:8 row_mask:0xf bank_mask:0xc
	v_mov_b32_dpp v128, v224 quad_perm:[0,1,2,3] row_mask:0xf bank_mask:0x3
	v_mov_b32_dpp v129, v225 quad_perm:[0,1,2,3] row_mask:0xf bank_mask:0x3
	v_mov_b32_dpp v130, v226 quad_perm:[0,1,2,3] row_mask:0xf bank_mask:0x3
	v_mov_b32_dpp v131, v227 quad_perm:[0,1,2,3] row_mask:0xf bank_mask:0x3
	v_pk_add_f32 v[108:109], v[108:109], v[140:141]
	v_lshl_add_u64 v[114:115], v[112:113], 2, s[78:79]
	v_lshlrev_b64 v[112:113], 1, v[112:113]
	v_mul_f32_e32 v117, v108, v108
	v_pk_add_f32 v[110:111], v[110:111], v[142:143]
	v_lshl_add_u64 v[118:119], s[2:3], 0, v[112:113]
	v_fmac_f32_e32 v117, v109, v109
	v_pk_add_f32 v[106:107], v[106:107], v[138:139]
	v_pk_add_f32 v[104:105], v[104:105], v[136:137]
	global_store_dwordx4 v[114:115], v[108:111], off
	v_cvt_pk_bf16_f32 v120, v108, v109
	v_cvt_pk_bf16_f32 v121, v110, v111
	s_nop 1
	v_mov_b32_e32 v240, v120
	v_mov_b32_e32 v241, v121
	v_lshl_add_u64 v[244:245], v[118:119], 0, v[246:247]
	v_fmac_f32_e32 v117, v110, v110
	global_store_dwordx4 v[114:115], v[104:107], off offset:64
	v_or_b32_e32 v108, 32, v112
	v_mov_b32_e32 v109, v113
	v_cvt_pk_bf16_f32 v110, v104, v105
	v_mul_f32_e32 v104, v104, v104
	v_lshl_add_u64 v[108:109], s[2:3], 0, v[108:109]
	v_fmac_f32_e32 v104, v105, v105
	v_pk_add_f32 v[102:103], v[102:103], v[134:135]
	v_pk_add_f32 v[100:101], v[100:101], v[132:133]
	v_fmac_f32_e32 v117, v111, v111
	v_cvt_pk_bf16_f32 v111, v106, v107
	v_mov_b32_e32 v242, v110
	v_mov_b32_e32 v243, v111
	s_nop 1
	v_permlane16_swap_b32 v240, v242
	v_permlane16_swap_b32 v241, v243
	global_store_dwordx4 v[244:245], v[240:243], off
	v_fmac_f32_e32 v104, v106, v106
	global_store_dwordx4 v[114:115], v[100:103], off offset:512
	v_cvt_pk_bf16_f32 v106, v100, v101
	v_fmac_f32_e32 v104, v107, v107
	v_add_f32_e32 v107, v117, v104
	v_mul_f32_e32 v100, v100, v100
	v_fmac_f32_e32 v100, v101, v101
	v_fmac_f32_e32 v100, v102, v102
	v_fmac_f32_e32 v100, v103, v103
	v_add_f32_e32 v107, v107, v100
	v_pk_add_f32 v[100:101], v[98:99], v[130:131]
	v_pk_add_f32 v[98:99], v[96:97], v[128:129]
	v_or_b32_e32 v104, 0x100, v112
	v_mul_f32_e32 v96, v98, v98
	v_fmac_f32_e32 v96, v99, v99
	v_fmac_f32_e32 v96, v100, v100
	v_fmac_f32_e32 v96, v101, v101
	v_add_f32_e32 v96, v107, v96
	ds_bpermute_b32 v97, v189, v96
	v_mov_b32_e32 v105, v113
	v_or_b32_e32 v112, 0x120, v112
	v_lshl_add_u64 v[104:105], s[2:3], 0, v[104:105]
	v_cvt_pk_bf16_f32 v107, v102, v103
	s_waitcnt lgkmcnt(0)
	v_add_f32_e32 v96, v96, v97
	ds_bpermute_b32 v97, v116, v96
	v_lshl_add_u64 v[102:103], s[2:3], 0, v[112:113]
	s_nop 1
	v_mov_b32_e32 v240, v106
	v_mov_b32_e32 v241, v107
	v_lshl_add_u64 v[244:245], v[104:105], 0, v[246:247]
	global_store_dwordx4 v[114:115], v[98:101], off offset:576
	s_nop 1
	v_cvt_pk_bf16_f32 v98, v98, v99
	v_cvt_pk_bf16_f32 v99, v100, v101
	v_mov_b32_e32 v242, v98
	v_mov_b32_e32 v243, v99
	s_nop 1
	v_permlane16_swap_b32 v240, v242
	v_permlane16_swap_b32 v241, v243
	global_store_dwordx4 v[244:245], v[240:243], off
	s_and_saveexec_b64 s[30:31], s[6:7]
	s_cbranch_execz .LBB0_1485
	v_lshlrev_b64 v[98:99], 6, v[168:169]
	v_lshl_add_u64 v[98:99], s[4:5], 0, v[98:99]
	v_lshl_add_u64 v[98:99], s[28:29], 2, v[98:99]
	s_lshl_b32 s12, s55, 2
	v_lshl_add_u64 v[98:99], v[98:99], 0, s[12:13]
	s_waitcnt lgkmcnt(0)
	v_add_f32_e32 v96, v96, v97
	flat_store_dword v[98:99], v96
.LBB0_1485:
	s_or_b64 exec, exec, s[30:31]
	v_or_b32_e32 v114, 32, v164
	v_mov_b32_e32 v115, v165
	s_waitcnt lgkmcnt(0)
	v_lshlrev_b64 v[96:97], 12, v[114:115]
	v_lshl_add_u64 v[96:97], v[166:167], 0, v[96:97]
	v_lshl_add_u64 v[232:233], v[96:97], 0, v[248:249]
	v_lshl_add_u64 v[234:235], v[232:233], 0, v[250:251]
	global_load_dwordx4 v[118:121], v[232:233], off
	global_load_dwordx4 v[122:125], v[234:235], off
	global_load_dwordx4 v[126:129], v[232:233], off offset:512
	global_load_dwordx4 v[130:133], v[234:235], off offset:512
	v_or_b32_e32 v112, 48, v164
	v_mov_b32_e32 v113, v165
	v_lshlrev_b64 v[96:97], 12, v[112:113]
	v_lshl_add_u64 v[96:97], v[166:167], 0, v[96:97]
	v_lshl_add_u64 v[236:237], v[96:97], 0, v[248:249]
	v_lshl_add_u64 v[238:239], v[236:237], 0, v[250:251]
	global_load_dwordx4 v[108:111], v[236:237], off
	global_load_dwordx4 v[104:107], v[238:239], off
	global_load_dwordx4 v[100:103], v[236:237], off offset:512
	s_nop 0
	global_load_dwordx4 v[96:99], v[238:239], off offset:512
	v_lshlrev_b64 v[134:135], 10, v[114:115]
	v_lshl_add_u64 v[134:135], v[134:135], 0, v[162:163]
	v_lshl_add_u64 v[136:137], v[134:135], 2, s[78:79]
	v_lshlrev_b64 v[134:135], 1, v[134:135]
	v_lshl_add_u64 v[138:139], s[2:3], 0, v[134:135]
	s_waitcnt vmcnt(0)
	v_or_b32_e32 v140, 32, v134
	v_mov_b32_e32 v141, v135
	v_or_b32_e32 v142, 0x100, v134
	v_mov_b32_e32 v143, v135
	v_or_b32_e32 v134, 0x120, v134
	v_lshl_add_u64 v[140:141], s[2:3], 0, v[140:141]
	v_lshl_add_u64 v[142:143], s[2:3], 0, v[142:143]
	s_waitcnt vmcnt(0)
	v_mov_b32_dpp v224, v118 row_ror:8 row_mask:0xf bank_mask:0xf
	v_mov_b32_dpp v225, v119 row_ror:8 row_mask:0xf bank_mask:0xf
	v_mov_b32_dpp v226, v120 row_ror:8 row_mask:0xf bank_mask:0xf
	v_mov_b32_dpp v227, v121 row_ror:8 row_mask:0xf bank_mask:0xf
	v_mov_b32_dpp v118, v122 row_ror:8 row_mask:0xf bank_mask:0xc
	v_mov_b32_dpp v119, v123 row_ror:8 row_mask:0xf bank_mask:0xc
	v_mov_b32_dpp v120, v124 row_ror:8 row_mask:0xf bank_mask:0xc
	v_mov_b32_dpp v121, v125 row_ror:8 row_mask:0xf bank_mask:0xc
	v_mov_b32_dpp v122, v224 quad_perm:[0,1,2,3] row_mask:0xf bank_mask:0x3
	v_mov_b32_dpp v123, v225 quad_perm:[0,1,2,3] row_mask:0xf bank_mask:0x3
	v_mov_b32_dpp v124, v226 quad_perm:[0,1,2,3] row_mask:0xf bank_mask:0x3
	v_mov_b32_dpp v125, v227 quad_perm:[0,1,2,3] row_mask:0xf bank_mask:0x3
	v_mov_b32_dpp v224, v126 row_ror:8 row_mask:0xf bank_mask:0xf
	v_mov_b32_dpp v225, v127 row_ror:8 row_mask:0xf bank_mask:0xf
	v_mov_b32_dpp v226, v128 row_ror:8 row_mask:0xf bank_mask:0xf
	v_mov_b32_dpp v227, v129 row_ror:8 row_mask:0xf bank_mask:0xf
	v_mov_b32_dpp v126, v130 row_ror:8 row_mask:0xf bank_mask:0xc
	v_mov_b32_dpp v127, v131 row_ror:8 row_mask:0xf bank_mask:0xc
	v_mov_b32_dpp v128, v132 row_ror:8 row_mask:0xf bank_mask:0xc
	v_mov_b32_dpp v129, v133 row_ror:8 row_mask:0xf bank_mask:0xc
	v_mov_b32_dpp v130, v224 quad_perm:[0,1,2,3] row_mask:0xf bank_mask:0x3
	v_mov_b32_dpp v131, v225 quad_perm:[0,1,2,3] row_mask:0xf bank_mask:0x3
	v_mov_b32_dpp v132, v226 quad_perm:[0,1,2,3] row_mask:0xf bank_mask:0x3
	v_mov_b32_dpp v133, v227 quad_perm:[0,1,2,3] row_mask:0xf bank_mask:0x3
	v_pk_add_f32 v[92:93], v[92:93], v[118:119]
	v_pk_add_f32 v[88:89], v[88:89], v[122:123]
	v_pk_add_f32 v[84:85], v[84:85], v[126:127]
	v_mul_f32_e32 v117, v92, v92
	v_mul_f32_e32 v122, v88, v88
	v_pk_add_f32 v[94:95], v[94:95], v[120:121]
	v_pk_add_f32 v[90:91], v[90:91], v[124:125]
	v_pk_add_f32 v[118:119], v[80:81], v[130:131]
	v_mul_f32_e32 v123, v84, v84
	v_fmac_f32_e32 v117, v93, v93
	v_fmac_f32_e32 v122, v89, v89
	v_pk_add_f32 v[86:87], v[86:87], v[128:129]
	v_mul_f32_e32 v124, v118, v118
	v_fmac_f32_e32 v123, v85, v85
	v_fmac_f32_e32 v117, v94, v94
	v_fmac_f32_e32 v122, v90, v90
	v_pk_add_f32 v[120:121], v[82:83], v[132:133]
	v_cvt_pk_bf16_f32 v80, v92, v93
	v_fmac_f32_e32 v124, v119, v119
	v_fmac_f32_e32 v123, v86, v86
	v_fmac_f32_e32 v117, v95, v95
	v_fmac_f32_e32 v122, v91, v91
	global_store_dwordx4 v[136:137], v[92:95], off
	v_cvt_pk_bf16_f32 v81, v94, v95
	s_nop 1
	v_mov_b32_e32 v240, v80
	v_mov_b32_e32 v241, v81
	v_lshl_add_u64 v[244:245], v[138:139], 0, v[246:247]
	v_fmac_f32_e32 v124, v120, v120
	v_fmac_f32_e32 v123, v87, v87
	v_add_f32_e32 v80, v117, v122
	v_add_f32_e32 v80, v80, v123
	v_fmac_f32_e32 v124, v121, v121
	v_add_f32_e32 v80, v80, v124
	ds_bpermute_b32 v81, v189, v80
	v_cvt_pk_bf16_f32 v82, v88, v89
	v_cvt_pk_bf16_f32 v83, v90, v91
	v_cvt_pk_bf16_f32 v92, v84, v85
	global_store_dwordx4 v[136:137], v[88:91], off offset:64
	v_mov_b32_e32 v242, v82
	v_mov_b32_e32 v243, v83
	s_nop 1
	v_permlane16_swap_b32 v240, v242
	v_permlane16_swap_b32 v241, v243
	global_store_dwordx4 v[244:245], v[240:243], off
	s_waitcnt lgkmcnt(0)
	v_add_f32_e32 v80, v80, v81
	ds_bpermute_b32 v81, v116, v80
	v_cvt_pk_bf16_f32 v93, v86, v87
	v_lshl_add_u64 v[82:83], s[2:3], 0, v[134:135]
	global_store_dwordx4 v[136:137], v[84:87], off offset:512
	s_nop 1
	v_mov_b32_e32 v240, v92
	v_mov_b32_e32 v241, v93
	v_lshl_add_u64 v[244:245], v[142:143], 0, v[246:247]
	global_store_dwordx4 v[136:137], v[118:121], off offset:576
	v_cvt_pk_bf16_f32 v84, v118, v119
	v_cvt_pk_bf16_f32 v85, v120, v121
	v_mov_b32_e32 v242, v84
	v_mov_b32_e32 v243, v85
	s_nop 1
	v_permlane16_swap_b32 v240, v242
	v_permlane16_swap_b32 v241, v243
	global_store_dwordx4 v[244:245], v[240:243], off
	s_and_saveexec_b64 s[30:31], s[6:7]
	s_cbranch_execz .LBB0_1487
	v_lshlrev_b64 v[82:83], 6, v[114:115]
	v_lshl_add_u64 v[82:83], s[4:5], 0, v[82:83]
	v_lshl_add_u64 v[82:83], s[28:29], 2, v[82:83]
	s_lshl_b32 s12, s55, 2
	v_lshl_add_u64 v[82:83], v[82:83], 0, s[12:13]
	s_waitcnt lgkmcnt(0)
	v_add_f32_e32 v80, v80, v81
	flat_store_dword v[82:83], v80
.LBB0_1487:
	s_or_b64 exec, exec, s[30:31]
	s_waitcnt lgkmcnt(0)
	v_lshlrev_b64 v[80:81], 10, v[112:113]
	v_lshl_add_u64 v[80:81], v[80:81], 0, v[162:163]
	v_lshl_add_u64 v[82:83], v[80:81], 2, s[78:79]
	v_lshlrev_b64 v[80:81], 1, v[80:81]
	v_mov_b32_dpp v224, v108 row_ror:8 row_mask:0xf bank_mask:0xf
	v_mov_b32_dpp v225, v109 row_ror:8 row_mask:0xf bank_mask:0xf
	v_mov_b32_dpp v226, v110 row_ror:8 row_mask:0xf bank_mask:0xf
	v_mov_b32_dpp v227, v111 row_ror:8 row_mask:0xf bank_mask:0xf
	v_mov_b32_dpp v108, v104 row_ror:8 row_mask:0xf bank_mask:0xc
	v_mov_b32_dpp v109, v105 row_ror:8 row_mask:0xf bank_mask:0xc
	v_mov_b32_dpp v110, v106 row_ror:8 row_mask:0xf bank_mask:0xc
	v_mov_b32_dpp v111, v107 row_ror:8 row_mask:0xf bank_mask:0xc
	v_mov_b32_dpp v104, v224 quad_perm:[0,1,2,3] row_mask:0xf bank_mask:0x3
	v_mov_b32_dpp v105, v225 quad_perm:[0,1,2,3] row_mask:0xf bank_mask:0x3
	v_mov_b32_dpp v106, v226 quad_perm:[0,1,2,3] row_mask:0xf bank_mask:0x3
	v_mov_b32_dpp v107, v227 quad_perm:[0,1,2,3] row_mask:0xf bank_mask:0x3
	v_mov_b32_dpp v224, v100 row_ror:8 row_mask:0xf bank_mask:0xf
	v_mov_b32_dpp v225, v101 row_ror:8 row_mask:0xf bank_mask:0xf
	v_mov_b32_dpp v226, v102 row_ror:8 row_mask:0xf bank_mask:0xf
	v_mov_b32_dpp v227, v103 row_ror:8 row_mask:0xf bank_mask:0xf
	v_mov_b32_dpp v100, v96 row_ror:8 row_mask:0xf bank_mask:0xc
	v_mov_b32_dpp v101, v97 row_ror:8 row_mask:0xf bank_mask:0xc
	v_mov_b32_dpp v102, v98 row_ror:8 row_mask:0xf bank_mask:0xc
	v_mov_b32_dpp v103, v99 row_ror:8 row_mask:0xf bank_mask:0xc
	v_mov_b32_dpp v96, v224 quad_perm:[0,1,2,3] row_mask:0xf bank_mask:0x3
	v_mov_b32_dpp v97, v225 quad_perm:[0,1,2,3] row_mask:0xf bank_mask:0x3
	v_mov_b32_dpp v98, v226 quad_perm:[0,1,2,3] row_mask:0xf bank_mask:0x3
	v_mov_b32_dpp v99, v227 quad_perm:[0,1,2,3] row_mask:0xf bank_mask:0x3
	v_pk_add_f32 v[78:79], v[78:79], v[110:111]
	v_pk_add_f32 v[76:77], v[76:77], v[108:109]
	v_lshl_add_u64 v[84:85], s[2:3], 0, v[80:81]
	global_store_dwordx4 v[82:83], v[76:79], off
	v_cvt_pk_bf16_f32 v86, v76, v77
	v_cvt_pk_bf16_f32 v87, v78, v79
	s_nop 1
	v_mov_b32_e32 v240, v86
	v_mov_b32_e32 v241, v87
	v_lshl_add_u64 v[244:245], v[84:85], 0, v[246:247]
	v_mul_f32_e32 v84, v76, v76
	v_fmac_f32_e32 v84, v77, v77
	v_pk_add_f32 v[74:75], v[74:75], v[106:107]
	v_pk_add_f32 v[72:73], v[72:73], v[104:105]
	v_fmac_f32_e32 v84, v78, v78
	global_store_dwordx4 v[82:83], v[72:75], off offset:64
	v_or_b32_e32 v76, 32, v80
	v_mov_b32_e32 v77, v81
	v_cvt_pk_bf16_f32 v78, v72, v73
	v_mul_f32_e32 v72, v72, v72
	v_lshl_add_u64 v[76:77], s[2:3], 0, v[76:77]
	v_fmac_f32_e32 v72, v73, v73
	v_pk_add_f32 v[70:71], v[70:71], v[102:103]
	v_pk_add_f32 v[68:69], v[68:69], v[100:101]
	v_fmac_f32_e32 v84, v79, v79
	v_cvt_pk_bf16_f32 v79, v74, v75
	v_mov_b32_e32 v242, v78
	v_mov_b32_e32 v243, v79
	s_nop 1
	v_permlane16_swap_b32 v240, v242
	v_permlane16_swap_b32 v241, v243
	global_store_dwordx4 v[244:245], v[240:243], off
	v_fmac_f32_e32 v72, v74, v74
	global_store_dwordx4 v[82:83], v[68:71], off offset:512
	v_cvt_pk_bf16_f32 v74, v68, v69
	v_fmac_f32_e32 v72, v75, v75
	v_add_f32_e32 v75, v84, v72
	v_mul_f32_e32 v68, v68, v68
	v_fmac_f32_e32 v68, v69, v69
	v_fmac_f32_e32 v68, v70, v70
	v_fmac_f32_e32 v68, v71, v71
	v_add_f32_e32 v75, v75, v68
	v_pk_add_f32 v[68:69], v[66:67], v[98:99]
	v_pk_add_f32 v[66:67], v[64:65], v[96:97]
	v_or_b32_e32 v72, 0x100, v80
	v_mul_f32_e32 v64, v66, v66
	v_fmac_f32_e32 v64, v67, v67
	v_fmac_f32_e32 v64, v68, v68
	v_fmac_f32_e32 v64, v69, v69
	v_add_f32_e32 v64, v75, v64
	ds_bpermute_b32 v65, v189, v64
	v_mov_b32_e32 v73, v81
	v_or_b32_e32 v80, 0x120, v80
	v_lshl_add_u64 v[72:73], s[2:3], 0, v[72:73]
	v_cvt_pk_bf16_f32 v75, v70, v71
	s_waitcnt lgkmcnt(0)
	v_add_f32_e32 v64, v64, v65
	ds_bpermute_b32 v65, v116, v64
	v_lshl_add_u64 v[70:71], s[2:3], 0, v[80:81]
	s_nop 1
	v_mov_b32_e32 v240, v74
	v_mov_b32_e32 v241, v75
	v_lshl_add_u64 v[244:245], v[72:73], 0, v[246:247]
	global_store_dwordx4 v[82:83], v[66:69], off offset:576
	s_nop 1
	v_cvt_pk_bf16_f32 v66, v66, v67
	v_cvt_pk_bf16_f32 v67, v68, v69
	v_mov_b32_e32 v242, v66
	v_mov_b32_e32 v243, v67
	s_nop 1
	v_permlane16_swap_b32 v240, v242
	v_permlane16_swap_b32 v241, v243
	global_store_dwordx4 v[244:245], v[240:243], off
	s_and_saveexec_b64 s[30:31], s[6:7]
	s_cbranch_execz .LBB0_1489
	v_lshlrev_b64 v[66:67], 6, v[112:113]
	v_lshl_add_u64 v[66:67], s[4:5], 0, v[66:67]
	v_lshl_add_u64 v[66:67], s[28:29], 2, v[66:67]
	s_lshl_b32 s12, s55, 2
	v_lshl_add_u64 v[66:67], v[66:67], 0, s[12:13]
	s_waitcnt lgkmcnt(0)
	v_add_f32_e32 v64, v64, v65
	flat_store_dword v[66:67], v64
.LBB0_1489:
	s_or_b64 exec, exec, s[30:31]
	v_lshl_add_u64 v[82:83], v[164:165], 0, s[10:11]
	s_waitcnt lgkmcnt(0)
	v_lshlrev_b64 v[64:65], 12, v[82:83]
	v_lshl_add_u64 v[64:65], v[166:167], 0, v[64:65]
	v_lshl_add_u64 v[232:233], v[64:65], 0, v[248:249]
	v_lshl_add_u64 v[234:235], v[232:233], 0, v[250:251]
	global_load_dwordx4 v[84:87], v[232:233], off
	global_load_dwordx4 v[88:91], v[234:235], off
	global_load_dwordx4 v[92:95], v[232:233], off offset:512
	global_load_dwordx4 v[96:99], v[234:235], off offset:512
	v_lshl_add_u64 v[80:81], v[164:165], 0, s[14:15]
	v_lshlrev_b64 v[64:65], 12, v[80:81]
	v_lshl_add_u64 v[64:65], v[166:167], 0, v[64:65]
	v_lshl_add_u64 v[236:237], v[64:65], 0, v[248:249]
	v_lshl_add_u64 v[238:239], v[236:237], 0, v[250:251]
	global_load_dwordx4 v[76:79], v[236:237], off
	global_load_dwordx4 v[72:75], v[238:239], off
	global_load_dwordx4 v[68:71], v[236:237], off offset:512
	s_nop 0
	global_load_dwordx4 v[64:67], v[238:239], off offset:512
	v_lshlrev_b64 v[100:101], 10, v[82:83]
	v_lshl_add_u64 v[100:101], v[100:101], 0, v[162:163]
	v_lshl_add_u64 v[102:103], v[100:101], 2, s[78:79]
	v_lshlrev_b64 v[100:101], 1, v[100:101]
	v_lshl_add_u64 v[104:105], s[2:3], 0, v[100:101]
	s_waitcnt vmcnt(0)
	v_or_b32_e32 v106, 32, v100
	v_mov_b32_e32 v107, v101
	v_or_b32_e32 v108, 0x100, v100
	v_mov_b32_e32 v109, v101
	v_or_b32_e32 v100, 0x120, v100
	v_lshl_add_u64 v[106:107], s[2:3], 0, v[106:107]
	v_lshl_add_u64 v[108:109], s[2:3], 0, v[108:109]
	s_waitcnt vmcnt(0)
	v_mov_b32_dpp v224, v84 row_ror:8 row_mask:0xf bank_mask:0xf
	v_mov_b32_dpp v225, v85 row_ror:8 row_mask:0xf bank_mask:0xf
	v_mov_b32_dpp v226, v86 row_ror:8 row_mask:0xf bank_mask:0xf
	v_mov_b32_dpp v227, v87 row_ror:8 row_mask:0xf bank_mask:0xf
	v_mov_b32_dpp v84, v88 row_ror:8 row_mask:0xf bank_mask:0xc
	v_mov_b32_dpp v85, v89 row_ror:8 row_mask:0xf bank_mask:0xc
	v_mov_b32_dpp v86, v90 row_ror:8 row_mask:0xf bank_mask:0xc
	v_mov_b32_dpp v87, v91 row_ror:8 row_mask:0xf bank_mask:0xc
	v_mov_b32_dpp v88, v224 quad_perm:[0,1,2,3] row_mask:0xf bank_mask:0x3
	v_mov_b32_dpp v89, v225 quad_perm:[0,1,2,3] row_mask:0xf bank_mask:0x3
	v_mov_b32_dpp v90, v226 quad_perm:[0,1,2,3] row_mask:0xf bank_mask:0x3
	v_mov_b32_dpp v91, v227 quad_perm:[0,1,2,3] row_mask:0xf bank_mask:0x3
	v_mov_b32_dpp v224, v92 row_ror:8 row_mask:0xf bank_mask:0xf
	v_mov_b32_dpp v225, v93 row_ror:8 row_mask:0xf bank_mask:0xf
	v_mov_b32_dpp v226, v94 row_ror:8 row_mask:0xf bank_mask:0xf
	v_mov_b32_dpp v227, v95 row_ror:8 row_mask:0xf bank_mask:0xf
	v_mov_b32_dpp v92, v96 row_ror:8 row_mask:0xf bank_mask:0xc
	v_mov_b32_dpp v93, v97 row_ror:8 row_mask:0xf bank_mask:0xc
	v_mov_b32_dpp v94, v98 row_ror:8 row_mask:0xf bank_mask:0xc
	v_mov_b32_dpp v95, v99 row_ror:8 row_mask:0xf bank_mask:0xc
	v_mov_b32_dpp v96, v224 quad_perm:[0,1,2,3] row_mask:0xf bank_mask:0x3
	v_mov_b32_dpp v97, v225 quad_perm:[0,1,2,3] row_mask:0xf bank_mask:0x3
	v_mov_b32_dpp v98, v226 quad_perm:[0,1,2,3] row_mask:0xf bank_mask:0x3
	v_mov_b32_dpp v99, v227 quad_perm:[0,1,2,3] row_mask:0xf bank_mask:0x3
	v_pk_add_f32 v[60:61], v[60:61], v[84:85]
	v_pk_add_f32 v[56:57], v[56:57], v[88:89]
	v_pk_add_f32 v[52:53], v[52:53], v[92:93]
	v_mul_f32_e32 v88, v60, v60
	v_mul_f32_e32 v89, v56, v56
	v_pk_add_f32 v[62:63], v[62:63], v[86:87]
	v_pk_add_f32 v[58:59], v[58:59], v[90:91]
	v_pk_add_f32 v[84:85], v[48:49], v[96:97]
	v_mul_f32_e32 v90, v52, v52
	v_fmac_f32_e32 v88, v61, v61
	v_fmac_f32_e32 v89, v57, v57
	v_pk_add_f32 v[54:55], v[54:55], v[94:95]
	v_mul_f32_e32 v91, v84, v84
	v_fmac_f32_e32 v90, v53, v53
	v_fmac_f32_e32 v88, v62, v62
	v_fmac_f32_e32 v89, v58, v58
	v_pk_add_f32 v[86:87], v[50:51], v[98:99]
	v_cvt_pk_bf16_f32 v48, v60, v61
	v_fmac_f32_e32 v91, v85, v85
	v_fmac_f32_e32 v90, v54, v54
	v_fmac_f32_e32 v88, v63, v63
	v_fmac_f32_e32 v89, v59, v59
	global_store_dwordx4 v[102:103], v[60:63], off
	v_cvt_pk_bf16_f32 v49, v62, v63
	s_nop 1
	v_mov_b32_e32 v240, v48
	v_mov_b32_e32 v241, v49
	v_lshl_add_u64 v[244:245], v[104:105], 0, v[246:247]
	v_fmac_f32_e32 v91, v86, v86
	v_fmac_f32_e32 v90, v55, v55
	v_add_f32_e32 v48, v88, v89
	v_add_f32_e32 v48, v48, v90
	v_fmac_f32_e32 v91, v87, v87
	v_add_f32_e32 v48, v48, v91
	ds_bpermute_b32 v49, v189, v48
	v_cvt_pk_bf16_f32 v50, v56, v57
	v_cvt_pk_bf16_f32 v51, v58, v59
	v_cvt_pk_bf16_f32 v60, v52, v53
	global_store_dwordx4 v[102:103], v[56:59], off offset:64
	v_mov_b32_e32 v242, v50
	v_mov_b32_e32 v243, v51
	s_nop 1
	v_permlane16_swap_b32 v240, v242
	v_permlane16_swap_b32 v241, v243
	global_store_dwordx4 v[244:245], v[240:243], off
	s_waitcnt lgkmcnt(0)
	v_add_f32_e32 v48, v48, v49
	ds_bpermute_b32 v49, v116, v48
	v_cvt_pk_bf16_f32 v61, v54, v55
	v_lshl_add_u64 v[50:51], s[2:3], 0, v[100:101]
	global_store_dwordx4 v[102:103], v[52:55], off offset:512
	s_nop 1
	v_mov_b32_e32 v240, v60
	v_mov_b32_e32 v241, v61
	v_lshl_add_u64 v[244:245], v[108:109], 0, v[246:247]
	global_store_dwordx4 v[102:103], v[84:87], off offset:576
	v_cvt_pk_bf16_f32 v52, v84, v85
	v_cvt_pk_bf16_f32 v53, v86, v87
	v_mov_b32_e32 v242, v52
	v_mov_b32_e32 v243, v53
	s_nop 1
	v_permlane16_swap_b32 v240, v242
	v_permlane16_swap_b32 v241, v243
	global_store_dwordx4 v[244:245], v[240:243], off
	s_and_saveexec_b64 s[30:31], s[6:7]
	s_cbranch_execz .LBB0_1491
	v_lshlrev_b64 v[50:51], 6, v[82:83]
	v_lshl_add_u64 v[50:51], s[4:5], 0, v[50:51]
	v_lshl_add_u64 v[50:51], s[28:29], 2, v[50:51]
	s_lshl_b32 s12, s55, 2
	v_lshl_add_u64 v[50:51], v[50:51], 0, s[12:13]
	s_waitcnt lgkmcnt(0)
	v_add_f32_e32 v48, v48, v49
	flat_store_dword v[50:51], v48
.LBB0_1491:
	s_or_b64 exec, exec, s[30:31]
	s_waitcnt lgkmcnt(0)
	v_lshlrev_b64 v[48:49], 10, v[80:81]
	v_lshl_add_u64 v[48:49], v[48:49], 0, v[162:163]
	v_lshl_add_u64 v[50:51], v[48:49], 2, s[78:79]
	v_lshlrev_b64 v[48:49], 1, v[48:49]
	v_mov_b32_dpp v224, v76 row_ror:8 row_mask:0xf bank_mask:0xf
	v_mov_b32_dpp v225, v77 row_ror:8 row_mask:0xf bank_mask:0xf
	v_mov_b32_dpp v226, v78 row_ror:8 row_mask:0xf bank_mask:0xf
	v_mov_b32_dpp v227, v79 row_ror:8 row_mask:0xf bank_mask:0xf
	v_mov_b32_dpp v76, v72 row_ror:8 row_mask:0xf bank_mask:0xc
	v_mov_b32_dpp v77, v73 row_ror:8 row_mask:0xf bank_mask:0xc
	v_mov_b32_dpp v78, v74 row_ror:8 row_mask:0xf bank_mask:0xc
	v_mov_b32_dpp v79, v75 row_ror:8 row_mask:0xf bank_mask:0xc
	v_mov_b32_dpp v72, v224 quad_perm:[0,1,2,3] row_mask:0xf bank_mask:0x3
	v_mov_b32_dpp v73, v225 quad_perm:[0,1,2,3] row_mask:0xf bank_mask:0x3
	v_mov_b32_dpp v74, v226 quad_perm:[0,1,2,3] row_mask:0xf bank_mask:0x3
	v_mov_b32_dpp v75, v227 quad_perm:[0,1,2,3] row_mask:0xf bank_mask:0x3
	v_mov_b32_dpp v224, v68 row_ror:8 row_mask:0xf bank_mask:0xf
	v_mov_b32_dpp v225, v69 row_ror:8 row_mask:0xf bank_mask:0xf
	v_mov_b32_dpp v226, v70 row_ror:8 row_mask:0xf bank_mask:0xf
	v_mov_b32_dpp v227, v71 row_ror:8 row_mask:0xf bank_mask:0xf
	v_mov_b32_dpp v68, v64 row_ror:8 row_mask:0xf bank_mask:0xc
	v_mov_b32_dpp v69, v65 row_ror:8 row_mask:0xf bank_mask:0xc
	v_mov_b32_dpp v70, v66 row_ror:8 row_mask:0xf bank_mask:0xc
	v_mov_b32_dpp v71, v67 row_ror:8 row_mask:0xf bank_mask:0xc
	v_mov_b32_dpp v64, v224 quad_perm:[0,1,2,3] row_mask:0xf bank_mask:0x3
	v_mov_b32_dpp v65, v225 quad_perm:[0,1,2,3] row_mask:0xf bank_mask:0x3
	v_mov_b32_dpp v66, v226 quad_perm:[0,1,2,3] row_mask:0xf bank_mask:0x3
	v_mov_b32_dpp v67, v227 quad_perm:[0,1,2,3] row_mask:0xf bank_mask:0x3
	v_pk_add_f32 v[46:47], v[46:47], v[78:79]
	v_pk_add_f32 v[44:45], v[44:45], v[76:77]
	v_lshl_add_u64 v[52:53], s[2:3], 0, v[48:49]
	global_store_dwordx4 v[50:51], v[44:47], off
	v_cvt_pk_bf16_f32 v54, v44, v45
	v_cvt_pk_bf16_f32 v55, v46, v47
	s_nop 1
	v_mov_b32_e32 v240, v54
	v_mov_b32_e32 v241, v55
	v_lshl_add_u64 v[244:245], v[52:53], 0, v[246:247]
	v_mul_f32_e32 v52, v44, v44
	v_fmac_f32_e32 v52, v45, v45
	v_pk_add_f32 v[42:43], v[42:43], v[74:75]
	v_pk_add_f32 v[40:41], v[40:41], v[72:73]
	v_fmac_f32_e32 v52, v46, v46
	global_store_dwordx4 v[50:51], v[40:43], off offset:64
	v_or_b32_e32 v44, 32, v48
	v_mov_b32_e32 v45, v49
	v_cvt_pk_bf16_f32 v46, v40, v41
	v_mul_f32_e32 v40, v40, v40
	v_lshl_add_u64 v[44:45], s[2:3], 0, v[44:45]
	v_fmac_f32_e32 v40, v41, v41
	v_pk_add_f32 v[38:39], v[38:39], v[70:71]
	v_pk_add_f32 v[36:37], v[36:37], v[68:69]
	v_fmac_f32_e32 v52, v47, v47
	v_cvt_pk_bf16_f32 v47, v42, v43
	v_mov_b32_e32 v242, v46
	v_mov_b32_e32 v243, v47
	s_nop 1
	v_permlane16_swap_b32 v240, v242
	v_permlane16_swap_b32 v241, v243
	global_store_dwordx4 v[244:245], v[240:243], off
	v_fmac_f32_e32 v40, v42, v42
	global_store_dwordx4 v[50:51], v[36:39], off offset:512
	v_cvt_pk_bf16_f32 v42, v36, v37
	v_fmac_f32_e32 v40, v43, v43
	v_add_f32_e32 v43, v52, v40
	v_mul_f32_e32 v36, v36, v36
	v_fmac_f32_e32 v36, v37, v37
	v_fmac_f32_e32 v36, v38, v38
	v_fmac_f32_e32 v36, v39, v39
	v_add_f32_e32 v43, v43, v36
	v_pk_add_f32 v[36:37], v[34:35], v[66:67]
	v_pk_add_f32 v[34:35], v[32:33], v[64:65]
	v_or_b32_e32 v40, 0x100, v48
	v_mul_f32_e32 v32, v34, v34
	v_fmac_f32_e32 v32, v35, v35
	v_fmac_f32_e32 v32, v36, v36
	v_fmac_f32_e32 v32, v37, v37
	v_add_f32_e32 v32, v43, v32
	ds_bpermute_b32 v33, v189, v32
	v_mov_b32_e32 v41, v49
	v_or_b32_e32 v48, 0x120, v48
	v_lshl_add_u64 v[40:41], s[2:3], 0, v[40:41]
	v_cvt_pk_bf16_f32 v43, v38, v39
	s_waitcnt lgkmcnt(0)
	v_add_f32_e32 v32, v32, v33
	ds_bpermute_b32 v33, v116, v32
	v_lshl_add_u64 v[38:39], s[2:3], 0, v[48:49]
	s_nop 1
	v_mov_b32_e32 v240, v42
	v_mov_b32_e32 v241, v43
	v_lshl_add_u64 v[244:245], v[40:41], 0, v[246:247]
	global_store_dwordx4 v[50:51], v[34:37], off offset:576
	s_nop 1
	v_cvt_pk_bf16_f32 v34, v34, v35
	v_cvt_pk_bf16_f32 v35, v36, v37
	v_mov_b32_e32 v242, v34
	v_mov_b32_e32 v243, v35
	s_nop 1
	v_permlane16_swap_b32 v240, v242
	v_permlane16_swap_b32 v241, v243
	global_store_dwordx4 v[244:245], v[240:243], off
	s_and_saveexec_b64 s[30:31], s[6:7]
	s_cbranch_execz .LBB0_1493
	v_lshlrev_b64 v[34:35], 6, v[80:81]
	v_lshl_add_u64 v[34:35], s[4:5], 0, v[34:35]
	v_lshl_add_u64 v[34:35], s[28:29], 2, v[34:35]
	s_lshl_b32 s12, s55, 2
	v_lshl_add_u64 v[34:35], v[34:35], 0, s[12:13]
	s_waitcnt lgkmcnt(0)
	v_add_f32_e32 v32, v32, v33
	flat_store_dword v[34:35], v32
.LBB0_1493:
	s_or_b64 exec, exec, s[30:31]
	v_lshl_add_u64 v[50:51], v[164:165], 0, s[16:17]
	s_waitcnt lgkmcnt(0)
	v_lshlrev_b64 v[32:33], 12, v[50:51]
	v_lshl_add_u64 v[32:33], v[166:167], 0, v[32:33]
	v_lshl_add_u64 v[232:233], v[32:33], 0, v[248:249]
	v_lshl_add_u64 v[234:235], v[232:233], 0, v[250:251]
	global_load_dwordx4 v[52:55], v[232:233], off
	global_load_dwordx4 v[56:59], v[234:235], off
	global_load_dwordx4 v[60:63], v[232:233], off offset:512
	global_load_dwordx4 v[64:67], v[234:235], off offset:512
	v_lshl_add_u64 v[48:49], v[164:165], 0, s[18:19]
	v_lshlrev_b64 v[32:33], 12, v[48:49]
	v_lshl_add_u64 v[32:33], v[166:167], 0, v[32:33]
	v_lshl_add_u64 v[236:237], v[32:33], 0, v[248:249]
	v_lshl_add_u64 v[238:239], v[236:237], 0, v[250:251]
	global_load_dwordx4 v[44:47], v[236:237], off
	global_load_dwordx4 v[40:43], v[238:239], off
	global_load_dwordx4 v[36:39], v[236:237], off offset:512
	s_nop 0
	global_load_dwordx4 v[32:35], v[238:239], off offset:512
	v_lshlrev_b64 v[68:69], 10, v[50:51]
	v_lshl_add_u64 v[68:69], v[68:69], 0, v[162:163]
	v_lshl_add_u64 v[70:71], v[68:69], 2, s[78:79]
	v_lshlrev_b64 v[68:69], 1, v[68:69]
	v_lshl_add_u64 v[72:73], s[2:3], 0, v[68:69]
	s_waitcnt vmcnt(0)
	v_or_b32_e32 v74, 32, v68
	v_mov_b32_e32 v75, v69
	v_or_b32_e32 v76, 0x100, v68
	v_mov_b32_e32 v77, v69
	v_or_b32_e32 v68, 0x120, v68
	v_lshl_add_u64 v[74:75], s[2:3], 0, v[74:75]
	v_lshl_add_u64 v[76:77], s[2:3], 0, v[76:77]
	s_waitcnt vmcnt(0)
	v_mov_b32_dpp v224, v52 row_ror:8 row_mask:0xf bank_mask:0xf
	v_mov_b32_dpp v225, v53 row_ror:8 row_mask:0xf bank_mask:0xf
	v_mov_b32_dpp v226, v54 row_ror:8 row_mask:0xf bank_mask:0xf
	v_mov_b32_dpp v227, v55 row_ror:8 row_mask:0xf bank_mask:0xf
	v_mov_b32_dpp v52, v56 row_ror:8 row_mask:0xf bank_mask:0xc
	v_mov_b32_dpp v53, v57 row_ror:8 row_mask:0xf bank_mask:0xc
	v_mov_b32_dpp v54, v58 row_ror:8 row_mask:0xf bank_mask:0xc
	v_mov_b32_dpp v55, v59 row_ror:8 row_mask:0xf bank_mask:0xc
	v_mov_b32_dpp v56, v224 quad_perm:[0,1,2,3] row_mask:0xf bank_mask:0x3
	v_mov_b32_dpp v57, v225 quad_perm:[0,1,2,3] row_mask:0xf bank_mask:0x3
	v_mov_b32_dpp v58, v226 quad_perm:[0,1,2,3] row_mask:0xf bank_mask:0x3
	v_mov_b32_dpp v59, v227 quad_perm:[0,1,2,3] row_mask:0xf bank_mask:0x3
	v_mov_b32_dpp v224, v60 row_ror:8 row_mask:0xf bank_mask:0xf
	v_mov_b32_dpp v225, v61 row_ror:8 row_mask:0xf bank_mask:0xf
	v_mov_b32_dpp v226, v62 row_ror:8 row_mask:0xf bank_mask:0xf
	v_mov_b32_dpp v227, v63 row_ror:8 row_mask:0xf bank_mask:0xf
	v_mov_b32_dpp v60, v64 row_ror:8 row_mask:0xf bank_mask:0xc
	v_mov_b32_dpp v61, v65 row_ror:8 row_mask:0xf bank_mask:0xc
	v_mov_b32_dpp v62, v66 row_ror:8 row_mask:0xf bank_mask:0xc
	v_mov_b32_dpp v63, v67 row_ror:8 row_mask:0xf bank_mask:0xc
	v_mov_b32_dpp v64, v224 quad_perm:[0,1,2,3] row_mask:0xf bank_mask:0x3
	v_mov_b32_dpp v65, v225 quad_perm:[0,1,2,3] row_mask:0xf bank_mask:0x3
	v_mov_b32_dpp v66, v226 quad_perm:[0,1,2,3] row_mask:0xf bank_mask:0x3
	v_mov_b32_dpp v67, v227 quad_perm:[0,1,2,3] row_mask:0xf bank_mask:0x3
	v_pk_add_f32 v[28:29], v[28:29], v[52:53]
	v_pk_add_f32 v[24:25], v[24:25], v[56:57]
	v_pk_add_f32 v[20:21], v[20:21], v[60:61]
	v_mul_f32_e32 v56, v28, v28
	v_mul_f32_e32 v57, v24, v24
	v_pk_add_f32 v[30:31], v[30:31], v[54:55]
	v_pk_add_f32 v[26:27], v[26:27], v[58:59]
	v_pk_add_f32 v[52:53], v[16:17], v[64:65]
	v_mul_f32_e32 v58, v20, v20
	v_fmac_f32_e32 v56, v29, v29
	v_fmac_f32_e32 v57, v25, v25
	v_pk_add_f32 v[22:23], v[22:23], v[62:63]
	v_mul_f32_e32 v59, v52, v52
	v_fmac_f32_e32 v58, v21, v21
	v_fmac_f32_e32 v56, v30, v30
	v_fmac_f32_e32 v57, v26, v26
	v_pk_add_f32 v[54:55], v[18:19], v[66:67]
	v_cvt_pk_bf16_f32 v16, v28, v29
	v_fmac_f32_e32 v59, v53, v53
	v_fmac_f32_e32 v58, v22, v22
	v_fmac_f32_e32 v56, v31, v31
	v_fmac_f32_e32 v57, v27, v27
	global_store_dwordx4 v[70:71], v[28:31], off
	v_cvt_pk_bf16_f32 v17, v30, v31
	s_nop 1
	v_mov_b32_e32 v240, v16
	v_mov_b32_e32 v241, v17
	v_lshl_add_u64 v[244:245], v[72:73], 0, v[246:247]
	v_fmac_f32_e32 v59, v54, v54
	v_fmac_f32_e32 v58, v23, v23
	v_add_f32_e32 v16, v56, v57
	v_add_f32_e32 v16, v16, v58
	v_fmac_f32_e32 v59, v55, v55
	v_add_f32_e32 v16, v16, v59
	ds_bpermute_b32 v17, v189, v16
	v_cvt_pk_bf16_f32 v18, v24, v25
	v_cvt_pk_bf16_f32 v19, v26, v27
	v_cvt_pk_bf16_f32 v28, v20, v21
	global_store_dwordx4 v[70:71], v[24:27], off offset:64
	v_mov_b32_e32 v242, v18
	v_mov_b32_e32 v243, v19
	s_nop 1
	v_permlane16_swap_b32 v240, v242
	v_permlane16_swap_b32 v241, v243
	global_store_dwordx4 v[244:245], v[240:243], off
	s_waitcnt lgkmcnt(0)
	v_add_f32_e32 v16, v16, v17
	ds_bpermute_b32 v17, v116, v16
	v_cvt_pk_bf16_f32 v29, v22, v23
	v_lshl_add_u64 v[18:19], s[2:3], 0, v[68:69]
	global_store_dwordx4 v[70:71], v[20:23], off offset:512
	s_nop 1
	v_mov_b32_e32 v240, v28
	v_mov_b32_e32 v241, v29
	v_lshl_add_u64 v[244:245], v[76:77], 0, v[246:247]
	global_store_dwordx4 v[70:71], v[52:55], off offset:576
	v_cvt_pk_bf16_f32 v20, v52, v53
	v_cvt_pk_bf16_f32 v21, v54, v55
	v_mov_b32_e32 v242, v20
	v_mov_b32_e32 v243, v21
	s_nop 1
	v_permlane16_swap_b32 v240, v242
	v_permlane16_swap_b32 v241, v243
	global_store_dwordx4 v[244:245], v[240:243], off
	s_and_saveexec_b64 s[30:31], s[6:7]
	s_cbranch_execz .LBB0_1495
	v_lshlrev_b64 v[18:19], 6, v[50:51]
	v_lshl_add_u64 v[18:19], s[4:5], 0, v[18:19]
	v_lshl_add_u64 v[18:19], s[28:29], 2, v[18:19]
	s_lshl_b32 s12, s55, 2
	v_lshl_add_u64 v[18:19], v[18:19], 0, s[12:13]
	s_waitcnt lgkmcnt(0)
	v_add_f32_e32 v16, v16, v17
	flat_store_dword v[18:19], v16
.LBB0_1495:
	s_or_b64 exec, exec, s[30:31]
	s_waitcnt lgkmcnt(0)
	v_lshlrev_b64 v[16:17], 10, v[48:49]
	v_lshl_add_u64 v[16:17], v[16:17], 0, v[162:163]
	v_lshl_add_u64 v[18:19], v[16:17], 2, s[78:79]
	v_lshlrev_b64 v[16:17], 1, v[16:17]
	v_mov_b32_dpp v224, v44 row_ror:8 row_mask:0xf bank_mask:0xf
	v_mov_b32_dpp v225, v45 row_ror:8 row_mask:0xf bank_mask:0xf
	v_mov_b32_dpp v226, v46 row_ror:8 row_mask:0xf bank_mask:0xf
	v_mov_b32_dpp v227, v47 row_ror:8 row_mask:0xf bank_mask:0xf
	v_mov_b32_dpp v44, v40 row_ror:8 row_mask:0xf bank_mask:0xc
	v_mov_b32_dpp v45, v41 row_ror:8 row_mask:0xf bank_mask:0xc
	v_mov_b32_dpp v46, v42 row_ror:8 row_mask:0xf bank_mask:0xc
	v_mov_b32_dpp v47, v43 row_ror:8 row_mask:0xf bank_mask:0xc
	v_mov_b32_dpp v40, v224 quad_perm:[0,1,2,3] row_mask:0xf bank_mask:0x3
	v_mov_b32_dpp v41, v225 quad_perm:[0,1,2,3] row_mask:0xf bank_mask:0x3
	v_mov_b32_dpp v42, v226 quad_perm:[0,1,2,3] row_mask:0xf bank_mask:0x3
	v_mov_b32_dpp v43, v227 quad_perm:[0,1,2,3] row_mask:0xf bank_mask:0x3
	v_mov_b32_dpp v224, v36 row_ror:8 row_mask:0xf bank_mask:0xf
	v_mov_b32_dpp v225, v37 row_ror:8 row_mask:0xf bank_mask:0xf
	v_mov_b32_dpp v226, v38 row_ror:8 row_mask:0xf bank_mask:0xf
	v_mov_b32_dpp v227, v39 row_ror:8 row_mask:0xf bank_mask:0xf
	v_mov_b32_dpp v36, v32 row_ror:8 row_mask:0xf bank_mask:0xc
	v_mov_b32_dpp v37, v33 row_ror:8 row_mask:0xf bank_mask:0xc
	v_mov_b32_dpp v38, v34 row_ror:8 row_mask:0xf bank_mask:0xc
	v_mov_b32_dpp v39, v35 row_ror:8 row_mask:0xf bank_mask:0xc
	v_mov_b32_dpp v32, v224 quad_perm:[0,1,2,3] row_mask:0xf bank_mask:0x3
	v_mov_b32_dpp v33, v225 quad_perm:[0,1,2,3] row_mask:0xf bank_mask:0x3
	v_mov_b32_dpp v34, v226 quad_perm:[0,1,2,3] row_mask:0xf bank_mask:0x3
	v_mov_b32_dpp v35, v227 quad_perm:[0,1,2,3] row_mask:0xf bank_mask:0x3
	v_pk_add_f32 v[14:15], v[14:15], v[46:47]
	v_pk_add_f32 v[12:13], v[12:13], v[44:45]
	v_lshl_add_u64 v[20:21], s[2:3], 0, v[16:17]
	global_store_dwordx4 v[18:19], v[12:15], off
	v_cvt_pk_bf16_f32 v22, v12, v13
	v_cvt_pk_bf16_f32 v23, v14, v15
	s_nop 1
	v_mov_b32_e32 v240, v22
	v_mov_b32_e32 v241, v23
	v_lshl_add_u64 v[244:245], v[20:21], 0, v[246:247]
	v_mul_f32_e32 v20, v12, v12
	v_fmac_f32_e32 v20, v13, v13
	v_pk_add_f32 v[10:11], v[10:11], v[42:43]
	v_pk_add_f32 v[8:9], v[8:9], v[40:41]
	v_fmac_f32_e32 v20, v14, v14
	global_store_dwordx4 v[18:19], v[8:11], off offset:64
	v_or_b32_e32 v12, 32, v16
	v_mov_b32_e32 v13, v17
	v_cvt_pk_bf16_f32 v14, v8, v9
	v_mul_f32_e32 v8, v8, v8
	v_lshl_add_u64 v[12:13], s[2:3], 0, v[12:13]
	v_fmac_f32_e32 v8, v9, v9
	v_pk_add_f32 v[6:7], v[6:7], v[38:39]
	v_pk_add_f32 v[4:5], v[4:5], v[36:37]
	v_fmac_f32_e32 v20, v15, v15
	v_cvt_pk_bf16_f32 v15, v10, v11
	v_mov_b32_e32 v242, v14
	v_mov_b32_e32 v243, v15
	s_nop 1
	v_permlane16_swap_b32 v240, v242
	v_permlane16_swap_b32 v241, v243
	global_store_dwordx4 v[244:245], v[240:243], off
	v_fmac_f32_e32 v8, v10, v10
	global_store_dwordx4 v[18:19], v[4:7], off offset:512
	v_cvt_pk_bf16_f32 v10, v4, v5
	v_fmac_f32_e32 v8, v11, v11
	v_add_f32_e32 v11, v20, v8
	v_mul_f32_e32 v4, v4, v4
	v_fmac_f32_e32 v4, v5, v5
	v_fmac_f32_e32 v4, v6, v6
	v_fmac_f32_e32 v4, v7, v7
	v_add_f32_e32 v11, v11, v4
	v_pk_add_f32 v[4:5], v[2:3], v[34:35]
	v_pk_add_f32 v[2:3], v[0:1], v[32:33]
	v_or_b32_e32 v8, 0x100, v16
	v_mul_f32_e32 v0, v2, v2
	v_fmac_f32_e32 v0, v3, v3
	v_fmac_f32_e32 v0, v4, v4
	v_fmac_f32_e32 v0, v5, v5
	v_add_f32_e32 v0, v11, v0
	ds_bpermute_b32 v1, v189, v0
	v_mov_b32_e32 v9, v17
	v_or_b32_e32 v16, 0x120, v16
	v_lshl_add_u64 v[8:9], s[2:3], 0, v[8:9]
	v_cvt_pk_bf16_f32 v11, v6, v7
	s_waitcnt lgkmcnt(0)
	v_add_f32_e32 v0, v0, v1
	ds_bpermute_b32 v1, v116, v0
	v_lshl_add_u64 v[6:7], s[2:3], 0, v[16:17]
	s_nop 1
	v_mov_b32_e32 v240, v10
	v_mov_b32_e32 v241, v11
	v_lshl_add_u64 v[244:245], v[8:9], 0, v[246:247]
	global_store_dwordx4 v[18:19], v[2:5], off offset:576
	s_nop 1
	v_cvt_pk_bf16_f32 v2, v2, v3
	v_cvt_pk_bf16_f32 v3, v4, v5
	v_mov_b32_e32 v242, v2
	v_mov_b32_e32 v243, v3
	s_nop 1
	v_permlane16_swap_b32 v240, v242
	v_permlane16_swap_b32 v241, v243
	global_store_dwordx4 v[244:245], v[240:243], off
	s_and_saveexec_b64 s[30:31], s[6:7]
	s_cbranch_execz .LBB0_1472
	v_lshlrev_b64 v[2:3], 6, v[48:49]
	v_lshl_add_u64 v[2:3], s[4:5], 0, v[2:3]
	v_lshl_add_u64 v[2:3], s[28:29], 2, v[2:3]
	s_lshl_b32 s12, s55, 2
	v_lshl_add_u64 v[2:3], v[2:3], 0, s[12:13]
	s_waitcnt lgkmcnt(0)
	v_add_f32_e32 v0, v0, v1
	flat_store_dword v[2:3], v0
	s_branch .LBB0_1472

.LBB0_1642:
	ds_read_b128 v[128:131], v170
	ds_read_b128 v[132:135], v171
	ds_read_b128 v[136:139], v172
	ds_read_b128 v[140:143], v173
	s_add_u32 s28, s26, 0xfff50080
	s_addc_u32 s29, s27, -1
	s_cmp_eq_u32 s65, 40
	s_cselect_b32 s31, s11, s29
	s_cselect_b32 s30, s10, s28
	s_cselect_b32 s29, s13, s64
	s_cselect_b32 s28, s12, s25
	s_mov_b32 m0, s59
	v_lshl_add_u64 v[214:215], s[26:27], 0, v[156:157]
	ds_read_b128 v[162:165], v151
	ds_read_b128 v[166:169], v151 offset:1024
	ds_read_b128 v[190:193], v151 offset:2048
	ds_read_b128 v[194:197], v151 offset:3072
	ds_read_b128 v[198:201], v151 offset:4096
	ds_read_b128 v[202:205], v151 offset:5120
	ds_read_b128 v[206:209], v151 offset:6144
	ds_read_b128 v[210:213], v151 offset:7168
	global_load_lds_dwordx4 v[214:215], off
	v_lshl_add_u64 v[214:215], s[26:27], 0, v[154:155]
	s_mov_b32 m0, s60
	s_nop 0
	global_load_lds_dwordx4 v[214:215], off
	s_waitcnt lgkmcnt(8)
	s_barrier
	s_waitcnt lgkmcnt(0)
	s_setprio 1
	s_waitcnt lgkmcnt(0)
	v_mfma_f32_16x16x32_bf16 v[124:127], v[128:131], v[162:165], v[124:127]
	v_mfma_f32_16x16x32_bf16 v[120:123], v[136:139], v[162:165], v[120:123]
	v_mfma_f32_16x16x32_bf16 v[108:111], v[128:131], v[190:193], v[108:111]
	v_mfma_f32_16x16x32_bf16 v[104:107], v[136:139], v[190:193], v[104:107]
	v_mfma_f32_16x16x32_bf16 v[92:95], v[128:131], v[198:201], v[92:95]
	v_mfma_f32_16x16x32_bf16 v[88:91], v[136:139], v[198:201], v[88:91]
	v_mfma_f32_16x16x32_bf16 v[76:79], v[128:131], v[206:209], v[76:79]
	v_mfma_f32_16x16x32_bf16 v[72:75], v[136:139], v[206:209], v[72:75]
	v_mfma_f32_16x16x32_bf16 v[124:127], v[132:135], v[166:169], v[124:127]
	v_mfma_f32_16x16x32_bf16 v[120:123], v[140:143], v[166:169], v[120:123]
	v_mfma_f32_16x16x32_bf16 v[108:111], v[132:135], v[194:197], v[108:111]
	v_mfma_f32_16x16x32_bf16 v[104:107], v[140:143], v[194:197], v[104:107]
	v_mfma_f32_16x16x32_bf16 v[92:95], v[132:135], v[202:205], v[92:95]
	v_mfma_f32_16x16x32_bf16 v[88:91], v[140:143], v[202:205], v[88:91]
	v_mfma_f32_16x16x32_bf16 v[76:79], v[132:135], v[210:213], v[76:79]
	v_mfma_f32_16x16x32_bf16 v[72:75], v[140:143], v[210:213], v[72:75]
	s_setprio 0
	s_barrier
	s_mov_b32 m0, s42
	v_lshl_add_u64 v[230:231], s[28:29], 0, v[144:145]
	ds_read_b128 v[214:217], v174
	ds_read_b128 v[218:221], v175
	ds_read_b128 v[222:225], v177
	ds_read_b128 v[226:229], v178
	global_load_lds_dwordx4 v[230:231], off
	v_lshl_add_u64 v[232:233], s[28:29], 0, v[146:147]
	s_mov_b32 m0, s43
	s_nop 0
	global_load_lds_dwordx4 v[232:233], off
	s_barrier
	s_waitcnt lgkmcnt(0)
	s_setprio 1
	s_waitcnt lgkmcnt(0)
	v_mfma_f32_16x16x32_bf16 v[116:119], v[214:217], v[162:165], v[116:119]
	v_mfma_f32_16x16x32_bf16 v[112:115], v[222:225], v[162:165], v[112:115]
	v_mfma_f32_16x16x32_bf16 v[100:103], v[214:217], v[190:193], v[100:103]
	v_mfma_f32_16x16x32_bf16 v[96:99], v[222:225], v[190:193], v[96:99]
	v_mfma_f32_16x16x32_bf16 v[84:87], v[214:217], v[198:201], v[84:87]
	v_mfma_f32_16x16x32_bf16 v[80:83], v[222:225], v[198:201], v[80:83]
	v_mfma_f32_16x16x32_bf16 v[68:71], v[214:217], v[206:209], v[68:71]
	v_mfma_f32_16x16x32_bf16 v[64:67], v[222:225], v[206:209], v[64:67]
	v_mfma_f32_16x16x32_bf16 v[116:119], v[218:221], v[166:169], v[116:119]
	v_mfma_f32_16x16x32_bf16 v[112:115], v[226:229], v[166:169], v[112:115]
	v_mfma_f32_16x16x32_bf16 v[100:103], v[218:221], v[194:197], v[100:103]
	v_mfma_f32_16x16x32_bf16 v[96:99], v[226:229], v[194:197], v[96:99]
	v_mfma_f32_16x16x32_bf16 v[84:87], v[218:221], v[202:205], v[84:87]
	v_mfma_f32_16x16x32_bf16 v[80:83], v[226:229], v[202:205], v[80:83]
	v_mfma_f32_16x16x32_bf16 v[68:71], v[218:221], v[210:213], v[68:71]
	v_mfma_f32_16x16x32_bf16 v[64:67], v[226:229], v[210:213], v[64:67]
	s_setprio 0
	s_mov_b32 m0, s41
	v_lshl_add_u64 v[234:235], s[30:31], 0, v[144:145]
	s_barrier
	ds_read_b128 v[162:165], v151 offset:16384
	ds_read_b128 v[166:169], v151 offset:17408
	ds_read_b128 v[190:193], v151 offset:18432
	ds_read_b128 v[194:197], v151 offset:19456
	ds_read_b128 v[198:201], v151 offset:20480
	ds_read_b128 v[202:205], v151 offset:21504
	ds_read_b128 v[206:209], v151 offset:22528
	ds_read_b128 v[210:213], v151 offset:23552
	global_load_lds_dwordx4 v[234:235], off
	v_lshl_add_u64 v[236:237], s[30:31], 0, v[146:147]
	s_mov_b32 m0, s44
	s_nop 0
	global_load_lds_dwordx4 v[236:237], off
	s_barrier
	s_waitcnt lgkmcnt(0)
	s_setprio 1
	s_waitcnt lgkmcnt(0)
	v_mfma_f32_16x16x32_bf16 v[60:63], v[128:131], v[162:165], v[60:63]
	v_mfma_f32_16x16x32_bf16 v[56:59], v[136:139], v[162:165], v[56:59]
	v_mfma_f32_16x16x32_bf16 v[44:47], v[128:131], v[190:193], v[44:47]
	v_mfma_f32_16x16x32_bf16 v[40:43], v[136:139], v[190:193], v[40:43]
	v_mfma_f32_16x16x32_bf16 v[28:31], v[128:131], v[198:201], v[28:31]
	v_mfma_f32_16x16x32_bf16 v[24:27], v[136:139], v[198:201], v[24:27]
	v_mfma_f32_16x16x32_bf16 v[12:15], v[128:131], v[206:209], v[12:15]
	v_mfma_f32_16x16x32_bf16 v[8:11], v[136:139], v[206:209], v[8:11]
	v_mfma_f32_16x16x32_bf16 v[60:63], v[132:135], v[166:169], v[60:63]
	v_mfma_f32_16x16x32_bf16 v[56:59], v[140:143], v[166:169], v[56:59]
	v_mfma_f32_16x16x32_bf16 v[44:47], v[132:135], v[194:197], v[44:47]
	v_mfma_f32_16x16x32_bf16 v[40:43], v[140:143], v[194:197], v[40:43]
	v_mfma_f32_16x16x32_bf16 v[28:31], v[132:135], v[202:205], v[28:31]
	v_mfma_f32_16x16x32_bf16 v[24:27], v[140:143], v[202:205], v[24:27]
	v_mfma_f32_16x16x32_bf16 v[12:15], v[132:135], v[210:213], v[12:15]
	v_mfma_f32_16x16x32_bf16 v[8:11], v[140:143], v[210:213], v[8:11]
	s_setprio 0
	s_barrier
	s_add_u32 s66, s28, 0xb0000
	s_addc_u32 s67, s29, 0
	s_mov_b32 m0, s45
	v_lshl_add_u64 v[128:129], s[66:67], 0, v[144:145]
	global_load_lds_dwordx4 v[128:129], off
	v_lshl_add_u64 v[128:129], s[66:67], 0, v[146:147]
	s_mov_b32 m0, s46
	s_nop 0
	global_load_lds_dwordx4 v[128:129], off
	s_waitcnt vmcnt(6)
	s_barrier
	s_setprio 1
	v_mfma_f32_16x16x32_bf16 v[52:55], v[214:217], v[162:165], v[52:55]
	v_mfma_f32_16x16x32_bf16 v[48:51], v[222:225], v[162:165], v[48:51]
	v_mfma_f32_16x16x32_bf16 v[36:39], v[214:217], v[190:193], v[36:39]
	v_mfma_f32_16x16x32_bf16 v[32:35], v[222:225], v[190:193], v[32:35]
	v_mfma_f32_16x16x32_bf16 v[20:23], v[214:217], v[198:201], v[20:23]
	v_mfma_f32_16x16x32_bf16 v[16:19], v[222:225], v[198:201], v[16:19]
	v_mfma_f32_16x16x32_bf16 v[4:7], v[214:217], v[206:209], v[4:7]
	v_mfma_f32_16x16x32_bf16 v[0:3], v[222:225], v[206:209], v[0:3]
	v_mfma_f32_16x16x32_bf16 v[52:55], v[218:221], v[166:169], v[52:55]
	v_mfma_f32_16x16x32_bf16 v[48:51], v[226:229], v[166:169], v[48:51]
	v_mfma_f32_16x16x32_bf16 v[36:39], v[218:221], v[194:197], v[36:39]
	v_mfma_f32_16x16x32_bf16 v[32:35], v[226:229], v[194:197], v[32:35]
	v_mfma_f32_16x16x32_bf16 v[20:23], v[218:221], v[202:205], v[20:23]
	v_mfma_f32_16x16x32_bf16 v[16:19], v[226:229], v[202:205], v[16:19]
	v_mfma_f32_16x16x32_bf16 v[4:7], v[218:221], v[210:213], v[4:7]
	v_mfma_f32_16x16x32_bf16 v[0:3], v[226:229], v[210:213], v[0:3]
	s_setprio 0
	s_barrier
	ds_read_b128 v[128:131], v180
	ds_read_b128 v[132:135], v181
	ds_read_b128 v[136:139], v182
	ds_read_b128 v[140:143], v183
	s_add_u32 s30, s30, 0xb0000
	s_addc_u32 s31, s31, 0
	s_mov_b32 m0, s47
	v_lshl_add_u64 v[214:215], s[30:31], 0, v[144:145]
	ds_read_b128 v[162:165], v151 offset:32768
	ds_read_b128 v[166:169], v151 offset:33792
	ds_read_b128 v[190:193], v151 offset:34816
	ds_read_b128 v[194:197], v151 offset:35840
	ds_read_b128 v[198:201], v151 offset:36864
	ds_read_b128 v[202:205], v151 offset:37888
	ds_read_b128 v[206:209], v151 offset:38912
	ds_read_b128 v[210:213], v151 offset:39936
	global_load_lds_dwordx4 v[214:215], off
	v_lshl_add_u64 v[214:215], s[30:31], 0, v[146:147]
	s_mov_b32 m0, s48
	s_nop 0
	global_load_lds_dwordx4 v[214:215], off
	s_waitcnt lgkmcnt(8)
	s_barrier
	s_waitcnt lgkmcnt(0)
	s_setprio 1
	s_waitcnt lgkmcnt(0)
	v_mfma_f32_16x16x32_bf16 v[124:127], v[128:131], v[162:165], v[124:127]
	v_mfma_f32_16x16x32_bf16 v[120:123], v[136:139], v[162:165], v[120:123]
	v_mfma_f32_16x16x32_bf16 v[108:111], v[128:131], v[190:193], v[108:111]
	v_mfma_f32_16x16x32_bf16 v[104:107], v[136:139], v[190:193], v[104:107]
	v_mfma_f32_16x16x32_bf16 v[92:95], v[128:131], v[198:201], v[92:95]
	v_mfma_f32_16x16x32_bf16 v[88:91], v[136:139], v[198:201], v[88:91]
	v_mfma_f32_16x16x32_bf16 v[76:79], v[128:131], v[206:209], v[76:79]
	v_mfma_f32_16x16x32_bf16 v[72:75], v[136:139], v[206:209], v[72:75]
	v_mfma_f32_16x16x32_bf16 v[124:127], v[132:135], v[166:169], v[124:127]
	v_mfma_f32_16x16x32_bf16 v[120:123], v[140:143], v[166:169], v[120:123]
	v_mfma_f32_16x16x32_bf16 v[108:111], v[132:135], v[194:197], v[108:111]
	v_mfma_f32_16x16x32_bf16 v[104:107], v[140:143], v[194:197], v[104:107]
	v_mfma_f32_16x16x32_bf16 v[92:95], v[132:135], v[202:205], v[92:95]
	v_mfma_f32_16x16x32_bf16 v[88:91], v[140:143], v[202:205], v[88:91]
	v_mfma_f32_16x16x32_bf16 v[76:79], v[132:135], v[210:213], v[76:79]
	v_mfma_f32_16x16x32_bf16 v[72:75], v[140:143], v[210:213], v[72:75]
	s_setprio 0
	s_barrier
	s_mov_b32 m0, s52
	v_lshl_add_u64 v[230:231], v[230:231], 0, s[14:15]
	ds_read_b128 v[214:217], v184
	ds_read_b128 v[218:221], v185
	ds_read_b128 v[222:225], v186
	ds_read_b128 v[226:229], v187
	global_load_lds_dwordx4 v[230:231], off
	v_lshl_add_u64 v[230:231], v[232:233], 0, s[14:15]
	s_mov_b32 m0, s53
	s_nop 0
	global_load_lds_dwordx4 v[230:231], off
	s_barrier
	s_waitcnt lgkmcnt(0)
	s_setprio 1
	s_waitcnt lgkmcnt(0)
	v_mfma_f32_16x16x32_bf16 v[116:119], v[214:217], v[162:165], v[116:119]
	v_mfma_f32_16x16x32_bf16 v[112:115], v[222:225], v[162:165], v[112:115]
	v_mfma_f32_16x16x32_bf16 v[100:103], v[214:217], v[190:193], v[100:103]
	v_mfma_f32_16x16x32_bf16 v[96:99], v[222:225], v[190:193], v[96:99]
	v_mfma_f32_16x16x32_bf16 v[84:87], v[214:217], v[198:201], v[84:87]
	v_mfma_f32_16x16x32_bf16 v[80:83], v[222:225], v[198:201], v[80:83]
	v_mfma_f32_16x16x32_bf16 v[68:71], v[214:217], v[206:209], v[68:71]
	v_mfma_f32_16x16x32_bf16 v[64:67], v[222:225], v[206:209], v[64:67]
	v_mfma_f32_16x16x32_bf16 v[116:119], v[218:221], v[166:169], v[116:119]
	v_mfma_f32_16x16x32_bf16 v[112:115], v[226:229], v[166:169], v[112:115]
	v_mfma_f32_16x16x32_bf16 v[100:103], v[218:221], v[194:197], v[100:103]
	v_mfma_f32_16x16x32_bf16 v[96:99], v[226:229], v[194:197], v[96:99]
	v_mfma_f32_16x16x32_bf16 v[84:87], v[218:221], v[202:205], v[84:87]
	v_mfma_f32_16x16x32_bf16 v[80:83], v[226:229], v[202:205], v[80:83]
	v_mfma_f32_16x16x32_bf16 v[68:71], v[218:221], v[210:213], v[68:71]
	v_mfma_f32_16x16x32_bf16 v[64:67], v[226:229], v[210:213], v[64:67]
	s_setprio 0
	s_mov_b32 m0, s54
	v_lshl_add_u64 v[230:231], v[234:235], 0, s[14:15]
	s_barrier
	ds_read_b128 v[162:165], v151 offset:49152
	ds_read_b128 v[166:169], v151 offset:50176
	ds_read_b128 v[190:193], v151 offset:51200
	ds_read_b128 v[194:197], v151 offset:52224
	ds_read_b128 v[198:201], v151 offset:53248
	ds_read_b128 v[202:205], v151 offset:54272
	ds_read_b128 v[206:209], v151 offset:55296
	ds_read_b128 v[210:213], v151 offset:56320
	global_load_lds_dwordx4 v[230:231], off
	v_lshl_add_u64 v[230:231], v[236:237], 0, s[14:15]
	s_mov_b32 m0, s55
	s_nop 0
	global_load_lds_dwordx4 v[230:231], off
	s_barrier
	s_waitcnt lgkmcnt(0)
	s_setprio 1
	s_waitcnt lgkmcnt(0)
	v_mfma_f32_16x16x32_bf16 v[60:63], v[128:131], v[162:165], v[60:63]
	v_mfma_f32_16x16x32_bf16 v[56:59], v[136:139], v[162:165], v[56:59]
	v_mfma_f32_16x16x32_bf16 v[44:47], v[128:131], v[190:193], v[44:47]
	v_mfma_f32_16x16x32_bf16 v[40:43], v[136:139], v[190:193], v[40:43]
	v_mfma_f32_16x16x32_bf16 v[28:31], v[128:131], v[198:201], v[28:31]
	v_mfma_f32_16x16x32_bf16 v[24:27], v[136:139], v[198:201], v[24:27]
	v_mfma_f32_16x16x32_bf16 v[12:15], v[128:131], v[206:209], v[12:15]
	v_mfma_f32_16x16x32_bf16 v[8:11], v[136:139], v[206:209], v[8:11]
	v_mfma_f32_16x16x32_bf16 v[60:63], v[132:135], v[166:169], v[60:63]
	v_mfma_f32_16x16x32_bf16 v[56:59], v[140:143], v[166:169], v[56:59]
	v_mfma_f32_16x16x32_bf16 v[44:47], v[132:135], v[194:197], v[44:47]
	v_mfma_f32_16x16x32_bf16 v[40:43], v[140:143], v[194:197], v[40:43]
	v_mfma_f32_16x16x32_bf16 v[28:31], v[132:135], v[202:205], v[28:31]
	v_mfma_f32_16x16x32_bf16 v[24:27], v[140:143], v[202:205], v[24:27]
	v_mfma_f32_16x16x32_bf16 v[12:15], v[132:135], v[210:213], v[12:15]
	v_mfma_f32_16x16x32_bf16 v[8:11], v[140:143], v[210:213], v[8:11]
	s_setprio 0
	s_barrier
	s_add_u32 s28, s28, 0xb0080
	s_addc_u32 s29, s29, 0
	s_mov_b32 m0, s56
	v_lshl_add_u64 v[128:129], s[28:29], 0, v[144:145]
	global_load_lds_dwordx4 v[128:129], off
	v_lshl_add_u64 v[128:129], s[28:29], 0, v[146:147]
	s_mov_b32 m0, s57
	s_nop 0
	global_load_lds_dwordx4 v[128:129], off
	s_waitcnt vmcnt(6)
	s_barrier
	s_setprio 1
	v_mfma_f32_16x16x32_bf16 v[52:55], v[214:217], v[162:165], v[52:55]
	v_mfma_f32_16x16x32_bf16 v[48:51], v[222:225], v[162:165], v[48:51]
	v_mfma_f32_16x16x32_bf16 v[36:39], v[214:217], v[190:193], v[36:39]
	v_mfma_f32_16x16x32_bf16 v[32:35], v[222:225], v[190:193], v[32:35]
	v_mfma_f32_16x16x32_bf16 v[20:23], v[214:217], v[198:201], v[20:23]
	v_mfma_f32_16x16x32_bf16 v[16:19], v[222:225], v[198:201], v[16:19]
	v_mfma_f32_16x16x32_bf16 v[4:7], v[214:217], v[206:209], v[4:7]
	v_mfma_f32_16x16x32_bf16 v[0:3], v[222:225], v[206:209], v[0:3]
	v_mfma_f32_16x16x32_bf16 v[52:55], v[218:221], v[166:169], v[52:55]
	v_mfma_f32_16x16x32_bf16 v[48:51], v[226:229], v[166:169], v[48:51]
	v_mfma_f32_16x16x32_bf16 v[36:39], v[218:221], v[194:197], v[36:39]
	v_mfma_f32_16x16x32_bf16 v[32:35], v[226:229], v[194:197], v[32:35]
	v_mfma_f32_16x16x32_bf16 v[20:23], v[218:221], v[202:205], v[20:23]
	v_mfma_f32_16x16x32_bf16 v[16:19], v[226:229], v[202:205], v[16:19]
	v_mfma_f32_16x16x32_bf16 v[4:7], v[218:221], v[210:213], v[4:7]
	v_mfma_f32_16x16x32_bf16 v[0:3], v[226:229], v[210:213], v[0:3]
	s_setprio 0
	s_add_i32 s65, s65, 2
	s_add_u32 s25, s25, 0x100
	s_addc_u32 s64, s64, 0
	s_add_u32 s26, s26, 0x100
	s_addc_u32 s27, s27, 0
	s_cmp_gt_u32 s65, 41
	s_barrier
	s_cbranch_scc0 .LBB0_1642
	v_bfe_i32 v249, v176, 3, 1
	v_and_b32_e32 v248, 0xffff8040, v249
	v_mov_b32_e32 v250, 0x8000
	v_mov_b32_e32 v251, 0
	s_ashr_i32 s25, s24, 31
	s_lshl_b64 s[24:25], s[24:25], 8
	s_lshl_b32 s26, s16, 8
	v_lshl_add_u64 v[164:165], s[24:25], 0, v[148:149]
	s_ashr_i32 s27, s26, 31
	v_lshl_add_u64 v[166:167], s[26:27], 2, v[152:153]
	v_lshlrev_b64 v[128:129], 12, v[164:165]
	v_lshl_add_u64 v[128:129], v[166:167], 0, v[128:129]
	v_lshl_add_u64 v[232:233], v[128:129], 0, v[248:249]
	v_lshl_add_u64 v[234:235], v[232:233], 0, v[250:251]
	global_load_dwordx4 v[190:193], v[232:233], off
	global_load_dwordx4 v[194:197], v[234:235], off
	global_load_dwordx4 v[198:201], v[232:233], off offset:512
	global_load_dwordx4 v[202:205], v[234:235], off offset:512
	v_or_b32_e32 v168, 16, v164
	v_mov_b32_e32 v169, v165
	v_lshlrev_b64 v[128:129], 12, v[168:169]
	v_lshl_add_u64 v[128:129], v[166:167], 0, v[128:129]
	v_lshl_add_u64 v[236:237], v[128:129], 0, v[248:249]
	v_lshl_add_u64 v[238:239], v[236:237], 0, v[250:251]
	global_load_dwordx4 v[140:143], v[236:237], off
	global_load_dwordx4 v[136:139], v[238:239], off
	global_load_dwordx4 v[132:135], v[236:237], off offset:512
	s_nop 0
	global_load_dwordx4 v[128:131], v[238:239], off offset:512
	v_and_b32_e32 v163, 64, v188
	v_xor_b32_e32 v189, 16, v188
	v_add_u32_e32 v207, 64, v163
	v_xor_b32_e32 v206, 32, v188
	v_cmp_lt_i32_e32 vcc, v189, v207
	v_or_b32_e32 v162, s26, v150
	v_mov_b32_e32 v163, s27
	v_cndmask_b32_e32 v189, v188, v189, vcc
	v_cmp_lt_i32_e32 vcc, v206, v207
	s_waitcnt vmcnt(0)
	v_lshlrev_b32_e32 v189, 2, v189
	s_lshl_b32 s24, s16, 2
	v_cndmask_b32_e32 v216, v188, v206, vcc
	v_lshlrev_b64 v[206:207], 10, v[164:165]
	v_lshl_add_u64 v[206:207], v[206:207], 0, v[162:163]
	v_lshl_add_u64 v[208:209], v[206:207], 2, s[78:79]
	v_lshlrev_b64 v[206:207], 1, v[206:207]
	v_lshl_add_u64 v[210:211], s[2:3], 0, v[206:207]
	v_or_b32_e32 v212, 32, v206
	v_mov_b32_e32 v213, v207
	v_or_b32_e32 v214, 0x100, v206
	v_mov_b32_e32 v215, v207
	v_lshl_add_u64 v[212:213], s[2:3], 0, v[212:213]
	v_lshl_add_u64 v[214:215], s[2:3], 0, v[214:215]
	v_or_b32_e32 v206, 0x120, v206
	s_ashr_i32 s25, s24, 31
	s_waitcnt vmcnt(0)
	v_mov_b32_dpp v224, v190 row_ror:8 row_mask:0xf bank_mask:0xf
	v_mov_b32_dpp v225, v191 row_ror:8 row_mask:0xf bank_mask:0xf
	v_mov_b32_dpp v226, v192 row_ror:8 row_mask:0xf bank_mask:0xf
	v_mov_b32_dpp v227, v193 row_ror:8 row_mask:0xf bank_mask:0xf
	v_mov_b32_dpp v190, v194 row_ror:8 row_mask:0xf bank_mask:0xc
	v_mov_b32_dpp v191, v195 row_ror:8 row_mask:0xf bank_mask:0xc
	v_mov_b32_dpp v192, v196 row_ror:8 row_mask:0xf bank_mask:0xc
	v_mov_b32_dpp v193, v197 row_ror:8 row_mask:0xf bank_mask:0xc
	v_mov_b32_dpp v194, v224 quad_perm:[0,1,2,3] row_mask:0xf bank_mask:0x3
	v_mov_b32_dpp v195, v225 quad_perm:[0,1,2,3] row_mask:0xf bank_mask:0x3
	v_mov_b32_dpp v196, v226 quad_perm:[0,1,2,3] row_mask:0xf bank_mask:0x3
	v_mov_b32_dpp v197, v227 quad_perm:[0,1,2,3] row_mask:0xf bank_mask:0x3
	v_mov_b32_dpp v224, v198 row_ror:8 row_mask:0xf bank_mask:0xf
	v_mov_b32_dpp v225, v199 row_ror:8 row_mask:0xf bank_mask:0xf
	v_mov_b32_dpp v226, v200 row_ror:8 row_mask:0xf bank_mask:0xf
	v_mov_b32_dpp v227, v201 row_ror:8 row_mask:0xf bank_mask:0xf
	v_mov_b32_dpp v198, v202 row_ror:8 row_mask:0xf bank_mask:0xc
	v_mov_b32_dpp v199, v203 row_ror:8 row_mask:0xf bank_mask:0xc
	v_mov_b32_dpp v200, v204 row_ror:8 row_mask:0xf bank_mask:0xc
	v_mov_b32_dpp v201, v205 row_ror:8 row_mask:0xf bank_mask:0xc
	v_mov_b32_dpp v202, v224 quad_perm:[0,1,2,3] row_mask:0xf bank_mask:0x3
	v_mov_b32_dpp v203, v225 quad_perm:[0,1,2,3] row_mask:0xf bank_mask:0x3
	v_mov_b32_dpp v204, v226 quad_perm:[0,1,2,3] row_mask:0xf bank_mask:0x3
	v_mov_b32_dpp v205, v227 quad_perm:[0,1,2,3] row_mask:0xf bank_mask:0x3
	v_pk_fma_f32 v[126:127], v[126:127], 0.5, v[192:193] op_sel_hi:[1,0,1]
	v_pk_fma_f32 v[124:125], v[124:125], 0.5, v[190:191] op_sel_hi:[1,0,1]
	v_pk_fma_f32 v[120:121], v[120:121], 0.5, v[194:195] op_sel_hi:[1,0,1]
	v_pk_fma_f32 v[122:123], v[122:123], 0.5, v[196:197] op_sel_hi:[1,0,1]
	v_pk_fma_f32 v[116:117], v[116:117], 0.5, v[198:199] op_sel_hi:[1,0,1]
	v_pk_fma_f32 v[190:191], v[112:113], 0.5, v[202:203] op_sel_hi:[1,0,1]
	global_store_dwordx4 v[208:209], v[124:127], off
	v_cvt_pk_bf16_f32 v112, v124, v125
	v_mul_f32_e32 v196, v120, v120
	v_mul_f32_e32 v197, v116, v116
	v_mul_f32_e32 v124, v124, v124
	v_fmac_f32_e32 v124, v125, v125
	v_fmac_f32_e32 v196, v121, v121
	v_pk_fma_f32 v[118:119], v[118:119], 0.5, v[200:201] op_sel_hi:[1,0,1]
	v_mul_f32_e32 v198, v190, v190
	v_fmac_f32_e32 v197, v117, v117
	v_fmac_f32_e32 v124, v126, v126
	v_fmac_f32_e32 v196, v122, v122
	v_pk_fma_f32 v[192:193], v[114:115], 0.5, v[204:205] op_sel_hi:[1,0,1]
	v_fmac_f32_e32 v198, v191, v191
	v_fmac_f32_e32 v197, v118, v118
	v_fmac_f32_e32 v124, v127, v127
	v_fmac_f32_e32 v196, v123, v123
	v_cvt_pk_bf16_f32 v113, v126, v127
	v_bfe_u32 v246, v176, 4, 1
	v_mul_u32_u24_e32 v246, 24, v246
	v_mov_b32_e32 v247, 0
	s_nop 1
	v_mov_b32_e32 v240, v112
	v_mov_b32_e32 v241, v113
	v_lshl_add_u64 v[244:245], v[210:211], 0, v[246:247]
	v_fmac_f32_e32 v198, v192, v192
	v_fmac_f32_e32 v197, v119, v119
	v_add_f32_e32 v112, v124, v196
	v_fmac_f32_e32 v198, v193, v193
	v_add_f32_e32 v112, v112, v197
	v_add_f32_e32 v112, v112, v198
	ds_bpermute_b32 v113, v189, v112
	v_cvt_pk_bf16_f32 v114, v120, v121
	v_cvt_pk_bf16_f32 v115, v122, v123
	v_cvt_pk_bf16_f32 v194, v116, v117
	v_cvt_pk_bf16_f32 v195, v118, v119
	global_store_dwordx4 v[208:209], v[120:123], off offset:64
	v_mov_b32_e32 v242, v114
	v_mov_b32_e32 v243, v115
	s_nop 1
	v_permlane16_swap_b32 v240, v242
	v_permlane16_swap_b32 v241, v243
	global_store_dwordx4 v[244:245], v[240:243], off
	global_store_dwordx4 v[208:209], v[116:119], off offset:512
	s_nop 1
	v_mov_b32_e32 v240, v194
	v_mov_b32_e32 v241, v195
	v_lshl_add_u64 v[244:245], v[214:215], 0, v[246:247]
	global_store_dwordx4 v[208:209], v[190:193], off offset:576
	s_waitcnt lgkmcnt(0)
	v_add_f32_e32 v112, v112, v113
	v_lshlrev_b32_e32 v116, 2, v216
	ds_bpermute_b32 v113, v116, v112
	v_lshl_add_u64 v[114:115], s[2:3], 0, v[206:207]
	v_cvt_pk_bf16_f32 v118, v190, v191
	v_cvt_pk_bf16_f32 v119, v192, v193
	v_mov_b32_e32 v242, v118
	v_mov_b32_e32 v243, v119
	s_nop 1
	v_permlane16_swap_b32 v240, v242
	v_permlane16_swap_b32 v241, v243
	global_store_dwordx4 v[244:245], v[240:243], off
	s_and_saveexec_b64 s[26:27], s[6:7]
	s_cbranch_execz .LBB0_1645
	v_lshlrev_b64 v[114:115], 6, v[164:165]
	v_lshl_add_u64 v[114:115], s[4:5], 0, v[114:115]
	v_lshl_add_u64 v[114:115], s[24:25], 2, v[114:115]
	s_lshl_b32 s16, s49, 2
	v_lshl_add_u64 v[114:115], v[114:115], 0, s[16:17]
	s_waitcnt lgkmcnt(0)
	v_add_f32_e32 v112, v112, v113
	flat_store_dword v[114:115], v112
.LBB0_1645:
	s_or_b64 exec, exec, s[26:27]
	s_waitcnt lgkmcnt(0)
	v_lshlrev_b64 v[112:113], 10, v[168:169]
	v_lshl_add_u64 v[112:113], v[112:113], 0, v[162:163]
	v_mov_b32_dpp v224, v140 row_ror:8 row_mask:0xf bank_mask:0xf
	v_mov_b32_dpp v225, v141 row_ror:8 row_mask:0xf bank_mask:0xf
	v_mov_b32_dpp v226, v142 row_ror:8 row_mask:0xf bank_mask:0xf
	v_mov_b32_dpp v227, v143 row_ror:8 row_mask:0xf bank_mask:0xf
	v_mov_b32_dpp v140, v136 row_ror:8 row_mask:0xf bank_mask:0xc
	v_mov_b32_dpp v141, v137 row_ror:8 row_mask:0xf bank_mask:0xc
	v_mov_b32_dpp v142, v138 row_ror:8 row_mask:0xf bank_mask:0xc
	v_mov_b32_dpp v143, v139 row_ror:8 row_mask:0xf bank_mask:0xc
	v_mov_b32_dpp v136, v224 quad_perm:[0,1,2,3] row_mask:0xf bank_mask:0x3
	v_mov_b32_dpp v137, v225 quad_perm:[0,1,2,3] row_mask:0xf bank_mask:0x3
	v_mov_b32_dpp v138, v226 quad_perm:[0,1,2,3] row_mask:0xf bank_mask:0x3
	v_mov_b32_dpp v139, v227 quad_perm:[0,1,2,3] row_mask:0xf bank_mask:0x3
	v_mov_b32_dpp v224, v132 row_ror:8 row_mask:0xf bank_mask:0xf
	v_mov_b32_dpp v225, v133 row_ror:8 row_mask:0xf bank_mask:0xf
	v_mov_b32_dpp v226, v134 row_ror:8 row_mask:0xf bank_mask:0xf
	v_mov_b32_dpp v227, v135 row_ror:8 row_mask:0xf bank_mask:0xf
	v_mov_b32_dpp v132, v128 row_ror:8 row_mask:0xf bank_mask:0xc
	v_mov_b32_dpp v133, v129 row_ror:8 row_mask:0xf bank_mask:0xc
	v_mov_b32_dpp v134, v130 row_ror:8 row_mask:0xf bank_mask:0xc
	v_mov_b32_dpp v135, v131 row_ror:8 row_mask:0xf bank_mask:0xc
	v_mov_b32_dpp v128, v224 quad_perm:[0,1,2,3] row_mask:0xf bank_mask:0x3
	v_mov_b32_dpp v129, v225 quad_perm:[0,1,2,3] row_mask:0xf bank_mask:0x3
	v_mov_b32_dpp v130, v226 quad_perm:[0,1,2,3] row_mask:0xf bank_mask:0x3
	v_mov_b32_dpp v131, v227 quad_perm:[0,1,2,3] row_mask:0xf bank_mask:0x3
	v_pk_fma_f32 v[108:109], v[108:109], 0.5, v[140:141] op_sel_hi:[1,0,1]
	v_lshl_add_u64 v[114:115], v[112:113], 2, s[78:79]
	v_lshlrev_b64 v[112:113], 1, v[112:113]
	v_mul_f32_e32 v117, v108, v108
	v_pk_fma_f32 v[110:111], v[110:111], 0.5, v[142:143] op_sel_hi:[1,0,1]
	v_lshl_add_u64 v[118:119], s[2:3], 0, v[112:113]
	v_fmac_f32_e32 v117, v109, v109
	v_pk_fma_f32 v[106:107], v[106:107], 0.5, v[138:139] op_sel_hi:[1,0,1]
	v_pk_fma_f32 v[104:105], v[104:105], 0.5, v[136:137] op_sel_hi:[1,0,1]
	global_store_dwordx4 v[114:115], v[108:111], off
	v_cvt_pk_bf16_f32 v120, v108, v109
	v_cvt_pk_bf16_f32 v121, v110, v111
	s_nop 1
	v_mov_b32_e32 v240, v120
	v_mov_b32_e32 v241, v121
	v_lshl_add_u64 v[244:245], v[118:119], 0, v[246:247]
	v_fmac_f32_e32 v117, v110, v110
	global_store_dwordx4 v[114:115], v[104:107], off offset:64
	v_or_b32_e32 v108, 32, v112
	v_mov_b32_e32 v109, v113
	v_cvt_pk_bf16_f32 v110, v104, v105
	v_mul_f32_e32 v104, v104, v104
	v_lshl_add_u64 v[108:109], s[2:3], 0, v[108:109]
	v_fmac_f32_e32 v104, v105, v105
	v_pk_fma_f32 v[102:103], v[102:103], 0.5, v[134:135] op_sel_hi:[1,0,1]
	v_pk_fma_f32 v[100:101], v[100:101], 0.5, v[132:133] op_sel_hi:[1,0,1]
	v_fmac_f32_e32 v117, v111, v111
	v_cvt_pk_bf16_f32 v111, v106, v107
	v_mov_b32_e32 v242, v110
	v_mov_b32_e32 v243, v111
	s_nop 1
	v_permlane16_swap_b32 v240, v242
	v_permlane16_swap_b32 v241, v243
	global_store_dwordx4 v[244:245], v[240:243], off
	v_fmac_f32_e32 v104, v106, v106
	global_store_dwordx4 v[114:115], v[100:103], off offset:512
	v_cvt_pk_bf16_f32 v106, v100, v101
	v_fmac_f32_e32 v104, v107, v107
	v_add_f32_e32 v107, v117, v104
	v_mul_f32_e32 v100, v100, v100
	v_fmac_f32_e32 v100, v101, v101
	v_fmac_f32_e32 v100, v102, v102
	v_fmac_f32_e32 v100, v103, v103
	v_add_f32_e32 v107, v107, v100
	v_pk_fma_f32 v[100:101], v[98:99], 0.5, v[130:131] op_sel_hi:[1,0,1]
	v_pk_fma_f32 v[98:99], v[96:97], 0.5, v[128:129] op_sel_hi:[1,0,1]
	v_or_b32_e32 v104, 0x100, v112
	v_mul_f32_e32 v96, v98, v98
	v_fmac_f32_e32 v96, v99, v99
	v_fmac_f32_e32 v96, v100, v100
	v_fmac_f32_e32 v96, v101, v101
	v_add_f32_e32 v96, v107, v96
	ds_bpermute_b32 v97, v189, v96
	v_mov_b32_e32 v105, v113
	v_or_b32_e32 v112, 0x120, v112
	v_lshl_add_u64 v[104:105], s[2:3], 0, v[104:105]
	v_cvt_pk_bf16_f32 v107, v102, v103
	s_waitcnt lgkmcnt(0)
	v_add_f32_e32 v96, v96, v97
	ds_bpermute_b32 v97, v116, v96
	v_lshl_add_u64 v[102:103], s[2:3], 0, v[112:113]
	s_nop 1
	v_mov_b32_e32 v240, v106
	v_mov_b32_e32 v241, v107
	v_lshl_add_u64 v[244:245], v[104:105], 0, v[246:247]
	global_store_dwordx4 v[114:115], v[98:101], off offset:576
	s_nop 1
	v_cvt_pk_bf16_f32 v98, v98, v99
	v_cvt_pk_bf16_f32 v99, v100, v101
	v_mov_b32_e32 v242, v98
	v_mov_b32_e32 v243, v99
	s_nop 1
	v_permlane16_swap_b32 v240, v242
	v_permlane16_swap_b32 v241, v243
	global_store_dwordx4 v[244:245], v[240:243], off
	s_and_saveexec_b64 s[26:27], s[6:7]
	s_cbranch_execz .LBB0_1647
	v_lshlrev_b64 v[98:99], 6, v[168:169]
	v_lshl_add_u64 v[98:99], s[4:5], 0, v[98:99]
	v_lshl_add_u64 v[98:99], s[24:25], 2, v[98:99]
	s_lshl_b32 s16, s49, 2
	v_lshl_add_u64 v[98:99], v[98:99], 0, s[16:17]
	s_waitcnt lgkmcnt(0)
	v_add_f32_e32 v96, v96, v97
	flat_store_dword v[98:99], v96
.LBB0_1647:
	s_or_b64 exec, exec, s[26:27]
	v_or_b32_e32 v114, 32, v164
	v_mov_b32_e32 v115, v165
	s_waitcnt lgkmcnt(0)
	v_lshlrev_b64 v[96:97], 12, v[114:115]
	v_lshl_add_u64 v[96:97], v[166:167], 0, v[96:97]
	v_lshl_add_u64 v[232:233], v[96:97], 0, v[248:249]
	v_lshl_add_u64 v[234:235], v[232:233], 0, v[250:251]
	global_load_dwordx4 v[118:121], v[232:233], off
	global_load_dwordx4 v[122:125], v[234:235], off
	global_load_dwordx4 v[126:129], v[232:233], off offset:512
	global_load_dwordx4 v[130:133], v[234:235], off offset:512
	v_or_b32_e32 v112, 48, v164
	v_mov_b32_e32 v113, v165
	v_lshlrev_b64 v[96:97], 12, v[112:113]
	v_lshl_add_u64 v[96:97], v[166:167], 0, v[96:97]
	v_lshl_add_u64 v[236:237], v[96:97], 0, v[248:249]
	v_lshl_add_u64 v[238:239], v[236:237], 0, v[250:251]
	global_load_dwordx4 v[108:111], v[236:237], off
	global_load_dwordx4 v[104:107], v[238:239], off
	global_load_dwordx4 v[100:103], v[236:237], off offset:512
	s_nop 0
	global_load_dwordx4 v[96:99], v[238:239], off offset:512
	v_lshlrev_b64 v[134:135], 10, v[114:115]
	v_lshl_add_u64 v[134:135], v[134:135], 0, v[162:163]
	v_lshl_add_u64 v[136:137], v[134:135], 2, s[78:79]
	v_lshlrev_b64 v[134:135], 1, v[134:135]
	v_lshl_add_u64 v[138:139], s[2:3], 0, v[134:135]
	s_waitcnt vmcnt(0)
	v_or_b32_e32 v140, 32, v134
	v_mov_b32_e32 v141, v135
	v_or_b32_e32 v142, 0x100, v134
	v_mov_b32_e32 v143, v135
	v_or_b32_e32 v134, 0x120, v134
	v_lshl_add_u64 v[140:141], s[2:3], 0, v[140:141]
	v_lshl_add_u64 v[142:143], s[2:3], 0, v[142:143]
	s_waitcnt vmcnt(0)
	v_mov_b32_dpp v224, v118 row_ror:8 row_mask:0xf bank_mask:0xf
	v_mov_b32_dpp v225, v119 row_ror:8 row_mask:0xf bank_mask:0xf
	v_mov_b32_dpp v226, v120 row_ror:8 row_mask:0xf bank_mask:0xf
	v_mov_b32_dpp v227, v121 row_ror:8 row_mask:0xf bank_mask:0xf
	v_mov_b32_dpp v118, v122 row_ror:8 row_mask:0xf bank_mask:0xc
	v_mov_b32_dpp v119, v123 row_ror:8 row_mask:0xf bank_mask:0xc
	v_mov_b32_dpp v120, v124 row_ror:8 row_mask:0xf bank_mask:0xc
	v_mov_b32_dpp v121, v125 row_ror:8 row_mask:0xf bank_mask:0xc
	v_mov_b32_dpp v122, v224 quad_perm:[0,1,2,3] row_mask:0xf bank_mask:0x3
	v_mov_b32_dpp v123, v225 quad_perm:[0,1,2,3] row_mask:0xf bank_mask:0x3
	v_mov_b32_dpp v124, v226 quad_perm:[0,1,2,3] row_mask:0xf bank_mask:0x3
	v_mov_b32_dpp v125, v227 quad_perm:[0,1,2,3] row_mask:0xf bank_mask:0x3
	v_mov_b32_dpp v224, v126 row_ror:8 row_mask:0xf bank_mask:0xf
	v_mov_b32_dpp v225, v127 row_ror:8 row_mask:0xf bank_mask:0xf
	v_mov_b32_dpp v226, v128 row_ror:8 row_mask:0xf bank_mask:0xf
	v_mov_b32_dpp v227, v129 row_ror:8 row_mask:0xf bank_mask:0xf
	v_mov_b32_dpp v126, v130 row_ror:8 row_mask:0xf bank_mask:0xc
	v_mov_b32_dpp v127, v131 row_ror:8 row_mask:0xf bank_mask:0xc
	v_mov_b32_dpp v128, v132 row_ror:8 row_mask:0xf bank_mask:0xc
	v_mov_b32_dpp v129, v133 row_ror:8 row_mask:0xf bank_mask:0xc
	v_mov_b32_dpp v130, v224 quad_perm:[0,1,2,3] row_mask:0xf bank_mask:0x3
	v_mov_b32_dpp v131, v225 quad_perm:[0,1,2,3] row_mask:0xf bank_mask:0x3
	v_mov_b32_dpp v132, v226 quad_perm:[0,1,2,3] row_mask:0xf bank_mask:0x3
	v_mov_b32_dpp v133, v227 quad_perm:[0,1,2,3] row_mask:0xf bank_mask:0x3
	v_pk_fma_f32 v[92:93], v[92:93], 0.5, v[118:119] op_sel_hi:[1,0,1]
	v_pk_fma_f32 v[88:89], v[88:89], 0.5, v[122:123] op_sel_hi:[1,0,1]
	v_pk_fma_f32 v[84:85], v[84:85], 0.5, v[126:127] op_sel_hi:[1,0,1]
	v_mul_f32_e32 v117, v92, v92
	v_mul_f32_e32 v122, v88, v88
	v_pk_fma_f32 v[94:95], v[94:95], 0.5, v[120:121] op_sel_hi:[1,0,1]
	v_pk_fma_f32 v[90:91], v[90:91], 0.5, v[124:125] op_sel_hi:[1,0,1]
	v_pk_fma_f32 v[118:119], v[80:81], 0.5, v[130:131] op_sel_hi:[1,0,1]
	v_mul_f32_e32 v123, v84, v84
	v_fmac_f32_e32 v117, v93, v93
	v_fmac_f32_e32 v122, v89, v89
	v_pk_fma_f32 v[86:87], v[86:87], 0.5, v[128:129] op_sel_hi:[1,0,1]
	v_mul_f32_e32 v124, v118, v118
	v_fmac_f32_e32 v123, v85, v85
	v_fmac_f32_e32 v117, v94, v94
	v_fmac_f32_e32 v122, v90, v90
	v_pk_fma_f32 v[120:121], v[82:83], 0.5, v[132:133] op_sel_hi:[1,0,1]
	v_cvt_pk_bf16_f32 v80, v92, v93
	v_fmac_f32_e32 v124, v119, v119
	v_fmac_f32_e32 v123, v86, v86
	v_fmac_f32_e32 v117, v95, v95
	v_fmac_f32_e32 v122, v91, v91
	global_store_dwordx4 v[136:137], v[92:95], off
	v_cvt_pk_bf16_f32 v81, v94, v95
	s_nop 1
	v_mov_b32_e32 v240, v80
	v_mov_b32_e32 v241, v81
	v_lshl_add_u64 v[244:245], v[138:139], 0, v[246:247]
	v_fmac_f32_e32 v124, v120, v120
	v_fmac_f32_e32 v123, v87, v87
	v_add_f32_e32 v80, v117, v122
	v_add_f32_e32 v80, v80, v123
	v_fmac_f32_e32 v124, v121, v121
	v_add_f32_e32 v80, v80, v124
	ds_bpermute_b32 v81, v189, v80
	v_cvt_pk_bf16_f32 v82, v88, v89
	v_cvt_pk_bf16_f32 v83, v90, v91
	v_cvt_pk_bf16_f32 v92, v84, v85
	global_store_dwordx4 v[136:137], v[88:91], off offset:64
	v_mov_b32_e32 v242, v82
	v_mov_b32_e32 v243, v83
	s_nop 1
	v_permlane16_swap_b32 v240, v242
	v_permlane16_swap_b32 v241, v243
	global_store_dwordx4 v[244:245], v[240:243], off
	s_waitcnt lgkmcnt(0)
	v_add_f32_e32 v80, v80, v81
	ds_bpermute_b32 v81, v116, v80
	v_cvt_pk_bf16_f32 v93, v86, v87
	v_lshl_add_u64 v[82:83], s[2:3], 0, v[134:135]
	global_store_dwordx4 v[136:137], v[84:87], off offset:512
	s_nop 1
	v_mov_b32_e32 v240, v92
	v_mov_b32_e32 v241, v93
	v_lshl_add_u64 v[244:245], v[142:143], 0, v[246:247]
	global_store_dwordx4 v[136:137], v[118:121], off offset:576
	v_cvt_pk_bf16_f32 v84, v118, v119
	v_cvt_pk_bf16_f32 v85, v120, v121
	v_mov_b32_e32 v242, v84
	v_mov_b32_e32 v243, v85
	s_nop 1
	v_permlane16_swap_b32 v240, v242
	v_permlane16_swap_b32 v241, v243
	global_store_dwordx4 v[244:245], v[240:243], off
	s_and_saveexec_b64 s[26:27], s[6:7]
	s_cbranch_execz .LBB0_1649
	v_lshlrev_b64 v[82:83], 6, v[114:115]
	v_lshl_add_u64 v[82:83], s[4:5], 0, v[82:83]
	v_lshl_add_u64 v[82:83], s[24:25], 2, v[82:83]
	s_lshl_b32 s16, s49, 2
	v_lshl_add_u64 v[82:83], v[82:83], 0, s[16:17]
	s_waitcnt lgkmcnt(0)
	v_add_f32_e32 v80, v80, v81
	flat_store_dword v[82:83], v80
.LBB0_1649:
	s_or_b64 exec, exec, s[26:27]
	s_waitcnt lgkmcnt(0)
	v_lshlrev_b64 v[80:81], 10, v[112:113]
	v_lshl_add_u64 v[80:81], v[80:81], 0, v[162:163]
	v_lshl_add_u64 v[82:83], v[80:81], 2, s[78:79]
	v_lshlrev_b64 v[80:81], 1, v[80:81]
	v_mov_b32_dpp v224, v108 row_ror:8 row_mask:0xf bank_mask:0xf
	v_mov_b32_dpp v225, v109 row_ror:8 row_mask:0xf bank_mask:0xf
	v_mov_b32_dpp v226, v110 row_ror:8 row_mask:0xf bank_mask:0xf
	v_mov_b32_dpp v227, v111 row_ror:8 row_mask:0xf bank_mask:0xf
	v_mov_b32_dpp v108, v104 row_ror:8 row_mask:0xf bank_mask:0xc
	v_mov_b32_dpp v109, v105 row_ror:8 row_mask:0xf bank_mask:0xc
	v_mov_b32_dpp v110, v106 row_ror:8 row_mask:0xf bank_mask:0xc
	v_mov_b32_dpp v111, v107 row_ror:8 row_mask:0xf bank_mask:0xc
	v_mov_b32_dpp v104, v224 quad_perm:[0,1,2,3] row_mask:0xf bank_mask:0x3
	v_mov_b32_dpp v105, v225 quad_perm:[0,1,2,3] row_mask:0xf bank_mask:0x3
	v_mov_b32_dpp v106, v226 quad_perm:[0,1,2,3] row_mask:0xf bank_mask:0x3
	v_mov_b32_dpp v107, v227 quad_perm:[0,1,2,3] row_mask:0xf bank_mask:0x3
	v_mov_b32_dpp v224, v100 row_ror:8 row_mask:0xf bank_mask:0xf
	v_mov_b32_dpp v225, v101 row_ror:8 row_mask:0xf bank_mask:0xf
	v_mov_b32_dpp v226, v102 row_ror:8 row_mask:0xf bank_mask:0xf
	v_mov_b32_dpp v227, v103 row_ror:8 row_mask:0xf bank_mask:0xf
	v_mov_b32_dpp v100, v96 row_ror:8 row_mask:0xf bank_mask:0xc
	v_mov_b32_dpp v101, v97 row_ror:8 row_mask:0xf bank_mask:0xc
	v_mov_b32_dpp v102, v98 row_ror:8 row_mask:0xf bank_mask:0xc
	v_mov_b32_dpp v103, v99 row_ror:8 row_mask:0xf bank_mask:0xc
	v_mov_b32_dpp v96, v224 quad_perm:[0,1,2,3] row_mask:0xf bank_mask:0x3
	v_mov_b32_dpp v97, v225 quad_perm:[0,1,2,3] row_mask:0xf bank_mask:0x3
	v_mov_b32_dpp v98, v226 quad_perm:[0,1,2,3] row_mask:0xf bank_mask:0x3
	v_mov_b32_dpp v99, v227 quad_perm:[0,1,2,3] row_mask:0xf bank_mask:0x3
	v_pk_fma_f32 v[78:79], v[78:79], 0.5, v[110:111] op_sel_hi:[1,0,1]
	v_pk_fma_f32 v[76:77], v[76:77], 0.5, v[108:109] op_sel_hi:[1,0,1]
	v_lshl_add_u64 v[84:85], s[2:3], 0, v[80:81]
	global_store_dwordx4 v[82:83], v[76:79], off
	v_cvt_pk_bf16_f32 v86, v76, v77
	v_cvt_pk_bf16_f32 v87, v78, v79
	s_nop 1
	v_mov_b32_e32 v240, v86
	v_mov_b32_e32 v241, v87
	v_lshl_add_u64 v[244:245], v[84:85], 0, v[246:247]
	v_mul_f32_e32 v84, v76, v76
	v_fmac_f32_e32 v84, v77, v77
	v_pk_fma_f32 v[74:75], v[74:75], 0.5, v[106:107] op_sel_hi:[1,0,1]
	v_pk_fma_f32 v[72:73], v[72:73], 0.5, v[104:105] op_sel_hi:[1,0,1]
	v_fmac_f32_e32 v84, v78, v78
	global_store_dwordx4 v[82:83], v[72:75], off offset:64
	v_or_b32_e32 v76, 32, v80
	v_mov_b32_e32 v77, v81
	v_cvt_pk_bf16_f32 v78, v72, v73
	v_mul_f32_e32 v72, v72, v72
	v_lshl_add_u64 v[76:77], s[2:3], 0, v[76:77]
	v_fmac_f32_e32 v72, v73, v73
	v_pk_fma_f32 v[70:71], v[70:71], 0.5, v[102:103] op_sel_hi:[1,0,1]
	v_pk_fma_f32 v[68:69], v[68:69], 0.5, v[100:101] op_sel_hi:[1,0,1]
	v_fmac_f32_e32 v84, v79, v79
	v_cvt_pk_bf16_f32 v79, v74, v75
	v_mov_b32_e32 v242, v78
	v_mov_b32_e32 v243, v79
	s_nop 1
	v_permlane16_swap_b32 v240, v242
	v_permlane16_swap_b32 v241, v243
	global_store_dwordx4 v[244:245], v[240:243], off
	v_fmac_f32_e32 v72, v74, v74
	global_store_dwordx4 v[82:83], v[68:71], off offset:512
	v_cvt_pk_bf16_f32 v74, v68, v69
	v_fmac_f32_e32 v72, v75, v75
	v_add_f32_e32 v75, v84, v72
	v_mul_f32_e32 v68, v68, v68
	v_fmac_f32_e32 v68, v69, v69
	v_fmac_f32_e32 v68, v70, v70
	v_fmac_f32_e32 v68, v71, v71
	v_add_f32_e32 v75, v75, v68
	v_pk_fma_f32 v[68:69], v[66:67], 0.5, v[98:99] op_sel_hi:[1,0,1]
	v_pk_fma_f32 v[66:67], v[64:65], 0.5, v[96:97] op_sel_hi:[1,0,1]
	v_or_b32_e32 v72, 0x100, v80
	v_mul_f32_e32 v64, v66, v66
	v_fmac_f32_e32 v64, v67, v67
	v_fmac_f32_e32 v64, v68, v68
	v_fmac_f32_e32 v64, v69, v69
	v_add_f32_e32 v64, v75, v64
	ds_bpermute_b32 v65, v189, v64
	v_mov_b32_e32 v73, v81
	v_or_b32_e32 v80, 0x120, v80
	v_lshl_add_u64 v[72:73], s[2:3], 0, v[72:73]
	v_cvt_pk_bf16_f32 v75, v70, v71
	s_waitcnt lgkmcnt(0)
	v_add_f32_e32 v64, v64, v65
	ds_bpermute_b32 v65, v116, v64
	v_lshl_add_u64 v[70:71], s[2:3], 0, v[80:81]
	s_nop 1
	v_mov_b32_e32 v240, v74
	v_mov_b32_e32 v241, v75
	v_lshl_add_u64 v[244:245], v[72:73], 0, v[246:247]
	global_store_dwordx4 v[82:83], v[66:69], off offset:576
	s_nop 1
	v_cvt_pk_bf16_f32 v66, v66, v67
	v_cvt_pk_bf16_f32 v67, v68, v69
	v_mov_b32_e32 v242, v66
	v_mov_b32_e32 v243, v67
	s_nop 1
	v_permlane16_swap_b32 v240, v242
	v_permlane16_swap_b32 v241, v243
	global_store_dwordx4 v[244:245], v[240:243], off
	s_and_saveexec_b64 s[26:27], s[6:7]
	s_cbranch_execz .LBB0_1651
	v_lshlrev_b64 v[66:67], 6, v[112:113]
	v_lshl_add_u64 v[66:67], s[4:5], 0, v[66:67]
	v_lshl_add_u64 v[66:67], s[24:25], 2, v[66:67]
	s_lshl_b32 s16, s49, 2
	v_lshl_add_u64 v[66:67], v[66:67], 0, s[16:17]
	s_waitcnt lgkmcnt(0)
	v_add_f32_e32 v64, v64, v65
	flat_store_dword v[66:67], v64
.LBB0_1651:
	s_or_b64 exec, exec, s[26:27]
	v_lshl_add_u64 v[82:83], v[164:165], 0, s[14:15]
	s_waitcnt lgkmcnt(0)
	v_lshlrev_b64 v[64:65], 12, v[82:83]
	v_lshl_add_u64 v[64:65], v[166:167], 0, v[64:65]
	v_lshl_add_u64 v[232:233], v[64:65], 0, v[248:249]
	v_lshl_add_u64 v[234:235], v[232:233], 0, v[250:251]
	global_load_dwordx4 v[84:87], v[232:233], off
	global_load_dwordx4 v[88:91], v[234:235], off
	global_load_dwordx4 v[92:95], v[232:233], off offset:512
	global_load_dwordx4 v[96:99], v[234:235], off offset:512
	v_lshl_add_u64 v[80:81], v[164:165], 0, s[18:19]
	v_lshlrev_b64 v[64:65], 12, v[80:81]
	v_lshl_add_u64 v[64:65], v[166:167], 0, v[64:65]
	v_lshl_add_u64 v[236:237], v[64:65], 0, v[248:249]
	v_lshl_add_u64 v[238:239], v[236:237], 0, v[250:251]
	global_load_dwordx4 v[76:79], v[236:237], off
	global_load_dwordx4 v[72:75], v[238:239], off
	global_load_dwordx4 v[68:71], v[236:237], off offset:512
	s_nop 0
	global_load_dwordx4 v[64:67], v[238:239], off offset:512
	v_lshlrev_b64 v[100:101], 10, v[82:83]
	v_lshl_add_u64 v[100:101], v[100:101], 0, v[162:163]
	v_lshl_add_u64 v[102:103], v[100:101], 2, s[78:79]
	v_lshlrev_b64 v[100:101], 1, v[100:101]
	v_lshl_add_u64 v[104:105], s[2:3], 0, v[100:101]
	s_waitcnt vmcnt(0)
	v_or_b32_e32 v106, 32, v100
	v_mov_b32_e32 v107, v101
	v_or_b32_e32 v108, 0x100, v100
	v_mov_b32_e32 v109, v101
	v_or_b32_e32 v100, 0x120, v100
	v_lshl_add_u64 v[106:107], s[2:3], 0, v[106:107]
	v_lshl_add_u64 v[108:109], s[2:3], 0, v[108:109]
	s_waitcnt vmcnt(0)
	v_mov_b32_dpp v224, v84 row_ror:8 row_mask:0xf bank_mask:0xf
	v_mov_b32_dpp v225, v85 row_ror:8 row_mask:0xf bank_mask:0xf
	v_mov_b32_dpp v226, v86 row_ror:8 row_mask:0xf bank_mask:0xf
	v_mov_b32_dpp v227, v87 row_ror:8 row_mask:0xf bank_mask:0xf
	v_mov_b32_dpp v84, v88 row_ror:8 row_mask:0xf bank_mask:0xc
	v_mov_b32_dpp v85, v89 row_ror:8 row_mask:0xf bank_mask:0xc
	v_mov_b32_dpp v86, v90 row_ror:8 row_mask:0xf bank_mask:0xc
	v_mov_b32_dpp v87, v91 row_ror:8 row_mask:0xf bank_mask:0xc
	v_mov_b32_dpp v88, v224 quad_perm:[0,1,2,3] row_mask:0xf bank_mask:0x3
	v_mov_b32_dpp v89, v225 quad_perm:[0,1,2,3] row_mask:0xf bank_mask:0x3
	v_mov_b32_dpp v90, v226 quad_perm:[0,1,2,3] row_mask:0xf bank_mask:0x3
	v_mov_b32_dpp v91, v227 quad_perm:[0,1,2,3] row_mask:0xf bank_mask:0x3
	v_mov_b32_dpp v224, v92 row_ror:8 row_mask:0xf bank_mask:0xf
	v_mov_b32_dpp v225, v93 row_ror:8 row_mask:0xf bank_mask:0xf
	v_mov_b32_dpp v226, v94 row_ror:8 row_mask:0xf bank_mask:0xf
	v_mov_b32_dpp v227, v95 row_ror:8 row_mask:0xf bank_mask:0xf
	v_mov_b32_dpp v92, v96 row_ror:8 row_mask:0xf bank_mask:0xc
	v_mov_b32_dpp v93, v97 row_ror:8 row_mask:0xf bank_mask:0xc
	v_mov_b32_dpp v94, v98 row_ror:8 row_mask:0xf bank_mask:0xc
	v_mov_b32_dpp v95, v99 row_ror:8 row_mask:0xf bank_mask:0xc
	v_mov_b32_dpp v96, v224 quad_perm:[0,1,2,3] row_mask:0xf bank_mask:0x3
	v_mov_b32_dpp v97, v225 quad_perm:[0,1,2,3] row_mask:0xf bank_mask:0x3
	v_mov_b32_dpp v98, v226 quad_perm:[0,1,2,3] row_mask:0xf bank_mask:0x3
	v_mov_b32_dpp v99, v227 quad_perm:[0,1,2,3] row_mask:0xf bank_mask:0x3
	v_pk_fma_f32 v[60:61], v[60:61], 0.5, v[84:85] op_sel_hi:[1,0,1]
	v_pk_fma_f32 v[56:57], v[56:57], 0.5, v[88:89] op_sel_hi:[1,0,1]
	v_pk_fma_f32 v[52:53], v[52:53], 0.5, v[92:93] op_sel_hi:[1,0,1]
	v_mul_f32_e32 v88, v60, v60
	v_mul_f32_e32 v89, v56, v56
	v_pk_fma_f32 v[62:63], v[62:63], 0.5, v[86:87] op_sel_hi:[1,0,1]
	v_pk_fma_f32 v[58:59], v[58:59], 0.5, v[90:91] op_sel_hi:[1,0,1]
	v_pk_fma_f32 v[84:85], v[48:49], 0.5, v[96:97] op_sel_hi:[1,0,1]
	v_mul_f32_e32 v90, v52, v52
	v_fmac_f32_e32 v88, v61, v61
	v_fmac_f32_e32 v89, v57, v57
	v_pk_fma_f32 v[54:55], v[54:55], 0.5, v[94:95] op_sel_hi:[1,0,1]
	v_mul_f32_e32 v91, v84, v84
	v_fmac_f32_e32 v90, v53, v53
	v_fmac_f32_e32 v88, v62, v62
	v_fmac_f32_e32 v89, v58, v58
	v_pk_fma_f32 v[86:87], v[50:51], 0.5, v[98:99] op_sel_hi:[1,0,1]
	v_cvt_pk_bf16_f32 v48, v60, v61
	v_fmac_f32_e32 v91, v85, v85
	v_fmac_f32_e32 v90, v54, v54
	v_fmac_f32_e32 v88, v63, v63
	v_fmac_f32_e32 v89, v59, v59
	global_store_dwordx4 v[102:103], v[60:63], off
	v_cvt_pk_bf16_f32 v49, v62, v63
	s_nop 1
	v_mov_b32_e32 v240, v48
	v_mov_b32_e32 v241, v49
	v_lshl_add_u64 v[244:245], v[104:105], 0, v[246:247]
	v_fmac_f32_e32 v91, v86, v86
	v_fmac_f32_e32 v90, v55, v55
	v_add_f32_e32 v48, v88, v89
	v_add_f32_e32 v48, v48, v90
	v_fmac_f32_e32 v91, v87, v87
	v_add_f32_e32 v48, v48, v91
	ds_bpermute_b32 v49, v189, v48
	v_cvt_pk_bf16_f32 v50, v56, v57
	v_cvt_pk_bf16_f32 v51, v58, v59
	v_cvt_pk_bf16_f32 v60, v52, v53
	global_store_dwordx4 v[102:103], v[56:59], off offset:64
	v_mov_b32_e32 v242, v50
	v_mov_b32_e32 v243, v51
	s_nop 1
	v_permlane16_swap_b32 v240, v242
	v_permlane16_swap_b32 v241, v243
	global_store_dwordx4 v[244:245], v[240:243], off
	s_waitcnt lgkmcnt(0)
	v_add_f32_e32 v48, v48, v49
	ds_bpermute_b32 v49, v116, v48
	v_cvt_pk_bf16_f32 v61, v54, v55
	v_lshl_add_u64 v[50:51], s[2:3], 0, v[100:101]
	global_store_dwordx4 v[102:103], v[52:55], off offset:512
	s_nop 1
	v_mov_b32_e32 v240, v60
	v_mov_b32_e32 v241, v61
	v_lshl_add_u64 v[244:245], v[108:109], 0, v[246:247]
	global_store_dwordx4 v[102:103], v[84:87], off offset:576
	v_cvt_pk_bf16_f32 v52, v84, v85
	v_cvt_pk_bf16_f32 v53, v86, v87
	v_mov_b32_e32 v242, v52
	v_mov_b32_e32 v243, v53
	s_nop 1
	v_permlane16_swap_b32 v240, v242
	v_permlane16_swap_b32 v241, v243
	global_store_dwordx4 v[244:245], v[240:243], off
	s_and_saveexec_b64 s[26:27], s[6:7]
	s_cbranch_execz .LBB0_1653
	v_lshlrev_b64 v[50:51], 6, v[82:83]
	v_lshl_add_u64 v[50:51], s[4:5], 0, v[50:51]
	v_lshl_add_u64 v[50:51], s[24:25], 2, v[50:51]
	s_lshl_b32 s16, s49, 2
	v_lshl_add_u64 v[50:51], v[50:51], 0, s[16:17]
	s_waitcnt lgkmcnt(0)
	v_add_f32_e32 v48, v48, v49
	flat_store_dword v[50:51], v48
.LBB0_1653:
	s_or_b64 exec, exec, s[26:27]
	s_waitcnt lgkmcnt(0)
	v_lshlrev_b64 v[48:49], 10, v[80:81]
	v_lshl_add_u64 v[48:49], v[48:49], 0, v[162:163]
	v_lshl_add_u64 v[50:51], v[48:49], 2, s[78:79]
	v_lshlrev_b64 v[48:49], 1, v[48:49]
	v_mov_b32_dpp v224, v76 row_ror:8 row_mask:0xf bank_mask:0xf
	v_mov_b32_dpp v225, v77 row_ror:8 row_mask:0xf bank_mask:0xf
	v_mov_b32_dpp v226, v78 row_ror:8 row_mask:0xf bank_mask:0xf
	v_mov_b32_dpp v227, v79 row_ror:8 row_mask:0xf bank_mask:0xf
	v_mov_b32_dpp v76, v72 row_ror:8 row_mask:0xf bank_mask:0xc
	v_mov_b32_dpp v77, v73 row_ror:8 row_mask:0xf bank_mask:0xc
	v_mov_b32_dpp v78, v74 row_ror:8 row_mask:0xf bank_mask:0xc
	v_mov_b32_dpp v79, v75 row_ror:8 row_mask:0xf bank_mask:0xc
	v_mov_b32_dpp v72, v224 quad_perm:[0,1,2,3] row_mask:0xf bank_mask:0x3
	v_mov_b32_dpp v73, v225 quad_perm:[0,1,2,3] row_mask:0xf bank_mask:0x3
	v_mov_b32_dpp v74, v226 quad_perm:[0,1,2,3] row_mask:0xf bank_mask:0x3
	v_mov_b32_dpp v75, v227 quad_perm:[0,1,2,3] row_mask:0xf bank_mask:0x3
	v_mov_b32_dpp v224, v68 row_ror:8 row_mask:0xf bank_mask:0xf
	v_mov_b32_dpp v225, v69 row_ror:8 row_mask:0xf bank_mask:0xf
	v_mov_b32_dpp v226, v70 row_ror:8 row_mask:0xf bank_mask:0xf
	v_mov_b32_dpp v227, v71 row_ror:8 row_mask:0xf bank_mask:0xf
	v_mov_b32_dpp v68, v64 row_ror:8 row_mask:0xf bank_mask:0xc
	v_mov_b32_dpp v69, v65 row_ror:8 row_mask:0xf bank_mask:0xc
	v_mov_b32_dpp v70, v66 row_ror:8 row_mask:0xf bank_mask:0xc
	v_mov_b32_dpp v71, v67 row_ror:8 row_mask:0xf bank_mask:0xc
	v_mov_b32_dpp v64, v224 quad_perm:[0,1,2,3] row_mask:0xf bank_mask:0x3
	v_mov_b32_dpp v65, v225 quad_perm:[0,1,2,3] row_mask:0xf bank_mask:0x3
	v_mov_b32_dpp v66, v226 quad_perm:[0,1,2,3] row_mask:0xf bank_mask:0x3
	v_mov_b32_dpp v67, v227 quad_perm:[0,1,2,3] row_mask:0xf bank_mask:0x3
	v_pk_fma_f32 v[46:47], v[46:47], 0.5, v[78:79] op_sel_hi:[1,0,1]
	v_pk_fma_f32 v[44:45], v[44:45], 0.5, v[76:77] op_sel_hi:[1,0,1]
	v_lshl_add_u64 v[52:53], s[2:3], 0, v[48:49]
	global_store_dwordx4 v[50:51], v[44:47], off
	v_cvt_pk_bf16_f32 v54, v44, v45
	v_cvt_pk_bf16_f32 v55, v46, v47
	s_nop 1
	v_mov_b32_e32 v240, v54
	v_mov_b32_e32 v241, v55
	v_lshl_add_u64 v[244:245], v[52:53], 0, v[246:247]
	v_mul_f32_e32 v52, v44, v44
	v_fmac_f32_e32 v52, v45, v45
	v_pk_fma_f32 v[42:43], v[42:43], 0.5, v[74:75] op_sel_hi:[1,0,1]
	v_pk_fma_f32 v[40:41], v[40:41], 0.5, v[72:73] op_sel_hi:[1,0,1]
	v_fmac_f32_e32 v52, v46, v46
	global_store_dwordx4 v[50:51], v[40:43], off offset:64
	v_or_b32_e32 v44, 32, v48
	v_mov_b32_e32 v45, v49
	v_cvt_pk_bf16_f32 v46, v40, v41
	v_mul_f32_e32 v40, v40, v40
	v_lshl_add_u64 v[44:45], s[2:3], 0, v[44:45]
	v_fmac_f32_e32 v40, v41, v41
	v_pk_fma_f32 v[38:39], v[38:39], 0.5, v[70:71] op_sel_hi:[1,0,1]
	v_pk_fma_f32 v[36:37], v[36:37], 0.5, v[68:69] op_sel_hi:[1,0,1]
	v_fmac_f32_e32 v52, v47, v47
	v_cvt_pk_bf16_f32 v47, v42, v43
	v_mov_b32_e32 v242, v46
	v_mov_b32_e32 v243, v47
	s_nop 1
	v_permlane16_swap_b32 v240, v242
	v_permlane16_swap_b32 v241, v243
	global_store_dwordx4 v[244:245], v[240:243], off
	v_fmac_f32_e32 v40, v42, v42
	global_store_dwordx4 v[50:51], v[36:39], off offset:512
	v_cvt_pk_bf16_f32 v42, v36, v37
	v_fmac_f32_e32 v40, v43, v43
	v_add_f32_e32 v43, v52, v40
	v_mul_f32_e32 v36, v36, v36
	v_fmac_f32_e32 v36, v37, v37
	v_fmac_f32_e32 v36, v38, v38
	v_fmac_f32_e32 v36, v39, v39
	v_add_f32_e32 v43, v43, v36
	v_pk_fma_f32 v[36:37], v[34:35], 0.5, v[66:67] op_sel_hi:[1,0,1]
	v_pk_fma_f32 v[34:35], v[32:33], 0.5, v[64:65] op_sel_hi:[1,0,1]
	v_or_b32_e32 v40, 0x100, v48
	v_mul_f32_e32 v32, v34, v34
	v_fmac_f32_e32 v32, v35, v35
	v_fmac_f32_e32 v32, v36, v36
	v_fmac_f32_e32 v32, v37, v37
	v_add_f32_e32 v32, v43, v32
	ds_bpermute_b32 v33, v189, v32
	v_mov_b32_e32 v41, v49
	v_or_b32_e32 v48, 0x120, v48
	v_lshl_add_u64 v[40:41], s[2:3], 0, v[40:41]
	v_cvt_pk_bf16_f32 v43, v38, v39
	s_waitcnt lgkmcnt(0)
	v_add_f32_e32 v32, v32, v33
	ds_bpermute_b32 v33, v116, v32
	v_lshl_add_u64 v[38:39], s[2:3], 0, v[48:49]
	s_nop 1
	v_mov_b32_e32 v240, v42
	v_mov_b32_e32 v241, v43
	v_lshl_add_u64 v[244:245], v[40:41], 0, v[246:247]
	global_store_dwordx4 v[50:51], v[34:37], off offset:576
	s_nop 1
	v_cvt_pk_bf16_f32 v34, v34, v35
	v_cvt_pk_bf16_f32 v35, v36, v37
	v_mov_b32_e32 v242, v34
	v_mov_b32_e32 v243, v35
	s_nop 1
	v_permlane16_swap_b32 v240, v242
	v_permlane16_swap_b32 v241, v243
	global_store_dwordx4 v[244:245], v[240:243], off
	s_and_saveexec_b64 s[26:27], s[6:7]
	s_cbranch_execz .LBB0_1655
	v_lshlrev_b64 v[34:35], 6, v[80:81]
	v_lshl_add_u64 v[34:35], s[4:5], 0, v[34:35]
	v_lshl_add_u64 v[34:35], s[24:25], 2, v[34:35]
	s_lshl_b32 s16, s49, 2
	v_lshl_add_u64 v[34:35], v[34:35], 0, s[16:17]
	s_waitcnt lgkmcnt(0)
	v_add_f32_e32 v32, v32, v33
	flat_store_dword v[34:35], v32
.LBB0_1655:
	s_or_b64 exec, exec, s[26:27]
	v_lshl_add_u64 v[50:51], v[164:165], 0, s[20:21]
	s_waitcnt lgkmcnt(0)
	v_lshlrev_b64 v[32:33], 12, v[50:51]
	v_lshl_add_u64 v[32:33], v[166:167], 0, v[32:33]
	v_lshl_add_u64 v[232:233], v[32:33], 0, v[248:249]
	v_lshl_add_u64 v[234:235], v[232:233], 0, v[250:251]
	global_load_dwordx4 v[52:55], v[232:233], off
	global_load_dwordx4 v[56:59], v[234:235], off
	global_load_dwordx4 v[60:63], v[232:233], off offset:512
	global_load_dwordx4 v[64:67], v[234:235], off offset:512
	v_lshl_add_u64 v[48:49], v[164:165], 0, s[22:23]
	v_lshlrev_b64 v[32:33], 12, v[48:49]
	v_lshl_add_u64 v[32:33], v[166:167], 0, v[32:33]
	v_lshl_add_u64 v[236:237], v[32:33], 0, v[248:249]
	v_lshl_add_u64 v[238:239], v[236:237], 0, v[250:251]
	global_load_dwordx4 v[44:47], v[236:237], off
	global_load_dwordx4 v[40:43], v[238:239], off
	global_load_dwordx4 v[36:39], v[236:237], off offset:512
	s_nop 0
	global_load_dwordx4 v[32:35], v[238:239], off offset:512
	v_lshlrev_b64 v[68:69], 10, v[50:51]
	v_lshl_add_u64 v[68:69], v[68:69], 0, v[162:163]
	v_lshl_add_u64 v[70:71], v[68:69], 2, s[78:79]
	v_lshlrev_b64 v[68:69], 1, v[68:69]
	v_lshl_add_u64 v[72:73], s[2:3], 0, v[68:69]
	s_waitcnt vmcnt(0)
	v_or_b32_e32 v74, 32, v68
	v_mov_b32_e32 v75, v69
	v_or_b32_e32 v76, 0x100, v68
	v_mov_b32_e32 v77, v69
	v_or_b32_e32 v68, 0x120, v68
	v_lshl_add_u64 v[74:75], s[2:3], 0, v[74:75]
	v_lshl_add_u64 v[76:77], s[2:3], 0, v[76:77]
	s_waitcnt vmcnt(0)
	v_mov_b32_dpp v224, v52 row_ror:8 row_mask:0xf bank_mask:0xf
	v_mov_b32_dpp v225, v53 row_ror:8 row_mask:0xf bank_mask:0xf
	v_mov_b32_dpp v226, v54 row_ror:8 row_mask:0xf bank_mask:0xf
	v_mov_b32_dpp v227, v55 row_ror:8 row_mask:0xf bank_mask:0xf
	v_mov_b32_dpp v52, v56 row_ror:8 row_mask:0xf bank_mask:0xc
	v_mov_b32_dpp v53, v57 row_ror:8 row_mask:0xf bank_mask:0xc
	v_mov_b32_dpp v54, v58 row_ror:8 row_mask:0xf bank_mask:0xc
	v_mov_b32_dpp v55, v59 row_ror:8 row_mask:0xf bank_mask:0xc
	v_mov_b32_dpp v56, v224 quad_perm:[0,1,2,3] row_mask:0xf bank_mask:0x3
	v_mov_b32_dpp v57, v225 quad_perm:[0,1,2,3] row_mask:0xf bank_mask:0x3
	v_mov_b32_dpp v58, v226 quad_perm:[0,1,2,3] row_mask:0xf bank_mask:0x3
	v_mov_b32_dpp v59, v227 quad_perm:[0,1,2,3] row_mask:0xf bank_mask:0x3
	v_mov_b32_dpp v224, v60 row_ror:8 row_mask:0xf bank_mask:0xf
	v_mov_b32_dpp v225, v61 row_ror:8 row_mask:0xf bank_mask:0xf
	v_mov_b32_dpp v226, v62 row_ror:8 row_mask:0xf bank_mask:0xf
	v_mov_b32_dpp v227, v63 row_ror:8 row_mask:0xf bank_mask:0xf
	v_mov_b32_dpp v60, v64 row_ror:8 row_mask:0xf bank_mask:0xc
	v_mov_b32_dpp v61, v65 row_ror:8 row_mask:0xf bank_mask:0xc
	v_mov_b32_dpp v62, v66 row_ror:8 row_mask:0xf bank_mask:0xc
	v_mov_b32_dpp v63, v67 row_ror:8 row_mask:0xf bank_mask:0xc
	v_mov_b32_dpp v64, v224 quad_perm:[0,1,2,3] row_mask:0xf bank_mask:0x3
	v_mov_b32_dpp v65, v225 quad_perm:[0,1,2,3] row_mask:0xf bank_mask:0x3
	v_mov_b32_dpp v66, v226 quad_perm:[0,1,2,3] row_mask:0xf bank_mask:0x3
	v_mov_b32_dpp v67, v227 quad_perm:[0,1,2,3] row_mask:0xf bank_mask:0x3
	v_pk_fma_f32 v[28:29], v[28:29], 0.5, v[52:53] op_sel_hi:[1,0,1]
	v_pk_fma_f32 v[24:25], v[24:25], 0.5, v[56:57] op_sel_hi:[1,0,1]
	v_pk_fma_f32 v[20:21], v[20:21], 0.5, v[60:61] op_sel_hi:[1,0,1]
	v_mul_f32_e32 v56, v28, v28
	v_mul_f32_e32 v57, v24, v24
	v_pk_fma_f32 v[30:31], v[30:31], 0.5, v[54:55] op_sel_hi:[1,0,1]
	v_pk_fma_f32 v[26:27], v[26:27], 0.5, v[58:59] op_sel_hi:[1,0,1]
	v_pk_fma_f32 v[52:53], v[16:17], 0.5, v[64:65] op_sel_hi:[1,0,1]
	v_mul_f32_e32 v58, v20, v20
	v_fmac_f32_e32 v56, v29, v29
	v_fmac_f32_e32 v57, v25, v25
	v_pk_fma_f32 v[22:23], v[22:23], 0.5, v[62:63] op_sel_hi:[1,0,1]
	v_mul_f32_e32 v59, v52, v52
	v_fmac_f32_e32 v58, v21, v21
	v_fmac_f32_e32 v56, v30, v30
	v_fmac_f32_e32 v57, v26, v26
	v_pk_fma_f32 v[54:55], v[18:19], 0.5, v[66:67] op_sel_hi:[1,0,1]
	v_cvt_pk_bf16_f32 v16, v28, v29
	v_fmac_f32_e32 v59, v53, v53
	v_fmac_f32_e32 v58, v22, v22
	v_fmac_f32_e32 v56, v31, v31
	v_fmac_f32_e32 v57, v27, v27
	global_store_dwordx4 v[70:71], v[28:31], off
	v_cvt_pk_bf16_f32 v17, v30, v31
	s_nop 1
	v_mov_b32_e32 v240, v16
	v_mov_b32_e32 v241, v17
	v_lshl_add_u64 v[244:245], v[72:73], 0, v[246:247]
	v_fmac_f32_e32 v59, v54, v54
	v_fmac_f32_e32 v58, v23, v23
	v_add_f32_e32 v16, v56, v57
	v_add_f32_e32 v16, v16, v58
	v_fmac_f32_e32 v59, v55, v55
	v_add_f32_e32 v16, v16, v59
	ds_bpermute_b32 v17, v189, v16
	v_cvt_pk_bf16_f32 v18, v24, v25
	v_cvt_pk_bf16_f32 v19, v26, v27
	v_cvt_pk_bf16_f32 v28, v20, v21
	global_store_dwordx4 v[70:71], v[24:27], off offset:64
	v_mov_b32_e32 v242, v18
	v_mov_b32_e32 v243, v19
	s_nop 1
	v_permlane16_swap_b32 v240, v242
	v_permlane16_swap_b32 v241, v243
	global_store_dwordx4 v[244:245], v[240:243], off
	s_waitcnt lgkmcnt(0)
	v_add_f32_e32 v16, v16, v17
	ds_bpermute_b32 v17, v116, v16
	v_cvt_pk_bf16_f32 v29, v22, v23
	v_lshl_add_u64 v[18:19], s[2:3], 0, v[68:69]
	global_store_dwordx4 v[70:71], v[20:23], off offset:512
	s_nop 1
	v_mov_b32_e32 v240, v28
	v_mov_b32_e32 v241, v29
	v_lshl_add_u64 v[244:245], v[76:77], 0, v[246:247]
	global_store_dwordx4 v[70:71], v[52:55], off offset:576
	v_cvt_pk_bf16_f32 v20, v52, v53
	v_cvt_pk_bf16_f32 v21, v54, v55
	v_mov_b32_e32 v242, v20
	v_mov_b32_e32 v243, v21
	s_nop 1
	v_permlane16_swap_b32 v240, v242
	v_permlane16_swap_b32 v241, v243
	global_store_dwordx4 v[244:245], v[240:243], off
	s_and_saveexec_b64 s[26:27], s[6:7]
	s_cbranch_execz .LBB0_1657
	v_lshlrev_b64 v[18:19], 6, v[50:51]
	v_lshl_add_u64 v[18:19], s[4:5], 0, v[18:19]
	v_lshl_add_u64 v[18:19], s[24:25], 2, v[18:19]
	s_lshl_b32 s16, s49, 2
	v_lshl_add_u64 v[18:19], v[18:19], 0, s[16:17]
	s_waitcnt lgkmcnt(0)
	v_add_f32_e32 v16, v16, v17
	flat_store_dword v[18:19], v16
.LBB0_1657:
	s_or_b64 exec, exec, s[26:27]
	s_waitcnt lgkmcnt(0)
	v_lshlrev_b64 v[16:17], 10, v[48:49]
	v_lshl_add_u64 v[16:17], v[16:17], 0, v[162:163]
	v_lshl_add_u64 v[18:19], v[16:17], 2, s[78:79]
	v_lshlrev_b64 v[16:17], 1, v[16:17]
	v_mov_b32_dpp v224, v44 row_ror:8 row_mask:0xf bank_mask:0xf
	v_mov_b32_dpp v225, v45 row_ror:8 row_mask:0xf bank_mask:0xf
	v_mov_b32_dpp v226, v46 row_ror:8 row_mask:0xf bank_mask:0xf
	v_mov_b32_dpp v227, v47 row_ror:8 row_mask:0xf bank_mask:0xf
	v_mov_b32_dpp v44, v40 row_ror:8 row_mask:0xf bank_mask:0xc
	v_mov_b32_dpp v45, v41 row_ror:8 row_mask:0xf bank_mask:0xc
	v_mov_b32_dpp v46, v42 row_ror:8 row_mask:0xf bank_mask:0xc
	v_mov_b32_dpp v47, v43 row_ror:8 row_mask:0xf bank_mask:0xc
	v_mov_b32_dpp v40, v224 quad_perm:[0,1,2,3] row_mask:0xf bank_mask:0x3
	v_mov_b32_dpp v41, v225 quad_perm:[0,1,2,3] row_mask:0xf bank_mask:0x3
	v_mov_b32_dpp v42, v226 quad_perm:[0,1,2,3] row_mask:0xf bank_mask:0x3
	v_mov_b32_dpp v43, v227 quad_perm:[0,1,2,3] row_mask:0xf bank_mask:0x3
	v_mov_b32_dpp v224, v36 row_ror:8 row_mask:0xf bank_mask:0xf
	v_mov_b32_dpp v225, v37 row_ror:8 row_mask:0xf bank_mask:0xf
	v_mov_b32_dpp v226, v38 row_ror:8 row_mask:0xf bank_mask:0xf
	v_mov_b32_dpp v227, v39 row_ror:8 row_mask:0xf bank_mask:0xf
	v_mov_b32_dpp v36, v32 row_ror:8 row_mask:0xf bank_mask:0xc
	v_mov_b32_dpp v37, v33 row_ror:8 row_mask:0xf bank_mask:0xc
	v_mov_b32_dpp v38, v34 row_ror:8 row_mask:0xf bank_mask:0xc
	v_mov_b32_dpp v39, v35 row_ror:8 row_mask:0xf bank_mask:0xc
	v_mov_b32_dpp v32, v224 quad_perm:[0,1,2,3] row_mask:0xf bank_mask:0x3
	v_mov_b32_dpp v33, v225 quad_perm:[0,1,2,3] row_mask:0xf bank_mask:0x3
	v_mov_b32_dpp v34, v226 quad_perm:[0,1,2,3] row_mask:0xf bank_mask:0x3
	v_mov_b32_dpp v35, v227 quad_perm:[0,1,2,3] row_mask:0xf bank_mask:0x3
	v_pk_fma_f32 v[14:15], v[14:15], 0.5, v[46:47] op_sel_hi:[1,0,1]
	v_pk_fma_f32 v[12:13], v[12:13], 0.5, v[44:45] op_sel_hi:[1,0,1]
	v_lshl_add_u64 v[20:21], s[2:3], 0, v[16:17]
	global_store_dwordx4 v[18:19], v[12:15], off
	v_cvt_pk_bf16_f32 v22, v12, v13
	v_cvt_pk_bf16_f32 v23, v14, v15
	s_nop 1
	v_mov_b32_e32 v240, v22
	v_mov_b32_e32 v241, v23
	v_lshl_add_u64 v[244:245], v[20:21], 0, v[246:247]
	v_mul_f32_e32 v20, v12, v12
	v_fmac_f32_e32 v20, v13, v13
	v_pk_fma_f32 v[10:11], v[10:11], 0.5, v[42:43] op_sel_hi:[1,0,1]
	v_pk_fma_f32 v[8:9], v[8:9], 0.5, v[40:41] op_sel_hi:[1,0,1]
	v_fmac_f32_e32 v20, v14, v14
	global_store_dwordx4 v[18:19], v[8:11], off offset:64
	v_or_b32_e32 v12, 32, v16
	v_mov_b32_e32 v13, v17
	v_cvt_pk_bf16_f32 v14, v8, v9
	v_mul_f32_e32 v8, v8, v8
	v_lshl_add_u64 v[12:13], s[2:3], 0, v[12:13]
	v_fmac_f32_e32 v8, v9, v9
	v_pk_fma_f32 v[6:7], v[6:7], 0.5, v[38:39] op_sel_hi:[1,0,1]
	v_pk_fma_f32 v[4:5], v[4:5], 0.5, v[36:37] op_sel_hi:[1,0,1]
	v_fmac_f32_e32 v20, v15, v15
	v_cvt_pk_bf16_f32 v15, v10, v11
	v_mov_b32_e32 v242, v14
	v_mov_b32_e32 v243, v15
	s_nop 1
	v_permlane16_swap_b32 v240, v242
	v_permlane16_swap_b32 v241, v243
	global_store_dwordx4 v[244:245], v[240:243], off
	v_fmac_f32_e32 v8, v10, v10
	global_store_dwordx4 v[18:19], v[4:7], off offset:512
	v_cvt_pk_bf16_f32 v10, v4, v5
	v_fmac_f32_e32 v8, v11, v11
	v_add_f32_e32 v11, v20, v8
	v_mul_f32_e32 v4, v4, v4
	v_fmac_f32_e32 v4, v5, v5
	v_fmac_f32_e32 v4, v6, v6
	v_fmac_f32_e32 v4, v7, v7
	v_add_f32_e32 v11, v11, v4
	v_pk_fma_f32 v[4:5], v[2:3], 0.5, v[34:35] op_sel_hi:[1,0,1]
	v_pk_fma_f32 v[2:3], v[0:1], 0.5, v[32:33] op_sel_hi:[1,0,1]
	v_or_b32_e32 v8, 0x100, v16
	v_mul_f32_e32 v0, v2, v2
	v_fmac_f32_e32 v0, v3, v3
	v_fmac_f32_e32 v0, v4, v4
	v_fmac_f32_e32 v0, v5, v5
	v_add_f32_e32 v0, v11, v0
	ds_bpermute_b32 v1, v189, v0
	v_mov_b32_e32 v9, v17
	v_or_b32_e32 v16, 0x120, v16
	v_lshl_add_u64 v[8:9], s[2:3], 0, v[8:9]
	v_cvt_pk_bf16_f32 v11, v6, v7
	s_waitcnt lgkmcnt(0)
	v_add_f32_e32 v0, v0, v1
	ds_bpermute_b32 v1, v116, v0
	v_lshl_add_u64 v[6:7], s[2:3], 0, v[16:17]
	s_nop 1
	v_mov_b32_e32 v240, v10
	v_mov_b32_e32 v241, v11
	v_lshl_add_u64 v[244:245], v[8:9], 0, v[246:247]
	global_store_dwordx4 v[18:19], v[2:5], off offset:576
	s_nop 1
	v_cvt_pk_bf16_f32 v2, v2, v3
	v_cvt_pk_bf16_f32 v3, v4, v5
	v_mov_b32_e32 v242, v2
	v_mov_b32_e32 v243, v3
	s_nop 1
	v_permlane16_swap_b32 v240, v242
	v_permlane16_swap_b32 v241, v243
	global_store_dwordx4 v[244:245], v[240:243], off
	s_and_saveexec_b64 s[26:27], s[6:7]
	s_cbranch_execz .LBB0_1630
	v_lshlrev_b64 v[2:3], 6, v[48:49]
	v_lshl_add_u64 v[2:3], s[4:5], 0, v[2:3]
	v_lshl_add_u64 v[2:3], s[24:25], 2, v[2:3]
	s_lshl_b32 s16, s49, 2
	v_lshl_add_u64 v[2:3], v[2:3], 0, s[16:17]
	s_waitcnt lgkmcnt(0)
	v_add_f32_e32 v0, v0, v1
	flat_store_dword v[2:3], v0
	s_branch .LBB0_1630

.LBB0_1812:
	ds_read_b128 v[128:131], v173
	ds_read_b128 v[132:135], v174
	ds_read_b128 v[136:139], v175
	ds_read_b128 v[140:143], v177
	s_add_u32 s30, s28, 0xfff50080
	s_addc_u32 s31, s29, -1
	s_cmp_eq_u32 s67, 40
	s_cselect_b32 s35, s11, s31
	s_cselect_b32 s34, s10, s30
	s_cselect_b32 s31, s13, s66
	s_cselect_b32 s30, s12, s27
	s_mov_b32 m0, s61
	v_lshl_add_u64 v[216:217], s[28:29], 0, v[156:157]
	ds_read_b128 v[162:165], v172
	ds_read_b128 v[166:169], v172 offset:1024
	ds_read_b128 v[192:195], v172 offset:2048
	ds_read_b128 v[196:199], v172 offset:3072
	ds_read_b128 v[200:203], v172 offset:4096
	ds_read_b128 v[204:207], v172 offset:5120
	ds_read_b128 v[208:211], v172 offset:6144
	ds_read_b128 v[212:215], v172 offset:7168
	global_load_lds_dwordx4 v[216:217], off
	v_lshl_add_u64 v[216:217], s[28:29], 0, v[154:155]
	s_mov_b32 m0, s62
	s_nop 0
	global_load_lds_dwordx4 v[216:217], off
	s_waitcnt lgkmcnt(8)
	s_barrier
	s_waitcnt lgkmcnt(0)
	s_setprio 1
	s_waitcnt lgkmcnt(0)
	v_mfma_f32_16x16x32_bf16 v[124:127], v[128:131], v[162:165], v[124:127]
	v_mfma_f32_16x16x32_bf16 v[120:123], v[136:139], v[162:165], v[120:123]
	v_mfma_f32_16x16x32_bf16 v[108:111], v[128:131], v[192:195], v[108:111]
	v_mfma_f32_16x16x32_bf16 v[104:107], v[136:139], v[192:195], v[104:107]
	v_mfma_f32_16x16x32_bf16 v[92:95], v[128:131], v[200:203], v[92:95]
	v_mfma_f32_16x16x32_bf16 v[88:91], v[136:139], v[200:203], v[88:91]
	v_mfma_f32_16x16x32_bf16 v[76:79], v[128:131], v[208:211], v[76:79]
	v_mfma_f32_16x16x32_bf16 v[72:75], v[136:139], v[208:211], v[72:75]
	v_mfma_f32_16x16x32_bf16 v[124:127], v[132:135], v[166:169], v[124:127]
	v_mfma_f32_16x16x32_bf16 v[120:123], v[140:143], v[166:169], v[120:123]
	v_mfma_f32_16x16x32_bf16 v[108:111], v[132:135], v[196:199], v[108:111]
	v_mfma_f32_16x16x32_bf16 v[104:107], v[140:143], v[196:199], v[104:107]
	v_mfma_f32_16x16x32_bf16 v[92:95], v[132:135], v[204:207], v[92:95]
	v_mfma_f32_16x16x32_bf16 v[88:91], v[140:143], v[204:207], v[88:91]
	v_mfma_f32_16x16x32_bf16 v[76:79], v[132:135], v[212:215], v[76:79]
	v_mfma_f32_16x16x32_bf16 v[72:75], v[140:143], v[212:215], v[72:75]
	s_setprio 0
	s_barrier
	s_mov_b32 m0, s44
	v_lshl_add_u64 v[232:233], s[30:31], 0, v[144:145]
	ds_read_b128 v[216:219], v178
	ds_read_b128 v[220:223], v180
	ds_read_b128 v[224:227], v181
	ds_read_b128 v[228:231], v182
	global_load_lds_dwordx4 v[232:233], off
	v_lshl_add_u64 v[234:235], s[30:31], 0, v[146:147]
	s_mov_b32 m0, s45
	s_nop 0
	global_load_lds_dwordx4 v[234:235], off
	s_barrier
	s_waitcnt lgkmcnt(0)
	s_setprio 1
	s_waitcnt lgkmcnt(0)
	v_mfma_f32_16x16x32_bf16 v[116:119], v[216:219], v[162:165], v[116:119]
	v_mfma_f32_16x16x32_bf16 v[112:115], v[224:227], v[162:165], v[112:115]
	v_mfma_f32_16x16x32_bf16 v[100:103], v[216:219], v[192:195], v[100:103]
	v_mfma_f32_16x16x32_bf16 v[96:99], v[224:227], v[192:195], v[96:99]
	v_mfma_f32_16x16x32_bf16 v[84:87], v[216:219], v[200:203], v[84:87]
	v_mfma_f32_16x16x32_bf16 v[80:83], v[224:227], v[200:203], v[80:83]
	v_mfma_f32_16x16x32_bf16 v[68:71], v[216:219], v[208:211], v[68:71]
	v_mfma_f32_16x16x32_bf16 v[64:67], v[224:227], v[208:211], v[64:67]
	v_mfma_f32_16x16x32_bf16 v[116:119], v[220:223], v[166:169], v[116:119]
	v_mfma_f32_16x16x32_bf16 v[112:115], v[228:231], v[166:169], v[112:115]
	v_mfma_f32_16x16x32_bf16 v[100:103], v[220:223], v[196:199], v[100:103]
	v_mfma_f32_16x16x32_bf16 v[96:99], v[228:231], v[196:199], v[96:99]
	v_mfma_f32_16x16x32_bf16 v[84:87], v[220:223], v[204:207], v[84:87]
	v_mfma_f32_16x16x32_bf16 v[80:83], v[228:231], v[204:207], v[80:83]
	v_mfma_f32_16x16x32_bf16 v[68:71], v[220:223], v[212:215], v[68:71]
	v_mfma_f32_16x16x32_bf16 v[64:67], v[228:231], v[212:215], v[64:67]
	s_setprio 0
	s_mov_b32 m0, s43
	v_lshl_add_u64 v[236:237], s[34:35], 0, v[144:145]
	s_barrier
	ds_read_b128 v[162:165], v172 offset:16384
	ds_read_b128 v[166:169], v172 offset:17408
	ds_read_b128 v[192:195], v172 offset:18432
	ds_read_b128 v[196:199], v172 offset:19456
	ds_read_b128 v[200:203], v172 offset:20480
	ds_read_b128 v[204:207], v172 offset:21504
	ds_read_b128 v[208:211], v172 offset:22528
	ds_read_b128 v[212:215], v172 offset:23552
	global_load_lds_dwordx4 v[236:237], off
	v_lshl_add_u64 v[238:239], s[34:35], 0, v[146:147]
	s_mov_b32 m0, s46
	s_nop 0
	global_load_lds_dwordx4 v[238:239], off
	s_barrier
	s_waitcnt lgkmcnt(0)
	s_setprio 1
	s_waitcnt lgkmcnt(0)
	v_mfma_f32_16x16x32_bf16 v[60:63], v[128:131], v[162:165], v[60:63]
	v_mfma_f32_16x16x32_bf16 v[56:59], v[136:139], v[162:165], v[56:59]
	v_mfma_f32_16x16x32_bf16 v[44:47], v[128:131], v[192:195], v[44:47]
	v_mfma_f32_16x16x32_bf16 v[40:43], v[136:139], v[192:195], v[40:43]
	v_mfma_f32_16x16x32_bf16 v[28:31], v[128:131], v[200:203], v[28:31]
	v_mfma_f32_16x16x32_bf16 v[24:27], v[136:139], v[200:203], v[24:27]
	v_mfma_f32_16x16x32_bf16 v[12:15], v[128:131], v[208:211], v[12:15]
	v_mfma_f32_16x16x32_bf16 v[8:11], v[136:139], v[208:211], v[8:11]
	v_mfma_f32_16x16x32_bf16 v[60:63], v[132:135], v[166:169], v[60:63]
	v_mfma_f32_16x16x32_bf16 v[56:59], v[140:143], v[166:169], v[56:59]
	v_mfma_f32_16x16x32_bf16 v[44:47], v[132:135], v[196:199], v[44:47]
	v_mfma_f32_16x16x32_bf16 v[40:43], v[140:143], v[196:199], v[40:43]
	v_mfma_f32_16x16x32_bf16 v[28:31], v[132:135], v[204:207], v[28:31]
	v_mfma_f32_16x16x32_bf16 v[24:27], v[140:143], v[204:207], v[24:27]
	v_mfma_f32_16x16x32_bf16 v[12:15], v[132:135], v[212:215], v[12:15]
	v_mfma_f32_16x16x32_bf16 v[8:11], v[140:143], v[212:215], v[8:11]
	s_setprio 0
	s_barrier
	s_add_u32 s68, s30, 0xb0000
	s_addc_u32 s69, s31, 0
	s_mov_b32 m0, s47
	v_lshl_add_u64 v[128:129], s[68:69], 0, v[144:145]
	global_load_lds_dwordx4 v[128:129], off
	v_lshl_add_u64 v[128:129], s[68:69], 0, v[146:147]
	s_mov_b32 m0, s48
	s_nop 0
	global_load_lds_dwordx4 v[128:129], off
	s_waitcnt vmcnt(6)
	s_barrier
	s_setprio 1
	v_mfma_f32_16x16x32_bf16 v[52:55], v[216:219], v[162:165], v[52:55]
	v_mfma_f32_16x16x32_bf16 v[48:51], v[224:227], v[162:165], v[48:51]
	v_mfma_f32_16x16x32_bf16 v[36:39], v[216:219], v[192:195], v[36:39]
	v_mfma_f32_16x16x32_bf16 v[32:35], v[224:227], v[192:195], v[32:35]
	v_mfma_f32_16x16x32_bf16 v[20:23], v[216:219], v[200:203], v[20:23]
	v_mfma_f32_16x16x32_bf16 v[16:19], v[224:227], v[200:203], v[16:19]
	v_mfma_f32_16x16x32_bf16 v[4:7], v[216:219], v[208:211], v[4:7]
	v_mfma_f32_16x16x32_bf16 v[0:3], v[224:227], v[208:211], v[0:3]
	v_mfma_f32_16x16x32_bf16 v[52:55], v[220:223], v[166:169], v[52:55]
	v_mfma_f32_16x16x32_bf16 v[48:51], v[228:231], v[166:169], v[48:51]
	v_mfma_f32_16x16x32_bf16 v[36:39], v[220:223], v[196:199], v[36:39]
	v_mfma_f32_16x16x32_bf16 v[32:35], v[228:231], v[196:199], v[32:35]
	v_mfma_f32_16x16x32_bf16 v[20:23], v[220:223], v[204:207], v[20:23]
	v_mfma_f32_16x16x32_bf16 v[16:19], v[228:231], v[204:207], v[16:19]
	v_mfma_f32_16x16x32_bf16 v[4:7], v[220:223], v[212:215], v[4:7]
	v_mfma_f32_16x16x32_bf16 v[0:3], v[228:231], v[212:215], v[0:3]
	s_setprio 0
	s_barrier
	ds_read_b128 v[128:131], v183
	ds_read_b128 v[132:135], v184
	ds_read_b128 v[136:139], v185
	ds_read_b128 v[140:143], v186
	s_add_u32 s34, s34, 0xb0000
	s_addc_u32 s35, s35, 0
	s_mov_b32 m0, s49
	v_lshl_add_u64 v[216:217], s[34:35], 0, v[144:145]
	ds_read_b128 v[162:165], v172 offset:32768
	ds_read_b128 v[166:169], v172 offset:33792
	ds_read_b128 v[192:195], v172 offset:34816
	ds_read_b128 v[196:199], v172 offset:35840
	ds_read_b128 v[200:203], v172 offset:36864
	ds_read_b128 v[204:207], v172 offset:37888
	ds_read_b128 v[208:211], v172 offset:38912
	ds_read_b128 v[212:215], v172 offset:39936
	global_load_lds_dwordx4 v[216:217], off
	v_lshl_add_u64 v[216:217], s[34:35], 0, v[146:147]
	s_mov_b32 m0, s52
	s_nop 0
	global_load_lds_dwordx4 v[216:217], off
	s_waitcnt lgkmcnt(8)
	s_barrier
	s_waitcnt lgkmcnt(0)
	s_setprio 1
	s_waitcnt lgkmcnt(0)
	v_mfma_f32_16x16x32_bf16 v[124:127], v[128:131], v[162:165], v[124:127]
	v_mfma_f32_16x16x32_bf16 v[120:123], v[136:139], v[162:165], v[120:123]
	v_mfma_f32_16x16x32_bf16 v[108:111], v[128:131], v[192:195], v[108:111]
	v_mfma_f32_16x16x32_bf16 v[104:107], v[136:139], v[192:195], v[104:107]
	v_mfma_f32_16x16x32_bf16 v[92:95], v[128:131], v[200:203], v[92:95]
	v_mfma_f32_16x16x32_bf16 v[88:91], v[136:139], v[200:203], v[88:91]
	v_mfma_f32_16x16x32_bf16 v[76:79], v[128:131], v[208:211], v[76:79]
	v_mfma_f32_16x16x32_bf16 v[72:75], v[136:139], v[208:211], v[72:75]
	v_mfma_f32_16x16x32_bf16 v[124:127], v[132:135], v[166:169], v[124:127]
	v_mfma_f32_16x16x32_bf16 v[120:123], v[140:143], v[166:169], v[120:123]
	v_mfma_f32_16x16x32_bf16 v[108:111], v[132:135], v[196:199], v[108:111]
	v_mfma_f32_16x16x32_bf16 v[104:107], v[140:143], v[196:199], v[104:107]
	v_mfma_f32_16x16x32_bf16 v[92:95], v[132:135], v[204:207], v[92:95]
	v_mfma_f32_16x16x32_bf16 v[88:91], v[140:143], v[204:207], v[88:91]
	v_mfma_f32_16x16x32_bf16 v[76:79], v[132:135], v[212:215], v[76:79]
	v_mfma_f32_16x16x32_bf16 v[72:75], v[140:143], v[212:215], v[72:75]
	s_setprio 0
	s_barrier
	s_mov_b32 m0, s54
	v_lshl_add_u64 v[232:233], v[232:233], 0, s[16:17]
	ds_read_b128 v[216:219], v187
	ds_read_b128 v[220:223], v188
	ds_read_b128 v[224:227], v189
	ds_read_b128 v[228:231], v190
	global_load_lds_dwordx4 v[232:233], off
	v_lshl_add_u64 v[232:233], v[234:235], 0, s[16:17]
	s_mov_b32 m0, s55
	s_nop 0
	global_load_lds_dwordx4 v[232:233], off
	s_barrier
	s_waitcnt lgkmcnt(0)
	s_setprio 1
	s_waitcnt lgkmcnt(0)
	v_mfma_f32_16x16x32_bf16 v[116:119], v[216:219], v[162:165], v[116:119]
	v_mfma_f32_16x16x32_bf16 v[112:115], v[224:227], v[162:165], v[112:115]
	v_mfma_f32_16x16x32_bf16 v[100:103], v[216:219], v[192:195], v[100:103]
	v_mfma_f32_16x16x32_bf16 v[96:99], v[224:227], v[192:195], v[96:99]
	v_mfma_f32_16x16x32_bf16 v[84:87], v[216:219], v[200:203], v[84:87]
	v_mfma_f32_16x16x32_bf16 v[80:83], v[224:227], v[200:203], v[80:83]
	v_mfma_f32_16x16x32_bf16 v[68:71], v[216:219], v[208:211], v[68:71]
	v_mfma_f32_16x16x32_bf16 v[64:67], v[224:227], v[208:211], v[64:67]
	v_mfma_f32_16x16x32_bf16 v[116:119], v[220:223], v[166:169], v[116:119]
	v_mfma_f32_16x16x32_bf16 v[112:115], v[228:231], v[166:169], v[112:115]
	v_mfma_f32_16x16x32_bf16 v[100:103], v[220:223], v[196:199], v[100:103]
	v_mfma_f32_16x16x32_bf16 v[96:99], v[228:231], v[196:199], v[96:99]
	v_mfma_f32_16x16x32_bf16 v[84:87], v[220:223], v[204:207], v[84:87]
	v_mfma_f32_16x16x32_bf16 v[80:83], v[228:231], v[204:207], v[80:83]
	v_mfma_f32_16x16x32_bf16 v[68:71], v[220:223], v[212:215], v[68:71]
	v_mfma_f32_16x16x32_bf16 v[64:67], v[228:231], v[212:215], v[64:67]
	s_setprio 0
	s_mov_b32 m0, s56
	v_lshl_add_u64 v[232:233], v[236:237], 0, s[16:17]
	s_barrier
	ds_read_b128 v[162:165], v172 offset:49152
	ds_read_b128 v[166:169], v172 offset:50176
	ds_read_b128 v[192:195], v172 offset:51200
	ds_read_b128 v[196:199], v172 offset:52224
	ds_read_b128 v[200:203], v172 offset:53248
	ds_read_b128 v[204:207], v172 offset:54272
	ds_read_b128 v[208:211], v172 offset:55296
	ds_read_b128 v[212:215], v172 offset:56320
	global_load_lds_dwordx4 v[232:233], off
	v_lshl_add_u64 v[232:233], v[238:239], 0, s[16:17]
	s_mov_b32 m0, s57
	s_nop 0
	global_load_lds_dwordx4 v[232:233], off
	s_barrier
	s_waitcnt lgkmcnt(0)
	s_setprio 1
	s_waitcnt lgkmcnt(0)
	v_mfma_f32_16x16x32_bf16 v[60:63], v[128:131], v[162:165], v[60:63]
	v_mfma_f32_16x16x32_bf16 v[56:59], v[136:139], v[162:165], v[56:59]
	v_mfma_f32_16x16x32_bf16 v[44:47], v[128:131], v[192:195], v[44:47]
	v_mfma_f32_16x16x32_bf16 v[40:43], v[136:139], v[192:195], v[40:43]
	v_mfma_f32_16x16x32_bf16 v[28:31], v[128:131], v[200:203], v[28:31]
	v_mfma_f32_16x16x32_bf16 v[24:27], v[136:139], v[200:203], v[24:27]
	v_mfma_f32_16x16x32_bf16 v[12:15], v[128:131], v[208:211], v[12:15]
	v_mfma_f32_16x16x32_bf16 v[8:11], v[136:139], v[208:211], v[8:11]
	v_mfma_f32_16x16x32_bf16 v[60:63], v[132:135], v[166:169], v[60:63]
	v_mfma_f32_16x16x32_bf16 v[56:59], v[140:143], v[166:169], v[56:59]
	v_mfma_f32_16x16x32_bf16 v[44:47], v[132:135], v[196:199], v[44:47]
	v_mfma_f32_16x16x32_bf16 v[40:43], v[140:143], v[196:199], v[40:43]
	v_mfma_f32_16x16x32_bf16 v[28:31], v[132:135], v[204:207], v[28:31]
	v_mfma_f32_16x16x32_bf16 v[24:27], v[140:143], v[204:207], v[24:27]
	v_mfma_f32_16x16x32_bf16 v[12:15], v[132:135], v[212:215], v[12:15]
	v_mfma_f32_16x16x32_bf16 v[8:11], v[140:143], v[212:215], v[8:11]
	s_setprio 0
	s_barrier
	s_add_u32 s30, s30, 0xb0080
	s_addc_u32 s31, s31, 0
	s_mov_b32 m0, s58
	v_lshl_add_u64 v[128:129], s[30:31], 0, v[144:145]
	global_load_lds_dwordx4 v[128:129], off
	v_lshl_add_u64 v[128:129], s[30:31], 0, v[146:147]
	s_mov_b32 m0, s59
	s_nop 0
	global_load_lds_dwordx4 v[128:129], off
	s_waitcnt vmcnt(6)
	s_barrier
	s_setprio 1
	v_mfma_f32_16x16x32_bf16 v[52:55], v[216:219], v[162:165], v[52:55]
	v_mfma_f32_16x16x32_bf16 v[48:51], v[224:227], v[162:165], v[48:51]
	v_mfma_f32_16x16x32_bf16 v[36:39], v[216:219], v[192:195], v[36:39]
	v_mfma_f32_16x16x32_bf16 v[32:35], v[224:227], v[192:195], v[32:35]
	v_mfma_f32_16x16x32_bf16 v[20:23], v[216:219], v[200:203], v[20:23]
	v_mfma_f32_16x16x32_bf16 v[16:19], v[224:227], v[200:203], v[16:19]
	v_mfma_f32_16x16x32_bf16 v[4:7], v[216:219], v[208:211], v[4:7]
	v_mfma_f32_16x16x32_bf16 v[0:3], v[224:227], v[208:211], v[0:3]
	v_mfma_f32_16x16x32_bf16 v[52:55], v[220:223], v[166:169], v[52:55]
	v_mfma_f32_16x16x32_bf16 v[48:51], v[228:231], v[166:169], v[48:51]
	v_mfma_f32_16x16x32_bf16 v[36:39], v[220:223], v[196:199], v[36:39]
	v_mfma_f32_16x16x32_bf16 v[32:35], v[228:231], v[196:199], v[32:35]
	v_mfma_f32_16x16x32_bf16 v[20:23], v[220:223], v[204:207], v[20:23]
	v_mfma_f32_16x16x32_bf16 v[16:19], v[228:231], v[204:207], v[16:19]
	v_mfma_f32_16x16x32_bf16 v[4:7], v[220:223], v[212:215], v[4:7]
	v_mfma_f32_16x16x32_bf16 v[0:3], v[228:231], v[212:215], v[0:3]
	s_setprio 0
	s_add_i32 s67, s67, 2
	s_add_u32 s27, s27, 0x100
	s_addc_u32 s66, s66, 0
	s_add_u32 s28, s28, 0x100
	s_addc_u32 s29, s29, 0
	s_cmp_gt_u32 s67, 41
	s_barrier
	s_cbranch_scc0 .LBB0_1812
	v_bfe_i32 v249, v176, 3, 1
	v_and_b32_e32 v248, 0xffff8040, v249
	v_mov_b32_e32 v250, 0x8000
	v_mov_b32_e32 v251, 0
	s_ashr_i32 s27, s26, 31
	s_lshl_b64 s[26:27], s[26:27], 8
	s_lshl_b32 s28, s18, 8
	v_lshl_add_u64 v[164:165], s[26:27], 0, v[148:149]
	s_ashr_i32 s29, s28, 31
	v_lshl_add_u64 v[166:167], s[28:29], 2, v[152:153]
	v_lshlrev_b64 v[128:129], 12, v[164:165]
	v_lshl_add_u64 v[128:129], v[166:167], 0, v[128:129]
	v_lshl_add_u64 v[232:233], v[128:129], 0, v[248:249]
	v_lshl_add_u64 v[234:235], v[232:233], 0, v[250:251]
	global_load_dwordx4 v[194:197], v[232:233], off
	global_load_dwordx4 v[198:201], v[234:235], off
	global_load_dwordx4 v[202:205], v[232:233], off offset:512
	global_load_dwordx4 v[206:209], v[234:235], off offset:512
	v_or_b32_e32 v168, 16, v164
	v_mov_b32_e32 v169, v165
	v_lshlrev_b64 v[128:129], 12, v[168:169]
	v_lshl_add_u64 v[128:129], v[166:167], 0, v[128:129]
	v_lshl_add_u64 v[236:237], v[128:129], 0, v[248:249]
	v_lshl_add_u64 v[238:239], v[236:237], 0, v[250:251]
	global_load_dwordx4 v[140:143], v[236:237], off
	global_load_dwordx4 v[136:139], v[238:239], off
	global_load_dwordx4 v[132:135], v[236:237], off offset:512
	s_nop 0
	global_load_dwordx4 v[128:131], v[238:239], off offset:512
	v_and_b32_e32 v163, 64, v191
	v_xor_b32_e32 v192, 16, v191
	v_add_u32_e32 v210, 64, v163
	v_xor_b32_e32 v193, 32, v191
	v_cmp_lt_i32_e32 vcc, v192, v210
	v_or_b32_e32 v162, s28, v150
	v_mov_b32_e32 v163, s29
	v_cndmask_b32_e32 v192, v191, v192, vcc
	v_cmp_lt_i32_e32 vcc, v193, v210
	v_lshlrev_b64 v[210:211], 10, v[164:165]
	v_lshl_add_u64 v[210:211], v[210:211], 0, v[162:163]
	v_lshl_add_u64 v[212:213], v[210:211], 2, s[78:79]
	s_waitcnt vmcnt(0)
	v_lshlrev_b64 v[210:211], 1, v[210:211]
	v_lshl_add_u64 v[214:215], s[4:5], 0, v[210:211]
	v_lshlrev_b32_e32 v192, 2, v192
	v_or_b32_e32 v216, 32, v210
	v_mov_b32_e32 v217, v211
	v_cndmask_b32_e32 v193, v191, v193, vcc
	v_or_b32_e32 v218, 0x100, v210
	v_mov_b32_e32 v219, v211
	v_lshl_add_u64 v[216:217], s[4:5], 0, v[216:217]
	v_lshl_add_u64 v[218:219], s[4:5], 0, v[218:219]
	s_lshl_b32 s26, s18, 2
	v_or_b32_e32 v210, 0x120, v210
	s_ashr_i32 s27, s26, 31
	s_waitcnt vmcnt(0)
	v_mov_b32_dpp v224, v194 row_ror:8 row_mask:0xf bank_mask:0xf
	v_mov_b32_dpp v225, v195 row_ror:8 row_mask:0xf bank_mask:0xf
	v_mov_b32_dpp v226, v196 row_ror:8 row_mask:0xf bank_mask:0xf
	v_mov_b32_dpp v227, v197 row_ror:8 row_mask:0xf bank_mask:0xf
	v_mov_b32_dpp v194, v198 row_ror:8 row_mask:0xf bank_mask:0xc
	v_mov_b32_dpp v195, v199 row_ror:8 row_mask:0xf bank_mask:0xc
	v_mov_b32_dpp v196, v200 row_ror:8 row_mask:0xf bank_mask:0xc
	v_mov_b32_dpp v197, v201 row_ror:8 row_mask:0xf bank_mask:0xc
	v_mov_b32_dpp v198, v224 quad_perm:[0,1,2,3] row_mask:0xf bank_mask:0x3
	v_mov_b32_dpp v199, v225 quad_perm:[0,1,2,3] row_mask:0xf bank_mask:0x3
	v_mov_b32_dpp v200, v226 quad_perm:[0,1,2,3] row_mask:0xf bank_mask:0x3
	v_mov_b32_dpp v201, v227 quad_perm:[0,1,2,3] row_mask:0xf bank_mask:0x3
	v_mov_b32_dpp v224, v202 row_ror:8 row_mask:0xf bank_mask:0xf
	v_mov_b32_dpp v225, v203 row_ror:8 row_mask:0xf bank_mask:0xf
	v_mov_b32_dpp v226, v204 row_ror:8 row_mask:0xf bank_mask:0xf
	v_mov_b32_dpp v227, v205 row_ror:8 row_mask:0xf bank_mask:0xf
	v_mov_b32_dpp v202, v206 row_ror:8 row_mask:0xf bank_mask:0xc
	v_mov_b32_dpp v203, v207 row_ror:8 row_mask:0xf bank_mask:0xc
	v_mov_b32_dpp v204, v208 row_ror:8 row_mask:0xf bank_mask:0xc
	v_mov_b32_dpp v205, v209 row_ror:8 row_mask:0xf bank_mask:0xc
	v_mov_b32_dpp v206, v224 quad_perm:[0,1,2,3] row_mask:0xf bank_mask:0x3
	v_mov_b32_dpp v207, v225 quad_perm:[0,1,2,3] row_mask:0xf bank_mask:0x3
	v_mov_b32_dpp v208, v226 quad_perm:[0,1,2,3] row_mask:0xf bank_mask:0x3
	v_mov_b32_dpp v209, v227 quad_perm:[0,1,2,3] row_mask:0xf bank_mask:0x3
	v_pk_fma_f32 v[126:127], v[126:127], 0.5, v[196:197] op_sel_hi:[1,0,1]
	v_pk_fma_f32 v[124:125], v[124:125], 0.5, v[194:195] op_sel_hi:[1,0,1]
	v_pk_fma_f32 v[120:121], v[120:121], 0.5, v[198:199] op_sel_hi:[1,0,1]
	v_pk_fma_f32 v[122:123], v[122:123], 0.5, v[200:201] op_sel_hi:[1,0,1]
	v_pk_fma_f32 v[116:117], v[116:117], 0.5, v[202:203] op_sel_hi:[1,0,1]
	v_pk_fma_f32 v[194:195], v[112:113], 0.5, v[206:207] op_sel_hi:[1,0,1]
	global_store_dwordx4 v[212:213], v[124:127], off
	v_cvt_pk_bf16_f32 v112, v124, v125
	v_mul_f32_e32 v200, v120, v120
	v_mul_f32_e32 v201, v116, v116
	v_mul_f32_e32 v124, v124, v124
	v_fmac_f32_e32 v124, v125, v125
	v_fmac_f32_e32 v200, v121, v121
	v_pk_fma_f32 v[118:119], v[118:119], 0.5, v[204:205] op_sel_hi:[1,0,1]
	v_mul_f32_e32 v202, v194, v194
	v_fmac_f32_e32 v201, v117, v117
	v_fmac_f32_e32 v124, v126, v126
	v_fmac_f32_e32 v200, v122, v122
	v_pk_fma_f32 v[196:197], v[114:115], 0.5, v[208:209] op_sel_hi:[1,0,1]
	v_fmac_f32_e32 v202, v195, v195
	v_fmac_f32_e32 v201, v118, v118
	v_fmac_f32_e32 v124, v127, v127
	v_fmac_f32_e32 v200, v123, v123
	v_cvt_pk_bf16_f32 v113, v126, v127
	v_bfe_u32 v246, v176, 4, 1
	v_mul_u32_u24_e32 v246, 24, v246
	v_mov_b32_e32 v247, 0
	s_nop 1
	v_mov_b32_e32 v240, v112
	v_mov_b32_e32 v241, v113
	v_lshl_add_u64 v[244:245], v[214:215], 0, v[246:247]
	v_fmac_f32_e32 v202, v196, v196
	v_fmac_f32_e32 v201, v119, v119
	v_add_f32_e32 v112, v124, v200
	v_fmac_f32_e32 v202, v197, v197
	v_add_f32_e32 v112, v112, v201
	v_add_f32_e32 v112, v112, v202
	ds_bpermute_b32 v113, v192, v112
	v_cvt_pk_bf16_f32 v114, v120, v121
	v_cvt_pk_bf16_f32 v115, v122, v123
	v_cvt_pk_bf16_f32 v198, v116, v117
	v_cvt_pk_bf16_f32 v199, v118, v119
	global_store_dwordx4 v[212:213], v[120:123], off offset:64
	v_mov_b32_e32 v242, v114
	v_mov_b32_e32 v243, v115
	s_nop 1
	v_permlane16_swap_b32 v240, v242
	v_permlane16_swap_b32 v241, v243
	global_store_dwordx4 v[244:245], v[240:243], off
	global_store_dwordx4 v[212:213], v[116:119], off offset:512
	s_nop 1
	v_mov_b32_e32 v240, v198
	v_mov_b32_e32 v241, v199
	v_lshl_add_u64 v[244:245], v[218:219], 0, v[246:247]
	global_store_dwordx4 v[212:213], v[194:197], off offset:576
	s_waitcnt lgkmcnt(0)
	v_add_f32_e32 v112, v112, v113
	v_lshlrev_b32_e32 v116, 2, v193
	ds_bpermute_b32 v113, v116, v112
	v_lshl_add_u64 v[114:115], s[4:5], 0, v[210:211]
	v_cvt_pk_bf16_f32 v118, v194, v195
	v_cvt_pk_bf16_f32 v119, v196, v197
	v_mov_b32_e32 v242, v118
	v_mov_b32_e32 v243, v119
	s_nop 1
	v_permlane16_swap_b32 v240, v242
	v_permlane16_swap_b32 v241, v243
	global_store_dwordx4 v[244:245], v[240:243], off
	s_and_saveexec_b64 s[28:29], s[6:7]
	s_cbranch_execz .LBB0_1815
	v_lshlrev_b64 v[114:115], 6, v[164:165]
	v_lshl_add_u64 v[114:115], s[14:15], 0, v[114:115]
	v_lshl_add_u64 v[114:115], s[26:27], 2, v[114:115]
	s_lshl_b32 s18, s53, 2
	v_lshl_add_u64 v[114:115], v[114:115], 0, s[18:19]
	s_waitcnt lgkmcnt(0)
	v_add_f32_e32 v112, v112, v113
	flat_store_dword v[114:115], v112
.LBB0_1815:
	s_or_b64 exec, exec, s[28:29]
	s_waitcnt lgkmcnt(0)
	v_lshlrev_b64 v[112:113], 10, v[168:169]
	v_lshl_add_u64 v[112:113], v[112:113], 0, v[162:163]
	v_mov_b32_dpp v224, v140 row_ror:8 row_mask:0xf bank_mask:0xf
	v_mov_b32_dpp v225, v141 row_ror:8 row_mask:0xf bank_mask:0xf
	v_mov_b32_dpp v226, v142 row_ror:8 row_mask:0xf bank_mask:0xf
	v_mov_b32_dpp v227, v143 row_ror:8 row_mask:0xf bank_mask:0xf
	v_mov_b32_dpp v140, v136 row_ror:8 row_mask:0xf bank_mask:0xc
	v_mov_b32_dpp v141, v137 row_ror:8 row_mask:0xf bank_mask:0xc
	v_mov_b32_dpp v142, v138 row_ror:8 row_mask:0xf bank_mask:0xc
	v_mov_b32_dpp v143, v139 row_ror:8 row_mask:0xf bank_mask:0xc
	v_mov_b32_dpp v136, v224 quad_perm:[0,1,2,3] row_mask:0xf bank_mask:0x3
	v_mov_b32_dpp v137, v225 quad_perm:[0,1,2,3] row_mask:0xf bank_mask:0x3
	v_mov_b32_dpp v138, v226 quad_perm:[0,1,2,3] row_mask:0xf bank_mask:0x3
	v_mov_b32_dpp v139, v227 quad_perm:[0,1,2,3] row_mask:0xf bank_mask:0x3
	v_mov_b32_dpp v224, v132 row_ror:8 row_mask:0xf bank_mask:0xf
	v_mov_b32_dpp v225, v133 row_ror:8 row_mask:0xf bank_mask:0xf
	v_mov_b32_dpp v226, v134 row_ror:8 row_mask:0xf bank_mask:0xf
	v_mov_b32_dpp v227, v135 row_ror:8 row_mask:0xf bank_mask:0xf
	v_mov_b32_dpp v132, v128 row_ror:8 row_mask:0xf bank_mask:0xc
	v_mov_b32_dpp v133, v129 row_ror:8 row_mask:0xf bank_mask:0xc
	v_mov_b32_dpp v134, v130 row_ror:8 row_mask:0xf bank_mask:0xc
	v_mov_b32_dpp v135, v131 row_ror:8 row_mask:0xf bank_mask:0xc
	v_mov_b32_dpp v128, v224 quad_perm:[0,1,2,3] row_mask:0xf bank_mask:0x3
	v_mov_b32_dpp v129, v225 quad_perm:[0,1,2,3] row_mask:0xf bank_mask:0x3
	v_mov_b32_dpp v130, v226 quad_perm:[0,1,2,3] row_mask:0xf bank_mask:0x3
	v_mov_b32_dpp v131, v227 quad_perm:[0,1,2,3] row_mask:0xf bank_mask:0x3
	v_pk_fma_f32 v[108:109], v[108:109], 0.5, v[140:141] op_sel_hi:[1,0,1]
	v_lshl_add_u64 v[114:115], v[112:113], 2, s[78:79]
	v_lshlrev_b64 v[112:113], 1, v[112:113]
	v_mul_f32_e32 v117, v108, v108
	v_pk_fma_f32 v[110:111], v[110:111], 0.5, v[142:143] op_sel_hi:[1,0,1]
	v_lshl_add_u64 v[118:119], s[4:5], 0, v[112:113]
	v_fmac_f32_e32 v117, v109, v109
	v_pk_fma_f32 v[106:107], v[106:107], 0.5, v[138:139] op_sel_hi:[1,0,1]
	v_pk_fma_f32 v[104:105], v[104:105], 0.5, v[136:137] op_sel_hi:[1,0,1]
	global_store_dwordx4 v[114:115], v[108:111], off
	v_cvt_pk_bf16_f32 v120, v108, v109
	v_cvt_pk_bf16_f32 v121, v110, v111
	s_nop 1
	v_mov_b32_e32 v240, v120
	v_mov_b32_e32 v241, v121
	v_lshl_add_u64 v[244:245], v[118:119], 0, v[246:247]
	v_fmac_f32_e32 v117, v110, v110
	global_store_dwordx4 v[114:115], v[104:107], off offset:64
	v_or_b32_e32 v108, 32, v112
	v_mov_b32_e32 v109, v113
	v_cvt_pk_bf16_f32 v110, v104, v105
	v_mul_f32_e32 v104, v104, v104
	v_lshl_add_u64 v[108:109], s[4:5], 0, v[108:109]
	v_fmac_f32_e32 v104, v105, v105
	v_pk_fma_f32 v[102:103], v[102:103], 0.5, v[134:135] op_sel_hi:[1,0,1]
	v_pk_fma_f32 v[100:101], v[100:101], 0.5, v[132:133] op_sel_hi:[1,0,1]
	v_fmac_f32_e32 v117, v111, v111
	v_cvt_pk_bf16_f32 v111, v106, v107
	v_mov_b32_e32 v242, v110
	v_mov_b32_e32 v243, v111
	s_nop 1
	v_permlane16_swap_b32 v240, v242
	v_permlane16_swap_b32 v241, v243
	global_store_dwordx4 v[244:245], v[240:243], off
	v_fmac_f32_e32 v104, v106, v106
	global_store_dwordx4 v[114:115], v[100:103], off offset:512
	v_cvt_pk_bf16_f32 v106, v100, v101
	v_fmac_f32_e32 v104, v107, v107
	v_add_f32_e32 v107, v117, v104
	v_mul_f32_e32 v100, v100, v100
	v_fmac_f32_e32 v100, v101, v101
	v_fmac_f32_e32 v100, v102, v102
	v_fmac_f32_e32 v100, v103, v103
	v_add_f32_e32 v107, v107, v100
	v_pk_fma_f32 v[100:101], v[98:99], 0.5, v[130:131] op_sel_hi:[1,0,1]
	v_pk_fma_f32 v[98:99], v[96:97], 0.5, v[128:129] op_sel_hi:[1,0,1]
	v_or_b32_e32 v104, 0x100, v112
	v_mul_f32_e32 v96, v98, v98
	v_fmac_f32_e32 v96, v99, v99
	v_fmac_f32_e32 v96, v100, v100
	v_fmac_f32_e32 v96, v101, v101
	v_add_f32_e32 v96, v107, v96
	ds_bpermute_b32 v97, v192, v96
	v_mov_b32_e32 v105, v113
	v_or_b32_e32 v112, 0x120, v112
	v_lshl_add_u64 v[104:105], s[4:5], 0, v[104:105]
	v_cvt_pk_bf16_f32 v107, v102, v103
	s_waitcnt lgkmcnt(0)
	v_add_f32_e32 v96, v96, v97
	ds_bpermute_b32 v97, v116, v96
	v_lshl_add_u64 v[102:103], s[4:5], 0, v[112:113]
	s_nop 1
	v_mov_b32_e32 v240, v106
	v_mov_b32_e32 v241, v107
	v_lshl_add_u64 v[244:245], v[104:105], 0, v[246:247]
	global_store_dwordx4 v[114:115], v[98:101], off offset:576
	s_nop 1
	v_cvt_pk_bf16_f32 v98, v98, v99
	v_cvt_pk_bf16_f32 v99, v100, v101
	v_mov_b32_e32 v242, v98
	v_mov_b32_e32 v243, v99
	s_nop 1
	v_permlane16_swap_b32 v240, v242
	v_permlane16_swap_b32 v241, v243
	global_store_dwordx4 v[244:245], v[240:243], off
	s_and_saveexec_b64 s[28:29], s[6:7]
	s_cbranch_execz .LBB0_1817
	v_lshlrev_b64 v[98:99], 6, v[168:169]
	v_lshl_add_u64 v[98:99], s[14:15], 0, v[98:99]
	v_lshl_add_u64 v[98:99], s[26:27], 2, v[98:99]
	s_lshl_b32 s18, s53, 2
	v_lshl_add_u64 v[98:99], v[98:99], 0, s[18:19]
	s_waitcnt lgkmcnt(0)
	v_add_f32_e32 v96, v96, v97
	flat_store_dword v[98:99], v96
.LBB0_1817:
	s_or_b64 exec, exec, s[28:29]
	v_or_b32_e32 v114, 32, v164
	v_mov_b32_e32 v115, v165
	s_waitcnt lgkmcnt(0)
	v_lshlrev_b64 v[96:97], 12, v[114:115]
	v_lshl_add_u64 v[96:97], v[166:167], 0, v[96:97]
	v_lshl_add_u64 v[232:233], v[96:97], 0, v[248:249]
	v_lshl_add_u64 v[234:235], v[232:233], 0, v[250:251]
	global_load_dwordx4 v[118:121], v[232:233], off
	global_load_dwordx4 v[122:125], v[234:235], off
	global_load_dwordx4 v[126:129], v[232:233], off offset:512
	global_load_dwordx4 v[130:133], v[234:235], off offset:512
	v_or_b32_e32 v112, 48, v164
	v_mov_b32_e32 v113, v165
	v_lshlrev_b64 v[96:97], 12, v[112:113]
	v_lshl_add_u64 v[96:97], v[166:167], 0, v[96:97]
	v_lshl_add_u64 v[236:237], v[96:97], 0, v[248:249]
	v_lshl_add_u64 v[238:239], v[236:237], 0, v[250:251]
	global_load_dwordx4 v[108:111], v[236:237], off
	global_load_dwordx4 v[104:107], v[238:239], off
	global_load_dwordx4 v[100:103], v[236:237], off offset:512
	s_nop 0
	global_load_dwordx4 v[96:99], v[238:239], off offset:512
	v_lshlrev_b64 v[134:135], 10, v[114:115]
	v_lshl_add_u64 v[134:135], v[134:135], 0, v[162:163]
	v_lshl_add_u64 v[136:137], v[134:135], 2, s[78:79]
	v_lshlrev_b64 v[134:135], 1, v[134:135]
	v_lshl_add_u64 v[138:139], s[4:5], 0, v[134:135]
	s_waitcnt vmcnt(0)
	v_or_b32_e32 v140, 32, v134
	v_mov_b32_e32 v141, v135
	v_or_b32_e32 v142, 0x100, v134
	v_mov_b32_e32 v143, v135
	v_or_b32_e32 v134, 0x120, v134
	v_lshl_add_u64 v[140:141], s[4:5], 0, v[140:141]
	v_lshl_add_u64 v[142:143], s[4:5], 0, v[142:143]
	s_waitcnt vmcnt(0)
	v_mov_b32_dpp v224, v118 row_ror:8 row_mask:0xf bank_mask:0xf
	v_mov_b32_dpp v225, v119 row_ror:8 row_mask:0xf bank_mask:0xf
	v_mov_b32_dpp v226, v120 row_ror:8 row_mask:0xf bank_mask:0xf
	v_mov_b32_dpp v227, v121 row_ror:8 row_mask:0xf bank_mask:0xf
	v_mov_b32_dpp v118, v122 row_ror:8 row_mask:0xf bank_mask:0xc
	v_mov_b32_dpp v119, v123 row_ror:8 row_mask:0xf bank_mask:0xc
	v_mov_b32_dpp v120, v124 row_ror:8 row_mask:0xf bank_mask:0xc
	v_mov_b32_dpp v121, v125 row_ror:8 row_mask:0xf bank_mask:0xc
	v_mov_b32_dpp v122, v224 quad_perm:[0,1,2,3] row_mask:0xf bank_mask:0x3
	v_mov_b32_dpp v123, v225 quad_perm:[0,1,2,3] row_mask:0xf bank_mask:0x3
	v_mov_b32_dpp v124, v226 quad_perm:[0,1,2,3] row_mask:0xf bank_mask:0x3
	v_mov_b32_dpp v125, v227 quad_perm:[0,1,2,3] row_mask:0xf bank_mask:0x3
	v_mov_b32_dpp v224, v126 row_ror:8 row_mask:0xf bank_mask:0xf
	v_mov_b32_dpp v225, v127 row_ror:8 row_mask:0xf bank_mask:0xf
	v_mov_b32_dpp v226, v128 row_ror:8 row_mask:0xf bank_mask:0xf
	v_mov_b32_dpp v227, v129 row_ror:8 row_mask:0xf bank_mask:0xf
	v_mov_b32_dpp v126, v130 row_ror:8 row_mask:0xf bank_mask:0xc
	v_mov_b32_dpp v127, v131 row_ror:8 row_mask:0xf bank_mask:0xc
	v_mov_b32_dpp v128, v132 row_ror:8 row_mask:0xf bank_mask:0xc
	v_mov_b32_dpp v129, v133 row_ror:8 row_mask:0xf bank_mask:0xc
	v_mov_b32_dpp v130, v224 quad_perm:[0,1,2,3] row_mask:0xf bank_mask:0x3
	v_mov_b32_dpp v131, v225 quad_perm:[0,1,2,3] row_mask:0xf bank_mask:0x3
	v_mov_b32_dpp v132, v226 quad_perm:[0,1,2,3] row_mask:0xf bank_mask:0x3
	v_mov_b32_dpp v133, v227 quad_perm:[0,1,2,3] row_mask:0xf bank_mask:0x3
	v_pk_fma_f32 v[92:93], v[92:93], 0.5, v[118:119] op_sel_hi:[1,0,1]
	v_pk_fma_f32 v[88:89], v[88:89], 0.5, v[122:123] op_sel_hi:[1,0,1]
	v_pk_fma_f32 v[84:85], v[84:85], 0.5, v[126:127] op_sel_hi:[1,0,1]
	v_mul_f32_e32 v117, v92, v92
	v_mul_f32_e32 v122, v88, v88
	v_pk_fma_f32 v[94:95], v[94:95], 0.5, v[120:121] op_sel_hi:[1,0,1]
	v_pk_fma_f32 v[90:91], v[90:91], 0.5, v[124:125] op_sel_hi:[1,0,1]
	v_pk_fma_f32 v[118:119], v[80:81], 0.5, v[130:131] op_sel_hi:[1,0,1]
	v_mul_f32_e32 v123, v84, v84
	v_fmac_f32_e32 v117, v93, v93
	v_fmac_f32_e32 v122, v89, v89
	v_pk_fma_f32 v[86:87], v[86:87], 0.5, v[128:129] op_sel_hi:[1,0,1]
	v_mul_f32_e32 v124, v118, v118
	v_fmac_f32_e32 v123, v85, v85
	v_fmac_f32_e32 v117, v94, v94
	v_fmac_f32_e32 v122, v90, v90
	v_pk_fma_f32 v[120:121], v[82:83], 0.5, v[132:133] op_sel_hi:[1,0,1]
	v_cvt_pk_bf16_f32 v80, v92, v93
	v_fmac_f32_e32 v124, v119, v119
	v_fmac_f32_e32 v123, v86, v86
	v_fmac_f32_e32 v117, v95, v95
	v_fmac_f32_e32 v122, v91, v91
	global_store_dwordx4 v[136:137], v[92:95], off
	v_cvt_pk_bf16_f32 v81, v94, v95
	s_nop 1
	v_mov_b32_e32 v240, v80
	v_mov_b32_e32 v241, v81
	v_lshl_add_u64 v[244:245], v[138:139], 0, v[246:247]
	v_fmac_f32_e32 v124, v120, v120
	v_fmac_f32_e32 v123, v87, v87
	v_add_f32_e32 v80, v117, v122
	v_add_f32_e32 v80, v80, v123
	v_fmac_f32_e32 v124, v121, v121
	v_add_f32_e32 v80, v80, v124
	ds_bpermute_b32 v81, v192, v80
	v_cvt_pk_bf16_f32 v82, v88, v89
	v_cvt_pk_bf16_f32 v83, v90, v91
	v_cvt_pk_bf16_f32 v92, v84, v85
	global_store_dwordx4 v[136:137], v[88:91], off offset:64
	v_mov_b32_e32 v242, v82
	v_mov_b32_e32 v243, v83
	s_nop 1
	v_permlane16_swap_b32 v240, v242
	v_permlane16_swap_b32 v241, v243
	global_store_dwordx4 v[244:245], v[240:243], off
	s_waitcnt lgkmcnt(0)
	v_add_f32_e32 v80, v80, v81
	ds_bpermute_b32 v81, v116, v80
	v_cvt_pk_bf16_f32 v93, v86, v87
	v_lshl_add_u64 v[82:83], s[4:5], 0, v[134:135]
	global_store_dwordx4 v[136:137], v[84:87], off offset:512
	s_nop 1
	v_mov_b32_e32 v240, v92
	v_mov_b32_e32 v241, v93
	v_lshl_add_u64 v[244:245], v[142:143], 0, v[246:247]
	global_store_dwordx4 v[136:137], v[118:121], off offset:576
	v_cvt_pk_bf16_f32 v84, v118, v119
	v_cvt_pk_bf16_f32 v85, v120, v121
	v_mov_b32_e32 v242, v84
	v_mov_b32_e32 v243, v85
	s_nop 1
	v_permlane16_swap_b32 v240, v242
	v_permlane16_swap_b32 v241, v243
	global_store_dwordx4 v[244:245], v[240:243], off
	s_and_saveexec_b64 s[28:29], s[6:7]
	s_cbranch_execz .LBB0_1819
	v_lshlrev_b64 v[82:83], 6, v[114:115]
	v_lshl_add_u64 v[82:83], s[14:15], 0, v[82:83]
	v_lshl_add_u64 v[82:83], s[26:27], 2, v[82:83]
	s_lshl_b32 s18, s53, 2
	v_lshl_add_u64 v[82:83], v[82:83], 0, s[18:19]
	s_waitcnt lgkmcnt(0)
	v_add_f32_e32 v80, v80, v81
	flat_store_dword v[82:83], v80
.LBB0_1819:
	s_or_b64 exec, exec, s[28:29]
	s_waitcnt lgkmcnt(0)
	v_lshlrev_b64 v[80:81], 10, v[112:113]
	v_lshl_add_u64 v[80:81], v[80:81], 0, v[162:163]
	v_lshl_add_u64 v[82:83], v[80:81], 2, s[78:79]
	v_lshlrev_b64 v[80:81], 1, v[80:81]
	v_mov_b32_dpp v224, v108 row_ror:8 row_mask:0xf bank_mask:0xf
	v_mov_b32_dpp v225, v109 row_ror:8 row_mask:0xf bank_mask:0xf
	v_mov_b32_dpp v226, v110 row_ror:8 row_mask:0xf bank_mask:0xf
	v_mov_b32_dpp v227, v111 row_ror:8 row_mask:0xf bank_mask:0xf
	v_mov_b32_dpp v108, v104 row_ror:8 row_mask:0xf bank_mask:0xc
	v_mov_b32_dpp v109, v105 row_ror:8 row_mask:0xf bank_mask:0xc
	v_mov_b32_dpp v110, v106 row_ror:8 row_mask:0xf bank_mask:0xc
	v_mov_b32_dpp v111, v107 row_ror:8 row_mask:0xf bank_mask:0xc
	v_mov_b32_dpp v104, v224 quad_perm:[0,1,2,3] row_mask:0xf bank_mask:0x3
	v_mov_b32_dpp v105, v225 quad_perm:[0,1,2,3] row_mask:0xf bank_mask:0x3
	v_mov_b32_dpp v106, v226 quad_perm:[0,1,2,3] row_mask:0xf bank_mask:0x3
	v_mov_b32_dpp v107, v227 quad_perm:[0,1,2,3] row_mask:0xf bank_mask:0x3
	v_mov_b32_dpp v224, v100 row_ror:8 row_mask:0xf bank_mask:0xf
	v_mov_b32_dpp v225, v101 row_ror:8 row_mask:0xf bank_mask:0xf
	v_mov_b32_dpp v226, v102 row_ror:8 row_mask:0xf bank_mask:0xf
	v_mov_b32_dpp v227, v103 row_ror:8 row_mask:0xf bank_mask:0xf
	v_mov_b32_dpp v100, v96 row_ror:8 row_mask:0xf bank_mask:0xc
	v_mov_b32_dpp v101, v97 row_ror:8 row_mask:0xf bank_mask:0xc
	v_mov_b32_dpp v102, v98 row_ror:8 row_mask:0xf bank_mask:0xc
	v_mov_b32_dpp v103, v99 row_ror:8 row_mask:0xf bank_mask:0xc
	v_mov_b32_dpp v96, v224 quad_perm:[0,1,2,3] row_mask:0xf bank_mask:0x3
	v_mov_b32_dpp v97, v225 quad_perm:[0,1,2,3] row_mask:0xf bank_mask:0x3
	v_mov_b32_dpp v98, v226 quad_perm:[0,1,2,3] row_mask:0xf bank_mask:0x3
	v_mov_b32_dpp v99, v227 quad_perm:[0,1,2,3] row_mask:0xf bank_mask:0x3
	v_pk_fma_f32 v[78:79], v[78:79], 0.5, v[110:111] op_sel_hi:[1,0,1]
	v_pk_fma_f32 v[76:77], v[76:77], 0.5, v[108:109] op_sel_hi:[1,0,1]
	v_lshl_add_u64 v[84:85], s[4:5], 0, v[80:81]
	global_store_dwordx4 v[82:83], v[76:79], off
	v_cvt_pk_bf16_f32 v86, v76, v77
	v_cvt_pk_bf16_f32 v87, v78, v79
	s_nop 1
	v_mov_b32_e32 v240, v86
	v_mov_b32_e32 v241, v87
	v_lshl_add_u64 v[244:245], v[84:85], 0, v[246:247]
	v_mul_f32_e32 v84, v76, v76
	v_fmac_f32_e32 v84, v77, v77
	v_pk_fma_f32 v[74:75], v[74:75], 0.5, v[106:107] op_sel_hi:[1,0,1]
	v_pk_fma_f32 v[72:73], v[72:73], 0.5, v[104:105] op_sel_hi:[1,0,1]
	v_fmac_f32_e32 v84, v78, v78
	global_store_dwordx4 v[82:83], v[72:75], off offset:64
	v_or_b32_e32 v76, 32, v80
	v_mov_b32_e32 v77, v81
	v_cvt_pk_bf16_f32 v78, v72, v73
	v_mul_f32_e32 v72, v72, v72
	v_lshl_add_u64 v[76:77], s[4:5], 0, v[76:77]
	v_fmac_f32_e32 v72, v73, v73
	v_pk_fma_f32 v[70:71], v[70:71], 0.5, v[102:103] op_sel_hi:[1,0,1]
	v_pk_fma_f32 v[68:69], v[68:69], 0.5, v[100:101] op_sel_hi:[1,0,1]
	v_fmac_f32_e32 v84, v79, v79
	v_cvt_pk_bf16_f32 v79, v74, v75
	v_mov_b32_e32 v242, v78
	v_mov_b32_e32 v243, v79
	s_nop 1
	v_permlane16_swap_b32 v240, v242
	v_permlane16_swap_b32 v241, v243
	global_store_dwordx4 v[244:245], v[240:243], off
	v_fmac_f32_e32 v72, v74, v74
	global_store_dwordx4 v[82:83], v[68:71], off offset:512
	v_cvt_pk_bf16_f32 v74, v68, v69
	v_fmac_f32_e32 v72, v75, v75
	v_add_f32_e32 v75, v84, v72
	v_mul_f32_e32 v68, v68, v68
	v_fmac_f32_e32 v68, v69, v69
	v_fmac_f32_e32 v68, v70, v70
	v_fmac_f32_e32 v68, v71, v71
	v_add_f32_e32 v75, v75, v68
	v_pk_fma_f32 v[68:69], v[66:67], 0.5, v[98:99] op_sel_hi:[1,0,1]
	v_pk_fma_f32 v[66:67], v[64:65], 0.5, v[96:97] op_sel_hi:[1,0,1]
	v_or_b32_e32 v72, 0x100, v80
	v_mul_f32_e32 v64, v66, v66
	v_fmac_f32_e32 v64, v67, v67
	v_fmac_f32_e32 v64, v68, v68
	v_fmac_f32_e32 v64, v69, v69
	v_add_f32_e32 v64, v75, v64
	ds_bpermute_b32 v65, v192, v64
	v_mov_b32_e32 v73, v81
	v_or_b32_e32 v80, 0x120, v80
	v_lshl_add_u64 v[72:73], s[4:5], 0, v[72:73]
	v_cvt_pk_bf16_f32 v75, v70, v71
	s_waitcnt lgkmcnt(0)
	v_add_f32_e32 v64, v64, v65
	ds_bpermute_b32 v65, v116, v64
	v_lshl_add_u64 v[70:71], s[4:5], 0, v[80:81]
	s_nop 1
	v_mov_b32_e32 v240, v74
	v_mov_b32_e32 v241, v75
	v_lshl_add_u64 v[244:245], v[72:73], 0, v[246:247]
	global_store_dwordx4 v[82:83], v[66:69], off offset:576
	s_nop 1
	v_cvt_pk_bf16_f32 v66, v66, v67
	v_cvt_pk_bf16_f32 v67, v68, v69
	v_mov_b32_e32 v242, v66
	v_mov_b32_e32 v243, v67
	s_nop 1
	v_permlane16_swap_b32 v240, v242
	v_permlane16_swap_b32 v241, v243
	global_store_dwordx4 v[244:245], v[240:243], off
	s_and_saveexec_b64 s[28:29], s[6:7]
	s_cbranch_execz .LBB0_1821
	v_lshlrev_b64 v[66:67], 6, v[112:113]
	v_lshl_add_u64 v[66:67], s[14:15], 0, v[66:67]
	v_lshl_add_u64 v[66:67], s[26:27], 2, v[66:67]
	s_lshl_b32 s18, s53, 2
	v_lshl_add_u64 v[66:67], v[66:67], 0, s[18:19]
	s_waitcnt lgkmcnt(0)
	v_add_f32_e32 v64, v64, v65
	flat_store_dword v[66:67], v64
.LBB0_1821:
	s_or_b64 exec, exec, s[28:29]
	v_lshl_add_u64 v[82:83], v[164:165], 0, s[16:17]
	s_waitcnt lgkmcnt(0)
	v_lshlrev_b64 v[64:65], 12, v[82:83]
	v_lshl_add_u64 v[64:65], v[166:167], 0, v[64:65]
	v_lshl_add_u64 v[232:233], v[64:65], 0, v[248:249]
	v_lshl_add_u64 v[234:235], v[232:233], 0, v[250:251]
	global_load_dwordx4 v[84:87], v[232:233], off
	global_load_dwordx4 v[88:91], v[234:235], off
	global_load_dwordx4 v[92:95], v[232:233], off offset:512
	global_load_dwordx4 v[96:99], v[234:235], off offset:512
	v_lshl_add_u64 v[80:81], v[164:165], 0, s[20:21]
	v_lshlrev_b64 v[64:65], 12, v[80:81]
	v_lshl_add_u64 v[64:65], v[166:167], 0, v[64:65]
	v_lshl_add_u64 v[236:237], v[64:65], 0, v[248:249]
	v_lshl_add_u64 v[238:239], v[236:237], 0, v[250:251]
	global_load_dwordx4 v[76:79], v[236:237], off
	global_load_dwordx4 v[72:75], v[238:239], off
	global_load_dwordx4 v[68:71], v[236:237], off offset:512
	s_nop 0
	global_load_dwordx4 v[64:67], v[238:239], off offset:512
	v_lshlrev_b64 v[100:101], 10, v[82:83]
	v_lshl_add_u64 v[100:101], v[100:101], 0, v[162:163]
	v_lshl_add_u64 v[102:103], v[100:101], 2, s[78:79]
	v_lshlrev_b64 v[100:101], 1, v[100:101]
	v_lshl_add_u64 v[104:105], s[4:5], 0, v[100:101]
	s_waitcnt vmcnt(0)
	v_or_b32_e32 v106, 32, v100
	v_mov_b32_e32 v107, v101
	v_or_b32_e32 v108, 0x100, v100
	v_mov_b32_e32 v109, v101
	v_or_b32_e32 v100, 0x120, v100
	v_lshl_add_u64 v[106:107], s[4:5], 0, v[106:107]
	v_lshl_add_u64 v[108:109], s[4:5], 0, v[108:109]
	s_waitcnt vmcnt(0)
	v_mov_b32_dpp v224, v84 row_ror:8 row_mask:0xf bank_mask:0xf
	v_mov_b32_dpp v225, v85 row_ror:8 row_mask:0xf bank_mask:0xf
	v_mov_b32_dpp v226, v86 row_ror:8 row_mask:0xf bank_mask:0xf
	v_mov_b32_dpp v227, v87 row_ror:8 row_mask:0xf bank_mask:0xf
	v_mov_b32_dpp v84, v88 row_ror:8 row_mask:0xf bank_mask:0xc
	v_mov_b32_dpp v85, v89 row_ror:8 row_mask:0xf bank_mask:0xc
	v_mov_b32_dpp v86, v90 row_ror:8 row_mask:0xf bank_mask:0xc
	v_mov_b32_dpp v87, v91 row_ror:8 row_mask:0xf bank_mask:0xc
	v_mov_b32_dpp v88, v224 quad_perm:[0,1,2,3] row_mask:0xf bank_mask:0x3
	v_mov_b32_dpp v89, v225 quad_perm:[0,1,2,3] row_mask:0xf bank_mask:0x3
	v_mov_b32_dpp v90, v226 quad_perm:[0,1,2,3] row_mask:0xf bank_mask:0x3
	v_mov_b32_dpp v91, v227 quad_perm:[0,1,2,3] row_mask:0xf bank_mask:0x3
	v_mov_b32_dpp v224, v92 row_ror:8 row_mask:0xf bank_mask:0xf
	v_mov_b32_dpp v225, v93 row_ror:8 row_mask:0xf bank_mask:0xf
	v_mov_b32_dpp v226, v94 row_ror:8 row_mask:0xf bank_mask:0xf
	v_mov_b32_dpp v227, v95 row_ror:8 row_mask:0xf bank_mask:0xf
	v_mov_b32_dpp v92, v96 row_ror:8 row_mask:0xf bank_mask:0xc
	v_mov_b32_dpp v93, v97 row_ror:8 row_mask:0xf bank_mask:0xc
	v_mov_b32_dpp v94, v98 row_ror:8 row_mask:0xf bank_mask:0xc
	v_mov_b32_dpp v95, v99 row_ror:8 row_mask:0xf bank_mask:0xc
	v_mov_b32_dpp v96, v224 quad_perm:[0,1,2,3] row_mask:0xf bank_mask:0x3
	v_mov_b32_dpp v97, v225 quad_perm:[0,1,2,3] row_mask:0xf bank_mask:0x3
	v_mov_b32_dpp v98, v226 quad_perm:[0,1,2,3] row_mask:0xf bank_mask:0x3
	v_mov_b32_dpp v99, v227 quad_perm:[0,1,2,3] row_mask:0xf bank_mask:0x3
	v_pk_fma_f32 v[60:61], v[60:61], 0.5, v[84:85] op_sel_hi:[1,0,1]
	v_pk_fma_f32 v[56:57], v[56:57], 0.5, v[88:89] op_sel_hi:[1,0,1]
	v_pk_fma_f32 v[52:53], v[52:53], 0.5, v[92:93] op_sel_hi:[1,0,1]
	v_mul_f32_e32 v88, v60, v60
	v_mul_f32_e32 v89, v56, v56
	v_pk_fma_f32 v[62:63], v[62:63], 0.5, v[86:87] op_sel_hi:[1,0,1]
	v_pk_fma_f32 v[58:59], v[58:59], 0.5, v[90:91] op_sel_hi:[1,0,1]
	v_pk_fma_f32 v[84:85], v[48:49], 0.5, v[96:97] op_sel_hi:[1,0,1]
	v_mul_f32_e32 v90, v52, v52
	v_fmac_f32_e32 v88, v61, v61
	v_fmac_f32_e32 v89, v57, v57
	v_pk_fma_f32 v[54:55], v[54:55], 0.5, v[94:95] op_sel_hi:[1,0,1]
	v_mul_f32_e32 v91, v84, v84
	v_fmac_f32_e32 v90, v53, v53
	v_fmac_f32_e32 v88, v62, v62
	v_fmac_f32_e32 v89, v58, v58
	v_pk_fma_f32 v[86:87], v[50:51], 0.5, v[98:99] op_sel_hi:[1,0,1]
	v_cvt_pk_bf16_f32 v48, v60, v61
	v_fmac_f32_e32 v91, v85, v85
	v_fmac_f32_e32 v90, v54, v54
	v_fmac_f32_e32 v88, v63, v63
	v_fmac_f32_e32 v89, v59, v59
	global_store_dwordx4 v[102:103], v[60:63], off
	v_cvt_pk_bf16_f32 v49, v62, v63
	s_nop 1
	v_mov_b32_e32 v240, v48
	v_mov_b32_e32 v241, v49
	v_lshl_add_u64 v[244:245], v[104:105], 0, v[246:247]
	v_fmac_f32_e32 v91, v86, v86
	v_fmac_f32_e32 v90, v55, v55
	v_add_f32_e32 v48, v88, v89
	v_add_f32_e32 v48, v48, v90
	v_fmac_f32_e32 v91, v87, v87
	v_add_f32_e32 v48, v48, v91
	ds_bpermute_b32 v49, v192, v48
	v_cvt_pk_bf16_f32 v50, v56, v57
	v_cvt_pk_bf16_f32 v51, v58, v59
	v_cvt_pk_bf16_f32 v60, v52, v53
	global_store_dwordx4 v[102:103], v[56:59], off offset:64
	v_mov_b32_e32 v242, v50
	v_mov_b32_e32 v243, v51
	s_nop 1
	v_permlane16_swap_b32 v240, v242
	v_permlane16_swap_b32 v241, v243
	global_store_dwordx4 v[244:245], v[240:243], off
	s_waitcnt lgkmcnt(0)
	v_add_f32_e32 v48, v48, v49
	ds_bpermute_b32 v49, v116, v48
	v_cvt_pk_bf16_f32 v61, v54, v55
	v_lshl_add_u64 v[50:51], s[4:5], 0, v[100:101]
	global_store_dwordx4 v[102:103], v[52:55], off offset:512
	s_nop 1
	v_mov_b32_e32 v240, v60
	v_mov_b32_e32 v241, v61
	v_lshl_add_u64 v[244:245], v[108:109], 0, v[246:247]
	global_store_dwordx4 v[102:103], v[84:87], off offset:576
	v_cvt_pk_bf16_f32 v52, v84, v85
	v_cvt_pk_bf16_f32 v53, v86, v87
	v_mov_b32_e32 v242, v52
	v_mov_b32_e32 v243, v53
	s_nop 1
	v_permlane16_swap_b32 v240, v242
	v_permlane16_swap_b32 v241, v243
	global_store_dwordx4 v[244:245], v[240:243], off
	s_and_saveexec_b64 s[28:29], s[6:7]
	s_cbranch_execz .LBB0_1823
	v_lshlrev_b64 v[50:51], 6, v[82:83]
	v_lshl_add_u64 v[50:51], s[14:15], 0, v[50:51]
	v_lshl_add_u64 v[50:51], s[26:27], 2, v[50:51]
	s_lshl_b32 s18, s53, 2
	v_lshl_add_u64 v[50:51], v[50:51], 0, s[18:19]
	s_waitcnt lgkmcnt(0)
	v_add_f32_e32 v48, v48, v49
	flat_store_dword v[50:51], v48
.LBB0_1823:
	s_or_b64 exec, exec, s[28:29]
	s_waitcnt lgkmcnt(0)
	v_lshlrev_b64 v[48:49], 10, v[80:81]
	v_lshl_add_u64 v[48:49], v[48:49], 0, v[162:163]
	v_lshl_add_u64 v[50:51], v[48:49], 2, s[78:79]
	v_lshlrev_b64 v[48:49], 1, v[48:49]
	v_mov_b32_dpp v224, v76 row_ror:8 row_mask:0xf bank_mask:0xf
	v_mov_b32_dpp v225, v77 row_ror:8 row_mask:0xf bank_mask:0xf
	v_mov_b32_dpp v226, v78 row_ror:8 row_mask:0xf bank_mask:0xf
	v_mov_b32_dpp v227, v79 row_ror:8 row_mask:0xf bank_mask:0xf
	v_mov_b32_dpp v76, v72 row_ror:8 row_mask:0xf bank_mask:0xc
	v_mov_b32_dpp v77, v73 row_ror:8 row_mask:0xf bank_mask:0xc
	v_mov_b32_dpp v78, v74 row_ror:8 row_mask:0xf bank_mask:0xc
	v_mov_b32_dpp v79, v75 row_ror:8 row_mask:0xf bank_mask:0xc
	v_mov_b32_dpp v72, v224 quad_perm:[0,1,2,3] row_mask:0xf bank_mask:0x3
	v_mov_b32_dpp v73, v225 quad_perm:[0,1,2,3] row_mask:0xf bank_mask:0x3
	v_mov_b32_dpp v74, v226 quad_perm:[0,1,2,3] row_mask:0xf bank_mask:0x3
	v_mov_b32_dpp v75, v227 quad_perm:[0,1,2,3] row_mask:0xf bank_mask:0x3
	v_mov_b32_dpp v224, v68 row_ror:8 row_mask:0xf bank_mask:0xf
	v_mov_b32_dpp v225, v69 row_ror:8 row_mask:0xf bank_mask:0xf
	v_mov_b32_dpp v226, v70 row_ror:8 row_mask:0xf bank_mask:0xf
	v_mov_b32_dpp v227, v71 row_ror:8 row_mask:0xf bank_mask:0xf
	v_mov_b32_dpp v68, v64 row_ror:8 row_mask:0xf bank_mask:0xc
	v_mov_b32_dpp v69, v65 row_ror:8 row_mask:0xf bank_mask:0xc
	v_mov_b32_dpp v70, v66 row_ror:8 row_mask:0xf bank_mask:0xc
	v_mov_b32_dpp v71, v67 row_ror:8 row_mask:0xf bank_mask:0xc
	v_mov_b32_dpp v64, v224 quad_perm:[0,1,2,3] row_mask:0xf bank_mask:0x3
	v_mov_b32_dpp v65, v225 quad_perm:[0,1,2,3] row_mask:0xf bank_mask:0x3
	v_mov_b32_dpp v66, v226 quad_perm:[0,1,2,3] row_mask:0xf bank_mask:0x3
	v_mov_b32_dpp v67, v227 quad_perm:[0,1,2,3] row_mask:0xf bank_mask:0x3
	v_pk_fma_f32 v[46:47], v[46:47], 0.5, v[78:79] op_sel_hi:[1,0,1]
	v_pk_fma_f32 v[44:45], v[44:45], 0.5, v[76:77] op_sel_hi:[1,0,1]
	v_lshl_add_u64 v[52:53], s[4:5], 0, v[48:49]
	global_store_dwordx4 v[50:51], v[44:47], off
	v_cvt_pk_bf16_f32 v54, v44, v45
	v_cvt_pk_bf16_f32 v55, v46, v47
	s_nop 1
	v_mov_b32_e32 v240, v54
	v_mov_b32_e32 v241, v55
	v_lshl_add_u64 v[244:245], v[52:53], 0, v[246:247]
	v_mul_f32_e32 v52, v44, v44
	v_fmac_f32_e32 v52, v45, v45
	v_pk_fma_f32 v[42:43], v[42:43], 0.5, v[74:75] op_sel_hi:[1,0,1]
	v_pk_fma_f32 v[40:41], v[40:41], 0.5, v[72:73] op_sel_hi:[1,0,1]
	v_fmac_f32_e32 v52, v46, v46
	global_store_dwordx4 v[50:51], v[40:43], off offset:64
	v_or_b32_e32 v44, 32, v48
	v_mov_b32_e32 v45, v49
	v_cvt_pk_bf16_f32 v46, v40, v41
	v_mul_f32_e32 v40, v40, v40
	v_lshl_add_u64 v[44:45], s[4:5], 0, v[44:45]
	v_fmac_f32_e32 v40, v41, v41
	v_pk_fma_f32 v[38:39], v[38:39], 0.5, v[70:71] op_sel_hi:[1,0,1]
	v_pk_fma_f32 v[36:37], v[36:37], 0.5, v[68:69] op_sel_hi:[1,0,1]
	v_fmac_f32_e32 v52, v47, v47
	v_cvt_pk_bf16_f32 v47, v42, v43
	v_mov_b32_e32 v242, v46
	v_mov_b32_e32 v243, v47
	s_nop 1
	v_permlane16_swap_b32 v240, v242
	v_permlane16_swap_b32 v241, v243
	global_store_dwordx4 v[244:245], v[240:243], off
	v_fmac_f32_e32 v40, v42, v42
	global_store_dwordx4 v[50:51], v[36:39], off offset:512
	v_cvt_pk_bf16_f32 v42, v36, v37
	v_fmac_f32_e32 v40, v43, v43
	v_add_f32_e32 v43, v52, v40
	v_mul_f32_e32 v36, v36, v36
	v_fmac_f32_e32 v36, v37, v37
	v_fmac_f32_e32 v36, v38, v38
	v_fmac_f32_e32 v36, v39, v39
	v_add_f32_e32 v43, v43, v36
	v_pk_fma_f32 v[36:37], v[34:35], 0.5, v[66:67] op_sel_hi:[1,0,1]
	v_pk_fma_f32 v[34:35], v[32:33], 0.5, v[64:65] op_sel_hi:[1,0,1]
	v_or_b32_e32 v40, 0x100, v48
	v_mul_f32_e32 v32, v34, v34
	v_fmac_f32_e32 v32, v35, v35
	v_fmac_f32_e32 v32, v36, v36
	v_fmac_f32_e32 v32, v37, v37
	v_add_f32_e32 v32, v43, v32
	ds_bpermute_b32 v33, v192, v32
	v_mov_b32_e32 v41, v49
	v_or_b32_e32 v48, 0x120, v48
	v_lshl_add_u64 v[40:41], s[4:5], 0, v[40:41]
	v_cvt_pk_bf16_f32 v43, v38, v39
	s_waitcnt lgkmcnt(0)
	v_add_f32_e32 v32, v32, v33
	ds_bpermute_b32 v33, v116, v32
	v_lshl_add_u64 v[38:39], s[4:5], 0, v[48:49]
	s_nop 1
	v_mov_b32_e32 v240, v42
	v_mov_b32_e32 v241, v43
	v_lshl_add_u64 v[244:245], v[40:41], 0, v[246:247]
	global_store_dwordx4 v[50:51], v[34:37], off offset:576
	s_nop 1
	v_cvt_pk_bf16_f32 v34, v34, v35
	v_cvt_pk_bf16_f32 v35, v36, v37
	v_mov_b32_e32 v242, v34
	v_mov_b32_e32 v243, v35
	s_nop 1
	v_permlane16_swap_b32 v240, v242
	v_permlane16_swap_b32 v241, v243
	global_store_dwordx4 v[244:245], v[240:243], off
	s_and_saveexec_b64 s[28:29], s[6:7]
	s_cbranch_execz .LBB0_1825
	v_lshlrev_b64 v[34:35], 6, v[80:81]
	v_lshl_add_u64 v[34:35], s[14:15], 0, v[34:35]
	v_lshl_add_u64 v[34:35], s[26:27], 2, v[34:35]
	s_lshl_b32 s18, s53, 2
	v_lshl_add_u64 v[34:35], v[34:35], 0, s[18:19]
	s_waitcnt lgkmcnt(0)
	v_add_f32_e32 v32, v32, v33
	flat_store_dword v[34:35], v32
.LBB0_1825:
	s_or_b64 exec, exec, s[28:29]
	v_lshl_add_u64 v[50:51], v[164:165], 0, s[22:23]
	s_waitcnt lgkmcnt(0)
	v_lshlrev_b64 v[32:33], 12, v[50:51]
	v_lshl_add_u64 v[32:33], v[166:167], 0, v[32:33]
	v_lshl_add_u64 v[232:233], v[32:33], 0, v[248:249]
	v_lshl_add_u64 v[234:235], v[232:233], 0, v[250:251]
	global_load_dwordx4 v[52:55], v[232:233], off
	global_load_dwordx4 v[56:59], v[234:235], off
	global_load_dwordx4 v[60:63], v[232:233], off offset:512
	global_load_dwordx4 v[64:67], v[234:235], off offset:512
	v_lshl_add_u64 v[48:49], v[164:165], 0, s[24:25]
	v_lshlrev_b64 v[32:33], 12, v[48:49]
	v_lshl_add_u64 v[32:33], v[166:167], 0, v[32:33]
	v_lshl_add_u64 v[236:237], v[32:33], 0, v[248:249]
	v_lshl_add_u64 v[238:239], v[236:237], 0, v[250:251]
	global_load_dwordx4 v[44:47], v[236:237], off
	global_load_dwordx4 v[40:43], v[238:239], off
	global_load_dwordx4 v[36:39], v[236:237], off offset:512
	s_nop 0
	global_load_dwordx4 v[32:35], v[238:239], off offset:512
	v_lshlrev_b64 v[68:69], 10, v[50:51]
	v_lshl_add_u64 v[68:69], v[68:69], 0, v[162:163]
	v_lshl_add_u64 v[70:71], v[68:69], 2, s[78:79]
	v_lshlrev_b64 v[68:69], 1, v[68:69]
	v_lshl_add_u64 v[72:73], s[4:5], 0, v[68:69]
	s_waitcnt vmcnt(0)
	v_or_b32_e32 v74, 32, v68
	v_mov_b32_e32 v75, v69
	v_or_b32_e32 v76, 0x100, v68
	v_mov_b32_e32 v77, v69
	v_or_b32_e32 v68, 0x120, v68
	v_lshl_add_u64 v[74:75], s[4:5], 0, v[74:75]
	v_lshl_add_u64 v[76:77], s[4:5], 0, v[76:77]
	s_waitcnt vmcnt(0)
	v_mov_b32_dpp v224, v52 row_ror:8 row_mask:0xf bank_mask:0xf
	v_mov_b32_dpp v225, v53 row_ror:8 row_mask:0xf bank_mask:0xf
	v_mov_b32_dpp v226, v54 row_ror:8 row_mask:0xf bank_mask:0xf
	v_mov_b32_dpp v227, v55 row_ror:8 row_mask:0xf bank_mask:0xf
	v_mov_b32_dpp v52, v56 row_ror:8 row_mask:0xf bank_mask:0xc
	v_mov_b32_dpp v53, v57 row_ror:8 row_mask:0xf bank_mask:0xc
	v_mov_b32_dpp v54, v58 row_ror:8 row_mask:0xf bank_mask:0xc
	v_mov_b32_dpp v55, v59 row_ror:8 row_mask:0xf bank_mask:0xc
	v_mov_b32_dpp v56, v224 quad_perm:[0,1,2,3] row_mask:0xf bank_mask:0x3
	v_mov_b32_dpp v57, v225 quad_perm:[0,1,2,3] row_mask:0xf bank_mask:0x3
	v_mov_b32_dpp v58, v226 quad_perm:[0,1,2,3] row_mask:0xf bank_mask:0x3
	v_mov_b32_dpp v59, v227 quad_perm:[0,1,2,3] row_mask:0xf bank_mask:0x3
	v_mov_b32_dpp v224, v60 row_ror:8 row_mask:0xf bank_mask:0xf
	v_mov_b32_dpp v225, v61 row_ror:8 row_mask:0xf bank_mask:0xf
	v_mov_b32_dpp v226, v62 row_ror:8 row_mask:0xf bank_mask:0xf
	v_mov_b32_dpp v227, v63 row_ror:8 row_mask:0xf bank_mask:0xf
	v_mov_b32_dpp v60, v64 row_ror:8 row_mask:0xf bank_mask:0xc
	v_mov_b32_dpp v61, v65 row_ror:8 row_mask:0xf bank_mask:0xc
	v_mov_b32_dpp v62, v66 row_ror:8 row_mask:0xf bank_mask:0xc
	v_mov_b32_dpp v63, v67 row_ror:8 row_mask:0xf bank_mask:0xc
	v_mov_b32_dpp v64, v224 quad_perm:[0,1,2,3] row_mask:0xf bank_mask:0x3
	v_mov_b32_dpp v65, v225 quad_perm:[0,1,2,3] row_mask:0xf bank_mask:0x3
	v_mov_b32_dpp v66, v226 quad_perm:[0,1,2,3] row_mask:0xf bank_mask:0x3
	v_mov_b32_dpp v67, v227 quad_perm:[0,1,2,3] row_mask:0xf bank_mask:0x3
	v_pk_fma_f32 v[28:29], v[28:29], 0.5, v[52:53] op_sel_hi:[1,0,1]
	v_pk_fma_f32 v[24:25], v[24:25], 0.5, v[56:57] op_sel_hi:[1,0,1]
	v_pk_fma_f32 v[20:21], v[20:21], 0.5, v[60:61] op_sel_hi:[1,0,1]
	v_mul_f32_e32 v56, v28, v28
	v_mul_f32_e32 v57, v24, v24
	v_pk_fma_f32 v[30:31], v[30:31], 0.5, v[54:55] op_sel_hi:[1,0,1]
	v_pk_fma_f32 v[26:27], v[26:27], 0.5, v[58:59] op_sel_hi:[1,0,1]
	v_pk_fma_f32 v[52:53], v[16:17], 0.5, v[64:65] op_sel_hi:[1,0,1]
	v_mul_f32_e32 v58, v20, v20
	v_fmac_f32_e32 v56, v29, v29
	v_fmac_f32_e32 v57, v25, v25
	v_pk_fma_f32 v[22:23], v[22:23], 0.5, v[62:63] op_sel_hi:[1,0,1]
	v_mul_f32_e32 v59, v52, v52
	v_fmac_f32_e32 v58, v21, v21
	v_fmac_f32_e32 v56, v30, v30
	v_fmac_f32_e32 v57, v26, v26
	v_pk_fma_f32 v[54:55], v[18:19], 0.5, v[66:67] op_sel_hi:[1,0,1]
	v_cvt_pk_bf16_f32 v16, v28, v29
	v_fmac_f32_e32 v59, v53, v53
	v_fmac_f32_e32 v58, v22, v22
	v_fmac_f32_e32 v56, v31, v31
	v_fmac_f32_e32 v57, v27, v27
	global_store_dwordx4 v[70:71], v[28:31], off
	v_cvt_pk_bf16_f32 v17, v30, v31
	s_nop 1
	v_mov_b32_e32 v240, v16
	v_mov_b32_e32 v241, v17
	v_lshl_add_u64 v[244:245], v[72:73], 0, v[246:247]
	v_fmac_f32_e32 v59, v54, v54
	v_fmac_f32_e32 v58, v23, v23
	v_add_f32_e32 v16, v56, v57
	v_add_f32_e32 v16, v16, v58
	v_fmac_f32_e32 v59, v55, v55
	v_add_f32_e32 v16, v16, v59
	ds_bpermute_b32 v17, v192, v16
	v_cvt_pk_bf16_f32 v18, v24, v25
	v_cvt_pk_bf16_f32 v19, v26, v27
	v_cvt_pk_bf16_f32 v28, v20, v21
	global_store_dwordx4 v[70:71], v[24:27], off offset:64
	v_mov_b32_e32 v242, v18
	v_mov_b32_e32 v243, v19
	s_nop 1
	v_permlane16_swap_b32 v240, v242
	v_permlane16_swap_b32 v241, v243
	global_store_dwordx4 v[244:245], v[240:243], off
	s_waitcnt lgkmcnt(0)
	v_add_f32_e32 v16, v16, v17
	ds_bpermute_b32 v17, v116, v16
	v_cvt_pk_bf16_f32 v29, v22, v23
	v_lshl_add_u64 v[18:19], s[4:5], 0, v[68:69]
	global_store_dwordx4 v[70:71], v[20:23], off offset:512
	s_nop 1
	v_mov_b32_e32 v240, v28
	v_mov_b32_e32 v241, v29
	v_lshl_add_u64 v[244:245], v[76:77], 0, v[246:247]
	global_store_dwordx4 v[70:71], v[52:55], off offset:576
	v_cvt_pk_bf16_f32 v20, v52, v53
	v_cvt_pk_bf16_f32 v21, v54, v55
	v_mov_b32_e32 v242, v20
	v_mov_b32_e32 v243, v21
	s_nop 1
	v_permlane16_swap_b32 v240, v242
	v_permlane16_swap_b32 v241, v243
	global_store_dwordx4 v[244:245], v[240:243], off
	s_and_saveexec_b64 s[28:29], s[6:7]
	s_cbranch_execz .LBB0_1827
	v_lshlrev_b64 v[18:19], 6, v[50:51]
	v_lshl_add_u64 v[18:19], s[14:15], 0, v[18:19]
	v_lshl_add_u64 v[18:19], s[26:27], 2, v[18:19]
	s_lshl_b32 s18, s53, 2
	v_lshl_add_u64 v[18:19], v[18:19], 0, s[18:19]
	s_waitcnt lgkmcnt(0)
	v_add_f32_e32 v16, v16, v17
	flat_store_dword v[18:19], v16
.LBB0_1827:
	s_or_b64 exec, exec, s[28:29]
	s_waitcnt lgkmcnt(0)
	v_lshlrev_b64 v[16:17], 10, v[48:49]
	v_lshl_add_u64 v[16:17], v[16:17], 0, v[162:163]
	v_lshl_add_u64 v[18:19], v[16:17], 2, s[78:79]
	v_lshlrev_b64 v[16:17], 1, v[16:17]
	v_mov_b32_dpp v224, v44 row_ror:8 row_mask:0xf bank_mask:0xf
	v_mov_b32_dpp v225, v45 row_ror:8 row_mask:0xf bank_mask:0xf
	v_mov_b32_dpp v226, v46 row_ror:8 row_mask:0xf bank_mask:0xf
	v_mov_b32_dpp v227, v47 row_ror:8 row_mask:0xf bank_mask:0xf
	v_mov_b32_dpp v44, v40 row_ror:8 row_mask:0xf bank_mask:0xc
	v_mov_b32_dpp v45, v41 row_ror:8 row_mask:0xf bank_mask:0xc
	v_mov_b32_dpp v46, v42 row_ror:8 row_mask:0xf bank_mask:0xc
	v_mov_b32_dpp v47, v43 row_ror:8 row_mask:0xf bank_mask:0xc
	v_mov_b32_dpp v40, v224 quad_perm:[0,1,2,3] row_mask:0xf bank_mask:0x3
	v_mov_b32_dpp v41, v225 quad_perm:[0,1,2,3] row_mask:0xf bank_mask:0x3
	v_mov_b32_dpp v42, v226 quad_perm:[0,1,2,3] row_mask:0xf bank_mask:0x3
	v_mov_b32_dpp v43, v227 quad_perm:[0,1,2,3] row_mask:0xf bank_mask:0x3
	v_mov_b32_dpp v224, v36 row_ror:8 row_mask:0xf bank_mask:0xf
	v_mov_b32_dpp v225, v37 row_ror:8 row_mask:0xf bank_mask:0xf
	v_mov_b32_dpp v226, v38 row_ror:8 row_mask:0xf bank_mask:0xf
	v_mov_b32_dpp v227, v39 row_ror:8 row_mask:0xf bank_mask:0xf
	v_mov_b32_dpp v36, v32 row_ror:8 row_mask:0xf bank_mask:0xc
	v_mov_b32_dpp v37, v33 row_ror:8 row_mask:0xf bank_mask:0xc
	v_mov_b32_dpp v38, v34 row_ror:8 row_mask:0xf bank_mask:0xc
	v_mov_b32_dpp v39, v35 row_ror:8 row_mask:0xf bank_mask:0xc
	v_mov_b32_dpp v32, v224 quad_perm:[0,1,2,3] row_mask:0xf bank_mask:0x3
	v_mov_b32_dpp v33, v225 quad_perm:[0,1,2,3] row_mask:0xf bank_mask:0x3
	v_mov_b32_dpp v34, v226 quad_perm:[0,1,2,3] row_mask:0xf bank_mask:0x3
	v_mov_b32_dpp v35, v227 quad_perm:[0,1,2,3] row_mask:0xf bank_mask:0x3
	v_pk_fma_f32 v[14:15], v[14:15], 0.5, v[46:47] op_sel_hi:[1,0,1]
	v_pk_fma_f32 v[12:13], v[12:13], 0.5, v[44:45] op_sel_hi:[1,0,1]
	v_lshl_add_u64 v[20:21], s[4:5], 0, v[16:17]
	global_store_dwordx4 v[18:19], v[12:15], off
	v_cvt_pk_bf16_f32 v22, v12, v13
	v_cvt_pk_bf16_f32 v23, v14, v15
	s_nop 1
	v_mov_b32_e32 v240, v22
	v_mov_b32_e32 v241, v23
	v_lshl_add_u64 v[244:245], v[20:21], 0, v[246:247]
	v_mul_f32_e32 v20, v12, v12
	v_fmac_f32_e32 v20, v13, v13
	v_pk_fma_f32 v[10:11], v[10:11], 0.5, v[42:43] op_sel_hi:[1,0,1]
	v_pk_fma_f32 v[8:9], v[8:9], 0.5, v[40:41] op_sel_hi:[1,0,1]
	v_fmac_f32_e32 v20, v14, v14
	global_store_dwordx4 v[18:19], v[8:11], off offset:64
	v_or_b32_e32 v12, 32, v16
	v_mov_b32_e32 v13, v17
	v_cvt_pk_bf16_f32 v14, v8, v9
	v_mul_f32_e32 v8, v8, v8
	v_lshl_add_u64 v[12:13], s[4:5], 0, v[12:13]
	v_fmac_f32_e32 v8, v9, v9
	v_pk_fma_f32 v[6:7], v[6:7], 0.5, v[38:39] op_sel_hi:[1,0,1]
	v_pk_fma_f32 v[4:5], v[4:5], 0.5, v[36:37] op_sel_hi:[1,0,1]
	v_fmac_f32_e32 v20, v15, v15
	v_cvt_pk_bf16_f32 v15, v10, v11
	v_mov_b32_e32 v242, v14
	v_mov_b32_e32 v243, v15
	s_nop 1
	v_permlane16_swap_b32 v240, v242
	v_permlane16_swap_b32 v241, v243
	global_store_dwordx4 v[244:245], v[240:243], off
	v_fmac_f32_e32 v8, v10, v10
	global_store_dwordx4 v[18:19], v[4:7], off offset:512
	v_cvt_pk_bf16_f32 v10, v4, v5
	v_fmac_f32_e32 v8, v11, v11
	v_add_f32_e32 v11, v20, v8
	v_mul_f32_e32 v4, v4, v4
	v_fmac_f32_e32 v4, v5, v5
	v_fmac_f32_e32 v4, v6, v6
	v_fmac_f32_e32 v4, v7, v7
	v_add_f32_e32 v11, v11, v4
	v_pk_fma_f32 v[4:5], v[2:3], 0.5, v[34:35] op_sel_hi:[1,0,1]
	v_pk_fma_f32 v[2:3], v[0:1], 0.5, v[32:33] op_sel_hi:[1,0,1]
	v_or_b32_e32 v8, 0x100, v16
	v_mul_f32_e32 v0, v2, v2
	v_fmac_f32_e32 v0, v3, v3
	v_fmac_f32_e32 v0, v4, v4
	v_fmac_f32_e32 v0, v5, v5
	v_add_f32_e32 v0, v11, v0
	ds_bpermute_b32 v1, v192, v0
	v_mov_b32_e32 v9, v17
	v_or_b32_e32 v16, 0x120, v16
	v_lshl_add_u64 v[8:9], s[4:5], 0, v[8:9]
	v_cvt_pk_bf16_f32 v11, v6, v7
	s_waitcnt lgkmcnt(0)
	v_add_f32_e32 v0, v0, v1
	ds_bpermute_b32 v1, v116, v0
	v_lshl_add_u64 v[6:7], s[4:5], 0, v[16:17]
	s_nop 1
	v_mov_b32_e32 v240, v10
	v_mov_b32_e32 v241, v11
	v_lshl_add_u64 v[244:245], v[8:9], 0, v[246:247]
	global_store_dwordx4 v[18:19], v[2:5], off offset:576
	s_nop 1
	v_cvt_pk_bf16_f32 v2, v2, v3
	v_cvt_pk_bf16_f32 v3, v4, v5
	v_mov_b32_e32 v242, v2
	v_mov_b32_e32 v243, v3
	s_nop 1
	v_permlane16_swap_b32 v240, v242
	v_permlane16_swap_b32 v241, v243
	global_store_dwordx4 v[244:245], v[240:243], off
	s_and_saveexec_b64 s[28:29], s[6:7]
	s_cbranch_execz .LBB0_1800
	v_lshlrev_b64 v[2:3], 6, v[48:49]
	v_lshl_add_u64 v[2:3], s[14:15], 0, v[2:3]
	v_lshl_add_u64 v[2:3], s[26:27], 2, v[2:3]
	s_lshl_b32 s18, s53, 2
	v_lshl_add_u64 v[2:3], v[2:3], 0, s[18:19]
	s_waitcnt lgkmcnt(0)
	v_add_f32_e32 v0, v0, v1
	flat_store_dword v[2:3], v0
	s_branch .LBB0_1800

.LBB0_2164:
	ds_read_b128 v[128:131], v170
	ds_read_b128 v[132:135], v171
	ds_read_b128 v[136:139], v172
	ds_read_b128 v[140:143], v173
	s_add_u32 s34, s30, 0xfffc0080
	s_addc_u32 s35, s31, -1
	s_cmp_eq_u32 s67, 12
	s_cselect_b32 s37, s23, s35
	s_cselect_b32 s36, s29, s34
	s_cselect_b32 s35, s21, s66
	s_cselect_b32 s34, s64, s65
	s_mov_b32 m0, s61
	v_lshl_add_u64 v[212:213], s[30:31], 0, v[156:157]
	ds_read_b128 v[162:165], v151
	ds_read_b128 v[166:169], v151 offset:1024
	ds_read_b128 v[188:191], v151 offset:2048
	ds_read_b128 v[192:195], v151 offset:3072
	ds_read_b128 v[196:199], v151 offset:4096
	ds_read_b128 v[200:203], v151 offset:5120
	ds_read_b128 v[204:207], v151 offset:6144
	ds_read_b128 v[208:211], v151 offset:7168
	global_load_lds_dwordx4 v[212:213], off
	v_lshl_add_u64 v[212:213], s[30:31], 0, v[154:155]
	s_mov_b32 m0, s62
	s_nop 0
	global_load_lds_dwordx4 v[212:213], off
	s_waitcnt lgkmcnt(8)
	s_barrier
	s_waitcnt lgkmcnt(0)
	s_setprio 1
	s_waitcnt lgkmcnt(0)
	v_mfma_f32_16x16x32_bf16 v[124:127], v[128:131], v[162:165], v[124:127]
	v_mfma_f32_16x16x32_bf16 v[120:123], v[136:139], v[162:165], v[120:123]
	v_mfma_f32_16x16x32_bf16 v[108:111], v[128:131], v[188:191], v[108:111]
	v_mfma_f32_16x16x32_bf16 v[104:107], v[136:139], v[188:191], v[104:107]
	v_mfma_f32_16x16x32_bf16 v[92:95], v[128:131], v[196:199], v[92:95]
	v_mfma_f32_16x16x32_bf16 v[88:91], v[136:139], v[196:199], v[88:91]
	v_mfma_f32_16x16x32_bf16 v[76:79], v[128:131], v[204:207], v[76:79]
	v_mfma_f32_16x16x32_bf16 v[72:75], v[136:139], v[204:207], v[72:75]
	v_mfma_f32_16x16x32_bf16 v[124:127], v[132:135], v[166:169], v[124:127]
	v_mfma_f32_16x16x32_bf16 v[120:123], v[140:143], v[166:169], v[120:123]
	v_mfma_f32_16x16x32_bf16 v[108:111], v[132:135], v[192:195], v[108:111]
	v_mfma_f32_16x16x32_bf16 v[104:107], v[140:143], v[192:195], v[104:107]
	v_mfma_f32_16x16x32_bf16 v[92:95], v[132:135], v[200:203], v[92:95]
	v_mfma_f32_16x16x32_bf16 v[88:91], v[140:143], v[200:203], v[88:91]
	v_mfma_f32_16x16x32_bf16 v[76:79], v[132:135], v[208:211], v[76:79]
	v_mfma_f32_16x16x32_bf16 v[72:75], v[140:143], v[208:211], v[72:75]
	s_setprio 0
	s_barrier
	s_mov_b32 m0, s46
	v_lshl_add_u64 v[228:229], s[34:35], 0, v[144:145]
	ds_read_b128 v[212:215], v174
	ds_read_b128 v[216:219], v175
	ds_read_b128 v[220:223], v177
	ds_read_b128 v[224:227], v178
	global_load_lds_dwordx4 v[228:229], off
	v_lshl_add_u64 v[230:231], s[34:35], 0, v[146:147]
	s_mov_b32 m0, s47
	s_nop 0
	global_load_lds_dwordx4 v[230:231], off
	s_barrier
	s_waitcnt lgkmcnt(0)
	s_setprio 1
	s_waitcnt lgkmcnt(0)
	v_mfma_f32_16x16x32_bf16 v[116:119], v[212:215], v[162:165], v[116:119]
	v_mfma_f32_16x16x32_bf16 v[112:115], v[220:223], v[162:165], v[112:115]
	v_mfma_f32_16x16x32_bf16 v[100:103], v[212:215], v[188:191], v[100:103]
	v_mfma_f32_16x16x32_bf16 v[96:99], v[220:223], v[188:191], v[96:99]
	v_mfma_f32_16x16x32_bf16 v[84:87], v[212:215], v[196:199], v[84:87]
	v_mfma_f32_16x16x32_bf16 v[80:83], v[220:223], v[196:199], v[80:83]
	v_mfma_f32_16x16x32_bf16 v[68:71], v[212:215], v[204:207], v[68:71]
	v_mfma_f32_16x16x32_bf16 v[64:67], v[220:223], v[204:207], v[64:67]
	v_mfma_f32_16x16x32_bf16 v[116:119], v[216:219], v[166:169], v[116:119]
	v_mfma_f32_16x16x32_bf16 v[112:115], v[224:227], v[166:169], v[112:115]
	v_mfma_f32_16x16x32_bf16 v[100:103], v[216:219], v[192:195], v[100:103]
	v_mfma_f32_16x16x32_bf16 v[96:99], v[224:227], v[192:195], v[96:99]
	v_mfma_f32_16x16x32_bf16 v[84:87], v[216:219], v[200:203], v[84:87]
	v_mfma_f32_16x16x32_bf16 v[80:83], v[224:227], v[200:203], v[80:83]
	v_mfma_f32_16x16x32_bf16 v[68:71], v[216:219], v[208:211], v[68:71]
	v_mfma_f32_16x16x32_bf16 v[64:67], v[224:227], v[208:211], v[64:67]
	s_setprio 0
	s_mov_b32 m0, s45
	v_lshl_add_u64 v[232:233], s[36:37], 0, v[144:145]
	s_barrier
	ds_read_b128 v[162:165], v151 offset:16384
	ds_read_b128 v[166:169], v151 offset:17408
	ds_read_b128 v[188:191], v151 offset:18432
	ds_read_b128 v[192:195], v151 offset:19456
	ds_read_b128 v[196:199], v151 offset:20480
	ds_read_b128 v[200:203], v151 offset:21504
	ds_read_b128 v[204:207], v151 offset:22528
	ds_read_b128 v[208:211], v151 offset:23552
	global_load_lds_dwordx4 v[232:233], off
	v_lshl_add_u64 v[234:235], s[36:37], 0, v[146:147]
	s_mov_b32 m0, s48
	s_nop 0
	global_load_lds_dwordx4 v[234:235], off
	s_barrier
	s_waitcnt lgkmcnt(0)
	s_setprio 1
	s_waitcnt lgkmcnt(0)
	v_mfma_f32_16x16x32_bf16 v[60:63], v[128:131], v[162:165], v[60:63]
	v_mfma_f32_16x16x32_bf16 v[56:59], v[136:139], v[162:165], v[56:59]
	v_mfma_f32_16x16x32_bf16 v[44:47], v[128:131], v[188:191], v[44:47]
	v_mfma_f32_16x16x32_bf16 v[40:43], v[136:139], v[188:191], v[40:43]
	v_mfma_f32_16x16x32_bf16 v[28:31], v[128:131], v[196:199], v[28:31]
	v_mfma_f32_16x16x32_bf16 v[24:27], v[136:139], v[196:199], v[24:27]
	v_mfma_f32_16x16x32_bf16 v[12:15], v[128:131], v[204:207], v[12:15]
	v_mfma_f32_16x16x32_bf16 v[8:11], v[136:139], v[204:207], v[8:11]
	v_mfma_f32_16x16x32_bf16 v[60:63], v[132:135], v[166:169], v[60:63]
	v_mfma_f32_16x16x32_bf16 v[56:59], v[140:143], v[166:169], v[56:59]
	v_mfma_f32_16x16x32_bf16 v[44:47], v[132:135], v[192:195], v[44:47]
	v_mfma_f32_16x16x32_bf16 v[40:43], v[140:143], v[192:195], v[40:43]
	v_mfma_f32_16x16x32_bf16 v[28:31], v[132:135], v[200:203], v[28:31]
	v_mfma_f32_16x16x32_bf16 v[24:27], v[140:143], v[200:203], v[24:27]
	v_mfma_f32_16x16x32_bf16 v[12:15], v[132:135], v[208:211], v[12:15]
	v_mfma_f32_16x16x32_bf16 v[8:11], v[140:143], v[208:211], v[8:11]
	s_setprio 0
	s_barrier
	s_add_u32 s68, s34, 0x40000
	s_addc_u32 s69, s35, 0
	s_mov_b32 m0, s49
	v_lshl_add_u64 v[128:129], s[68:69], 0, v[144:145]
	global_load_lds_dwordx4 v[128:129], off
	v_lshl_add_u64 v[128:129], s[68:69], 0, v[146:147]
	s_mov_b32 m0, s50
	s_nop 0
	global_load_lds_dwordx4 v[128:129], off
	s_waitcnt vmcnt(6)
	s_barrier
	s_setprio 1
	v_mfma_f32_16x16x32_bf16 v[52:55], v[212:215], v[162:165], v[52:55]
	v_mfma_f32_16x16x32_bf16 v[48:51], v[220:223], v[162:165], v[48:51]
	v_mfma_f32_16x16x32_bf16 v[36:39], v[212:215], v[188:191], v[36:39]
	v_mfma_f32_16x16x32_bf16 v[32:35], v[220:223], v[188:191], v[32:35]
	v_mfma_f32_16x16x32_bf16 v[20:23], v[212:215], v[196:199], v[20:23]
	v_mfma_f32_16x16x32_bf16 v[16:19], v[220:223], v[196:199], v[16:19]
	v_mfma_f32_16x16x32_bf16 v[4:7], v[212:215], v[204:207], v[4:7]
	v_mfma_f32_16x16x32_bf16 v[0:3], v[220:223], v[204:207], v[0:3]
	v_mfma_f32_16x16x32_bf16 v[52:55], v[216:219], v[166:169], v[52:55]
	v_mfma_f32_16x16x32_bf16 v[48:51], v[224:227], v[166:169], v[48:51]
	v_mfma_f32_16x16x32_bf16 v[36:39], v[216:219], v[192:195], v[36:39]
	v_mfma_f32_16x16x32_bf16 v[32:35], v[224:227], v[192:195], v[32:35]
	v_mfma_f32_16x16x32_bf16 v[20:23], v[216:219], v[200:203], v[20:23]
	v_mfma_f32_16x16x32_bf16 v[16:19], v[224:227], v[200:203], v[16:19]
	v_mfma_f32_16x16x32_bf16 v[4:7], v[216:219], v[208:211], v[4:7]
	v_mfma_f32_16x16x32_bf16 v[0:3], v[224:227], v[208:211], v[0:3]
	s_setprio 0
	s_barrier
	ds_read_b128 v[128:131], v179
	ds_read_b128 v[132:135], v180
	ds_read_b128 v[136:139], v181
	ds_read_b128 v[140:143], v182
	s_add_u32 s36, s36, 0x40000
	s_addc_u32 s37, s37, 0
	s_mov_b32 m0, s51
	v_lshl_add_u64 v[212:213], s[36:37], 0, v[144:145]
	ds_read_b128 v[162:165], v151 offset:32768
	ds_read_b128 v[166:169], v151 offset:33792
	ds_read_b128 v[188:191], v151 offset:34816
	ds_read_b128 v[192:195], v151 offset:35840
	ds_read_b128 v[196:199], v151 offset:36864
	ds_read_b128 v[200:203], v151 offset:37888
	ds_read_b128 v[204:207], v151 offset:38912
	ds_read_b128 v[208:211], v151 offset:39936
	global_load_lds_dwordx4 v[212:213], off
	v_lshl_add_u64 v[212:213], s[36:37], 0, v[146:147]
	s_mov_b32 m0, s52
	s_nop 0
	global_load_lds_dwordx4 v[212:213], off
	s_waitcnt lgkmcnt(8)
	s_barrier
	s_waitcnt lgkmcnt(0)
	s_setprio 1
	s_waitcnt lgkmcnt(0)
	v_mfma_f32_16x16x32_bf16 v[124:127], v[128:131], v[162:165], v[124:127]
	v_mfma_f32_16x16x32_bf16 v[120:123], v[136:139], v[162:165], v[120:123]
	v_mfma_f32_16x16x32_bf16 v[108:111], v[128:131], v[188:191], v[108:111]
	v_mfma_f32_16x16x32_bf16 v[104:107], v[136:139], v[188:191], v[104:107]
	v_mfma_f32_16x16x32_bf16 v[92:95], v[128:131], v[196:199], v[92:95]
	v_mfma_f32_16x16x32_bf16 v[88:91], v[136:139], v[196:199], v[88:91]
	v_mfma_f32_16x16x32_bf16 v[76:79], v[128:131], v[204:207], v[76:79]
	v_mfma_f32_16x16x32_bf16 v[72:75], v[136:139], v[204:207], v[72:75]
	v_mfma_f32_16x16x32_bf16 v[124:127], v[132:135], v[166:169], v[124:127]
	v_mfma_f32_16x16x32_bf16 v[120:123], v[140:143], v[166:169], v[120:123]
	v_mfma_f32_16x16x32_bf16 v[108:111], v[132:135], v[192:195], v[108:111]
	v_mfma_f32_16x16x32_bf16 v[104:107], v[140:143], v[192:195], v[104:107]
	v_mfma_f32_16x16x32_bf16 v[92:95], v[132:135], v[200:203], v[92:95]
	v_mfma_f32_16x16x32_bf16 v[88:91], v[140:143], v[200:203], v[88:91]
	v_mfma_f32_16x16x32_bf16 v[76:79], v[132:135], v[208:211], v[76:79]
	v_mfma_f32_16x16x32_bf16 v[72:75], v[140:143], v[208:211], v[72:75]
	s_setprio 0
	s_barrier
	s_mov_b32 m0, s54
	v_lshl_add_u64 v[228:229], v[228:229], 0, s[10:11]
	ds_read_b128 v[212:215], v183
	ds_read_b128 v[216:219], v184
	ds_read_b128 v[220:223], v185
	ds_read_b128 v[224:227], v186
	global_load_lds_dwordx4 v[228:229], off
	v_lshl_add_u64 v[228:229], v[230:231], 0, s[10:11]
	s_mov_b32 m0, s55
	s_nop 0
	global_load_lds_dwordx4 v[228:229], off
	s_barrier
	s_waitcnt lgkmcnt(0)
	s_setprio 1
	s_waitcnt lgkmcnt(0)
	v_mfma_f32_16x16x32_bf16 v[116:119], v[212:215], v[162:165], v[116:119]
	v_mfma_f32_16x16x32_bf16 v[112:115], v[220:223], v[162:165], v[112:115]
	v_mfma_f32_16x16x32_bf16 v[100:103], v[212:215], v[188:191], v[100:103]
	v_mfma_f32_16x16x32_bf16 v[96:99], v[220:223], v[188:191], v[96:99]
	v_mfma_f32_16x16x32_bf16 v[84:87], v[212:215], v[196:199], v[84:87]
	v_mfma_f32_16x16x32_bf16 v[80:83], v[220:223], v[196:199], v[80:83]
	v_mfma_f32_16x16x32_bf16 v[68:71], v[212:215], v[204:207], v[68:71]
	v_mfma_f32_16x16x32_bf16 v[64:67], v[220:223], v[204:207], v[64:67]
	v_mfma_f32_16x16x32_bf16 v[116:119], v[216:219], v[166:169], v[116:119]
	v_mfma_f32_16x16x32_bf16 v[112:115], v[224:227], v[166:169], v[112:115]
	v_mfma_f32_16x16x32_bf16 v[100:103], v[216:219], v[192:195], v[100:103]
	v_mfma_f32_16x16x32_bf16 v[96:99], v[224:227], v[192:195], v[96:99]
	v_mfma_f32_16x16x32_bf16 v[84:87], v[216:219], v[200:203], v[84:87]
	v_mfma_f32_16x16x32_bf16 v[80:83], v[224:227], v[200:203], v[80:83]
	v_mfma_f32_16x16x32_bf16 v[68:71], v[216:219], v[208:211], v[68:71]
	v_mfma_f32_16x16x32_bf16 v[64:67], v[224:227], v[208:211], v[64:67]
	s_setprio 0
	s_mov_b32 m0, s56
	v_lshl_add_u64 v[228:229], v[232:233], 0, s[10:11]
	s_barrier
	ds_read_b128 v[162:165], v151 offset:49152
	ds_read_b128 v[166:169], v151 offset:50176
	ds_read_b128 v[188:191], v151 offset:51200
	ds_read_b128 v[192:195], v151 offset:52224
	ds_read_b128 v[196:199], v151 offset:53248
	ds_read_b128 v[200:203], v151 offset:54272
	ds_read_b128 v[204:207], v151 offset:55296
	ds_read_b128 v[208:211], v151 offset:56320
	global_load_lds_dwordx4 v[228:229], off
	v_lshl_add_u64 v[228:229], v[234:235], 0, s[10:11]
	s_mov_b32 m0, s57
	s_nop 0
	global_load_lds_dwordx4 v[228:229], off
	s_barrier
	s_waitcnt lgkmcnt(0)
	s_setprio 1
	s_waitcnt lgkmcnt(0)
	v_mfma_f32_16x16x32_bf16 v[60:63], v[128:131], v[162:165], v[60:63]
	v_mfma_f32_16x16x32_bf16 v[56:59], v[136:139], v[162:165], v[56:59]
	v_mfma_f32_16x16x32_bf16 v[44:47], v[128:131], v[188:191], v[44:47]
	v_mfma_f32_16x16x32_bf16 v[40:43], v[136:139], v[188:191], v[40:43]
	v_mfma_f32_16x16x32_bf16 v[28:31], v[128:131], v[196:199], v[28:31]
	v_mfma_f32_16x16x32_bf16 v[24:27], v[136:139], v[196:199], v[24:27]
	v_mfma_f32_16x16x32_bf16 v[12:15], v[128:131], v[204:207], v[12:15]
	v_mfma_f32_16x16x32_bf16 v[8:11], v[136:139], v[204:207], v[8:11]
	v_mfma_f32_16x16x32_bf16 v[60:63], v[132:135], v[166:169], v[60:63]
	v_mfma_f32_16x16x32_bf16 v[56:59], v[140:143], v[166:169], v[56:59]
	v_mfma_f32_16x16x32_bf16 v[44:47], v[132:135], v[192:195], v[44:47]
	v_mfma_f32_16x16x32_bf16 v[40:43], v[140:143], v[192:195], v[40:43]
	v_mfma_f32_16x16x32_bf16 v[28:31], v[132:135], v[200:203], v[28:31]
	v_mfma_f32_16x16x32_bf16 v[24:27], v[140:143], v[200:203], v[24:27]
	v_mfma_f32_16x16x32_bf16 v[12:15], v[132:135], v[208:211], v[12:15]
	v_mfma_f32_16x16x32_bf16 v[8:11], v[140:143], v[208:211], v[8:11]
	s_setprio 0
	s_barrier
	s_add_u32 s34, s34, 0x40080
	s_addc_u32 s35, s35, 0
	s_mov_b32 m0, s58
	v_lshl_add_u64 v[128:129], s[34:35], 0, v[144:145]
	global_load_lds_dwordx4 v[128:129], off
	v_lshl_add_u64 v[128:129], s[34:35], 0, v[146:147]
	s_mov_b32 m0, s59
	s_nop 0
	global_load_lds_dwordx4 v[128:129], off
	s_waitcnt vmcnt(6)
	s_barrier
	s_setprio 1
	v_mfma_f32_16x16x32_bf16 v[52:55], v[212:215], v[162:165], v[52:55]
	v_mfma_f32_16x16x32_bf16 v[48:51], v[220:223], v[162:165], v[48:51]
	v_mfma_f32_16x16x32_bf16 v[36:39], v[212:215], v[188:191], v[36:39]
	v_mfma_f32_16x16x32_bf16 v[32:35], v[220:223], v[188:191], v[32:35]
	v_mfma_f32_16x16x32_bf16 v[20:23], v[212:215], v[196:199], v[20:23]
	v_mfma_f32_16x16x32_bf16 v[16:19], v[220:223], v[196:199], v[16:19]
	v_mfma_f32_16x16x32_bf16 v[4:7], v[212:215], v[204:207], v[4:7]
	v_mfma_f32_16x16x32_bf16 v[0:3], v[220:223], v[204:207], v[0:3]
	v_mfma_f32_16x16x32_bf16 v[52:55], v[216:219], v[166:169], v[52:55]
	v_mfma_f32_16x16x32_bf16 v[48:51], v[224:227], v[166:169], v[48:51]
	v_mfma_f32_16x16x32_bf16 v[36:39], v[216:219], v[192:195], v[36:39]
	v_mfma_f32_16x16x32_bf16 v[32:35], v[224:227], v[192:195], v[32:35]
	v_mfma_f32_16x16x32_bf16 v[20:23], v[216:219], v[200:203], v[20:23]
	v_mfma_f32_16x16x32_bf16 v[16:19], v[224:227], v[200:203], v[16:19]
	v_mfma_f32_16x16x32_bf16 v[4:7], v[216:219], v[208:211], v[4:7]
	v_mfma_f32_16x16x32_bf16 v[0:3], v[224:227], v[208:211], v[0:3]
	s_setprio 0
	s_add_i32 s67, s67, 2
	s_add_u32 s65, s65, 0x100
	s_addc_u32 s66, s66, 0
	s_add_u32 s30, s30, 0x100
	s_addc_u32 s31, s31, 0
	s_cmp_gt_u32 s67, 13
	s_barrier
	s_cbranch_scc0 .LBB0_2164
	v_bfe_i32 v249, v176, 3, 1
	v_and_b32_e32 v248, 0xffff8040, v249
	v_mov_b32_e32 v250, 0x8000
	v_mov_b32_e32 v251, 0
	s_ashr_i32 s29, s28, 31
	s_lshl_b64 s[28:29], s[28:29], 8
	s_lshl_b32 s30, s12, 8
	v_lshl_add_u64 v[164:165], s[28:29], 0, v[148:149]
	s_ashr_i32 s31, s30, 31
	v_lshl_add_u64 v[166:167], s[30:31], 2, v[152:153]
	v_lshlrev_b64 v[128:129], 12, v[164:165]
	v_lshl_add_u64 v[128:129], v[166:167], 0, v[128:129]
	v_lshl_add_u64 v[232:233], v[128:129], 0, v[248:249]
	v_lshl_add_u64 v[234:235], v[232:233], 0, v[250:251]
	global_load_dwordx4 v[190:193], v[232:233], off
	global_load_dwordx4 v[194:197], v[234:235], off
	global_load_dwordx4 v[198:201], v[232:233], off offset:512
	global_load_dwordx4 v[202:205], v[234:235], off offset:512
	v_or_b32_e32 v168, 16, v164
	v_mov_b32_e32 v169, v165
	v_lshlrev_b64 v[128:129], 12, v[168:169]
	v_lshl_add_u64 v[128:129], v[166:167], 0, v[128:129]
	v_lshl_add_u64 v[236:237], v[128:129], 0, v[248:249]
	v_lshl_add_u64 v[238:239], v[236:237], 0, v[250:251]
	global_load_dwordx4 v[140:143], v[236:237], off
	global_load_dwordx4 v[136:139], v[238:239], off
	global_load_dwordx4 v[132:135], v[236:237], off offset:512
	s_nop 0
	global_load_dwordx4 v[128:131], v[238:239], off offset:512
	v_and_b32_e32 v163, 64, v187
	v_xor_b32_e32 v188, 16, v187
	v_add_u32_e32 v206, 64, v163
	v_xor_b32_e32 v189, 32, v187
	v_cmp_lt_i32_e32 vcc, v188, v206
	v_or_b32_e32 v162, s30, v150
	v_mov_b32_e32 v163, s31
	v_cndmask_b32_e32 v188, v187, v188, vcc
	v_cmp_lt_i32_e32 vcc, v189, v206
	v_lshlrev_b64 v[206:207], 10, v[164:165]
	v_lshl_add_u64 v[206:207], v[206:207], 0, v[162:163]
	v_lshl_add_u64 v[208:209], v[206:207], 2, s[78:79]
	s_waitcnt vmcnt(0)
	v_lshlrev_b64 v[206:207], 1, v[206:207]
	v_lshl_add_u64 v[210:211], s[2:3], 0, v[206:207]
	v_lshlrev_b32_e32 v188, 2, v188
	v_or_b32_e32 v212, 32, v206
	v_mov_b32_e32 v213, v207
	v_cndmask_b32_e32 v189, v187, v189, vcc
	v_or_b32_e32 v214, 0x100, v206
	v_mov_b32_e32 v215, v207
	v_lshl_add_u64 v[212:213], s[2:3], 0, v[212:213]
	v_lshl_add_u64 v[214:215], s[2:3], 0, v[214:215]
	s_lshl_b32 s28, s12, 2
	v_or_b32_e32 v206, 0x120, v206
	s_ashr_i32 s29, s28, 31
	s_waitcnt vmcnt(0)
	v_mov_b32_dpp v224, v190 row_ror:8 row_mask:0xf bank_mask:0xf
	v_mov_b32_dpp v225, v191 row_ror:8 row_mask:0xf bank_mask:0xf
	v_mov_b32_dpp v226, v192 row_ror:8 row_mask:0xf bank_mask:0xf
	v_mov_b32_dpp v227, v193 row_ror:8 row_mask:0xf bank_mask:0xf
	v_mov_b32_dpp v190, v194 row_ror:8 row_mask:0xf bank_mask:0xc
	v_mov_b32_dpp v191, v195 row_ror:8 row_mask:0xf bank_mask:0xc
	v_mov_b32_dpp v192, v196 row_ror:8 row_mask:0xf bank_mask:0xc
	v_mov_b32_dpp v193, v197 row_ror:8 row_mask:0xf bank_mask:0xc
	v_mov_b32_dpp v194, v224 quad_perm:[0,1,2,3] row_mask:0xf bank_mask:0x3
	v_mov_b32_dpp v195, v225 quad_perm:[0,1,2,3] row_mask:0xf bank_mask:0x3
	v_mov_b32_dpp v196, v226 quad_perm:[0,1,2,3] row_mask:0xf bank_mask:0x3
	v_mov_b32_dpp v197, v227 quad_perm:[0,1,2,3] row_mask:0xf bank_mask:0x3
	v_mov_b32_dpp v224, v198 row_ror:8 row_mask:0xf bank_mask:0xf
	v_mov_b32_dpp v225, v199 row_ror:8 row_mask:0xf bank_mask:0xf
	v_mov_b32_dpp v226, v200 row_ror:8 row_mask:0xf bank_mask:0xf
	v_mov_b32_dpp v227, v201 row_ror:8 row_mask:0xf bank_mask:0xf
	v_mov_b32_dpp v198, v202 row_ror:8 row_mask:0xf bank_mask:0xc
	v_mov_b32_dpp v199, v203 row_ror:8 row_mask:0xf bank_mask:0xc
	v_mov_b32_dpp v200, v204 row_ror:8 row_mask:0xf bank_mask:0xc
	v_mov_b32_dpp v201, v205 row_ror:8 row_mask:0xf bank_mask:0xc
	v_mov_b32_dpp v202, v224 quad_perm:[0,1,2,3] row_mask:0xf bank_mask:0x3
	v_mov_b32_dpp v203, v225 quad_perm:[0,1,2,3] row_mask:0xf bank_mask:0x3
	v_mov_b32_dpp v204, v226 quad_perm:[0,1,2,3] row_mask:0xf bank_mask:0x3
	v_mov_b32_dpp v205, v227 quad_perm:[0,1,2,3] row_mask:0xf bank_mask:0x3
	v_pk_add_f32 v[126:127], v[126:127], v[192:193]
	v_pk_add_f32 v[124:125], v[124:125], v[190:191]
	v_pk_add_f32 v[120:121], v[120:121], v[194:195]
	v_pk_add_f32 v[122:123], v[122:123], v[196:197]
	v_pk_add_f32 v[116:117], v[116:117], v[198:199]
	v_pk_add_f32 v[190:191], v[112:113], v[202:203]
	global_store_dwordx4 v[208:209], v[124:127], off
	v_cvt_pk_bf16_f32 v112, v124, v125
	v_mul_f32_e32 v196, v120, v120
	v_mul_f32_e32 v197, v116, v116
	v_mul_f32_e32 v124, v124, v124
	v_fmac_f32_e32 v124, v125, v125
	v_fmac_f32_e32 v196, v121, v121
	v_pk_add_f32 v[118:119], v[118:119], v[200:201]
	v_mul_f32_e32 v198, v190, v190
	v_fmac_f32_e32 v197, v117, v117
	v_fmac_f32_e32 v124, v126, v126
	v_fmac_f32_e32 v196, v122, v122
	v_pk_add_f32 v[192:193], v[114:115], v[204:205]
	v_fmac_f32_e32 v198, v191, v191
	v_fmac_f32_e32 v197, v118, v118
	v_fmac_f32_e32 v124, v127, v127
	v_fmac_f32_e32 v196, v123, v123
	v_cvt_pk_bf16_f32 v113, v126, v127
	v_bfe_u32 v246, v176, 4, 1
	v_mul_u32_u24_e32 v246, 24, v246
	v_mov_b32_e32 v247, 0
	s_nop 1
	v_mov_b32_e32 v240, v112
	v_mov_b32_e32 v241, v113
	v_lshl_add_u64 v[244:245], v[210:211], 0, v[246:247]
	v_fmac_f32_e32 v198, v192, v192
	v_fmac_f32_e32 v197, v119, v119
	v_add_f32_e32 v112, v124, v196
	v_fmac_f32_e32 v198, v193, v193
	v_add_f32_e32 v112, v112, v197
	v_add_f32_e32 v112, v112, v198
	ds_bpermute_b32 v113, v188, v112
	v_cvt_pk_bf16_f32 v114, v120, v121
	v_cvt_pk_bf16_f32 v115, v122, v123
	v_cvt_pk_bf16_f32 v194, v116, v117
	v_cvt_pk_bf16_f32 v195, v118, v119
	global_store_dwordx4 v[208:209], v[120:123], off offset:64
	v_mov_b32_e32 v242, v114
	v_mov_b32_e32 v243, v115
	s_nop 1
	v_permlane16_swap_b32 v240, v242
	v_permlane16_swap_b32 v241, v243
	global_store_dwordx4 v[244:245], v[240:243], off
	global_store_dwordx4 v[208:209], v[116:119], off offset:512
	s_nop 1
	v_mov_b32_e32 v240, v194
	v_mov_b32_e32 v241, v195
	v_lshl_add_u64 v[244:245], v[214:215], 0, v[246:247]
	global_store_dwordx4 v[208:209], v[190:193], off offset:576
	s_waitcnt lgkmcnt(0)
	v_add_f32_e32 v112, v112, v113
	v_lshlrev_b32_e32 v116, 2, v189
	ds_bpermute_b32 v113, v116, v112
	v_lshl_add_u64 v[114:115], s[2:3], 0, v[206:207]
	v_cvt_pk_bf16_f32 v118, v190, v191
	v_cvt_pk_bf16_f32 v119, v192, v193
	v_mov_b32_e32 v242, v118
	v_mov_b32_e32 v243, v119
	s_nop 1
	v_permlane16_swap_b32 v240, v242
	v_permlane16_swap_b32 v241, v243
	global_store_dwordx4 v[244:245], v[240:243], off
	s_and_saveexec_b64 s[30:31], s[6:7]
	s_cbranch_execz .LBB0_2167
	v_lshlrev_b64 v[114:115], 6, v[164:165]
	v_lshl_add_u64 v[114:115], s[4:5], 0, v[114:115]
	v_lshl_add_u64 v[114:115], s[28:29], 2, v[114:115]
	s_lshl_b32 s12, s53, 2
	v_lshl_add_u64 v[114:115], v[114:115], 0, s[12:13]
	s_waitcnt lgkmcnt(0)
	v_add_f32_e32 v112, v112, v113
	flat_store_dword v[114:115], v112
.LBB0_2167:
	s_or_b64 exec, exec, s[30:31]
	s_waitcnt lgkmcnt(0)
	v_lshlrev_b64 v[112:113], 10, v[168:169]
	v_lshl_add_u64 v[112:113], v[112:113], 0, v[162:163]
	v_mov_b32_dpp v224, v140 row_ror:8 row_mask:0xf bank_mask:0xf
	v_mov_b32_dpp v225, v141 row_ror:8 row_mask:0xf bank_mask:0xf
	v_mov_b32_dpp v226, v142 row_ror:8 row_mask:0xf bank_mask:0xf
	v_mov_b32_dpp v227, v143 row_ror:8 row_mask:0xf bank_mask:0xf
	v_mov_b32_dpp v140, v136 row_ror:8 row_mask:0xf bank_mask:0xc
	v_mov_b32_dpp v141, v137 row_ror:8 row_mask:0xf bank_mask:0xc
	v_mov_b32_dpp v142, v138 row_ror:8 row_mask:0xf bank_mask:0xc
	v_mov_b32_dpp v143, v139 row_ror:8 row_mask:0xf bank_mask:0xc
	v_mov_b32_dpp v136, v224 quad_perm:[0,1,2,3] row_mask:0xf bank_mask:0x3
	v_mov_b32_dpp v137, v225 quad_perm:[0,1,2,3] row_mask:0xf bank_mask:0x3
	v_mov_b32_dpp v138, v226 quad_perm:[0,1,2,3] row_mask:0xf bank_mask:0x3
	v_mov_b32_dpp v139, v227 quad_perm:[0,1,2,3] row_mask:0xf bank_mask:0x3
	v_mov_b32_dpp v224, v132 row_ror:8 row_mask:0xf bank_mask:0xf
	v_mov_b32_dpp v225, v133 row_ror:8 row_mask:0xf bank_mask:0xf
	v_mov_b32_dpp v226, v134 row_ror:8 row_mask:0xf bank_mask:0xf
	v_mov_b32_dpp v227, v135 row_ror:8 row_mask:0xf bank_mask:0xf
	v_mov_b32_dpp v132, v128 row_ror:8 row_mask:0xf bank_mask:0xc
	v_mov_b32_dpp v133, v129 row_ror:8 row_mask:0xf bank_mask:0xc
	v_mov_b32_dpp v134, v130 row_ror:8 row_mask:0xf bank_mask:0xc
	v_mov_b32_dpp v135, v131 row_ror:8 row_mask:0xf bank_mask:0xc
	v_mov_b32_dpp v128, v224 quad_perm:[0,1,2,3] row_mask:0xf bank_mask:0x3
	v_mov_b32_dpp v129, v225 quad_perm:[0,1,2,3] row_mask:0xf bank_mask:0x3
	v_mov_b32_dpp v130, v226 quad_perm:[0,1,2,3] row_mask:0xf bank_mask:0x3
	v_mov_b32_dpp v131, v227 quad_perm:[0,1,2,3] row_mask:0xf bank_mask:0x3
	v_pk_add_f32 v[108:109], v[108:109], v[140:141]
	v_lshl_add_u64 v[114:115], v[112:113], 2, s[78:79]
	v_lshlrev_b64 v[112:113], 1, v[112:113]
	v_mul_f32_e32 v117, v108, v108
	v_pk_add_f32 v[110:111], v[110:111], v[142:143]
	v_lshl_add_u64 v[118:119], s[2:3], 0, v[112:113]
	v_fmac_f32_e32 v117, v109, v109
	v_pk_add_f32 v[106:107], v[106:107], v[138:139]
	v_pk_add_f32 v[104:105], v[104:105], v[136:137]
	global_store_dwordx4 v[114:115], v[108:111], off
	v_cvt_pk_bf16_f32 v120, v108, v109
	v_cvt_pk_bf16_f32 v121, v110, v111
	s_nop 1
	v_mov_b32_e32 v240, v120
	v_mov_b32_e32 v241, v121
	v_lshl_add_u64 v[244:245], v[118:119], 0, v[246:247]
	v_fmac_f32_e32 v117, v110, v110
	global_store_dwordx4 v[114:115], v[104:107], off offset:64
	v_or_b32_e32 v108, 32, v112
	v_mov_b32_e32 v109, v113
	v_cvt_pk_bf16_f32 v110, v104, v105
	v_mul_f32_e32 v104, v104, v104
	v_lshl_add_u64 v[108:109], s[2:3], 0, v[108:109]
	v_fmac_f32_e32 v104, v105, v105
	v_pk_add_f32 v[102:103], v[102:103], v[134:135]
	v_pk_add_f32 v[100:101], v[100:101], v[132:133]
	v_fmac_f32_e32 v117, v111, v111
	v_cvt_pk_bf16_f32 v111, v106, v107
	v_mov_b32_e32 v242, v110
	v_mov_b32_e32 v243, v111
	s_nop 1
	v_permlane16_swap_b32 v240, v242
	v_permlane16_swap_b32 v241, v243
	global_store_dwordx4 v[244:245], v[240:243], off
	v_fmac_f32_e32 v104, v106, v106
	global_store_dwordx4 v[114:115], v[100:103], off offset:512
	v_cvt_pk_bf16_f32 v106, v100, v101
	v_fmac_f32_e32 v104, v107, v107
	v_add_f32_e32 v107, v117, v104
	v_mul_f32_e32 v100, v100, v100
	v_fmac_f32_e32 v100, v101, v101
	v_fmac_f32_e32 v100, v102, v102
	v_fmac_f32_e32 v100, v103, v103
	v_add_f32_e32 v107, v107, v100
	v_pk_add_f32 v[100:101], v[98:99], v[130:131]
	v_pk_add_f32 v[98:99], v[96:97], v[128:129]
	v_or_b32_e32 v104, 0x100, v112
	v_mul_f32_e32 v96, v98, v98
	v_fmac_f32_e32 v96, v99, v99
	v_fmac_f32_e32 v96, v100, v100
	v_fmac_f32_e32 v96, v101, v101
	v_add_f32_e32 v96, v107, v96
	ds_bpermute_b32 v97, v188, v96
	v_mov_b32_e32 v105, v113
	v_or_b32_e32 v112, 0x120, v112
	v_lshl_add_u64 v[104:105], s[2:3], 0, v[104:105]
	v_cvt_pk_bf16_f32 v107, v102, v103
	s_waitcnt lgkmcnt(0)
	v_add_f32_e32 v96, v96, v97
	ds_bpermute_b32 v97, v116, v96
	v_lshl_add_u64 v[102:103], s[2:3], 0, v[112:113]
	s_nop 1
	v_mov_b32_e32 v240, v106
	v_mov_b32_e32 v241, v107
	v_lshl_add_u64 v[244:245], v[104:105], 0, v[246:247]
	global_store_dwordx4 v[114:115], v[98:101], off offset:576
	s_nop 1
	v_cvt_pk_bf16_f32 v98, v98, v99
	v_cvt_pk_bf16_f32 v99, v100, v101
	v_mov_b32_e32 v242, v98
	v_mov_b32_e32 v243, v99
	s_nop 1
	v_permlane16_swap_b32 v240, v242
	v_permlane16_swap_b32 v241, v243
	global_store_dwordx4 v[244:245], v[240:243], off
	s_and_saveexec_b64 s[30:31], s[6:7]
	s_cbranch_execz .LBB0_2169
	v_lshlrev_b64 v[98:99], 6, v[168:169]
	v_lshl_add_u64 v[98:99], s[4:5], 0, v[98:99]
	v_lshl_add_u64 v[98:99], s[28:29], 2, v[98:99]
	s_lshl_b32 s12, s53, 2
	v_lshl_add_u64 v[98:99], v[98:99], 0, s[12:13]
	s_waitcnt lgkmcnt(0)
	v_add_f32_e32 v96, v96, v97
	flat_store_dword v[98:99], v96
.LBB0_2169:
	s_or_b64 exec, exec, s[30:31]
	v_or_b32_e32 v114, 32, v164
	v_mov_b32_e32 v115, v165
	s_waitcnt lgkmcnt(0)
	v_lshlrev_b64 v[96:97], 12, v[114:115]
	v_lshl_add_u64 v[96:97], v[166:167], 0, v[96:97]
	v_lshl_add_u64 v[232:233], v[96:97], 0, v[248:249]
	v_lshl_add_u64 v[234:235], v[232:233], 0, v[250:251]
	global_load_dwordx4 v[118:121], v[232:233], off
	global_load_dwordx4 v[122:125], v[234:235], off
	global_load_dwordx4 v[126:129], v[232:233], off offset:512
	global_load_dwordx4 v[130:133], v[234:235], off offset:512
	v_or_b32_e32 v112, 48, v164
	v_mov_b32_e32 v113, v165
	v_lshlrev_b64 v[96:97], 12, v[112:113]
	v_lshl_add_u64 v[96:97], v[166:167], 0, v[96:97]
	v_lshl_add_u64 v[236:237], v[96:97], 0, v[248:249]
	v_lshl_add_u64 v[238:239], v[236:237], 0, v[250:251]
	global_load_dwordx4 v[108:111], v[236:237], off
	global_load_dwordx4 v[104:107], v[238:239], off
	global_load_dwordx4 v[100:103], v[236:237], off offset:512
	s_nop 0
	global_load_dwordx4 v[96:99], v[238:239], off offset:512
	v_lshlrev_b64 v[134:135], 10, v[114:115]
	v_lshl_add_u64 v[134:135], v[134:135], 0, v[162:163]
	v_lshl_add_u64 v[136:137], v[134:135], 2, s[78:79]
	v_lshlrev_b64 v[134:135], 1, v[134:135]
	v_lshl_add_u64 v[138:139], s[2:3], 0, v[134:135]
	s_waitcnt vmcnt(0)
	v_or_b32_e32 v140, 32, v134
	v_mov_b32_e32 v141, v135
	v_or_b32_e32 v142, 0x100, v134
	v_mov_b32_e32 v143, v135
	v_or_b32_e32 v134, 0x120, v134
	v_lshl_add_u64 v[140:141], s[2:3], 0, v[140:141]
	v_lshl_add_u64 v[142:143], s[2:3], 0, v[142:143]
	s_waitcnt vmcnt(0)
	v_mov_b32_dpp v224, v118 row_ror:8 row_mask:0xf bank_mask:0xf
	v_mov_b32_dpp v225, v119 row_ror:8 row_mask:0xf bank_mask:0xf
	v_mov_b32_dpp v226, v120 row_ror:8 row_mask:0xf bank_mask:0xf
	v_mov_b32_dpp v227, v121 row_ror:8 row_mask:0xf bank_mask:0xf
	v_mov_b32_dpp v118, v122 row_ror:8 row_mask:0xf bank_mask:0xc
	v_mov_b32_dpp v119, v123 row_ror:8 row_mask:0xf bank_mask:0xc
	v_mov_b32_dpp v120, v124 row_ror:8 row_mask:0xf bank_mask:0xc
	v_mov_b32_dpp v121, v125 row_ror:8 row_mask:0xf bank_mask:0xc
	v_mov_b32_dpp v122, v224 quad_perm:[0,1,2,3] row_mask:0xf bank_mask:0x3
	v_mov_b32_dpp v123, v225 quad_perm:[0,1,2,3] row_mask:0xf bank_mask:0x3
	v_mov_b32_dpp v124, v226 quad_perm:[0,1,2,3] row_mask:0xf bank_mask:0x3
	v_mov_b32_dpp v125, v227 quad_perm:[0,1,2,3] row_mask:0xf bank_mask:0x3
	v_mov_b32_dpp v224, v126 row_ror:8 row_mask:0xf bank_mask:0xf
	v_mov_b32_dpp v225, v127 row_ror:8 row_mask:0xf bank_mask:0xf
	v_mov_b32_dpp v226, v128 row_ror:8 row_mask:0xf bank_mask:0xf
	v_mov_b32_dpp v227, v129 row_ror:8 row_mask:0xf bank_mask:0xf
	v_mov_b32_dpp v126, v130 row_ror:8 row_mask:0xf bank_mask:0xc
	v_mov_b32_dpp v127, v131 row_ror:8 row_mask:0xf bank_mask:0xc
	v_mov_b32_dpp v128, v132 row_ror:8 row_mask:0xf bank_mask:0xc
	v_mov_b32_dpp v129, v133 row_ror:8 row_mask:0xf bank_mask:0xc
	v_mov_b32_dpp v130, v224 quad_perm:[0,1,2,3] row_mask:0xf bank_mask:0x3
	v_mov_b32_dpp v131, v225 quad_perm:[0,1,2,3] row_mask:0xf bank_mask:0x3
	v_mov_b32_dpp v132, v226 quad_perm:[0,1,2,3] row_mask:0xf bank_mask:0x3
	v_mov_b32_dpp v133, v227 quad_perm:[0,1,2,3] row_mask:0xf bank_mask:0x3
	v_pk_add_f32 v[92:93], v[92:93], v[118:119]
	v_pk_add_f32 v[88:89], v[88:89], v[122:123]
	v_pk_add_f32 v[84:85], v[84:85], v[126:127]
	v_mul_f32_e32 v117, v92, v92
	v_mul_f32_e32 v122, v88, v88
	v_pk_add_f32 v[94:95], v[94:95], v[120:121]
	v_pk_add_f32 v[90:91], v[90:91], v[124:125]
	v_pk_add_f32 v[118:119], v[80:81], v[130:131]
	v_mul_f32_e32 v123, v84, v84
	v_fmac_f32_e32 v117, v93, v93
	v_fmac_f32_e32 v122, v89, v89
	v_pk_add_f32 v[86:87], v[86:87], v[128:129]
	v_mul_f32_e32 v124, v118, v118
	v_fmac_f32_e32 v123, v85, v85
	v_fmac_f32_e32 v117, v94, v94
	v_fmac_f32_e32 v122, v90, v90
	v_pk_add_f32 v[120:121], v[82:83], v[132:133]
	v_cvt_pk_bf16_f32 v80, v92, v93
	v_fmac_f32_e32 v124, v119, v119
	v_fmac_f32_e32 v123, v86, v86
	v_fmac_f32_e32 v117, v95, v95
	v_fmac_f32_e32 v122, v91, v91
	global_store_dwordx4 v[136:137], v[92:95], off
	v_cvt_pk_bf16_f32 v81, v94, v95
	s_nop 1
	v_mov_b32_e32 v240, v80
	v_mov_b32_e32 v241, v81
	v_lshl_add_u64 v[244:245], v[138:139], 0, v[246:247]
	v_fmac_f32_e32 v124, v120, v120
	v_fmac_f32_e32 v123, v87, v87
	v_add_f32_e32 v80, v117, v122
	v_add_f32_e32 v80, v80, v123
	v_fmac_f32_e32 v124, v121, v121
	v_add_f32_e32 v80, v80, v124
	ds_bpermute_b32 v81, v188, v80
	v_cvt_pk_bf16_f32 v82, v88, v89
	v_cvt_pk_bf16_f32 v83, v90, v91
	v_cvt_pk_bf16_f32 v92, v84, v85
	global_store_dwordx4 v[136:137], v[88:91], off offset:64
	v_mov_b32_e32 v242, v82
	v_mov_b32_e32 v243, v83
	s_nop 1
	v_permlane16_swap_b32 v240, v242
	v_permlane16_swap_b32 v241, v243
	global_store_dwordx4 v[244:245], v[240:243], off
	s_waitcnt lgkmcnt(0)
	v_add_f32_e32 v80, v80, v81
	ds_bpermute_b32 v81, v116, v80
	v_cvt_pk_bf16_f32 v93, v86, v87
	v_lshl_add_u64 v[82:83], s[2:3], 0, v[134:135]
	global_store_dwordx4 v[136:137], v[84:87], off offset:512
	s_nop 1
	v_mov_b32_e32 v240, v92
	v_mov_b32_e32 v241, v93
	v_lshl_add_u64 v[244:245], v[142:143], 0, v[246:247]
	global_store_dwordx4 v[136:137], v[118:121], off offset:576
	v_cvt_pk_bf16_f32 v84, v118, v119
	v_cvt_pk_bf16_f32 v85, v120, v121
	v_mov_b32_e32 v242, v84
	v_mov_b32_e32 v243, v85
	s_nop 1
	v_permlane16_swap_b32 v240, v242
	v_permlane16_swap_b32 v241, v243
	global_store_dwordx4 v[244:245], v[240:243], off
	s_and_saveexec_b64 s[30:31], s[6:7]
	s_cbranch_execz .LBB0_2171
	v_lshlrev_b64 v[82:83], 6, v[114:115]
	v_lshl_add_u64 v[82:83], s[4:5], 0, v[82:83]
	v_lshl_add_u64 v[82:83], s[28:29], 2, v[82:83]
	s_lshl_b32 s12, s53, 2
	v_lshl_add_u64 v[82:83], v[82:83], 0, s[12:13]
	s_waitcnt lgkmcnt(0)
	v_add_f32_e32 v80, v80, v81
	flat_store_dword v[82:83], v80
.LBB0_2171:
	s_or_b64 exec, exec, s[30:31]
	s_waitcnt lgkmcnt(0)
	v_lshlrev_b64 v[80:81], 10, v[112:113]
	v_lshl_add_u64 v[80:81], v[80:81], 0, v[162:163]
	v_lshl_add_u64 v[82:83], v[80:81], 2, s[78:79]
	v_lshlrev_b64 v[80:81], 1, v[80:81]
	v_mov_b32_dpp v224, v108 row_ror:8 row_mask:0xf bank_mask:0xf
	v_mov_b32_dpp v225, v109 row_ror:8 row_mask:0xf bank_mask:0xf
	v_mov_b32_dpp v226, v110 row_ror:8 row_mask:0xf bank_mask:0xf
	v_mov_b32_dpp v227, v111 row_ror:8 row_mask:0xf bank_mask:0xf
	v_mov_b32_dpp v108, v104 row_ror:8 row_mask:0xf bank_mask:0xc
	v_mov_b32_dpp v109, v105 row_ror:8 row_mask:0xf bank_mask:0xc
	v_mov_b32_dpp v110, v106 row_ror:8 row_mask:0xf bank_mask:0xc
	v_mov_b32_dpp v111, v107 row_ror:8 row_mask:0xf bank_mask:0xc
	v_mov_b32_dpp v104, v224 quad_perm:[0,1,2,3] row_mask:0xf bank_mask:0x3
	v_mov_b32_dpp v105, v225 quad_perm:[0,1,2,3] row_mask:0xf bank_mask:0x3
	v_mov_b32_dpp v106, v226 quad_perm:[0,1,2,3] row_mask:0xf bank_mask:0x3
	v_mov_b32_dpp v107, v227 quad_perm:[0,1,2,3] row_mask:0xf bank_mask:0x3
	v_mov_b32_dpp v224, v100 row_ror:8 row_mask:0xf bank_mask:0xf
	v_mov_b32_dpp v225, v101 row_ror:8 row_mask:0xf bank_mask:0xf
	v_mov_b32_dpp v226, v102 row_ror:8 row_mask:0xf bank_mask:0xf
	v_mov_b32_dpp v227, v103 row_ror:8 row_mask:0xf bank_mask:0xf
	v_mov_b32_dpp v100, v96 row_ror:8 row_mask:0xf bank_mask:0xc
	v_mov_b32_dpp v101, v97 row_ror:8 row_mask:0xf bank_mask:0xc
	v_mov_b32_dpp v102, v98 row_ror:8 row_mask:0xf bank_mask:0xc
	v_mov_b32_dpp v103, v99 row_ror:8 row_mask:0xf bank_mask:0xc
	v_mov_b32_dpp v96, v224 quad_perm:[0,1,2,3] row_mask:0xf bank_mask:0x3
	v_mov_b32_dpp v97, v225 quad_perm:[0,1,2,3] row_mask:0xf bank_mask:0x3
	v_mov_b32_dpp v98, v226 quad_perm:[0,1,2,3] row_mask:0xf bank_mask:0x3
	v_mov_b32_dpp v99, v227 quad_perm:[0,1,2,3] row_mask:0xf bank_mask:0x3
	v_pk_add_f32 v[78:79], v[78:79], v[110:111]
	v_pk_add_f32 v[76:77], v[76:77], v[108:109]
	v_lshl_add_u64 v[84:85], s[2:3], 0, v[80:81]
	global_store_dwordx4 v[82:83], v[76:79], off
	v_cvt_pk_bf16_f32 v86, v76, v77
	v_cvt_pk_bf16_f32 v87, v78, v79
	s_nop 1
	v_mov_b32_e32 v240, v86
	v_mov_b32_e32 v241, v87
	v_lshl_add_u64 v[244:245], v[84:85], 0, v[246:247]
	v_mul_f32_e32 v84, v76, v76
	v_fmac_f32_e32 v84, v77, v77
	v_pk_add_f32 v[74:75], v[74:75], v[106:107]
	v_pk_add_f32 v[72:73], v[72:73], v[104:105]
	v_fmac_f32_e32 v84, v78, v78
	global_store_dwordx4 v[82:83], v[72:75], off offset:64
	v_or_b32_e32 v76, 32, v80
	v_mov_b32_e32 v77, v81
	v_cvt_pk_bf16_f32 v78, v72, v73
	v_mul_f32_e32 v72, v72, v72
	v_lshl_add_u64 v[76:77], s[2:3], 0, v[76:77]
	v_fmac_f32_e32 v72, v73, v73
	v_pk_add_f32 v[70:71], v[70:71], v[102:103]
	v_pk_add_f32 v[68:69], v[68:69], v[100:101]
	v_fmac_f32_e32 v84, v79, v79
	v_cvt_pk_bf16_f32 v79, v74, v75
	v_mov_b32_e32 v242, v78
	v_mov_b32_e32 v243, v79
	s_nop 1
	v_permlane16_swap_b32 v240, v242
	v_permlane16_swap_b32 v241, v243
	global_store_dwordx4 v[244:245], v[240:243], off
	v_fmac_f32_e32 v72, v74, v74
	global_store_dwordx4 v[82:83], v[68:71], off offset:512
	v_cvt_pk_bf16_f32 v74, v68, v69
	v_fmac_f32_e32 v72, v75, v75
	v_add_f32_e32 v75, v84, v72
	v_mul_f32_e32 v68, v68, v68
	v_fmac_f32_e32 v68, v69, v69
	v_fmac_f32_e32 v68, v70, v70
	v_fmac_f32_e32 v68, v71, v71
	v_add_f32_e32 v75, v75, v68
	v_pk_add_f32 v[68:69], v[66:67], v[98:99]
	v_pk_add_f32 v[66:67], v[64:65], v[96:97]
	v_or_b32_e32 v72, 0x100, v80
	v_mul_f32_e32 v64, v66, v66
	v_fmac_f32_e32 v64, v67, v67
	v_fmac_f32_e32 v64, v68, v68
	v_fmac_f32_e32 v64, v69, v69
	v_add_f32_e32 v64, v75, v64
	ds_bpermute_b32 v65, v188, v64
	v_mov_b32_e32 v73, v81
	v_or_b32_e32 v80, 0x120, v80
	v_lshl_add_u64 v[72:73], s[2:3], 0, v[72:73]
	v_cvt_pk_bf16_f32 v75, v70, v71
	s_waitcnt lgkmcnt(0)
	v_add_f32_e32 v64, v64, v65
	ds_bpermute_b32 v65, v116, v64
	v_lshl_add_u64 v[70:71], s[2:3], 0, v[80:81]
	s_nop 1
	v_mov_b32_e32 v240, v74
	v_mov_b32_e32 v241, v75
	v_lshl_add_u64 v[244:245], v[72:73], 0, v[246:247]
	global_store_dwordx4 v[82:83], v[66:69], off offset:576
	s_nop 1
	v_cvt_pk_bf16_f32 v66, v66, v67
	v_cvt_pk_bf16_f32 v67, v68, v69
	v_mov_b32_e32 v242, v66
	v_mov_b32_e32 v243, v67
	s_nop 1
	v_permlane16_swap_b32 v240, v242
	v_permlane16_swap_b32 v241, v243
	global_store_dwordx4 v[244:245], v[240:243], off
	s_and_saveexec_b64 s[30:31], s[6:7]
	s_cbranch_execz .LBB0_2173
	v_lshlrev_b64 v[66:67], 6, v[112:113]
	v_lshl_add_u64 v[66:67], s[4:5], 0, v[66:67]
	v_lshl_add_u64 v[66:67], s[28:29], 2, v[66:67]
	s_lshl_b32 s12, s53, 2
	v_lshl_add_u64 v[66:67], v[66:67], 0, s[12:13]
	s_waitcnt lgkmcnt(0)
	v_add_f32_e32 v64, v64, v65
	flat_store_dword v[66:67], v64
.LBB0_2173:
	s_or_b64 exec, exec, s[30:31]
	v_lshl_add_u64 v[82:83], v[164:165], 0, s[10:11]
	s_waitcnt lgkmcnt(0)
	v_lshlrev_b64 v[64:65], 12, v[82:83]
	v_lshl_add_u64 v[64:65], v[166:167], 0, v[64:65]
	v_lshl_add_u64 v[232:233], v[64:65], 0, v[248:249]
	v_lshl_add_u64 v[234:235], v[232:233], 0, v[250:251]
	global_load_dwordx4 v[84:87], v[232:233], off
	global_load_dwordx4 v[88:91], v[234:235], off
	global_load_dwordx4 v[92:95], v[232:233], off offset:512
	global_load_dwordx4 v[96:99], v[234:235], off offset:512
	v_lshl_add_u64 v[80:81], v[164:165], 0, s[14:15]
	v_lshlrev_b64 v[64:65], 12, v[80:81]
	v_lshl_add_u64 v[64:65], v[166:167], 0, v[64:65]
	v_lshl_add_u64 v[236:237], v[64:65], 0, v[248:249]
	v_lshl_add_u64 v[238:239], v[236:237], 0, v[250:251]
	global_load_dwordx4 v[76:79], v[236:237], off
	global_load_dwordx4 v[72:75], v[238:239], off
	global_load_dwordx4 v[68:71], v[236:237], off offset:512
	s_nop 0
	global_load_dwordx4 v[64:67], v[238:239], off offset:512
	v_lshlrev_b64 v[100:101], 10, v[82:83]
	v_lshl_add_u64 v[100:101], v[100:101], 0, v[162:163]
	v_lshl_add_u64 v[102:103], v[100:101], 2, s[78:79]
	v_lshlrev_b64 v[100:101], 1, v[100:101]
	v_lshl_add_u64 v[104:105], s[2:3], 0, v[100:101]
	s_waitcnt vmcnt(0)
	v_or_b32_e32 v106, 32, v100
	v_mov_b32_e32 v107, v101
	v_or_b32_e32 v108, 0x100, v100
	v_mov_b32_e32 v109, v101
	v_or_b32_e32 v100, 0x120, v100
	v_lshl_add_u64 v[106:107], s[2:3], 0, v[106:107]
	v_lshl_add_u64 v[108:109], s[2:3], 0, v[108:109]
	s_waitcnt vmcnt(0)
	v_mov_b32_dpp v224, v84 row_ror:8 row_mask:0xf bank_mask:0xf
	v_mov_b32_dpp v225, v85 row_ror:8 row_mask:0xf bank_mask:0xf
	v_mov_b32_dpp v226, v86 row_ror:8 row_mask:0xf bank_mask:0xf
	v_mov_b32_dpp v227, v87 row_ror:8 row_mask:0xf bank_mask:0xf
	v_mov_b32_dpp v84, v88 row_ror:8 row_mask:0xf bank_mask:0xc
	v_mov_b32_dpp v85, v89 row_ror:8 row_mask:0xf bank_mask:0xc
	v_mov_b32_dpp v86, v90 row_ror:8 row_mask:0xf bank_mask:0xc
	v_mov_b32_dpp v87, v91 row_ror:8 row_mask:0xf bank_mask:0xc
	v_mov_b32_dpp v88, v224 quad_perm:[0,1,2,3] row_mask:0xf bank_mask:0x3
	v_mov_b32_dpp v89, v225 quad_perm:[0,1,2,3] row_mask:0xf bank_mask:0x3
	v_mov_b32_dpp v90, v226 quad_perm:[0,1,2,3] row_mask:0xf bank_mask:0x3
	v_mov_b32_dpp v91, v227 quad_perm:[0,1,2,3] row_mask:0xf bank_mask:0x3
	v_mov_b32_dpp v224, v92 row_ror:8 row_mask:0xf bank_mask:0xf
	v_mov_b32_dpp v225, v93 row_ror:8 row_mask:0xf bank_mask:0xf
	v_mov_b32_dpp v226, v94 row_ror:8 row_mask:0xf bank_mask:0xf
	v_mov_b32_dpp v227, v95 row_ror:8 row_mask:0xf bank_mask:0xf
	v_mov_b32_dpp v92, v96 row_ror:8 row_mask:0xf bank_mask:0xc
	v_mov_b32_dpp v93, v97 row_ror:8 row_mask:0xf bank_mask:0xc
	v_mov_b32_dpp v94, v98 row_ror:8 row_mask:0xf bank_mask:0xc
	v_mov_b32_dpp v95, v99 row_ror:8 row_mask:0xf bank_mask:0xc
	v_mov_b32_dpp v96, v224 quad_perm:[0,1,2,3] row_mask:0xf bank_mask:0x3
	v_mov_b32_dpp v97, v225 quad_perm:[0,1,2,3] row_mask:0xf bank_mask:0x3
	v_mov_b32_dpp v98, v226 quad_perm:[0,1,2,3] row_mask:0xf bank_mask:0x3
	v_mov_b32_dpp v99, v227 quad_perm:[0,1,2,3] row_mask:0xf bank_mask:0x3
	v_pk_add_f32 v[60:61], v[60:61], v[84:85]
	v_pk_add_f32 v[56:57], v[56:57], v[88:89]
	v_pk_add_f32 v[52:53], v[52:53], v[92:93]
	v_mul_f32_e32 v88, v60, v60
	v_mul_f32_e32 v89, v56, v56
	v_pk_add_f32 v[62:63], v[62:63], v[86:87]
	v_pk_add_f32 v[58:59], v[58:59], v[90:91]
	v_pk_add_f32 v[84:85], v[48:49], v[96:97]
	v_mul_f32_e32 v90, v52, v52
	v_fmac_f32_e32 v88, v61, v61
	v_fmac_f32_e32 v89, v57, v57
	v_pk_add_f32 v[54:55], v[54:55], v[94:95]
	v_mul_f32_e32 v91, v84, v84
	v_fmac_f32_e32 v90, v53, v53
	v_fmac_f32_e32 v88, v62, v62
	v_fmac_f32_e32 v89, v58, v58
	v_pk_add_f32 v[86:87], v[50:51], v[98:99]
	v_cvt_pk_bf16_f32 v48, v60, v61
	v_fmac_f32_e32 v91, v85, v85
	v_fmac_f32_e32 v90, v54, v54
	v_fmac_f32_e32 v88, v63, v63
	v_fmac_f32_e32 v89, v59, v59
	global_store_dwordx4 v[102:103], v[60:63], off
	v_cvt_pk_bf16_f32 v49, v62, v63
	s_nop 1
	v_mov_b32_e32 v240, v48
	v_mov_b32_e32 v241, v49
	v_lshl_add_u64 v[244:245], v[104:105], 0, v[246:247]
	v_fmac_f32_e32 v91, v86, v86
	v_fmac_f32_e32 v90, v55, v55
	v_add_f32_e32 v48, v88, v89
	v_add_f32_e32 v48, v48, v90
	v_fmac_f32_e32 v91, v87, v87
	v_add_f32_e32 v48, v48, v91
	ds_bpermute_b32 v49, v188, v48
	v_cvt_pk_bf16_f32 v50, v56, v57
	v_cvt_pk_bf16_f32 v51, v58, v59
	v_cvt_pk_bf16_f32 v60, v52, v53
	global_store_dwordx4 v[102:103], v[56:59], off offset:64
	v_mov_b32_e32 v242, v50
	v_mov_b32_e32 v243, v51
	s_nop 1
	v_permlane16_swap_b32 v240, v242
	v_permlane16_swap_b32 v241, v243
	global_store_dwordx4 v[244:245], v[240:243], off
	s_waitcnt lgkmcnt(0)
	v_add_f32_e32 v48, v48, v49
	ds_bpermute_b32 v49, v116, v48
	v_cvt_pk_bf16_f32 v61, v54, v55
	v_lshl_add_u64 v[50:51], s[2:3], 0, v[100:101]
	global_store_dwordx4 v[102:103], v[52:55], off offset:512
	s_nop 1
	v_mov_b32_e32 v240, v60
	v_mov_b32_e32 v241, v61
	v_lshl_add_u64 v[244:245], v[108:109], 0, v[246:247]
	global_store_dwordx4 v[102:103], v[84:87], off offset:576
	v_cvt_pk_bf16_f32 v52, v84, v85
	v_cvt_pk_bf16_f32 v53, v86, v87
	v_mov_b32_e32 v242, v52
	v_mov_b32_e32 v243, v53
	s_nop 1
	v_permlane16_swap_b32 v240, v242
	v_permlane16_swap_b32 v241, v243
	global_store_dwordx4 v[244:245], v[240:243], off
	s_and_saveexec_b64 s[30:31], s[6:7]
	s_cbranch_execz .LBB0_2175
	v_lshlrev_b64 v[50:51], 6, v[82:83]
	v_lshl_add_u64 v[50:51], s[4:5], 0, v[50:51]
	v_lshl_add_u64 v[50:51], s[28:29], 2, v[50:51]
	s_lshl_b32 s12, s53, 2
	v_lshl_add_u64 v[50:51], v[50:51], 0, s[12:13]
	s_waitcnt lgkmcnt(0)
	v_add_f32_e32 v48, v48, v49
	flat_store_dword v[50:51], v48
.LBB0_2175:
	s_or_b64 exec, exec, s[30:31]
	s_waitcnt lgkmcnt(0)
	v_lshlrev_b64 v[48:49], 10, v[80:81]
	v_lshl_add_u64 v[48:49], v[48:49], 0, v[162:163]
	v_lshl_add_u64 v[50:51], v[48:49], 2, s[78:79]
	v_lshlrev_b64 v[48:49], 1, v[48:49]
	v_mov_b32_dpp v224, v76 row_ror:8 row_mask:0xf bank_mask:0xf
	v_mov_b32_dpp v225, v77 row_ror:8 row_mask:0xf bank_mask:0xf
	v_mov_b32_dpp v226, v78 row_ror:8 row_mask:0xf bank_mask:0xf
	v_mov_b32_dpp v227, v79 row_ror:8 row_mask:0xf bank_mask:0xf
	v_mov_b32_dpp v76, v72 row_ror:8 row_mask:0xf bank_mask:0xc
	v_mov_b32_dpp v77, v73 row_ror:8 row_mask:0xf bank_mask:0xc
	v_mov_b32_dpp v78, v74 row_ror:8 row_mask:0xf bank_mask:0xc
	v_mov_b32_dpp v79, v75 row_ror:8 row_mask:0xf bank_mask:0xc
	v_mov_b32_dpp v72, v224 quad_perm:[0,1,2,3] row_mask:0xf bank_mask:0x3
	v_mov_b32_dpp v73, v225 quad_perm:[0,1,2,3] row_mask:0xf bank_mask:0x3
	v_mov_b32_dpp v74, v226 quad_perm:[0,1,2,3] row_mask:0xf bank_mask:0x3
	v_mov_b32_dpp v75, v227 quad_perm:[0,1,2,3] row_mask:0xf bank_mask:0x3
	v_mov_b32_dpp v224, v68 row_ror:8 row_mask:0xf bank_mask:0xf
	v_mov_b32_dpp v225, v69 row_ror:8 row_mask:0xf bank_mask:0xf
	v_mov_b32_dpp v226, v70 row_ror:8 row_mask:0xf bank_mask:0xf
	v_mov_b32_dpp v227, v71 row_ror:8 row_mask:0xf bank_mask:0xf
	v_mov_b32_dpp v68, v64 row_ror:8 row_mask:0xf bank_mask:0xc
	v_mov_b32_dpp v69, v65 row_ror:8 row_mask:0xf bank_mask:0xc
	v_mov_b32_dpp v70, v66 row_ror:8 row_mask:0xf bank_mask:0xc
	v_mov_b32_dpp v71, v67 row_ror:8 row_mask:0xf bank_mask:0xc
	v_mov_b32_dpp v64, v224 quad_perm:[0,1,2,3] row_mask:0xf bank_mask:0x3
	v_mov_b32_dpp v65, v225 quad_perm:[0,1,2,3] row_mask:0xf bank_mask:0x3
	v_mov_b32_dpp v66, v226 quad_perm:[0,1,2,3] row_mask:0xf bank_mask:0x3
	v_mov_b32_dpp v67, v227 quad_perm:[0,1,2,3] row_mask:0xf bank_mask:0x3
	v_pk_add_f32 v[46:47], v[46:47], v[78:79]
	v_pk_add_f32 v[44:45], v[44:45], v[76:77]
	v_lshl_add_u64 v[52:53], s[2:3], 0, v[48:49]
	global_store_dwordx4 v[50:51], v[44:47], off
	v_cvt_pk_bf16_f32 v54, v44, v45
	v_cvt_pk_bf16_f32 v55, v46, v47
	s_nop 1
	v_mov_b32_e32 v240, v54
	v_mov_b32_e32 v241, v55
	v_lshl_add_u64 v[244:245], v[52:53], 0, v[246:247]
	v_mul_f32_e32 v52, v44, v44
	v_fmac_f32_e32 v52, v45, v45
	v_pk_add_f32 v[42:43], v[42:43], v[74:75]
	v_pk_add_f32 v[40:41], v[40:41], v[72:73]
	v_fmac_f32_e32 v52, v46, v46
	global_store_dwordx4 v[50:51], v[40:43], off offset:64
	v_or_b32_e32 v44, 32, v48
	v_mov_b32_e32 v45, v49
	v_cvt_pk_bf16_f32 v46, v40, v41
	v_mul_f32_e32 v40, v40, v40
	v_lshl_add_u64 v[44:45], s[2:3], 0, v[44:45]
	v_fmac_f32_e32 v40, v41, v41
	v_pk_add_f32 v[38:39], v[38:39], v[70:71]
	v_pk_add_f32 v[36:37], v[36:37], v[68:69]
	v_fmac_f32_e32 v52, v47, v47
	v_cvt_pk_bf16_f32 v47, v42, v43
	v_mov_b32_e32 v242, v46
	v_mov_b32_e32 v243, v47
	s_nop 1
	v_permlane16_swap_b32 v240, v242
	v_permlane16_swap_b32 v241, v243
	global_store_dwordx4 v[244:245], v[240:243], off
	v_fmac_f32_e32 v40, v42, v42
	global_store_dwordx4 v[50:51], v[36:39], off offset:512
	v_cvt_pk_bf16_f32 v42, v36, v37
	v_fmac_f32_e32 v40, v43, v43
	v_add_f32_e32 v43, v52, v40
	v_mul_f32_e32 v36, v36, v36
	v_fmac_f32_e32 v36, v37, v37
	v_fmac_f32_e32 v36, v38, v38
	v_fmac_f32_e32 v36, v39, v39
	v_add_f32_e32 v43, v43, v36
	v_pk_add_f32 v[36:37], v[34:35], v[66:67]
	v_pk_add_f32 v[34:35], v[32:33], v[64:65]
	v_or_b32_e32 v40, 0x100, v48
	v_mul_f32_e32 v32, v34, v34
	v_fmac_f32_e32 v32, v35, v35
	v_fmac_f32_e32 v32, v36, v36
	v_fmac_f32_e32 v32, v37, v37
	v_add_f32_e32 v32, v43, v32
	ds_bpermute_b32 v33, v188, v32
	v_mov_b32_e32 v41, v49
	v_or_b32_e32 v48, 0x120, v48
	v_lshl_add_u64 v[40:41], s[2:3], 0, v[40:41]
	v_cvt_pk_bf16_f32 v43, v38, v39
	s_waitcnt lgkmcnt(0)
	v_add_f32_e32 v32, v32, v33
	ds_bpermute_b32 v33, v116, v32
	v_lshl_add_u64 v[38:39], s[2:3], 0, v[48:49]
	s_nop 1
	v_mov_b32_e32 v240, v42
	v_mov_b32_e32 v241, v43
	v_lshl_add_u64 v[244:245], v[40:41], 0, v[246:247]
	global_store_dwordx4 v[50:51], v[34:37], off offset:576
	s_nop 1
	v_cvt_pk_bf16_f32 v34, v34, v35
	v_cvt_pk_bf16_f32 v35, v36, v37
	v_mov_b32_e32 v242, v34
	v_mov_b32_e32 v243, v35
	s_nop 1
	v_permlane16_swap_b32 v240, v242
	v_permlane16_swap_b32 v241, v243
	global_store_dwordx4 v[244:245], v[240:243], off
	s_and_saveexec_b64 s[30:31], s[6:7]
	s_cbranch_execz .LBB0_2177
	v_lshlrev_b64 v[34:35], 6, v[80:81]
	v_lshl_add_u64 v[34:35], s[4:5], 0, v[34:35]
	v_lshl_add_u64 v[34:35], s[28:29], 2, v[34:35]
	s_lshl_b32 s12, s53, 2
	v_lshl_add_u64 v[34:35], v[34:35], 0, s[12:13]
	s_waitcnt lgkmcnt(0)
	v_add_f32_e32 v32, v32, v33
	flat_store_dword v[34:35], v32
.LBB0_2177:
	s_or_b64 exec, exec, s[30:31]
	v_lshl_add_u64 v[50:51], v[164:165], 0, s[16:17]
	s_waitcnt lgkmcnt(0)
	v_lshlrev_b64 v[32:33], 12, v[50:51]
	v_lshl_add_u64 v[32:33], v[166:167], 0, v[32:33]
	v_lshl_add_u64 v[232:233], v[32:33], 0, v[248:249]
	v_lshl_add_u64 v[234:235], v[232:233], 0, v[250:251]
	global_load_dwordx4 v[52:55], v[232:233], off
	global_load_dwordx4 v[56:59], v[234:235], off
	global_load_dwordx4 v[60:63], v[232:233], off offset:512
	global_load_dwordx4 v[64:67], v[234:235], off offset:512
	v_lshl_add_u64 v[48:49], v[164:165], 0, s[18:19]
	v_lshlrev_b64 v[32:33], 12, v[48:49]
	v_lshl_add_u64 v[32:33], v[166:167], 0, v[32:33]
	v_lshl_add_u64 v[236:237], v[32:33], 0, v[248:249]
	v_lshl_add_u64 v[238:239], v[236:237], 0, v[250:251]
	global_load_dwordx4 v[44:47], v[236:237], off
	global_load_dwordx4 v[40:43], v[238:239], off
	global_load_dwordx4 v[36:39], v[236:237], off offset:512
	s_nop 0
	global_load_dwordx4 v[32:35], v[238:239], off offset:512
	v_lshlrev_b64 v[68:69], 10, v[50:51]
	v_lshl_add_u64 v[68:69], v[68:69], 0, v[162:163]
	v_lshl_add_u64 v[70:71], v[68:69], 2, s[78:79]
	v_lshlrev_b64 v[68:69], 1, v[68:69]
	v_lshl_add_u64 v[72:73], s[2:3], 0, v[68:69]
	s_waitcnt vmcnt(0)
	v_or_b32_e32 v74, 32, v68
	v_mov_b32_e32 v75, v69
	v_or_b32_e32 v76, 0x100, v68
	v_mov_b32_e32 v77, v69
	v_or_b32_e32 v68, 0x120, v68
	v_lshl_add_u64 v[74:75], s[2:3], 0, v[74:75]
	v_lshl_add_u64 v[76:77], s[2:3], 0, v[76:77]
	s_waitcnt vmcnt(0)
	v_mov_b32_dpp v224, v52 row_ror:8 row_mask:0xf bank_mask:0xf
	v_mov_b32_dpp v225, v53 row_ror:8 row_mask:0xf bank_mask:0xf
	v_mov_b32_dpp v226, v54 row_ror:8 row_mask:0xf bank_mask:0xf
	v_mov_b32_dpp v227, v55 row_ror:8 row_mask:0xf bank_mask:0xf
	v_mov_b32_dpp v52, v56 row_ror:8 row_mask:0xf bank_mask:0xc
	v_mov_b32_dpp v53, v57 row_ror:8 row_mask:0xf bank_mask:0xc
	v_mov_b32_dpp v54, v58 row_ror:8 row_mask:0xf bank_mask:0xc
	v_mov_b32_dpp v55, v59 row_ror:8 row_mask:0xf bank_mask:0xc
	v_mov_b32_dpp v56, v224 quad_perm:[0,1,2,3] row_mask:0xf bank_mask:0x3
	v_mov_b32_dpp v57, v225 quad_perm:[0,1,2,3] row_mask:0xf bank_mask:0x3
	v_mov_b32_dpp v58, v226 quad_perm:[0,1,2,3] row_mask:0xf bank_mask:0x3
	v_mov_b32_dpp v59, v227 quad_perm:[0,1,2,3] row_mask:0xf bank_mask:0x3
	v_mov_b32_dpp v224, v60 row_ror:8 row_mask:0xf bank_mask:0xf
	v_mov_b32_dpp v225, v61 row_ror:8 row_mask:0xf bank_mask:0xf
	v_mov_b32_dpp v226, v62 row_ror:8 row_mask:0xf bank_mask:0xf
	v_mov_b32_dpp v227, v63 row_ror:8 row_mask:0xf bank_mask:0xf
	v_mov_b32_dpp v60, v64 row_ror:8 row_mask:0xf bank_mask:0xc
	v_mov_b32_dpp v61, v65 row_ror:8 row_mask:0xf bank_mask:0xc
	v_mov_b32_dpp v62, v66 row_ror:8 row_mask:0xf bank_mask:0xc
	v_mov_b32_dpp v63, v67 row_ror:8 row_mask:0xf bank_mask:0xc
	v_mov_b32_dpp v64, v224 quad_perm:[0,1,2,3] row_mask:0xf bank_mask:0x3
	v_mov_b32_dpp v65, v225 quad_perm:[0,1,2,3] row_mask:0xf bank_mask:0x3
	v_mov_b32_dpp v66, v226 quad_perm:[0,1,2,3] row_mask:0xf bank_mask:0x3
	v_mov_b32_dpp v67, v227 quad_perm:[0,1,2,3] row_mask:0xf bank_mask:0x3
	v_pk_add_f32 v[28:29], v[28:29], v[52:53]
	v_pk_add_f32 v[24:25], v[24:25], v[56:57]
	v_pk_add_f32 v[20:21], v[20:21], v[60:61]
	v_mul_f32_e32 v56, v28, v28
	v_mul_f32_e32 v57, v24, v24
	v_pk_add_f32 v[30:31], v[30:31], v[54:55]
	v_pk_add_f32 v[26:27], v[26:27], v[58:59]
	v_pk_add_f32 v[52:53], v[16:17], v[64:65]
	v_mul_f32_e32 v58, v20, v20
	v_fmac_f32_e32 v56, v29, v29
	v_fmac_f32_e32 v57, v25, v25
	v_pk_add_f32 v[22:23], v[22:23], v[62:63]
	v_mul_f32_e32 v59, v52, v52
	v_fmac_f32_e32 v58, v21, v21
	v_fmac_f32_e32 v56, v30, v30
	v_fmac_f32_e32 v57, v26, v26
	v_pk_add_f32 v[54:55], v[18:19], v[66:67]
	v_cvt_pk_bf16_f32 v16, v28, v29
	v_fmac_f32_e32 v59, v53, v53
	v_fmac_f32_e32 v58, v22, v22
	v_fmac_f32_e32 v56, v31, v31
	v_fmac_f32_e32 v57, v27, v27
	global_store_dwordx4 v[70:71], v[28:31], off
	v_cvt_pk_bf16_f32 v17, v30, v31
	s_nop 1
	v_mov_b32_e32 v240, v16
	v_mov_b32_e32 v241, v17
	v_lshl_add_u64 v[244:245], v[72:73], 0, v[246:247]
	v_fmac_f32_e32 v59, v54, v54
	v_fmac_f32_e32 v58, v23, v23
	v_add_f32_e32 v16, v56, v57
	v_add_f32_e32 v16, v16, v58
	v_fmac_f32_e32 v59, v55, v55
	v_add_f32_e32 v16, v16, v59
	ds_bpermute_b32 v17, v188, v16
	v_cvt_pk_bf16_f32 v18, v24, v25
	v_cvt_pk_bf16_f32 v19, v26, v27
	v_cvt_pk_bf16_f32 v28, v20, v21
	global_store_dwordx4 v[70:71], v[24:27], off offset:64
	v_mov_b32_e32 v242, v18
	v_mov_b32_e32 v243, v19
	s_nop 1
	v_permlane16_swap_b32 v240, v242
	v_permlane16_swap_b32 v241, v243
	global_store_dwordx4 v[244:245], v[240:243], off
	s_waitcnt lgkmcnt(0)
	v_add_f32_e32 v16, v16, v17
	ds_bpermute_b32 v17, v116, v16
	v_cvt_pk_bf16_f32 v29, v22, v23
	v_lshl_add_u64 v[18:19], s[2:3], 0, v[68:69]
	global_store_dwordx4 v[70:71], v[20:23], off offset:512
	s_nop 1
	v_mov_b32_e32 v240, v28
	v_mov_b32_e32 v241, v29
	v_lshl_add_u64 v[244:245], v[76:77], 0, v[246:247]
	global_store_dwordx4 v[70:71], v[52:55], off offset:576
	v_cvt_pk_bf16_f32 v20, v52, v53
	v_cvt_pk_bf16_f32 v21, v54, v55
	v_mov_b32_e32 v242, v20
	v_mov_b32_e32 v243, v21
	s_nop 1
	v_permlane16_swap_b32 v240, v242
	v_permlane16_swap_b32 v241, v243
	global_store_dwordx4 v[244:245], v[240:243], off
	s_and_saveexec_b64 s[30:31], s[6:7]
	s_cbranch_execz .LBB0_2179
	v_lshlrev_b64 v[18:19], 6, v[50:51]
	v_lshl_add_u64 v[18:19], s[4:5], 0, v[18:19]
	v_lshl_add_u64 v[18:19], s[28:29], 2, v[18:19]
	s_lshl_b32 s12, s53, 2
	v_lshl_add_u64 v[18:19], v[18:19], 0, s[12:13]
	s_waitcnt lgkmcnt(0)
	v_add_f32_e32 v16, v16, v17
	flat_store_dword v[18:19], v16
.LBB0_2179:
	s_or_b64 exec, exec, s[30:31]
	s_waitcnt lgkmcnt(0)
	v_lshlrev_b64 v[16:17], 10, v[48:49]
	v_lshl_add_u64 v[16:17], v[16:17], 0, v[162:163]
	v_lshl_add_u64 v[18:19], v[16:17], 2, s[78:79]
	v_lshlrev_b64 v[16:17], 1, v[16:17]
	v_mov_b32_dpp v224, v44 row_ror:8 row_mask:0xf bank_mask:0xf
	v_mov_b32_dpp v225, v45 row_ror:8 row_mask:0xf bank_mask:0xf
	v_mov_b32_dpp v226, v46 row_ror:8 row_mask:0xf bank_mask:0xf
	v_mov_b32_dpp v227, v47 row_ror:8 row_mask:0xf bank_mask:0xf
	v_mov_b32_dpp v44, v40 row_ror:8 row_mask:0xf bank_mask:0xc
	v_mov_b32_dpp v45, v41 row_ror:8 row_mask:0xf bank_mask:0xc
	v_mov_b32_dpp v46, v42 row_ror:8 row_mask:0xf bank_mask:0xc
	v_mov_b32_dpp v47, v43 row_ror:8 row_mask:0xf bank_mask:0xc
	v_mov_b32_dpp v40, v224 quad_perm:[0,1,2,3] row_mask:0xf bank_mask:0x3
	v_mov_b32_dpp v41, v225 quad_perm:[0,1,2,3] row_mask:0xf bank_mask:0x3
	v_mov_b32_dpp v42, v226 quad_perm:[0,1,2,3] row_mask:0xf bank_mask:0x3
	v_mov_b32_dpp v43, v227 quad_perm:[0,1,2,3] row_mask:0xf bank_mask:0x3
	v_mov_b32_dpp v224, v36 row_ror:8 row_mask:0xf bank_mask:0xf
	v_mov_b32_dpp v225, v37 row_ror:8 row_mask:0xf bank_mask:0xf
	v_mov_b32_dpp v226, v38 row_ror:8 row_mask:0xf bank_mask:0xf
	v_mov_b32_dpp v227, v39 row_ror:8 row_mask:0xf bank_mask:0xf
	v_mov_b32_dpp v36, v32 row_ror:8 row_mask:0xf bank_mask:0xc
	v_mov_b32_dpp v37, v33 row_ror:8 row_mask:0xf bank_mask:0xc
	v_mov_b32_dpp v38, v34 row_ror:8 row_mask:0xf bank_mask:0xc
	v_mov_b32_dpp v39, v35 row_ror:8 row_mask:0xf bank_mask:0xc
	v_mov_b32_dpp v32, v224 quad_perm:[0,1,2,3] row_mask:0xf bank_mask:0x3
	v_mov_b32_dpp v33, v225 quad_perm:[0,1,2,3] row_mask:0xf bank_mask:0x3
	v_mov_b32_dpp v34, v226 quad_perm:[0,1,2,3] row_mask:0xf bank_mask:0x3
	v_mov_b32_dpp v35, v227 quad_perm:[0,1,2,3] row_mask:0xf bank_mask:0x3
	v_pk_add_f32 v[14:15], v[14:15], v[46:47]
	v_pk_add_f32 v[12:13], v[12:13], v[44:45]
	v_lshl_add_u64 v[20:21], s[2:3], 0, v[16:17]
	global_store_dwordx4 v[18:19], v[12:15], off
	v_cvt_pk_bf16_f32 v22, v12, v13
	v_cvt_pk_bf16_f32 v23, v14, v15
	s_nop 1
	v_mov_b32_e32 v240, v22
	v_mov_b32_e32 v241, v23
	v_lshl_add_u64 v[244:245], v[20:21], 0, v[246:247]
	v_mul_f32_e32 v20, v12, v12
	v_fmac_f32_e32 v20, v13, v13
	v_pk_add_f32 v[10:11], v[10:11], v[42:43]
	v_pk_add_f32 v[8:9], v[8:9], v[40:41]
	v_fmac_f32_e32 v20, v14, v14
	global_store_dwordx4 v[18:19], v[8:11], off offset:64
	v_or_b32_e32 v12, 32, v16
	v_mov_b32_e32 v13, v17
	v_cvt_pk_bf16_f32 v14, v8, v9
	v_mul_f32_e32 v8, v8, v8
	v_lshl_add_u64 v[12:13], s[2:3], 0, v[12:13]
	v_fmac_f32_e32 v8, v9, v9
	v_pk_add_f32 v[6:7], v[6:7], v[38:39]
	v_pk_add_f32 v[4:5], v[4:5], v[36:37]
	v_fmac_f32_e32 v20, v15, v15
	v_cvt_pk_bf16_f32 v15, v10, v11
	v_mov_b32_e32 v242, v14
	v_mov_b32_e32 v243, v15
	s_nop 1
	v_permlane16_swap_b32 v240, v242
	v_permlane16_swap_b32 v241, v243
	global_store_dwordx4 v[244:245], v[240:243], off
	v_fmac_f32_e32 v8, v10, v10
	global_store_dwordx4 v[18:19], v[4:7], off offset:512
	v_cvt_pk_bf16_f32 v10, v4, v5
	v_fmac_f32_e32 v8, v11, v11
	v_add_f32_e32 v11, v20, v8
	v_mul_f32_e32 v4, v4, v4
	v_fmac_f32_e32 v4, v5, v5
	v_fmac_f32_e32 v4, v6, v6
	v_fmac_f32_e32 v4, v7, v7
	v_add_f32_e32 v11, v11, v4
	v_pk_add_f32 v[4:5], v[2:3], v[34:35]
	v_pk_add_f32 v[2:3], v[0:1], v[32:33]
	v_or_b32_e32 v8, 0x100, v16
	v_mul_f32_e32 v0, v2, v2
	v_fmac_f32_e32 v0, v3, v3
	v_fmac_f32_e32 v0, v4, v4
	v_fmac_f32_e32 v0, v5, v5
	v_add_f32_e32 v0, v11, v0
	ds_bpermute_b32 v1, v188, v0
	v_mov_b32_e32 v9, v17
	v_or_b32_e32 v16, 0x120, v16
	v_lshl_add_u64 v[8:9], s[2:3], 0, v[8:9]
	v_cvt_pk_bf16_f32 v11, v6, v7
	s_waitcnt lgkmcnt(0)
	v_add_f32_e32 v0, v0, v1
	ds_bpermute_b32 v1, v116, v0
	v_lshl_add_u64 v[6:7], s[2:3], 0, v[16:17]
	s_nop 1
	v_mov_b32_e32 v240, v10
	v_mov_b32_e32 v241, v11
	v_lshl_add_u64 v[244:245], v[8:9], 0, v[246:247]
	global_store_dwordx4 v[18:19], v[2:5], off offset:576
	s_nop 1
	v_cvt_pk_bf16_f32 v2, v2, v3
	v_cvt_pk_bf16_f32 v3, v4, v5
	v_mov_b32_e32 v242, v2
	v_mov_b32_e32 v243, v3
	s_nop 1
	v_permlane16_swap_b32 v240, v242
	v_permlane16_swap_b32 v241, v243
	global_store_dwordx4 v[244:245], v[240:243], off
	s_and_saveexec_b64 s[30:31], s[6:7]
	s_cbranch_execz .LBB0_2156
	v_lshlrev_b64 v[2:3], 6, v[48:49]
	v_lshl_add_u64 v[2:3], s[4:5], 0, v[2:3]
	v_lshl_add_u64 v[2:3], s[28:29], 2, v[2:3]
	s_lshl_b32 s12, s53, 2
	v_lshl_add_u64 v[2:3], v[2:3], 0, s[12:13]
	s_waitcnt lgkmcnt(0)
	v_add_f32_e32 v0, v0, v1
	flat_store_dword v[2:3], v0
	s_branch .LBB0_2156

.LBB0_2323:
	ds_read_b128 v[146:149], v152
	ds_read_b128 v[168:171], v153
	ds_read_b128 v[172:175], v154
	ds_read_b128 v[178:181], v155
	s_add_u32 s20, s18, 0xfff50080
	s_addc_u32 s21, s19, -1
	s_cmp_eq_u32 s55, 40
	s_cselect_b32 s23, s7, s21
	s_cselect_b32 s22, s6, s20
	s_cselect_b32 s21, s9, s54
	s_cselect_b32 s20, s8, s17
	s_mov_b32 m0, s49
	v_lshl_add_u64 v[150:151], s[18:19], 0, v[140:141]
	ds_read_b128 v[182:185], v135
	ds_read_b128 v[186:189], v135 offset:1024
	ds_read_b128 v[190:193], v135 offset:2048
	ds_read_b128 v[194:197], v135 offset:3072
	ds_read_b128 v[198:201], v135 offset:4096
	ds_read_b128 v[202:205], v135 offset:5120
	ds_read_b128 v[206:209], v135 offset:6144
	ds_read_b128 v[210:213], v135 offset:7168
	global_load_lds_dwordx4 v[150:151], off
	v_lshl_add_u64 v[150:151], s[18:19], 0, v[138:139]
	s_mov_b32 m0, s50
	s_nop 0
	global_load_lds_dwordx4 v[150:151], off
	s_waitcnt lgkmcnt(8)
	s_barrier
	s_waitcnt lgkmcnt(0)
	s_setprio 1
	s_waitcnt lgkmcnt(0)
	v_mfma_f32_16x16x32_bf16 v[124:127], v[146:149], v[182:185], v[124:127]
	v_mfma_f32_16x16x32_bf16 v[120:123], v[172:175], v[182:185], v[120:123]
	v_mfma_f32_16x16x32_bf16 v[116:119], v[146:149], v[190:193], v[116:119]
	v_mfma_f32_16x16x32_bf16 v[112:115], v[172:175], v[190:193], v[112:115]
	v_mfma_f32_16x16x32_bf16 v[92:95], v[146:149], v[198:201], v[92:95]
	v_mfma_f32_16x16x32_bf16 v[88:91], v[172:175], v[198:201], v[88:91]
	v_mfma_f32_16x16x32_bf16 v[84:87], v[146:149], v[206:209], v[84:87]
	v_mfma_f32_16x16x32_bf16 v[80:83], v[172:175], v[206:209], v[80:83]
	v_mfma_f32_16x16x32_bf16 v[124:127], v[168:171], v[186:189], v[124:127]
	v_mfma_f32_16x16x32_bf16 v[120:123], v[178:181], v[186:189], v[120:123]
	v_mfma_f32_16x16x32_bf16 v[116:119], v[168:171], v[194:197], v[116:119]
	v_mfma_f32_16x16x32_bf16 v[112:115], v[178:181], v[194:197], v[112:115]
	v_mfma_f32_16x16x32_bf16 v[92:95], v[168:171], v[202:205], v[92:95]
	v_mfma_f32_16x16x32_bf16 v[88:91], v[178:181], v[202:205], v[88:91]
	v_mfma_f32_16x16x32_bf16 v[84:87], v[168:171], v[210:213], v[84:87]
	v_mfma_f32_16x16x32_bf16 v[80:83], v[178:181], v[210:213], v[80:83]
	s_setprio 0
	s_barrier
	s_mov_b32 m0, s34
	v_lshl_add_u64 v[150:151], s[20:21], 0, v[128:129]
	ds_read_b128 v[214:217], v156
	ds_read_b128 v[218:221], v157
	ds_read_b128 v[222:225], v158
	ds_read_b128 v[226:229], v159
	global_load_lds_dwordx4 v[150:151], off
	v_lshl_add_u64 v[230:231], s[20:21], 0, v[130:131]
	s_mov_b32 m0, s35
	s_nop 0
	global_load_lds_dwordx4 v[230:231], off
	s_barrier
	s_waitcnt lgkmcnt(0)
	s_setprio 1
	s_waitcnt lgkmcnt(0)
	v_mfma_f32_16x16x32_bf16 v[108:111], v[214:217], v[182:185], v[108:111]
	v_mfma_f32_16x16x32_bf16 v[104:107], v[222:225], v[182:185], v[104:107]
	v_mfma_f32_16x16x32_bf16 v[100:103], v[214:217], v[190:193], v[100:103]
	v_mfma_f32_16x16x32_bf16 v[96:99], v[222:225], v[190:193], v[96:99]
	v_mfma_f32_16x16x32_bf16 v[76:79], v[214:217], v[198:201], v[76:79]
	v_mfma_f32_16x16x32_bf16 v[72:75], v[222:225], v[198:201], v[72:75]
	v_mfma_f32_16x16x32_bf16 v[68:71], v[214:217], v[206:209], v[68:71]
	v_mfma_f32_16x16x32_bf16 v[64:67], v[222:225], v[206:209], v[64:67]
	v_mfma_f32_16x16x32_bf16 v[108:111], v[218:221], v[186:189], v[108:111]
	v_mfma_f32_16x16x32_bf16 v[104:107], v[226:229], v[186:189], v[104:107]
	v_mfma_f32_16x16x32_bf16 v[100:103], v[218:221], v[194:197], v[100:103]
	v_mfma_f32_16x16x32_bf16 v[96:99], v[226:229], v[194:197], v[96:99]
	v_mfma_f32_16x16x32_bf16 v[76:79], v[218:221], v[202:205], v[76:79]
	v_mfma_f32_16x16x32_bf16 v[72:75], v[226:229], v[202:205], v[72:75]
	v_mfma_f32_16x16x32_bf16 v[68:71], v[218:221], v[210:213], v[68:71]
	v_mfma_f32_16x16x32_bf16 v[64:67], v[226:229], v[210:213], v[64:67]
	s_setprio 0
	s_mov_b32 m0, s33
	v_lshl_add_u64 v[232:233], s[22:23], 0, v[128:129]
	s_barrier
	ds_read_b128 v[182:185], v135 offset:16384
	ds_read_b128 v[186:189], v135 offset:17408
	ds_read_b128 v[190:193], v135 offset:18432
	ds_read_b128 v[194:197], v135 offset:19456
	ds_read_b128 v[198:201], v135 offset:20480
	ds_read_b128 v[202:205], v135 offset:21504
	ds_read_b128 v[206:209], v135 offset:22528
	ds_read_b128 v[210:213], v135 offset:23552
	global_load_lds_dwordx4 v[232:233], off
	v_lshl_add_u64 v[234:235], s[22:23], 0, v[130:131]
	s_mov_b32 m0, s36
	s_nop 0
	global_load_lds_dwordx4 v[234:235], off
	s_barrier
	s_waitcnt lgkmcnt(0)
	s_setprio 1
	s_waitcnt lgkmcnt(0)
	v_mfma_f32_16x16x32_bf16 v[60:63], v[146:149], v[182:185], v[60:63]
	v_mfma_f32_16x16x32_bf16 v[56:59], v[172:175], v[182:185], v[56:59]
	v_mfma_f32_16x16x32_bf16 v[52:55], v[146:149], v[190:193], v[52:55]
	v_mfma_f32_16x16x32_bf16 v[48:51], v[172:175], v[190:193], v[48:51]
	v_mfma_f32_16x16x32_bf16 v[28:31], v[146:149], v[198:201], v[28:31]
	v_mfma_f32_16x16x32_bf16 v[24:27], v[172:175], v[198:201], v[24:27]
	v_mfma_f32_16x16x32_bf16 v[20:23], v[146:149], v[206:209], v[20:23]
	v_mfma_f32_16x16x32_bf16 v[16:19], v[172:175], v[206:209], v[16:19]
	v_mfma_f32_16x16x32_bf16 v[60:63], v[168:171], v[186:189], v[60:63]
	v_mfma_f32_16x16x32_bf16 v[56:59], v[178:181], v[186:189], v[56:59]
	v_mfma_f32_16x16x32_bf16 v[52:55], v[168:171], v[194:197], v[52:55]
	v_mfma_f32_16x16x32_bf16 v[48:51], v[178:181], v[194:197], v[48:51]
	v_mfma_f32_16x16x32_bf16 v[28:31], v[168:171], v[202:205], v[28:31]
	v_mfma_f32_16x16x32_bf16 v[24:27], v[178:181], v[202:205], v[24:27]
	v_mfma_f32_16x16x32_bf16 v[20:23], v[168:171], v[210:213], v[20:23]
	v_mfma_f32_16x16x32_bf16 v[16:19], v[178:181], v[210:213], v[16:19]
	s_setprio 0
	s_barrier
	s_add_u32 s56, s20, 0xb0000
	s_addc_u32 s57, s21, 0
	s_mov_b32 m0, s37
	v_lshl_add_u64 v[146:147], s[56:57], 0, v[128:129]
	global_load_lds_dwordx4 v[146:147], off
	v_lshl_add_u64 v[146:147], s[56:57], 0, v[130:131]
	s_mov_b32 m0, s38
	s_nop 0
	global_load_lds_dwordx4 v[146:147], off
	s_waitcnt vmcnt(6)
	s_barrier
	s_setprio 1
	v_mfma_f32_16x16x32_bf16 v[44:47], v[214:217], v[182:185], v[44:47]
	v_mfma_f32_16x16x32_bf16 v[40:43], v[222:225], v[182:185], v[40:43]
	v_mfma_f32_16x16x32_bf16 v[36:39], v[214:217], v[190:193], v[36:39]
	v_mfma_f32_16x16x32_bf16 v[32:35], v[222:225], v[190:193], v[32:35]
	v_mfma_f32_16x16x32_bf16 v[12:15], v[214:217], v[198:201], v[12:15]
	v_mfma_f32_16x16x32_bf16 v[8:11], v[222:225], v[198:201], v[8:11]
	v_mfma_f32_16x16x32_bf16 v[4:7], v[214:217], v[206:209], v[4:7]
	v_mfma_f32_16x16x32_bf16 v[0:3], v[222:225], v[206:209], v[0:3]
	v_mfma_f32_16x16x32_bf16 v[44:47], v[218:221], v[186:189], v[44:47]
	v_mfma_f32_16x16x32_bf16 v[40:43], v[226:229], v[186:189], v[40:43]
	v_mfma_f32_16x16x32_bf16 v[36:39], v[218:221], v[194:197], v[36:39]
	v_mfma_f32_16x16x32_bf16 v[32:35], v[226:229], v[194:197], v[32:35]
	v_mfma_f32_16x16x32_bf16 v[12:15], v[218:221], v[202:205], v[12:15]
	v_mfma_f32_16x16x32_bf16 v[8:11], v[226:229], v[202:205], v[8:11]
	v_mfma_f32_16x16x32_bf16 v[4:7], v[218:221], v[210:213], v[4:7]
	v_mfma_f32_16x16x32_bf16 v[0:3], v[226:229], v[210:213], v[0:3]
	s_setprio 0
	s_barrier
	ds_read_b128 v[146:149], v160
	ds_read_b128 v[168:171], v161
	ds_read_b128 v[172:175], v162
	ds_read_b128 v[178:181], v163
	s_add_u32 s22, s22, 0xb0000
	s_addc_u32 s23, s23, 0
	s_mov_b32 m0, s39
	v_lshl_add_u64 v[214:215], s[22:23], 0, v[128:129]
	ds_read_b128 v[182:185], v135 offset:32768
	ds_read_b128 v[186:189], v135 offset:33792
	ds_read_b128 v[190:193], v135 offset:34816
	ds_read_b128 v[194:197], v135 offset:35840
	ds_read_b128 v[198:201], v135 offset:36864
	ds_read_b128 v[202:205], v135 offset:37888
	ds_read_b128 v[206:209], v135 offset:38912
	ds_read_b128 v[210:213], v135 offset:39936
	global_load_lds_dwordx4 v[214:215], off
	v_lshl_add_u64 v[214:215], s[22:23], 0, v[130:131]
	s_mov_b32 m0, s40
	s_nop 0
	global_load_lds_dwordx4 v[214:215], off
	s_waitcnt lgkmcnt(8)
	s_barrier
	s_waitcnt lgkmcnt(0)
	s_setprio 1
	s_waitcnt lgkmcnt(0)
	v_mfma_f32_16x16x32_bf16 v[124:127], v[146:149], v[182:185], v[124:127]
	v_mfma_f32_16x16x32_bf16 v[120:123], v[172:175], v[182:185], v[120:123]
	v_mfma_f32_16x16x32_bf16 v[116:119], v[146:149], v[190:193], v[116:119]
	v_mfma_f32_16x16x32_bf16 v[112:115], v[172:175], v[190:193], v[112:115]
	v_mfma_f32_16x16x32_bf16 v[92:95], v[146:149], v[198:201], v[92:95]
	v_mfma_f32_16x16x32_bf16 v[88:91], v[172:175], v[198:201], v[88:91]
	v_mfma_f32_16x16x32_bf16 v[84:87], v[146:149], v[206:209], v[84:87]
	v_mfma_f32_16x16x32_bf16 v[80:83], v[172:175], v[206:209], v[80:83]
	v_mfma_f32_16x16x32_bf16 v[124:127], v[168:171], v[186:189], v[124:127]
	v_mfma_f32_16x16x32_bf16 v[120:123], v[178:181], v[186:189], v[120:123]
	v_mfma_f32_16x16x32_bf16 v[116:119], v[168:171], v[194:197], v[116:119]
	v_mfma_f32_16x16x32_bf16 v[112:115], v[178:181], v[194:197], v[112:115]
	v_mfma_f32_16x16x32_bf16 v[92:95], v[168:171], v[202:205], v[92:95]
	v_mfma_f32_16x16x32_bf16 v[88:91], v[178:181], v[202:205], v[88:91]
	v_mfma_f32_16x16x32_bf16 v[84:87], v[168:171], v[210:213], v[84:87]
	v_mfma_f32_16x16x32_bf16 v[80:83], v[178:181], v[210:213], v[80:83]
	s_setprio 0
	s_barrier
	s_mov_b32 m0, s41
	v_lshl_add_u64 v[150:151], v[150:151], 0, s[2:3]
	ds_read_b128 v[214:217], v164
	ds_read_b128 v[218:221], v165
	ds_read_b128 v[222:225], v166
	ds_read_b128 v[226:229], v167
	global_load_lds_dwordx4 v[150:151], off
	v_lshl_add_u64 v[150:151], v[230:231], 0, s[2:3]
	s_mov_b32 m0, s42
	s_nop 0
	global_load_lds_dwordx4 v[150:151], off
	s_barrier
	s_waitcnt lgkmcnt(0)
	s_setprio 1
	s_waitcnt lgkmcnt(0)
	v_mfma_f32_16x16x32_bf16 v[108:111], v[214:217], v[182:185], v[108:111]
	v_mfma_f32_16x16x32_bf16 v[104:107], v[222:225], v[182:185], v[104:107]
	v_mfma_f32_16x16x32_bf16 v[100:103], v[214:217], v[190:193], v[100:103]
	v_mfma_f32_16x16x32_bf16 v[96:99], v[222:225], v[190:193], v[96:99]
	v_mfma_f32_16x16x32_bf16 v[76:79], v[214:217], v[198:201], v[76:79]
	v_mfma_f32_16x16x32_bf16 v[72:75], v[222:225], v[198:201], v[72:75]
	v_mfma_f32_16x16x32_bf16 v[68:71], v[214:217], v[206:209], v[68:71]
	v_mfma_f32_16x16x32_bf16 v[64:67], v[222:225], v[206:209], v[64:67]
	v_mfma_f32_16x16x32_bf16 v[108:111], v[218:221], v[186:189], v[108:111]
	v_mfma_f32_16x16x32_bf16 v[104:107], v[226:229], v[186:189], v[104:107]
	v_mfma_f32_16x16x32_bf16 v[100:103], v[218:221], v[194:197], v[100:103]
	v_mfma_f32_16x16x32_bf16 v[96:99], v[226:229], v[194:197], v[96:99]
	v_mfma_f32_16x16x32_bf16 v[76:79], v[218:221], v[202:205], v[76:79]
	v_mfma_f32_16x16x32_bf16 v[72:75], v[226:229], v[202:205], v[72:75]
	v_mfma_f32_16x16x32_bf16 v[68:71], v[218:221], v[210:213], v[68:71]
	v_mfma_f32_16x16x32_bf16 v[64:67], v[226:229], v[210:213], v[64:67]
	s_setprio 0
	s_mov_b32 m0, s43
	v_lshl_add_u64 v[150:151], v[232:233], 0, s[2:3]
	s_barrier
	ds_read_b128 v[182:185], v135 offset:49152
	ds_read_b128 v[186:189], v135 offset:50176
	ds_read_b128 v[190:193], v135 offset:51200
	ds_read_b128 v[194:197], v135 offset:52224
	ds_read_b128 v[198:201], v135 offset:53248
	ds_read_b128 v[202:205], v135 offset:54272
	ds_read_b128 v[206:209], v135 offset:55296
	ds_read_b128 v[210:213], v135 offset:56320
	global_load_lds_dwordx4 v[150:151], off
	v_lshl_add_u64 v[150:151], v[234:235], 0, s[2:3]
	s_mov_b32 m0, s44
	s_nop 0
	global_load_lds_dwordx4 v[150:151], off
	s_barrier
	s_waitcnt lgkmcnt(0)
	s_setprio 1
	s_waitcnt lgkmcnt(0)
	v_mfma_f32_16x16x32_bf16 v[60:63], v[146:149], v[182:185], v[60:63]
	v_mfma_f32_16x16x32_bf16 v[56:59], v[172:175], v[182:185], v[56:59]
	v_mfma_f32_16x16x32_bf16 v[52:55], v[146:149], v[190:193], v[52:55]
	v_mfma_f32_16x16x32_bf16 v[48:51], v[172:175], v[190:193], v[48:51]
	v_mfma_f32_16x16x32_bf16 v[28:31], v[146:149], v[198:201], v[28:31]
	v_mfma_f32_16x16x32_bf16 v[24:27], v[172:175], v[198:201], v[24:27]
	v_mfma_f32_16x16x32_bf16 v[20:23], v[146:149], v[206:209], v[20:23]
	v_mfma_f32_16x16x32_bf16 v[16:19], v[172:175], v[206:209], v[16:19]
	v_mfma_f32_16x16x32_bf16 v[60:63], v[168:171], v[186:189], v[60:63]
	v_mfma_f32_16x16x32_bf16 v[56:59], v[178:181], v[186:189], v[56:59]
	v_mfma_f32_16x16x32_bf16 v[52:55], v[168:171], v[194:197], v[52:55]
	v_mfma_f32_16x16x32_bf16 v[48:51], v[178:181], v[194:197], v[48:51]
	v_mfma_f32_16x16x32_bf16 v[28:31], v[168:171], v[202:205], v[28:31]
	v_mfma_f32_16x16x32_bf16 v[24:27], v[178:181], v[202:205], v[24:27]
	v_mfma_f32_16x16x32_bf16 v[20:23], v[168:171], v[210:213], v[20:23]
	v_mfma_f32_16x16x32_bf16 v[16:19], v[178:181], v[210:213], v[16:19]
	s_setprio 0
	s_barrier
	s_add_u32 s20, s20, 0xb0080
	s_addc_u32 s21, s21, 0
	s_mov_b32 m0, s45
	v_lshl_add_u64 v[146:147], s[20:21], 0, v[128:129]
	global_load_lds_dwordx4 v[146:147], off
	v_lshl_add_u64 v[146:147], s[20:21], 0, v[130:131]
	s_mov_b32 m0, s46
	s_nop 0
	global_load_lds_dwordx4 v[146:147], off
	s_waitcnt vmcnt(6)
	s_barrier
	s_setprio 1
	v_mfma_f32_16x16x32_bf16 v[44:47], v[214:217], v[182:185], v[44:47]
	v_mfma_f32_16x16x32_bf16 v[40:43], v[222:225], v[182:185], v[40:43]
	v_mfma_f32_16x16x32_bf16 v[36:39], v[214:217], v[190:193], v[36:39]
	v_mfma_f32_16x16x32_bf16 v[32:35], v[222:225], v[190:193], v[32:35]
	v_mfma_f32_16x16x32_bf16 v[12:15], v[214:217], v[198:201], v[12:15]
	v_mfma_f32_16x16x32_bf16 v[8:11], v[222:225], v[198:201], v[8:11]
	v_mfma_f32_16x16x32_bf16 v[4:7], v[214:217], v[206:209], v[4:7]
	v_mfma_f32_16x16x32_bf16 v[0:3], v[222:225], v[206:209], v[0:3]
	v_mfma_f32_16x16x32_bf16 v[44:47], v[218:221], v[186:189], v[44:47]
	v_mfma_f32_16x16x32_bf16 v[40:43], v[226:229], v[186:189], v[40:43]
	v_mfma_f32_16x16x32_bf16 v[36:39], v[218:221], v[194:197], v[36:39]
	v_mfma_f32_16x16x32_bf16 v[32:35], v[226:229], v[194:197], v[32:35]
	v_mfma_f32_16x16x32_bf16 v[12:15], v[218:221], v[202:205], v[12:15]
	v_mfma_f32_16x16x32_bf16 v[8:11], v[226:229], v[202:205], v[8:11]
	v_mfma_f32_16x16x32_bf16 v[4:7], v[218:221], v[210:213], v[4:7]
	v_mfma_f32_16x16x32_bf16 v[0:3], v[226:229], v[210:213], v[0:3]
	s_setprio 0
	s_add_i32 s55, s55, 2
	s_add_u32 s17, s17, 0x100
	s_addc_u32 s54, s54, 0
	s_add_u32 s18, s18, 0x100
	s_addc_u32 s19, s19, 0
	s_cmp_gt_u32 s55, 41
	s_barrier
	s_cbranch_scc0 .LBB0_2323
	v_bfe_i32 v249, v176, 3, 1
	v_and_b32_e32 v248, 0xffff8040, v249
	v_mov_b32_e32 v250, 0x8000
	v_mov_b32_e32 v251, 0
	s_ashr_i32 s17, s16, 31
	s_lshl_b64 s[16:17], s[16:17], 8
	v_lshl_add_u64 v[146:147], s[16:17], 0, v[132:133]
	s_lshl_b32 s16, s53, 8
	s_ashr_i32 s17, s16, 31
	v_lshl_add_u64 v[148:149], s[16:17], 2, v[136:137]
	v_lshlrev_b64 v[150:151], 12, v[146:147]
	v_lshl_add_u64 v[146:147], v[148:149], 0, v[150:151]
	v_lshl_add_u64 v[232:233], v[146:147], 0, v[248:249]
	v_lshl_add_u64 v[234:235], v[232:233], 0, v[250:251]
	global_load_dwordx4 v[168:171], v[232:233], off
	global_load_dwordx4 v[172:175], v[234:235], off
	global_load_dwordx4 v[178:181], v[232:233], off offset:512
	global_load_dwordx4 v[182:185], v[234:235], off offset:512
	v_or_b32_e32 v202, 0x10000, v150
	v_mov_b32_e32 v203, v151
	v_lshl_add_u64 v[146:147], v[148:149], 0, v[202:203]
	v_lshl_add_u64 v[236:237], v[146:147], 0, v[248:249]
	v_lshl_add_u64 v[238:239], v[236:237], 0, v[250:251]
	global_load_dwordx4 v[186:189], v[236:237], off
	global_load_dwordx4 v[190:193], v[238:239], off
	global_load_dwordx4 v[194:197], v[236:237], off offset:512
	global_load_dwordx4 v[198:201], v[238:239], off offset:512
	v_or_b32_e32 v146, s16, v134
	v_mov_b32_e32 v147, s17
	v_lshlrev_b64 v[146:147], 2, v[146:147]
	v_lshl_add_u64 v[204:205], s[78:79], 0, v[150:151]
	v_lshl_add_u64 v[204:205], v[204:205], 0, v[146:147]
	v_lshl_add_u64 v[202:203], s[78:79], 0, v[202:203]
	v_or_b32_e32 v206, 0x20000, v150
	v_mov_b32_e32 v207, v151
	s_waitcnt vmcnt(0)
	v_lshl_add_u64 v[202:203], v[202:203], 0, v[146:147]
	v_lshl_add_u64 v[208:209], v[148:149], 0, v[206:207]
	s_and_b64 vcc, exec, s[4:5]
	s_mov_b32 s53, s51
	s_mov_b64 s[18:19], s[8:9]
	s_mov_b64 s[20:21], s[6:7]
	s_mov_b32 s16, s52
	s_waitcnt vmcnt(0)
	v_mov_b32_dpp v224, v168 row_ror:8 row_mask:0xf bank_mask:0xf
	v_mov_b32_dpp v225, v169 row_ror:8 row_mask:0xf bank_mask:0xf
	v_mov_b32_dpp v226, v170 row_ror:8 row_mask:0xf bank_mask:0xf
	v_mov_b32_dpp v227, v171 row_ror:8 row_mask:0xf bank_mask:0xf
	v_mov_b32_dpp v168, v172 row_ror:8 row_mask:0xf bank_mask:0xc
	v_mov_b32_dpp v169, v173 row_ror:8 row_mask:0xf bank_mask:0xc
	v_mov_b32_dpp v170, v174 row_ror:8 row_mask:0xf bank_mask:0xc
	v_mov_b32_dpp v171, v175 row_ror:8 row_mask:0xf bank_mask:0xc
	v_mov_b32_dpp v172, v224 quad_perm:[0,1,2,3] row_mask:0xf bank_mask:0x3
	v_mov_b32_dpp v173, v225 quad_perm:[0,1,2,3] row_mask:0xf bank_mask:0x3
	v_mov_b32_dpp v174, v226 quad_perm:[0,1,2,3] row_mask:0xf bank_mask:0x3
	v_mov_b32_dpp v175, v227 quad_perm:[0,1,2,3] row_mask:0xf bank_mask:0x3
	v_mov_b32_dpp v224, v178 row_ror:8 row_mask:0xf bank_mask:0xf
	v_mov_b32_dpp v225, v179 row_ror:8 row_mask:0xf bank_mask:0xf
	v_mov_b32_dpp v226, v180 row_ror:8 row_mask:0xf bank_mask:0xf
	v_mov_b32_dpp v227, v181 row_ror:8 row_mask:0xf bank_mask:0xf
	v_mov_b32_dpp v178, v182 row_ror:8 row_mask:0xf bank_mask:0xc
	v_mov_b32_dpp v179, v183 row_ror:8 row_mask:0xf bank_mask:0xc
	v_mov_b32_dpp v180, v184 row_ror:8 row_mask:0xf bank_mask:0xc
	v_mov_b32_dpp v181, v185 row_ror:8 row_mask:0xf bank_mask:0xc
	v_mov_b32_dpp v182, v224 quad_perm:[0,1,2,3] row_mask:0xf bank_mask:0x3
	v_mov_b32_dpp v183, v225 quad_perm:[0,1,2,3] row_mask:0xf bank_mask:0x3
	v_mov_b32_dpp v184, v226 quad_perm:[0,1,2,3] row_mask:0xf bank_mask:0x3
	v_mov_b32_dpp v185, v227 quad_perm:[0,1,2,3] row_mask:0xf bank_mask:0x3
	v_pk_fma_f32 v[126:127], v[126:127], 0.5, v[170:171] op_sel_hi:[1,0,1]
	v_pk_fma_f32 v[124:125], v[124:125], 0.5, v[168:169] op_sel_hi:[1,0,1]
	v_pk_fma_f32 v[122:123], v[122:123], 0.5, v[174:175] op_sel_hi:[1,0,1]
	v_pk_fma_f32 v[106:107], v[106:107], 0.5, v[184:185] op_sel_hi:[1,0,1]
	v_pk_fma_f32 v[104:105], v[104:105], 0.5, v[182:183] op_sel_hi:[1,0,1]
	v_pk_fma_f32 v[120:121], v[120:121], 0.5, v[172:173] op_sel_hi:[1,0,1]
	v_pk_fma_f32 v[110:111], v[110:111], 0.5, v[180:181] op_sel_hi:[1,0,1]
	v_pk_fma_f32 v[108:109], v[108:109], 0.5, v[178:179] op_sel_hi:[1,0,1]
	global_store_dwordx4 v[204:205], v[124:127], off
	global_store_dwordx4 v[204:205], v[120:123], off offset:64
	global_store_dwordx4 v[204:205], v[108:111], off offset:512
	global_store_dwordx4 v[204:205], v[104:107], off offset:576
	v_or_b32_e32 v168, 0x30000, v150
	v_mov_b32_e32 v169, v151
	v_mov_b32_dpp v224, v186 row_ror:8 row_mask:0xf bank_mask:0xf
	v_mov_b32_dpp v225, v187 row_ror:8 row_mask:0xf bank_mask:0xf
	v_mov_b32_dpp v226, v188 row_ror:8 row_mask:0xf bank_mask:0xf
	v_mov_b32_dpp v227, v189 row_ror:8 row_mask:0xf bank_mask:0xf
	v_mov_b32_dpp v186, v190 row_ror:8 row_mask:0xf bank_mask:0xc
	v_mov_b32_dpp v187, v191 row_ror:8 row_mask:0xf bank_mask:0xc
	v_mov_b32_dpp v188, v192 row_ror:8 row_mask:0xf bank_mask:0xc
	v_mov_b32_dpp v189, v193 row_ror:8 row_mask:0xf bank_mask:0xc
	v_mov_b32_dpp v190, v224 quad_perm:[0,1,2,3] row_mask:0xf bank_mask:0x3
	v_mov_b32_dpp v191, v225 quad_perm:[0,1,2,3] row_mask:0xf bank_mask:0x3
	v_mov_b32_dpp v192, v226 quad_perm:[0,1,2,3] row_mask:0xf bank_mask:0x3
	v_mov_b32_dpp v193, v227 quad_perm:[0,1,2,3] row_mask:0xf bank_mask:0x3
	v_mov_b32_dpp v224, v194 row_ror:8 row_mask:0xf bank_mask:0xf
	v_mov_b32_dpp v225, v195 row_ror:8 row_mask:0xf bank_mask:0xf
	v_mov_b32_dpp v226, v196 row_ror:8 row_mask:0xf bank_mask:0xf
	v_mov_b32_dpp v227, v197 row_ror:8 row_mask:0xf bank_mask:0xf
	v_mov_b32_dpp v194, v198 row_ror:8 row_mask:0xf bank_mask:0xc
	v_mov_b32_dpp v195, v199 row_ror:8 row_mask:0xf bank_mask:0xc
	v_mov_b32_dpp v196, v200 row_ror:8 row_mask:0xf bank_mask:0xc
	v_mov_b32_dpp v197, v201 row_ror:8 row_mask:0xf bank_mask:0xc
	v_mov_b32_dpp v198, v224 quad_perm:[0,1,2,3] row_mask:0xf bank_mask:0x3
	v_mov_b32_dpp v199, v225 quad_perm:[0,1,2,3] row_mask:0xf bank_mask:0x3
	v_mov_b32_dpp v200, v226 quad_perm:[0,1,2,3] row_mask:0xf bank_mask:0x3
	v_mov_b32_dpp v201, v227 quad_perm:[0,1,2,3] row_mask:0xf bank_mask:0x3
	v_pk_fma_f32 v[106:107], v[118:119], 0.5, v[188:189] op_sel_hi:[1,0,1]
	v_pk_fma_f32 v[104:105], v[116:117], 0.5, v[186:187] op_sel_hi:[1,0,1]
	v_pk_fma_f32 v[110:111], v[114:115], 0.5, v[192:193] op_sel_hi:[1,0,1]
	v_pk_fma_f32 v[108:109], v[112:113], 0.5, v[190:191] op_sel_hi:[1,0,1]
	v_pk_fma_f32 v[102:103], v[102:103], 0.5, v[196:197] op_sel_hi:[1,0,1]
	v_pk_fma_f32 v[100:101], v[100:101], 0.5, v[194:195] op_sel_hi:[1,0,1]
	v_pk_fma_f32 v[98:99], v[98:99], 0.5, v[200:201] op_sel_hi:[1,0,1]
	v_pk_fma_f32 v[96:97], v[96:97], 0.5, v[198:199] op_sel_hi:[1,0,1]
	global_store_dwordx4 v[202:203], v[104:107], off
	global_store_dwordx4 v[202:203], v[108:111], off offset:64
	global_store_dwordx4 v[202:203], v[100:103], off offset:512
	global_store_dwordx4 v[202:203], v[96:99], off offset:576
	v_lshl_add_u64 v[124:125], v[148:149], 0, v[168:169]
	v_lshl_add_u64 v[232:233], v[208:209], 0, v[248:249]
	v_lshl_add_u64 v[234:235], v[232:233], 0, v[250:251]
	global_load_dwordx4 v[96:99], v[232:233], off
	global_load_dwordx4 v[100:103], v[234:235], off
	global_load_dwordx4 v[104:107], v[232:233], off offset:512
	global_load_dwordx4 v[108:111], v[234:235], off offset:512
	v_lshl_add_u64 v[236:237], v[124:125], 0, v[248:249]
	v_lshl_add_u64 v[238:239], v[236:237], 0, v[250:251]
	global_load_dwordx4 v[112:115], v[236:237], off
	global_load_dwordx4 v[116:119], v[238:239], off
	global_load_dwordx4 v[120:123], v[236:237], off offset:512
	s_nop 0
	global_load_dwordx4 v[124:127], v[238:239], off offset:512
	v_lshl_add_u64 v[172:173], s[78:79], 0, v[206:207]
	v_lshl_add_u64 v[170:171], v[150:151], 0, s[10:11]
	v_lshl_add_u64 v[168:169], s[78:79], 0, v[168:169]
	v_lshl_add_u64 v[172:173], v[172:173], 0, v[146:147]
	v_lshl_add_u64 v[174:175], v[148:149], 0, v[170:171]
	v_lshl_add_u64 v[168:169], v[168:169], 0, v[146:147]
	s_waitcnt vmcnt(0)
	s_waitcnt vmcnt(0)
	v_mov_b32_dpp v224, v96 row_ror:8 row_mask:0xf bank_mask:0xf
	v_mov_b32_dpp v225, v97 row_ror:8 row_mask:0xf bank_mask:0xf
	v_mov_b32_dpp v226, v98 row_ror:8 row_mask:0xf bank_mask:0xf
	v_mov_b32_dpp v227, v99 row_ror:8 row_mask:0xf bank_mask:0xf
	v_mov_b32_dpp v96, v100 row_ror:8 row_mask:0xf bank_mask:0xc
	v_mov_b32_dpp v97, v101 row_ror:8 row_mask:0xf bank_mask:0xc
	v_mov_b32_dpp v98, v102 row_ror:8 row_mask:0xf bank_mask:0xc
	v_mov_b32_dpp v99, v103 row_ror:8 row_mask:0xf bank_mask:0xc
	v_mov_b32_dpp v100, v224 quad_perm:[0,1,2,3] row_mask:0xf bank_mask:0x3
	v_mov_b32_dpp v101, v225 quad_perm:[0,1,2,3] row_mask:0xf bank_mask:0x3
	v_mov_b32_dpp v102, v226 quad_perm:[0,1,2,3] row_mask:0xf bank_mask:0x3
	v_mov_b32_dpp v103, v227 quad_perm:[0,1,2,3] row_mask:0xf bank_mask:0x3
	v_mov_b32_dpp v224, v104 row_ror:8 row_mask:0xf bank_mask:0xf
	v_mov_b32_dpp v225, v105 row_ror:8 row_mask:0xf bank_mask:0xf
	v_mov_b32_dpp v226, v106 row_ror:8 row_mask:0xf bank_mask:0xf
	v_mov_b32_dpp v227, v107 row_ror:8 row_mask:0xf bank_mask:0xf
	v_mov_b32_dpp v104, v108 row_ror:8 row_mask:0xf bank_mask:0xc
	v_mov_b32_dpp v105, v109 row_ror:8 row_mask:0xf bank_mask:0xc
	v_mov_b32_dpp v106, v110 row_ror:8 row_mask:0xf bank_mask:0xc
	v_mov_b32_dpp v107, v111 row_ror:8 row_mask:0xf bank_mask:0xc
	v_mov_b32_dpp v108, v224 quad_perm:[0,1,2,3] row_mask:0xf bank_mask:0x3
	v_mov_b32_dpp v109, v225 quad_perm:[0,1,2,3] row_mask:0xf bank_mask:0x3
	v_mov_b32_dpp v110, v226 quad_perm:[0,1,2,3] row_mask:0xf bank_mask:0x3
	v_mov_b32_dpp v111, v227 quad_perm:[0,1,2,3] row_mask:0xf bank_mask:0x3
	v_pk_fma_f32 v[94:95], v[94:95], 0.5, v[98:99] op_sel_hi:[1,0,1]
	v_pk_fma_f32 v[92:93], v[92:93], 0.5, v[96:97] op_sel_hi:[1,0,1]
	v_lshl_add_u64 v[96:97], v[150:151], 0, s[12:13]
	v_pk_fma_f32 v[90:91], v[90:91], 0.5, v[102:103] op_sel_hi:[1,0,1]
	v_pk_fma_f32 v[88:89], v[88:89], 0.5, v[100:101] op_sel_hi:[1,0,1]
	v_pk_fma_f32 v[78:79], v[78:79], 0.5, v[106:107] op_sel_hi:[1,0,1]
	v_pk_fma_f32 v[76:77], v[76:77], 0.5, v[104:105] op_sel_hi:[1,0,1]
	v_pk_fma_f32 v[74:75], v[74:75], 0.5, v[110:111] op_sel_hi:[1,0,1]
	v_pk_fma_f32 v[72:73], v[72:73], 0.5, v[108:109] op_sel_hi:[1,0,1]
	v_mov_b32_dpp v224, v112 row_ror:8 row_mask:0xf bank_mask:0xf
	v_mov_b32_dpp v225, v113 row_ror:8 row_mask:0xf bank_mask:0xf
	v_mov_b32_dpp v226, v114 row_ror:8 row_mask:0xf bank_mask:0xf
	v_mov_b32_dpp v227, v115 row_ror:8 row_mask:0xf bank_mask:0xf
	v_mov_b32_dpp v112, v116 row_ror:8 row_mask:0xf bank_mask:0xc
	v_mov_b32_dpp v113, v117 row_ror:8 row_mask:0xf bank_mask:0xc
	v_mov_b32_dpp v114, v118 row_ror:8 row_mask:0xf bank_mask:0xc
	v_mov_b32_dpp v115, v119 row_ror:8 row_mask:0xf bank_mask:0xc
	v_mov_b32_dpp v116, v224 quad_perm:[0,1,2,3] row_mask:0xf bank_mask:0x3
	v_mov_b32_dpp v117, v225 quad_perm:[0,1,2,3] row_mask:0xf bank_mask:0x3
	v_mov_b32_dpp v118, v226 quad_perm:[0,1,2,3] row_mask:0xf bank_mask:0x3
	v_mov_b32_dpp v119, v227 quad_perm:[0,1,2,3] row_mask:0xf bank_mask:0x3
	v_mov_b32_dpp v224, v120 row_ror:8 row_mask:0xf bank_mask:0xf
	v_mov_b32_dpp v225, v121 row_ror:8 row_mask:0xf bank_mask:0xf
	v_mov_b32_dpp v226, v122 row_ror:8 row_mask:0xf bank_mask:0xf
	v_mov_b32_dpp v227, v123 row_ror:8 row_mask:0xf bank_mask:0xf
	v_mov_b32_dpp v120, v124 row_ror:8 row_mask:0xf bank_mask:0xc
	v_mov_b32_dpp v121, v125 row_ror:8 row_mask:0xf bank_mask:0xc
	v_mov_b32_dpp v122, v126 row_ror:8 row_mask:0xf bank_mask:0xc
	v_mov_b32_dpp v123, v127 row_ror:8 row_mask:0xf bank_mask:0xc
	v_mov_b32_dpp v124, v224 quad_perm:[0,1,2,3] row_mask:0xf bank_mask:0x3
	v_mov_b32_dpp v125, v225 quad_perm:[0,1,2,3] row_mask:0xf bank_mask:0x3
	v_mov_b32_dpp v126, v226 quad_perm:[0,1,2,3] row_mask:0xf bank_mask:0x3
	v_mov_b32_dpp v127, v227 quad_perm:[0,1,2,3] row_mask:0xf bank_mask:0x3
	v_pk_fma_f32 v[86:87], v[86:87], 0.5, v[114:115] op_sel_hi:[1,0,1]
	v_pk_fma_f32 v[84:85], v[84:85], 0.5, v[112:113] op_sel_hi:[1,0,1]
	v_pk_fma_f32 v[82:83], v[82:83], 0.5, v[118:119] op_sel_hi:[1,0,1]
	v_pk_fma_f32 v[80:81], v[80:81], 0.5, v[116:117] op_sel_hi:[1,0,1]
	v_pk_fma_f32 v[70:71], v[70:71], 0.5, v[122:123] op_sel_hi:[1,0,1]
	v_pk_fma_f32 v[68:69], v[68:69], 0.5, v[120:121] op_sel_hi:[1,0,1]
	v_pk_fma_f32 v[66:67], v[66:67], 0.5, v[126:127] op_sel_hi:[1,0,1]
	v_pk_fma_f32 v[64:65], v[64:65], 0.5, v[124:125] op_sel_hi:[1,0,1]
	global_store_dwordx4 v[172:173], v[92:95], off
	global_store_dwordx4 v[172:173], v[88:91], off offset:64
	global_store_dwordx4 v[172:173], v[76:79], off offset:512
	global_store_dwordx4 v[172:173], v[72:75], off offset:576
	global_store_dwordx4 v[168:169], v[84:87], off
	global_store_dwordx4 v[168:169], v[80:83], off offset:64
	global_store_dwordx4 v[168:169], v[68:71], off offset:512
	global_store_dwordx4 v[168:169], v[64:67], off offset:576
	v_lshl_add_u64 v[92:93], v[148:149], 0, v[96:97]
	v_lshl_add_u64 v[232:233], v[174:175], 0, v[248:249]
	v_lshl_add_u64 v[234:235], v[232:233], 0, v[250:251]
	global_load_dwordx4 v[64:67], v[232:233], off
	global_load_dwordx4 v[68:71], v[234:235], off
	global_load_dwordx4 v[72:75], v[232:233], off offset:512
	global_load_dwordx4 v[76:79], v[234:235], off offset:512
	v_lshl_add_u64 v[236:237], v[92:93], 0, v[248:249]
	v_lshl_add_u64 v[238:239], v[236:237], 0, v[250:251]
	global_load_dwordx4 v[80:83], v[236:237], off
	global_load_dwordx4 v[84:87], v[238:239], off
	global_load_dwordx4 v[88:91], v[236:237], off offset:512
	s_nop 0
	global_load_dwordx4 v[92:95], v[238:239], off offset:512
	v_lshl_add_u64 v[100:101], s[78:79], 0, v[170:171]
	v_lshl_add_u64 v[98:99], v[150:151], 0, s[14:15]
	v_lshl_add_u64 v[96:97], s[78:79], 0, v[96:97]
	v_lshl_add_u64 v[100:101], v[100:101], 0, v[146:147]
	v_lshl_add_u64 v[102:103], v[148:149], 0, v[98:99]
	v_lshl_add_u64 v[96:97], v[96:97], 0, v[146:147]
	s_waitcnt vmcnt(0)
	s_waitcnt vmcnt(0)
	v_mov_b32_dpp v224, v64 row_ror:8 row_mask:0xf bank_mask:0xf
	v_mov_b32_dpp v225, v65 row_ror:8 row_mask:0xf bank_mask:0xf
	v_mov_b32_dpp v226, v66 row_ror:8 row_mask:0xf bank_mask:0xf
	v_mov_b32_dpp v227, v67 row_ror:8 row_mask:0xf bank_mask:0xf
	v_mov_b32_dpp v64, v68 row_ror:8 row_mask:0xf bank_mask:0xc
	v_mov_b32_dpp v65, v69 row_ror:8 row_mask:0xf bank_mask:0xc
	v_mov_b32_dpp v66, v70 row_ror:8 row_mask:0xf bank_mask:0xc
	v_mov_b32_dpp v67, v71 row_ror:8 row_mask:0xf bank_mask:0xc
	v_mov_b32_dpp v68, v224 quad_perm:[0,1,2,3] row_mask:0xf bank_mask:0x3
	v_mov_b32_dpp v69, v225 quad_perm:[0,1,2,3] row_mask:0xf bank_mask:0x3
	v_mov_b32_dpp v70, v226 quad_perm:[0,1,2,3] row_mask:0xf bank_mask:0x3
	v_mov_b32_dpp v71, v227 quad_perm:[0,1,2,3] row_mask:0xf bank_mask:0x3
	v_mov_b32_dpp v224, v72 row_ror:8 row_mask:0xf bank_mask:0xf
	v_mov_b32_dpp v225, v73 row_ror:8 row_mask:0xf bank_mask:0xf
	v_mov_b32_dpp v226, v74 row_ror:8 row_mask:0xf bank_mask:0xf
	v_mov_b32_dpp v227, v75 row_ror:8 row_mask:0xf bank_mask:0xf
	v_mov_b32_dpp v72, v76 row_ror:8 row_mask:0xf bank_mask:0xc
	v_mov_b32_dpp v73, v77 row_ror:8 row_mask:0xf bank_mask:0xc
	v_mov_b32_dpp v74, v78 row_ror:8 row_mask:0xf bank_mask:0xc
	v_mov_b32_dpp v75, v79 row_ror:8 row_mask:0xf bank_mask:0xc
	v_mov_b32_dpp v76, v224 quad_perm:[0,1,2,3] row_mask:0xf bank_mask:0x3
	v_mov_b32_dpp v77, v225 quad_perm:[0,1,2,3] row_mask:0xf bank_mask:0x3
	v_mov_b32_dpp v78, v226 quad_perm:[0,1,2,3] row_mask:0xf bank_mask:0x3
	v_mov_b32_dpp v79, v227 quad_perm:[0,1,2,3] row_mask:0xf bank_mask:0x3
	v_pk_fma_f32 v[62:63], v[62:63], 0.5, v[66:67] op_sel_hi:[1,0,1]
	v_pk_fma_f32 v[60:61], v[60:61], 0.5, v[64:65] op_sel_hi:[1,0,1]
	v_lshl_add_u64 v[64:65], v[150:151], 0, s[0:1]
	v_pk_fma_f32 v[58:59], v[58:59], 0.5, v[70:71] op_sel_hi:[1,0,1]
	v_pk_fma_f32 v[56:57], v[56:57], 0.5, v[68:69] op_sel_hi:[1,0,1]
	v_pk_fma_f32 v[46:47], v[46:47], 0.5, v[74:75] op_sel_hi:[1,0,1]
	v_pk_fma_f32 v[44:45], v[44:45], 0.5, v[72:73] op_sel_hi:[1,0,1]
	v_pk_fma_f32 v[42:43], v[42:43], 0.5, v[78:79] op_sel_hi:[1,0,1]
	v_pk_fma_f32 v[40:41], v[40:41], 0.5, v[76:77] op_sel_hi:[1,0,1]
	v_mov_b32_dpp v224, v80 row_ror:8 row_mask:0xf bank_mask:0xf
	v_mov_b32_dpp v225, v81 row_ror:8 row_mask:0xf bank_mask:0xf
	v_mov_b32_dpp v226, v82 row_ror:8 row_mask:0xf bank_mask:0xf
	v_mov_b32_dpp v227, v83 row_ror:8 row_mask:0xf bank_mask:0xf
	v_mov_b32_dpp v80, v84 row_ror:8 row_mask:0xf bank_mask:0xc
	v_mov_b32_dpp v81, v85 row_ror:8 row_mask:0xf bank_mask:0xc
	v_mov_b32_dpp v82, v86 row_ror:8 row_mask:0xf bank_mask:0xc
	v_mov_b32_dpp v83, v87 row_ror:8 row_mask:0xf bank_mask:0xc
	v_mov_b32_dpp v84, v224 quad_perm:[0,1,2,3] row_mask:0xf bank_mask:0x3
	v_mov_b32_dpp v85, v225 quad_perm:[0,1,2,3] row_mask:0xf bank_mask:0x3
	v_mov_b32_dpp v86, v226 quad_perm:[0,1,2,3] row_mask:0xf bank_mask:0x3
	v_mov_b32_dpp v87, v227 quad_perm:[0,1,2,3] row_mask:0xf bank_mask:0x3
	v_mov_b32_dpp v224, v88 row_ror:8 row_mask:0xf bank_mask:0xf
	v_mov_b32_dpp v225, v89 row_ror:8 row_mask:0xf bank_mask:0xf
	v_mov_b32_dpp v226, v90 row_ror:8 row_mask:0xf bank_mask:0xf
	v_mov_b32_dpp v227, v91 row_ror:8 row_mask:0xf bank_mask:0xf
	v_mov_b32_dpp v88, v92 row_ror:8 row_mask:0xf bank_mask:0xc
	v_mov_b32_dpp v89, v93 row_ror:8 row_mask:0xf bank_mask:0xc
	v_mov_b32_dpp v90, v94 row_ror:8 row_mask:0xf bank_mask:0xc
	v_mov_b32_dpp v91, v95 row_ror:8 row_mask:0xf bank_mask:0xc
	v_mov_b32_dpp v92, v224 quad_perm:[0,1,2,3] row_mask:0xf bank_mask:0x3
	v_mov_b32_dpp v93, v225 quad_perm:[0,1,2,3] row_mask:0xf bank_mask:0x3
	v_mov_b32_dpp v94, v226 quad_perm:[0,1,2,3] row_mask:0xf bank_mask:0x3
	v_mov_b32_dpp v95, v227 quad_perm:[0,1,2,3] row_mask:0xf bank_mask:0x3
	v_pk_fma_f32 v[54:55], v[54:55], 0.5, v[82:83] op_sel_hi:[1,0,1]
	v_pk_fma_f32 v[52:53], v[52:53], 0.5, v[80:81] op_sel_hi:[1,0,1]
	v_pk_fma_f32 v[50:51], v[50:51], 0.5, v[86:87] op_sel_hi:[1,0,1]
	v_pk_fma_f32 v[48:49], v[48:49], 0.5, v[84:85] op_sel_hi:[1,0,1]
	v_pk_fma_f32 v[38:39], v[38:39], 0.5, v[90:91] op_sel_hi:[1,0,1]
	v_pk_fma_f32 v[36:37], v[36:37], 0.5, v[88:89] op_sel_hi:[1,0,1]
	v_pk_fma_f32 v[34:35], v[34:35], 0.5, v[94:95] op_sel_hi:[1,0,1]
	v_pk_fma_f32 v[32:33], v[32:33], 0.5, v[92:93] op_sel_hi:[1,0,1]
	global_store_dwordx4 v[100:101], v[60:63], off
	global_store_dwordx4 v[100:101], v[56:59], off offset:64
	global_store_dwordx4 v[100:101], v[44:47], off offset:512
	global_store_dwordx4 v[100:101], v[40:43], off offset:576
	global_store_dwordx4 v[96:97], v[52:55], off
	global_store_dwordx4 v[96:97], v[48:51], off offset:64
	global_store_dwordx4 v[96:97], v[36:39], off offset:512
	global_store_dwordx4 v[96:97], v[32:35], off offset:576
	v_lshl_add_u64 v[60:61], v[148:149], 0, v[64:65]
	v_lshl_add_u64 v[232:233], v[102:103], 0, v[248:249]
	v_lshl_add_u64 v[234:235], v[232:233], 0, v[250:251]
	global_load_dwordx4 v[32:35], v[232:233], off
	global_load_dwordx4 v[36:39], v[234:235], off
	global_load_dwordx4 v[40:43], v[232:233], off offset:512
	global_load_dwordx4 v[44:47], v[234:235], off offset:512
	v_lshl_add_u64 v[236:237], v[60:61], 0, v[248:249]
	v_lshl_add_u64 v[238:239], v[236:237], 0, v[250:251]
	global_load_dwordx4 v[48:51], v[236:237], off
	global_load_dwordx4 v[52:55], v[238:239], off
	global_load_dwordx4 v[56:59], v[236:237], off offset:512
	s_nop 0
	global_load_dwordx4 v[60:63], v[238:239], off offset:512
	s_waitcnt vmcnt(0)
	v_lshl_add_u64 v[66:67], s[78:79], 0, v[98:99]
	v_lshl_add_u64 v[64:65], s[78:79], 0, v[64:65]
	v_lshl_add_u64 v[66:67], v[66:67], 0, v[146:147]
	v_lshl_add_u64 v[64:65], v[64:65], 0, v[146:147]
	s_waitcnt vmcnt(0)
	v_mov_b32_dpp v224, v32 row_ror:8 row_mask:0xf bank_mask:0xf
	v_mov_b32_dpp v225, v33 row_ror:8 row_mask:0xf bank_mask:0xf
	v_mov_b32_dpp v226, v34 row_ror:8 row_mask:0xf bank_mask:0xf
	v_mov_b32_dpp v227, v35 row_ror:8 row_mask:0xf bank_mask:0xf
	v_mov_b32_dpp v32, v36 row_ror:8 row_mask:0xf bank_mask:0xc
	v_mov_b32_dpp v33, v37 row_ror:8 row_mask:0xf bank_mask:0xc
	v_mov_b32_dpp v34, v38 row_ror:8 row_mask:0xf bank_mask:0xc
	v_mov_b32_dpp v35, v39 row_ror:8 row_mask:0xf bank_mask:0xc
	v_mov_b32_dpp v36, v224 quad_perm:[0,1,2,3] row_mask:0xf bank_mask:0x3
	v_mov_b32_dpp v37, v225 quad_perm:[0,1,2,3] row_mask:0xf bank_mask:0x3
	v_mov_b32_dpp v38, v226 quad_perm:[0,1,2,3] row_mask:0xf bank_mask:0x3
	v_mov_b32_dpp v39, v227 quad_perm:[0,1,2,3] row_mask:0xf bank_mask:0x3
	v_mov_b32_dpp v224, v40 row_ror:8 row_mask:0xf bank_mask:0xf
	v_mov_b32_dpp v225, v41 row_ror:8 row_mask:0xf bank_mask:0xf
	v_mov_b32_dpp v226, v42 row_ror:8 row_mask:0xf bank_mask:0xf
	v_mov_b32_dpp v227, v43 row_ror:8 row_mask:0xf bank_mask:0xf
	v_mov_b32_dpp v40, v44 row_ror:8 row_mask:0xf bank_mask:0xc
	v_mov_b32_dpp v41, v45 row_ror:8 row_mask:0xf bank_mask:0xc
	v_mov_b32_dpp v42, v46 row_ror:8 row_mask:0xf bank_mask:0xc
	v_mov_b32_dpp v43, v47 row_ror:8 row_mask:0xf bank_mask:0xc
	v_mov_b32_dpp v44, v224 quad_perm:[0,1,2,3] row_mask:0xf bank_mask:0x3
	v_mov_b32_dpp v45, v225 quad_perm:[0,1,2,3] row_mask:0xf bank_mask:0x3
	v_mov_b32_dpp v46, v226 quad_perm:[0,1,2,3] row_mask:0xf bank_mask:0x3
	v_mov_b32_dpp v47, v227 quad_perm:[0,1,2,3] row_mask:0xf bank_mask:0x3
	v_pk_fma_f32 v[30:31], v[30:31], 0.5, v[34:35] op_sel_hi:[1,0,1]
	v_pk_fma_f32 v[28:29], v[28:29], 0.5, v[32:33] op_sel_hi:[1,0,1]
	v_pk_fma_f32 v[26:27], v[26:27], 0.5, v[38:39] op_sel_hi:[1,0,1]
	v_pk_fma_f32 v[24:25], v[24:25], 0.5, v[36:37] op_sel_hi:[1,0,1]
	v_pk_fma_f32 v[14:15], v[14:15], 0.5, v[42:43] op_sel_hi:[1,0,1]
	v_pk_fma_f32 v[12:13], v[12:13], 0.5, v[40:41] op_sel_hi:[1,0,1]
	v_pk_fma_f32 v[10:11], v[10:11], 0.5, v[46:47] op_sel_hi:[1,0,1]
	v_pk_fma_f32 v[8:9], v[8:9], 0.5, v[44:45] op_sel_hi:[1,0,1]
	v_mov_b32_dpp v224, v48 row_ror:8 row_mask:0xf bank_mask:0xf
	v_mov_b32_dpp v225, v49 row_ror:8 row_mask:0xf bank_mask:0xf
	v_mov_b32_dpp v226, v50 row_ror:8 row_mask:0xf bank_mask:0xf
	v_mov_b32_dpp v227, v51 row_ror:8 row_mask:0xf bank_mask:0xf
	v_mov_b32_dpp v48, v52 row_ror:8 row_mask:0xf bank_mask:0xc
	v_mov_b32_dpp v49, v53 row_ror:8 row_mask:0xf bank_mask:0xc
	v_mov_b32_dpp v50, v54 row_ror:8 row_mask:0xf bank_mask:0xc
	v_mov_b32_dpp v51, v55 row_ror:8 row_mask:0xf bank_mask:0xc
	v_mov_b32_dpp v52, v224 quad_perm:[0,1,2,3] row_mask:0xf bank_mask:0x3
	v_mov_b32_dpp v53, v225 quad_perm:[0,1,2,3] row_mask:0xf bank_mask:0x3
	v_mov_b32_dpp v54, v226 quad_perm:[0,1,2,3] row_mask:0xf bank_mask:0x3
	v_mov_b32_dpp v55, v227 quad_perm:[0,1,2,3] row_mask:0xf bank_mask:0x3
	v_mov_b32_dpp v224, v56 row_ror:8 row_mask:0xf bank_mask:0xf
	v_mov_b32_dpp v225, v57 row_ror:8 row_mask:0xf bank_mask:0xf
	v_mov_b32_dpp v226, v58 row_ror:8 row_mask:0xf bank_mask:0xf
	v_mov_b32_dpp v227, v59 row_ror:8 row_mask:0xf bank_mask:0xf
	v_mov_b32_dpp v56, v60 row_ror:8 row_mask:0xf bank_mask:0xc
	v_mov_b32_dpp v57, v61 row_ror:8 row_mask:0xf bank_mask:0xc
	v_mov_b32_dpp v58, v62 row_ror:8 row_mask:0xf bank_mask:0xc
	v_mov_b32_dpp v59, v63 row_ror:8 row_mask:0xf bank_mask:0xc
	v_mov_b32_dpp v60, v224 quad_perm:[0,1,2,3] row_mask:0xf bank_mask:0x3
	v_mov_b32_dpp v61, v225 quad_perm:[0,1,2,3] row_mask:0xf bank_mask:0x3
	v_mov_b32_dpp v62, v226 quad_perm:[0,1,2,3] row_mask:0xf bank_mask:0x3
	v_mov_b32_dpp v63, v227 quad_perm:[0,1,2,3] row_mask:0xf bank_mask:0x3
	v_pk_fma_f32 v[22:23], v[22:23], 0.5, v[50:51] op_sel_hi:[1,0,1]
	v_pk_fma_f32 v[20:21], v[20:21], 0.5, v[48:49] op_sel_hi:[1,0,1]
	v_pk_fma_f32 v[18:19], v[18:19], 0.5, v[54:55] op_sel_hi:[1,0,1]
	v_pk_fma_f32 v[16:17], v[16:17], 0.5, v[52:53] op_sel_hi:[1,0,1]
	v_pk_fma_f32 v[6:7], v[6:7], 0.5, v[58:59] op_sel_hi:[1,0,1]
	v_pk_fma_f32 v[4:5], v[4:5], 0.5, v[56:57] op_sel_hi:[1,0,1]
	v_pk_fma_f32 v[2:3], v[2:3], 0.5, v[62:63] op_sel_hi:[1,0,1]
	v_pk_fma_f32 v[0:1], v[0:1], 0.5, v[60:61] op_sel_hi:[1,0,1]
	global_store_dwordx4 v[66:67], v[28:31], off
	global_store_dwordx4 v[66:67], v[24:27], off offset:64
	global_store_dwordx4 v[66:67], v[12:15], off offset:512
	global_store_dwordx4 v[66:67], v[8:11], off offset:576
	global_store_dwordx4 v[64:65], v[20:23], off
	global_store_dwordx4 v[64:65], v[16:19], off offset:64
	global_store_dwordx4 v[64:65], v[4:7], off offset:512
	global_store_dwordx4 v[64:65], v[0:3], off offset:576
	s_cbranch_vccz .LBB0_2312
	s_waitcnt vmcnt(0)
	s_cmpk_gt_u32 s25, 0xff
	s_cbranch_scc1 .LBB0_2327
	s_barrier
